# s_setprio 1 around the MFMA segments of the staggered GEMMs
# baseline (speedup 1.0000x reference)
.Ldn_afdone:
	s_barrier
	s_lshr_b32 s1, s78, 2
	s_lshl_b32 s1, s1, 7
	s_lshl_b32 s2, s0, 8
	s_mul_i32 s3, s2, 0x1600
	s_add_u32 s68, s18, s3
	s_addc_u32 s69, s19, 0
	s_mul_i32 s3, s1, 0x1600
	s_add_u32 s70, s80, s3
	s_addc_u32 s71, s81, 0
	s_lshl_b32 s3, s2, 11
	s_lshl_b32 s12, s1, 1
	s_add_u32 s3, s3, s12
	s_add_u32 s74, s24, s3
	s_addc_u32 s75, s25, 0
	s_add_i32 s12, s0, -12
	s_lshr_b32 s12, s12, 2
	s_cmp_lt_u32 s0, 16
	s_cselect_b32 s12, 0, s12
	s_cselect_b32 s14, s52, s54
	s_cselect_b32 s15, s53, s55
	s_mul_i32 s13, s82, 5
	s_add_i32 s12, s12, s13
	s_mul_i32 s12, s12, 0x6000
	s_add_u32 s12, s12, 0x5000
	s_lshl_b32 s13, s1, 2
	s_add_u32 s12, s12, s13
	s_add_u32 s72, s30, s12
	s_addc_u32 s73, s31, 0
	s_and_b32 s12, s0, 15
	s_lshl_b32 s12, s12, 20
	s_add_u32 s12, s12, s13
	s_add_u32 s14, s14, s12
	s_addc_u32 s15, s15, 0
	s_add_u32 m0, s76, 0x0
	s_nop 0
	global_load_lds_dwordx4 v196, s[68:69]
	s_add_u32 m0, s76, 0x2000
	s_nop 0
	global_load_lds_dwordx4 v197, s[68:69]
	s_add_u32 m0, s76, 0x4000
	s_nop 0
	global_load_lds_dwordx4 v198, s[68:69]
	s_add_u32 m0, s76, 0x6000
	s_nop 0
	global_load_lds_dwordx4 v199, s[68:69]
	s_add_u32 m0, s76, 0x8000
	s_nop 0
	global_load_lds_dwordx4 v196, s[70:71]
	s_add_u32 m0, s76, 0xa000
	s_nop 0
	global_load_lds_dwordx4 v197, s[70:71]
	s_add_u32 s68, s68, 0x80
	s_addc_u32 s69, s69, 0
	s_add_u32 s70, s70, 0x80
	s_addc_u32 s71, s71, 0
	s_add_u32 m0, s76, 0xc000
	s_nop 0
	global_load_lds_dwordx4 v196, s[68:69]
	s_add_u32 m0, s76, 0xe000
	s_nop 0
	global_load_lds_dwordx4 v197, s[68:69]
	s_add_u32 m0, s76, 0x10000
	s_nop 0
	global_load_lds_dwordx4 v198, s[68:69]
	s_add_u32 m0, s76, 0x12000
	s_nop 0
	global_load_lds_dwordx4 v199, s[68:69]
	s_add_u32 m0, s76, 0x14000
	s_nop 0
	global_load_lds_dwordx4 v196, s[70:71]
	s_add_u32 m0, s76, 0x16000
	s_nop 0
	global_load_lds_dwordx4 v197, s[70:71]
	s_add_u32 s68, s68, 0x80
	s_addc_u32 s69, s69, 0
	s_add_u32 s70, s70, 0x80
	s_addc_u32 s71, s71, 0
	s_waitcnt vmcnt(6)
	s_barrier
	s_cmp_ge_u32 s76, 0x1000
	s_cbranch_scc1 .Ldn_streamB
	v_add_u32_e32 v204, 0x0, v200
	v_add_u32_e32 v205, 0x0, v202
	ds_read_b128 v[130:133], v204 offset:0
	ds_read_b128 v[134:137], v204 offset:2048
	ds_read_b128 v[138:141], v204 offset:4096
	ds_read_b128 v[142:145], v204 offset:6144
	ds_read_b128 v[146:149], v205 offset:0
	ds_read_b128 v[150:153], v205 offset:2048
	ds_read_b128 v[154:157], v205 offset:4096
	ds_read_b128 v[158:161], v205 offset:6144
	v_add_u32_e32 v204, 0x0, v201
	v_add_u32_e32 v205, 0x0, v203
	ds_read_b128 v[212:215], v204 offset:0
	ds_read_b128 v[216:219], v204 offset:2048
	ds_read_b128 v[220:223], v204 offset:4096
	ds_read_b128 v[224:227], v204 offset:6144
	ds_read_b128 v[228:231], v205 offset:0
	ds_read_b128 v[232:235], v205 offset:2048
	ds_read_b128 v[236:239], v205 offset:4096
	ds_read_b128 v[240:243], v205 offset:6144
	s_add_u32 m0, s76, 0x18000
	s_nop 0
	global_load_lds_dwordx4 v196, s[68:69]
	s_add_u32 m0, s76, 0x1a000
	s_nop 0
	global_load_lds_dwordx4 v197, s[68:69]
	s_add_u32 m0, s76, 0x1c000
	s_nop 0
	global_load_lds_dwordx4 v198, s[68:69]
	s_add_u32 m0, s76, 0x1e000
	s_nop 0
	global_load_lds_dwordx4 v199, s[68:69]
	s_add_u32 m0, s76, 0x20000
	s_nop 0
	global_load_lds_dwordx4 v196, s[70:71]
	s_add_u32 m0, s76, 0x22000
	s_nop 0
	global_load_lds_dwordx4 v197, s[70:71]
	s_add_u32 s68, s68, 0x80
	s_addc_u32 s69, s69, 0
	s_add_u32 s70, s70, 0x80
	s_addc_u32 s71, s71, 0
	global_load_dwordx4 v[174:177], v190, s[72:73] offset:0
	global_load_dwordx4 v[178:181], v190, s[72:73] offset:64
	global_load_dwordx4 v[182:185], v190, s[72:73] offset:128
	global_load_dwordx4 v[186:189], v190, s[72:73] offset:192
	global_load_dwordx2 v[66:67], v206, s[74:75] offset:0
	global_load_dwordx2 v[70:71], v206, s[74:75] offset:32
	global_load_dwordx2 v[74:75], v206, s[74:75] offset:64
	s_waitcnt lgkmcnt(0)
	s_barrier
	s_setprio 1
	v_mfma_f32_16x16x32_bf16 v[2:5], v[146:149], v[130:133], 0
	v_mfma_f32_16x16x32_bf16 v[6:9], v[150:153], v[130:133], 0
	v_mfma_f32_16x16x32_bf16 v[10:13], v[154:157], v[130:133], 0
	v_mfma_f32_16x16x32_bf16 v[14:17], v[158:161], v[130:133], 0
	v_mfma_f32_16x16x32_bf16 v[18:21], v[146:149], v[134:137], 0
	v_mfma_f32_16x16x32_bf16 v[22:25], v[150:153], v[134:137], 0
	v_mfma_f32_16x16x32_bf16 v[26:29], v[154:157], v[134:137], 0
	v_mfma_f32_16x16x32_bf16 v[30:33], v[158:161], v[134:137], 0
	v_mfma_f32_16x16x32_bf16 v[34:37], v[146:149], v[138:141], 0
	v_mfma_f32_16x16x32_bf16 v[38:41], v[150:153], v[138:141], 0
	v_mfma_f32_16x16x32_bf16 v[42:45], v[154:157], v[138:141], 0
	v_mfma_f32_16x16x32_bf16 v[46:49], v[158:161], v[138:141], 0
	v_mfma_f32_16x16x32_bf16 v[50:53], v[146:149], v[142:145], 0
	v_mfma_f32_16x16x32_bf16 v[54:57], v[150:153], v[142:145], 0
	v_mfma_f32_16x16x32_bf16 v[58:61], v[154:157], v[142:145], 0
	v_mfma_f32_16x16x32_bf16 v[62:65], v[158:161], v[142:145], 0
	v_mfma_f32_16x16x32_bf16 v[2:5], v[228:231], v[212:215], v[2:5]
	v_mfma_f32_16x16x32_bf16 v[6:9], v[232:235], v[212:215], v[6:9]
	v_mfma_f32_16x16x32_bf16 v[10:13], v[236:239], v[212:215], v[10:13]
	v_mfma_f32_16x16x32_bf16 v[14:17], v[240:243], v[212:215], v[14:17]
	v_mfma_f32_16x16x32_bf16 v[18:21], v[228:231], v[216:219], v[18:21]
	v_mfma_f32_16x16x32_bf16 v[22:25], v[232:235], v[216:219], v[22:25]
	v_mfma_f32_16x16x32_bf16 v[26:29], v[236:239], v[216:219], v[26:29]
	v_mfma_f32_16x16x32_bf16 v[30:33], v[240:243], v[216:219], v[30:33]
	v_mfma_f32_16x16x32_bf16 v[34:37], v[228:231], v[220:223], v[34:37]
	v_mfma_f32_16x16x32_bf16 v[38:41], v[232:235], v[220:223], v[38:41]
	v_mfma_f32_16x16x32_bf16 v[42:45], v[236:239], v[220:223], v[42:45]
	v_mfma_f32_16x16x32_bf16 v[46:49], v[240:243], v[220:223], v[46:49]
	v_mfma_f32_16x16x32_bf16 v[50:53], v[228:231], v[224:227], v[50:53]
	v_mfma_f32_16x16x32_bf16 v[54:57], v[232:235], v[224:227], v[54:57]
	v_mfma_f32_16x16x32_bf16 v[58:61], v[236:239], v[224:227], v[58:61]
	v_mfma_f32_16x16x32_bf16 v[62:65], v[240:243], v[224:227], v[62:65]
	s_setprio 0
	s_waitcnt vmcnt(13)
	s_barrier
	v_add_u32_e32 v204, 0xc000, v200
	v_add_u32_e32 v205, 0xc000, v202
	ds_read_b128 v[130:133], v204 offset:0
	ds_read_b128 v[134:137], v204 offset:2048
	ds_read_b128 v[138:141], v204 offset:4096
	ds_read_b128 v[142:145], v204 offset:6144
	ds_read_b128 v[146:149], v205 offset:0
	ds_read_b128 v[150:153], v205 offset:2048
	ds_read_b128 v[154:157], v205 offset:4096
	ds_read_b128 v[158:161], v205 offset:6144
	v_add_u32_e32 v204, 0xc000, v201
	v_add_u32_e32 v205, 0xc000, v203
	ds_read_b128 v[212:215], v204 offset:0
	ds_read_b128 v[216:219], v204 offset:2048
	ds_read_b128 v[220:223], v204 offset:4096
	ds_read_b128 v[224:227], v204 offset:6144
	ds_read_b128 v[228:231], v205 offset:0
	ds_read_b128 v[232:235], v205 offset:2048
	ds_read_b128 v[236:239], v205 offset:4096
	ds_read_b128 v[240:243], v205 offset:6144
	s_add_u32 m0, s76, 0x0
	s_nop 0
	global_load_lds_dwordx4 v196, s[68:69]
	s_add_u32 m0, s76, 0x2000
	s_nop 0
	global_load_lds_dwordx4 v197, s[68:69]
	s_add_u32 m0, s76, 0x4000
	s_nop 0
	global_load_lds_dwordx4 v198, s[68:69]
	s_add_u32 m0, s76, 0x6000
	s_nop 0
	global_load_lds_dwordx4 v199, s[68:69]
	s_add_u32 m0, s76, 0x8000
	s_nop 0
	global_load_lds_dwordx4 v196, s[70:71]
	s_add_u32 m0, s76, 0xa000
	s_nop 0
	global_load_lds_dwordx4 v197, s[70:71]
	s_add_u32 s68, s68, 0x80
	s_addc_u32 s69, s69, 0
	s_add_u32 s70, s70, 0x80
	s_addc_u32 s71, s71, 0
	global_load_dwordx2 v[78:79], v206, s[74:75] offset:96
	global_load_dwordx2 v[82:83], v207, s[74:75] offset:0
	global_load_dwordx2 v[86:87], v207, s[74:75] offset:32
	global_load_dwordx2 v[90:91], v207, s[74:75] offset:64
	global_load_dwordx2 v[94:95], v207, s[74:75] offset:96
	global_load_dwordx2 v[98:99], v208, s[74:75] offset:0
	global_load_dwordx2 v[102:103], v208, s[74:75] offset:32
	s_waitcnt lgkmcnt(0)
	s_barrier
	s_setprio 1
	v_mfma_f32_16x16x32_bf16 v[2:5], v[146:149], v[130:133], v[2:5]
	v_mfma_f32_16x16x32_bf16 v[6:9], v[150:153], v[130:133], v[6:9]
	v_mfma_f32_16x16x32_bf16 v[10:13], v[154:157], v[130:133], v[10:13]
	v_mfma_f32_16x16x32_bf16 v[14:17], v[158:161], v[130:133], v[14:17]
	v_mfma_f32_16x16x32_bf16 v[18:21], v[146:149], v[134:137], v[18:21]
	v_mfma_f32_16x16x32_bf16 v[22:25], v[150:153], v[134:137], v[22:25]
	v_mfma_f32_16x16x32_bf16 v[26:29], v[154:157], v[134:137], v[26:29]
	v_mfma_f32_16x16x32_bf16 v[30:33], v[158:161], v[134:137], v[30:33]
	v_mfma_f32_16x16x32_bf16 v[34:37], v[146:149], v[138:141], v[34:37]
	v_mfma_f32_16x16x32_bf16 v[38:41], v[150:153], v[138:141], v[38:41]
	v_mfma_f32_16x16x32_bf16 v[42:45], v[154:157], v[138:141], v[42:45]
	v_mfma_f32_16x16x32_bf16 v[46:49], v[158:161], v[138:141], v[46:49]
	v_mfma_f32_16x16x32_bf16 v[50:53], v[146:149], v[142:145], v[50:53]
	v_mfma_f32_16x16x32_bf16 v[54:57], v[150:153], v[142:145], v[54:57]
	v_mfma_f32_16x16x32_bf16 v[58:61], v[154:157], v[142:145], v[58:61]
	v_mfma_f32_16x16x32_bf16 v[62:65], v[158:161], v[142:145], v[62:65]
	v_mfma_f32_16x16x32_bf16 v[2:5], v[228:231], v[212:215], v[2:5]
	v_mfma_f32_16x16x32_bf16 v[6:9], v[232:235], v[212:215], v[6:9]
	v_mfma_f32_16x16x32_bf16 v[10:13], v[236:239], v[212:215], v[10:13]
	v_mfma_f32_16x16x32_bf16 v[14:17], v[240:243], v[212:215], v[14:17]
	v_mfma_f32_16x16x32_bf16 v[18:21], v[228:231], v[216:219], v[18:21]
	v_mfma_f32_16x16x32_bf16 v[22:25], v[232:235], v[216:219], v[22:25]
	v_mfma_f32_16x16x32_bf16 v[26:29], v[236:239], v[216:219], v[26:29]
	v_mfma_f32_16x16x32_bf16 v[30:33], v[240:243], v[216:219], v[30:33]
	v_mfma_f32_16x16x32_bf16 v[34:37], v[228:231], v[220:223], v[34:37]
	v_mfma_f32_16x16x32_bf16 v[38:41], v[232:235], v[220:223], v[38:41]
	v_mfma_f32_16x16x32_bf16 v[42:45], v[236:239], v[220:223], v[42:45]
	v_mfma_f32_16x16x32_bf16 v[46:49], v[240:243], v[220:223], v[46:49]
	v_mfma_f32_16x16x32_bf16 v[50:53], v[228:231], v[224:227], v[50:53]
	v_mfma_f32_16x16x32_bf16 v[54:57], v[232:235], v[224:227], v[54:57]
	v_mfma_f32_16x16x32_bf16 v[58:61], v[236:239], v[224:227], v[58:61]
	v_mfma_f32_16x16x32_bf16 v[62:65], v[240:243], v[224:227], v[62:65]
	s_setprio 0
	s_waitcnt vmcnt(20)
	s_barrier
	v_add_u32_e32 v204, 0x18000, v200
	v_add_u32_e32 v205, 0x18000, v202
	ds_read_b128 v[130:133], v204 offset:0
	ds_read_b128 v[134:137], v204 offset:2048
	ds_read_b128 v[138:141], v204 offset:4096
	ds_read_b128 v[142:145], v204 offset:6144
	ds_read_b128 v[146:149], v205 offset:0
	ds_read_b128 v[150:153], v205 offset:2048
	ds_read_b128 v[154:157], v205 offset:4096
	ds_read_b128 v[158:161], v205 offset:6144
	v_add_u32_e32 v204, 0x18000, v201
	v_add_u32_e32 v205, 0x18000, v203
	ds_read_b128 v[212:215], v204 offset:0
	ds_read_b128 v[216:219], v204 offset:2048
	ds_read_b128 v[220:223], v204 offset:4096
	ds_read_b128 v[224:227], v204 offset:6144
	ds_read_b128 v[228:231], v205 offset:0
	ds_read_b128 v[232:235], v205 offset:2048
	ds_read_b128 v[236:239], v205 offset:4096
	ds_read_b128 v[240:243], v205 offset:6144
	s_add_u32 m0, s76, 0xc000
	s_nop 0
	global_load_lds_dwordx4 v196, s[68:69]
	s_add_u32 m0, s76, 0xe000
	s_nop 0
	global_load_lds_dwordx4 v197, s[68:69]
	s_add_u32 m0, s76, 0x10000
	s_nop 0
	global_load_lds_dwordx4 v198, s[68:69]
	s_add_u32 m0, s76, 0x12000
	s_nop 0
	global_load_lds_dwordx4 v199, s[68:69]
	s_add_u32 m0, s76, 0x14000
	s_nop 0
	global_load_lds_dwordx4 v196, s[70:71]
	s_add_u32 m0, s76, 0x16000
	s_nop 0
	global_load_lds_dwordx4 v197, s[70:71]
	s_add_u32 s68, s68, 0x80
	s_addc_u32 s69, s69, 0
	s_add_u32 s70, s70, 0x80
	s_addc_u32 s71, s71, 0
	global_load_dwordx2 v[106:107], v208, s[74:75] offset:64
	global_load_dwordx2 v[110:111], v208, s[74:75] offset:96
	global_load_dwordx2 v[114:115], v209, s[74:75] offset:0
	global_load_dwordx2 v[118:119], v209, s[74:75] offset:32
	global_load_dwordx2 v[122:123], v209, s[74:75] offset:64
	global_load_dwordx2 v[126:127], v209, s[74:75] offset:96
	s_waitcnt lgkmcnt(0)
	s_barrier
	s_setprio 1
	v_mfma_f32_16x16x32_bf16 v[2:5], v[146:149], v[130:133], v[2:5]
	v_mfma_f32_16x16x32_bf16 v[6:9], v[150:153], v[130:133], v[6:9]
	v_mfma_f32_16x16x32_bf16 v[10:13], v[154:157], v[130:133], v[10:13]
	v_mfma_f32_16x16x32_bf16 v[14:17], v[158:161], v[130:133], v[14:17]
	v_mfma_f32_16x16x32_bf16 v[18:21], v[146:149], v[134:137], v[18:21]
	v_mfma_f32_16x16x32_bf16 v[22:25], v[150:153], v[134:137], v[22:25]
	v_mfma_f32_16x16x32_bf16 v[26:29], v[154:157], v[134:137], v[26:29]
	v_mfma_f32_16x16x32_bf16 v[30:33], v[158:161], v[134:137], v[30:33]
	v_mfma_f32_16x16x32_bf16 v[34:37], v[146:149], v[138:141], v[34:37]
	v_mfma_f32_16x16x32_bf16 v[38:41], v[150:153], v[138:141], v[38:41]
	v_mfma_f32_16x16x32_bf16 v[42:45], v[154:157], v[138:141], v[42:45]
	v_mfma_f32_16x16x32_bf16 v[46:49], v[158:161], v[138:141], v[46:49]
	v_mfma_f32_16x16x32_bf16 v[50:53], v[146:149], v[142:145], v[50:53]
	v_mfma_f32_16x16x32_bf16 v[54:57], v[150:153], v[142:145], v[54:57]
	v_mfma_f32_16x16x32_bf16 v[58:61], v[154:157], v[142:145], v[58:61]
	v_mfma_f32_16x16x32_bf16 v[62:65], v[158:161], v[142:145], v[62:65]
	v_mfma_f32_16x16x32_bf16 v[2:5], v[228:231], v[212:215], v[2:5]
	v_mfma_f32_16x16x32_bf16 v[6:9], v[232:235], v[212:215], v[6:9]
	v_mfma_f32_16x16x32_bf16 v[10:13], v[236:239], v[212:215], v[10:13]
	v_mfma_f32_16x16x32_bf16 v[14:17], v[240:243], v[212:215], v[14:17]
	v_mfma_f32_16x16x32_bf16 v[18:21], v[228:231], v[216:219], v[18:21]
	v_mfma_f32_16x16x32_bf16 v[22:25], v[232:235], v[216:219], v[22:25]
	v_mfma_f32_16x16x32_bf16 v[26:29], v[236:239], v[216:219], v[26:29]
	v_mfma_f32_16x16x32_bf16 v[30:33], v[240:243], v[216:219], v[30:33]
	v_mfma_f32_16x16x32_bf16 v[34:37], v[228:231], v[220:223], v[34:37]
	v_mfma_f32_16x16x32_bf16 v[38:41], v[232:235], v[220:223], v[38:41]
	v_mfma_f32_16x16x32_bf16 v[42:45], v[236:239], v[220:223], v[42:45]
	v_mfma_f32_16x16x32_bf16 v[46:49], v[240:243], v[220:223], v[46:49]
	v_mfma_f32_16x16x32_bf16 v[50:53], v[228:231], v[224:227], v[50:53]
	v_mfma_f32_16x16x32_bf16 v[54:57], v[232:235], v[224:227], v[54:57]
	v_mfma_f32_16x16x32_bf16 v[58:61], v[236:239], v[224:227], v[58:61]
	v_mfma_f32_16x16x32_bf16 v[62:65], v[240:243], v[224:227], v[62:65]
	s_setprio 0
	s_waitcnt vmcnt(19)
	s_barrier
	v_add_u32_e32 v204, 0x0, v200
	v_add_u32_e32 v205, 0x0, v202
	ds_read_b128 v[130:133], v204 offset:0
	ds_read_b128 v[134:137], v204 offset:2048
	ds_read_b128 v[138:141], v204 offset:4096
	ds_read_b128 v[142:145], v204 offset:6144
	ds_read_b128 v[146:149], v205 offset:0
	ds_read_b128 v[150:153], v205 offset:2048
	ds_read_b128 v[154:157], v205 offset:4096
	ds_read_b128 v[158:161], v205 offset:6144
	v_add_u32_e32 v204, 0x0, v201
	v_add_u32_e32 v205, 0x0, v203
	ds_read_b128 v[212:215], v204 offset:0
	ds_read_b128 v[216:219], v204 offset:2048
	ds_read_b128 v[220:223], v204 offset:4096
	ds_read_b128 v[224:227], v204 offset:6144
	ds_read_b128 v[228:231], v205 offset:0
	ds_read_b128 v[232:235], v205 offset:2048
	ds_read_b128 v[236:239], v205 offset:4096
	ds_read_b128 v[240:243], v205 offset:6144
	s_add_u32 m0, s76, 0x18000
	s_nop 0
	global_load_lds_dwordx4 v196, s[68:69]
	s_add_u32 m0, s76, 0x1a000
	s_nop 0
	global_load_lds_dwordx4 v197, s[68:69]
	s_add_u32 m0, s76, 0x1c000
	s_nop 0
	global_load_lds_dwordx4 v198, s[68:69]
	s_add_u32 m0, s76, 0x1e000
	s_nop 0
	global_load_lds_dwordx4 v199, s[68:69]
	s_add_u32 m0, s76, 0x20000
	s_nop 0
	global_load_lds_dwordx4 v196, s[70:71]
	s_add_u32 m0, s76, 0x22000
	s_nop 0
	global_load_lds_dwordx4 v197, s[70:71]
	s_add_u32 s68, s68, 0x80
	s_addc_u32 s69, s69, 0
	s_add_u32 s70, s70, 0x80
	s_addc_u32 s71, s71, 0
	s_waitcnt lgkmcnt(0)
	s_barrier
	s_setprio 1
	v_mfma_f32_16x16x32_bf16 v[2:5], v[146:149], v[130:133], v[2:5]
	v_mfma_f32_16x16x32_bf16 v[6:9], v[150:153], v[130:133], v[6:9]
	v_mfma_f32_16x16x32_bf16 v[10:13], v[154:157], v[130:133], v[10:13]
	v_mfma_f32_16x16x32_bf16 v[14:17], v[158:161], v[130:133], v[14:17]
	v_mfma_f32_16x16x32_bf16 v[18:21], v[146:149], v[134:137], v[18:21]
	v_mfma_f32_16x16x32_bf16 v[22:25], v[150:153], v[134:137], v[22:25]
	v_mfma_f32_16x16x32_bf16 v[26:29], v[154:157], v[134:137], v[26:29]
	v_mfma_f32_16x16x32_bf16 v[30:33], v[158:161], v[134:137], v[30:33]
	v_mfma_f32_16x16x32_bf16 v[34:37], v[146:149], v[138:141], v[34:37]
	v_mfma_f32_16x16x32_bf16 v[38:41], v[150:153], v[138:141], v[38:41]
	v_mfma_f32_16x16x32_bf16 v[42:45], v[154:157], v[138:141], v[42:45]
	v_mfma_f32_16x16x32_bf16 v[46:49], v[158:161], v[138:141], v[46:49]
	v_mfma_f32_16x16x32_bf16 v[50:53], v[146:149], v[142:145], v[50:53]
	v_mfma_f32_16x16x32_bf16 v[54:57], v[150:153], v[142:145], v[54:57]
	v_mfma_f32_16x16x32_bf16 v[58:61], v[154:157], v[142:145], v[58:61]
	v_mfma_f32_16x16x32_bf16 v[62:65], v[158:161], v[142:145], v[62:65]
	v_mfma_f32_16x16x32_bf16 v[2:5], v[228:231], v[212:215], v[2:5]
	v_mfma_f32_16x16x32_bf16 v[6:9], v[232:235], v[212:215], v[6:9]
	v_mfma_f32_16x16x32_bf16 v[10:13], v[236:239], v[212:215], v[10:13]
	v_mfma_f32_16x16x32_bf16 v[14:17], v[240:243], v[212:215], v[14:17]
	v_mfma_f32_16x16x32_bf16 v[18:21], v[228:231], v[216:219], v[18:21]
	v_mfma_f32_16x16x32_bf16 v[22:25], v[232:235], v[216:219], v[22:25]
	v_mfma_f32_16x16x32_bf16 v[26:29], v[236:239], v[216:219], v[26:29]
	v_mfma_f32_16x16x32_bf16 v[30:33], v[240:243], v[216:219], v[30:33]
	v_mfma_f32_16x16x32_bf16 v[34:37], v[228:231], v[220:223], v[34:37]
	v_mfma_f32_16x16x32_bf16 v[38:41], v[232:235], v[220:223], v[38:41]
	v_mfma_f32_16x16x32_bf16 v[42:45], v[236:239], v[220:223], v[42:45]
	v_mfma_f32_16x16x32_bf16 v[46:49], v[240:243], v[220:223], v[46:49]
	v_mfma_f32_16x16x32_bf16 v[50:53], v[228:231], v[224:227], v[50:53]
	v_mfma_f32_16x16x32_bf16 v[54:57], v[232:235], v[224:227], v[54:57]
	v_mfma_f32_16x16x32_bf16 v[58:61], v[236:239], v[224:227], v[58:61]
	v_mfma_f32_16x16x32_bf16 v[62:65], v[240:243], v[224:227], v[62:65]
	s_setprio 0
	s_waitcnt vmcnt(12)
	s_barrier
	v_add_u32_e32 v204, 0xc000, v200
	v_add_u32_e32 v205, 0xc000, v202
	ds_read_b128 v[130:133], v204 offset:0
	ds_read_b128 v[134:137], v204 offset:2048
	ds_read_b128 v[138:141], v204 offset:4096
	ds_read_b128 v[142:145], v204 offset:6144
	ds_read_b128 v[146:149], v205 offset:0
	ds_read_b128 v[150:153], v205 offset:2048
	ds_read_b128 v[154:157], v205 offset:4096
	ds_read_b128 v[158:161], v205 offset:6144
	v_add_u32_e32 v204, 0xc000, v201
	v_add_u32_e32 v205, 0xc000, v203
	ds_read_b128 v[212:215], v204 offset:0
	ds_read_b128 v[216:219], v204 offset:2048
	ds_read_b128 v[220:223], v204 offset:4096
	ds_read_b128 v[224:227], v204 offset:6144
	ds_read_b128 v[228:231], v205 offset:0
	ds_read_b128 v[232:235], v205 offset:2048
	ds_read_b128 v[236:239], v205 offset:4096
	ds_read_b128 v[240:243], v205 offset:6144
	s_add_u32 m0, s76, 0x0
	s_nop 0
	global_load_lds_dwordx4 v196, s[68:69]
	s_add_u32 m0, s76, 0x2000
	s_nop 0
	global_load_lds_dwordx4 v197, s[68:69]
	s_add_u32 m0, s76, 0x4000
	s_nop 0
	global_load_lds_dwordx4 v198, s[68:69]
	s_add_u32 m0, s76, 0x6000
	s_nop 0
	global_load_lds_dwordx4 v199, s[68:69]
	s_add_u32 m0, s76, 0x8000
	s_nop 0
	global_load_lds_dwordx4 v196, s[70:71]
	s_add_u32 m0, s76, 0xa000
	s_nop 0
	global_load_lds_dwordx4 v197, s[70:71]
	s_add_u32 s68, s68, 0x80
	s_addc_u32 s69, s69, 0
	s_add_u32 s70, s70, 0x80
	s_addc_u32 s71, s71, 0
	s_waitcnt lgkmcnt(0)
	s_barrier
	s_setprio 1
	v_mfma_f32_16x16x32_bf16 v[2:5], v[146:149], v[130:133], v[2:5]
	v_mfma_f32_16x16x32_bf16 v[6:9], v[150:153], v[130:133], v[6:9]
	v_mfma_f32_16x16x32_bf16 v[10:13], v[154:157], v[130:133], v[10:13]
	v_mfma_f32_16x16x32_bf16 v[14:17], v[158:161], v[130:133], v[14:17]
	v_mfma_f32_16x16x32_bf16 v[18:21], v[146:149], v[134:137], v[18:21]
	v_mfma_f32_16x16x32_bf16 v[22:25], v[150:153], v[134:137], v[22:25]
	v_mfma_f32_16x16x32_bf16 v[26:29], v[154:157], v[134:137], v[26:29]
	v_mfma_f32_16x16x32_bf16 v[30:33], v[158:161], v[134:137], v[30:33]
	v_mfma_f32_16x16x32_bf16 v[34:37], v[146:149], v[138:141], v[34:37]
	v_mfma_f32_16x16x32_bf16 v[38:41], v[150:153], v[138:141], v[38:41]
	v_mfma_f32_16x16x32_bf16 v[42:45], v[154:157], v[138:141], v[42:45]
	v_mfma_f32_16x16x32_bf16 v[46:49], v[158:161], v[138:141], v[46:49]
	v_mfma_f32_16x16x32_bf16 v[50:53], v[146:149], v[142:145], v[50:53]
	v_mfma_f32_16x16x32_bf16 v[54:57], v[150:153], v[142:145], v[54:57]
	v_mfma_f32_16x16x32_bf16 v[58:61], v[154:157], v[142:145], v[58:61]
	v_mfma_f32_16x16x32_bf16 v[62:65], v[158:161], v[142:145], v[62:65]
	v_mfma_f32_16x16x32_bf16 v[2:5], v[228:231], v[212:215], v[2:5]
	v_mfma_f32_16x16x32_bf16 v[6:9], v[232:235], v[212:215], v[6:9]
	v_mfma_f32_16x16x32_bf16 v[10:13], v[236:239], v[212:215], v[10:13]
	v_mfma_f32_16x16x32_bf16 v[14:17], v[240:243], v[212:215], v[14:17]
	v_mfma_f32_16x16x32_bf16 v[18:21], v[228:231], v[216:219], v[18:21]
	v_mfma_f32_16x16x32_bf16 v[22:25], v[232:235], v[216:219], v[22:25]
	v_mfma_f32_16x16x32_bf16 v[26:29], v[236:239], v[216:219], v[26:29]
	v_mfma_f32_16x16x32_bf16 v[30:33], v[240:243], v[216:219], v[30:33]
	v_mfma_f32_16x16x32_bf16 v[34:37], v[228:231], v[220:223], v[34:37]
	v_mfma_f32_16x16x32_bf16 v[38:41], v[232:235], v[220:223], v[38:41]
	v_mfma_f32_16x16x32_bf16 v[42:45], v[236:239], v[220:223], v[42:45]
	v_mfma_f32_16x16x32_bf16 v[46:49], v[240:243], v[220:223], v[46:49]
	v_mfma_f32_16x16x32_bf16 v[50:53], v[228:231], v[224:227], v[50:53]
	v_mfma_f32_16x16x32_bf16 v[54:57], v[232:235], v[224:227], v[54:57]
	v_mfma_f32_16x16x32_bf16 v[58:61], v[236:239], v[224:227], v[58:61]
	v_mfma_f32_16x16x32_bf16 v[62:65], v[240:243], v[224:227], v[62:65]
	s_setprio 0
	s_waitcnt vmcnt(6)
	s_barrier
	s_mov_b32 s16, 12
.Ldn_kloop1:
	v_add_u32_e32 v204, 0x18000, v200
	v_add_u32_e32 v205, 0x18000, v202
	ds_read_b128 v[130:133], v204 offset:0
	ds_read_b128 v[134:137], v204 offset:2048
	ds_read_b128 v[138:141], v204 offset:4096
	ds_read_b128 v[142:145], v204 offset:6144
	ds_read_b128 v[146:149], v205 offset:0
	ds_read_b128 v[150:153], v205 offset:2048
	ds_read_b128 v[154:157], v205 offset:4096
	ds_read_b128 v[158:161], v205 offset:6144
	v_add_u32_e32 v204, 0x18000, v201
	v_add_u32_e32 v205, 0x18000, v203
	ds_read_b128 v[212:215], v204 offset:0
	ds_read_b128 v[216:219], v204 offset:2048
	ds_read_b128 v[220:223], v204 offset:4096
	ds_read_b128 v[224:227], v204 offset:6144
	ds_read_b128 v[228:231], v205 offset:0
	ds_read_b128 v[232:235], v205 offset:2048
	ds_read_b128 v[236:239], v205 offset:4096
	ds_read_b128 v[240:243], v205 offset:6144
	s_add_u32 m0, s76, 0xc000
	s_nop 0
	global_load_lds_dwordx4 v196, s[68:69]
	s_add_u32 m0, s76, 0xe000
	s_nop 0
	global_load_lds_dwordx4 v197, s[68:69]
	s_add_u32 m0, s76, 0x10000
	s_nop 0
	global_load_lds_dwordx4 v198, s[68:69]
	s_add_u32 m0, s76, 0x12000
	s_nop 0
	global_load_lds_dwordx4 v199, s[68:69]
	s_add_u32 m0, s76, 0x14000
	s_nop 0
	global_load_lds_dwordx4 v196, s[70:71]
	s_add_u32 m0, s76, 0x16000
	s_nop 0
	global_load_lds_dwordx4 v197, s[70:71]
	s_add_u32 s68, s68, 0x80
	s_addc_u32 s69, s69, 0
	s_add_u32 s70, s70, 0x80
	s_addc_u32 s71, s71, 0
	s_waitcnt lgkmcnt(0)
	s_barrier
	s_setprio 1
	v_mfma_f32_16x16x32_bf16 v[2:5], v[146:149], v[130:133], v[2:5]
	v_mfma_f32_16x16x32_bf16 v[6:9], v[150:153], v[130:133], v[6:9]
	v_mfma_f32_16x16x32_bf16 v[10:13], v[154:157], v[130:133], v[10:13]
	v_mfma_f32_16x16x32_bf16 v[14:17], v[158:161], v[130:133], v[14:17]
	v_mfma_f32_16x16x32_bf16 v[18:21], v[146:149], v[134:137], v[18:21]
	v_mfma_f32_16x16x32_bf16 v[22:25], v[150:153], v[134:137], v[22:25]
	v_mfma_f32_16x16x32_bf16 v[26:29], v[154:157], v[134:137], v[26:29]
	v_mfma_f32_16x16x32_bf16 v[30:33], v[158:161], v[134:137], v[30:33]
	v_mfma_f32_16x16x32_bf16 v[34:37], v[146:149], v[138:141], v[34:37]
	v_mfma_f32_16x16x32_bf16 v[38:41], v[150:153], v[138:141], v[38:41]
	v_mfma_f32_16x16x32_bf16 v[42:45], v[154:157], v[138:141], v[42:45]
	v_mfma_f32_16x16x32_bf16 v[46:49], v[158:161], v[138:141], v[46:49]
	v_mfma_f32_16x16x32_bf16 v[50:53], v[146:149], v[142:145], v[50:53]
	v_mfma_f32_16x16x32_bf16 v[54:57], v[150:153], v[142:145], v[54:57]
	v_mfma_f32_16x16x32_bf16 v[58:61], v[154:157], v[142:145], v[58:61]
	v_mfma_f32_16x16x32_bf16 v[62:65], v[158:161], v[142:145], v[62:65]
	v_mfma_f32_16x16x32_bf16 v[2:5], v[228:231], v[212:215], v[2:5]
	v_mfma_f32_16x16x32_bf16 v[6:9], v[232:235], v[212:215], v[6:9]
	v_mfma_f32_16x16x32_bf16 v[10:13], v[236:239], v[212:215], v[10:13]
	v_mfma_f32_16x16x32_bf16 v[14:17], v[240:243], v[212:215], v[14:17]
	v_mfma_f32_16x16x32_bf16 v[18:21], v[228:231], v[216:219], v[18:21]
	v_mfma_f32_16x16x32_bf16 v[22:25], v[232:235], v[216:219], v[22:25]
	v_mfma_f32_16x16x32_bf16 v[26:29], v[236:239], v[216:219], v[26:29]
	v_mfma_f32_16x16x32_bf16 v[30:33], v[240:243], v[216:219], v[30:33]
	v_mfma_f32_16x16x32_bf16 v[34:37], v[228:231], v[220:223], v[34:37]
	v_mfma_f32_16x16x32_bf16 v[38:41], v[232:235], v[220:223], v[38:41]
	v_mfma_f32_16x16x32_bf16 v[42:45], v[236:239], v[220:223], v[42:45]
	v_mfma_f32_16x16x32_bf16 v[46:49], v[240:243], v[220:223], v[46:49]
	v_mfma_f32_16x16x32_bf16 v[50:53], v[228:231], v[224:227], v[50:53]
	v_mfma_f32_16x16x32_bf16 v[54:57], v[232:235], v[224:227], v[54:57]
	v_mfma_f32_16x16x32_bf16 v[58:61], v[236:239], v[224:227], v[58:61]
	v_mfma_f32_16x16x32_bf16 v[62:65], v[240:243], v[224:227], v[62:65]
	s_setprio 0
	s_waitcnt vmcnt(6)
	s_barrier
	v_add_u32_e32 v204, 0x0, v200
	v_add_u32_e32 v205, 0x0, v202
	ds_read_b128 v[130:133], v204 offset:0
	ds_read_b128 v[134:137], v204 offset:2048
	ds_read_b128 v[138:141], v204 offset:4096
	ds_read_b128 v[142:145], v204 offset:6144
	ds_read_b128 v[146:149], v205 offset:0
	ds_read_b128 v[150:153], v205 offset:2048
	ds_read_b128 v[154:157], v205 offset:4096
	ds_read_b128 v[158:161], v205 offset:6144
	v_add_u32_e32 v204, 0x0, v201
	v_add_u32_e32 v205, 0x0, v203
	ds_read_b128 v[212:215], v204 offset:0
	ds_read_b128 v[216:219], v204 offset:2048
	ds_read_b128 v[220:223], v204 offset:4096
	ds_read_b128 v[224:227], v204 offset:6144
	ds_read_b128 v[228:231], v205 offset:0
	ds_read_b128 v[232:235], v205 offset:2048
	ds_read_b128 v[236:239], v205 offset:4096
	ds_read_b128 v[240:243], v205 offset:6144
	s_add_u32 m0, s76, 0x18000
	s_nop 0
	global_load_lds_dwordx4 v196, s[68:69]
	s_add_u32 m0, s76, 0x1a000
	s_nop 0
	global_load_lds_dwordx4 v197, s[68:69]
	s_add_u32 m0, s76, 0x1c000
	s_nop 0
	global_load_lds_dwordx4 v198, s[68:69]
	s_add_u32 m0, s76, 0x1e000
	s_nop 0
	global_load_lds_dwordx4 v199, s[68:69]
	s_add_u32 m0, s76, 0x20000
	s_nop 0
	global_load_lds_dwordx4 v196, s[70:71]
	s_add_u32 m0, s76, 0x22000
	s_nop 0
	global_load_lds_dwordx4 v197, s[70:71]
	s_add_u32 s68, s68, 0x80
	s_addc_u32 s69, s69, 0
	s_add_u32 s70, s70, 0x80
	s_addc_u32 s71, s71, 0
	s_waitcnt lgkmcnt(0)
	s_barrier
	s_setprio 1
	v_mfma_f32_16x16x32_bf16 v[2:5], v[146:149], v[130:133], v[2:5]
	v_mfma_f32_16x16x32_bf16 v[6:9], v[150:153], v[130:133], v[6:9]
	v_mfma_f32_16x16x32_bf16 v[10:13], v[154:157], v[130:133], v[10:13]
	v_mfma_f32_16x16x32_bf16 v[14:17], v[158:161], v[130:133], v[14:17]
	v_mfma_f32_16x16x32_bf16 v[18:21], v[146:149], v[134:137], v[18:21]
	v_mfma_f32_16x16x32_bf16 v[22:25], v[150:153], v[134:137], v[22:25]
	v_mfma_f32_16x16x32_bf16 v[26:29], v[154:157], v[134:137], v[26:29]
	v_mfma_f32_16x16x32_bf16 v[30:33], v[158:161], v[134:137], v[30:33]
	v_mfma_f32_16x16x32_bf16 v[34:37], v[146:149], v[138:141], v[34:37]
	v_mfma_f32_16x16x32_bf16 v[38:41], v[150:153], v[138:141], v[38:41]
	v_mfma_f32_16x16x32_bf16 v[42:45], v[154:157], v[138:141], v[42:45]
	v_mfma_f32_16x16x32_bf16 v[46:49], v[158:161], v[138:141], v[46:49]
	v_mfma_f32_16x16x32_bf16 v[50:53], v[146:149], v[142:145], v[50:53]
	v_mfma_f32_16x16x32_bf16 v[54:57], v[150:153], v[142:145], v[54:57]
	v_mfma_f32_16x16x32_bf16 v[58:61], v[154:157], v[142:145], v[58:61]
	v_mfma_f32_16x16x32_bf16 v[62:65], v[158:161], v[142:145], v[62:65]
	v_mfma_f32_16x16x32_bf16 v[2:5], v[228:231], v[212:215], v[2:5]
	v_mfma_f32_16x16x32_bf16 v[6:9], v[232:235], v[212:215], v[6:9]
	v_mfma_f32_16x16x32_bf16 v[10:13], v[236:239], v[212:215], v[10:13]
	v_mfma_f32_16x16x32_bf16 v[14:17], v[240:243], v[212:215], v[14:17]
	v_mfma_f32_16x16x32_bf16 v[18:21], v[228:231], v[216:219], v[18:21]
	v_mfma_f32_16x16x32_bf16 v[22:25], v[232:235], v[216:219], v[22:25]
	v_mfma_f32_16x16x32_bf16 v[26:29], v[236:239], v[216:219], v[26:29]
	v_mfma_f32_16x16x32_bf16 v[30:33], v[240:243], v[216:219], v[30:33]
	v_mfma_f32_16x16x32_bf16 v[34:37], v[228:231], v[220:223], v[34:37]
	v_mfma_f32_16x16x32_bf16 v[38:41], v[232:235], v[220:223], v[38:41]
	v_mfma_f32_16x16x32_bf16 v[42:45], v[236:239], v[220:223], v[42:45]
	v_mfma_f32_16x16x32_bf16 v[46:49], v[240:243], v[220:223], v[46:49]
	v_mfma_f32_16x16x32_bf16 v[50:53], v[228:231], v[224:227], v[50:53]
	v_mfma_f32_16x16x32_bf16 v[54:57], v[232:235], v[224:227], v[54:57]
	v_mfma_f32_16x16x32_bf16 v[58:61], v[236:239], v[224:227], v[58:61]
	v_mfma_f32_16x16x32_bf16 v[62:65], v[240:243], v[224:227], v[62:65]
	s_setprio 0
	s_waitcnt vmcnt(6)
	s_barrier
	v_add_u32_e32 v204, 0xc000, v200
	v_add_u32_e32 v205, 0xc000, v202
	ds_read_b128 v[130:133], v204 offset:0
	ds_read_b128 v[134:137], v204 offset:2048
	ds_read_b128 v[138:141], v204 offset:4096
	ds_read_b128 v[142:145], v204 offset:6144
	ds_read_b128 v[146:149], v205 offset:0
	ds_read_b128 v[150:153], v205 offset:2048
	ds_read_b128 v[154:157], v205 offset:4096
	ds_read_b128 v[158:161], v205 offset:6144
	v_add_u32_e32 v204, 0xc000, v201
	v_add_u32_e32 v205, 0xc000, v203
	ds_read_b128 v[212:215], v204 offset:0
	ds_read_b128 v[216:219], v204 offset:2048
	ds_read_b128 v[220:223], v204 offset:4096
	ds_read_b128 v[224:227], v204 offset:6144
	ds_read_b128 v[228:231], v205 offset:0
	ds_read_b128 v[232:235], v205 offset:2048
	ds_read_b128 v[236:239], v205 offset:4096
	ds_read_b128 v[240:243], v205 offset:6144
	s_add_u32 m0, s76, 0x0
	s_nop 0
	global_load_lds_dwordx4 v196, s[68:69]
	s_add_u32 m0, s76, 0x2000
	s_nop 0
	global_load_lds_dwordx4 v197, s[68:69]
	s_add_u32 m0, s76, 0x4000
	s_nop 0
	global_load_lds_dwordx4 v198, s[68:69]
	s_add_u32 m0, s76, 0x6000
	s_nop 0
	global_load_lds_dwordx4 v199, s[68:69]
	s_add_u32 m0, s76, 0x8000
	s_nop 0
	global_load_lds_dwordx4 v196, s[70:71]
	s_add_u32 m0, s76, 0xa000
	s_nop 0
	global_load_lds_dwordx4 v197, s[70:71]
	s_add_u32 s68, s68, 0x80
	s_addc_u32 s69, s69, 0
	s_add_u32 s70, s70, 0x80
	s_addc_u32 s71, s71, 0
	s_waitcnt lgkmcnt(0)
	s_barrier
	s_setprio 1
	v_mfma_f32_16x16x32_bf16 v[2:5], v[146:149], v[130:133], v[2:5]
	v_mfma_f32_16x16x32_bf16 v[6:9], v[150:153], v[130:133], v[6:9]
	v_mfma_f32_16x16x32_bf16 v[10:13], v[154:157], v[130:133], v[10:13]
	v_mfma_f32_16x16x32_bf16 v[14:17], v[158:161], v[130:133], v[14:17]
	v_mfma_f32_16x16x32_bf16 v[18:21], v[146:149], v[134:137], v[18:21]
	v_mfma_f32_16x16x32_bf16 v[22:25], v[150:153], v[134:137], v[22:25]
	v_mfma_f32_16x16x32_bf16 v[26:29], v[154:157], v[134:137], v[26:29]
	v_mfma_f32_16x16x32_bf16 v[30:33], v[158:161], v[134:137], v[30:33]
	v_mfma_f32_16x16x32_bf16 v[34:37], v[146:149], v[138:141], v[34:37]
	v_mfma_f32_16x16x32_bf16 v[38:41], v[150:153], v[138:141], v[38:41]
	v_mfma_f32_16x16x32_bf16 v[42:45], v[154:157], v[138:141], v[42:45]
	v_mfma_f32_16x16x32_bf16 v[46:49], v[158:161], v[138:141], v[46:49]
	v_mfma_f32_16x16x32_bf16 v[50:53], v[146:149], v[142:145], v[50:53]
	v_mfma_f32_16x16x32_bf16 v[54:57], v[150:153], v[142:145], v[54:57]
	v_mfma_f32_16x16x32_bf16 v[58:61], v[154:157], v[142:145], v[58:61]
	v_mfma_f32_16x16x32_bf16 v[62:65], v[158:161], v[142:145], v[62:65]
	v_mfma_f32_16x16x32_bf16 v[2:5], v[228:231], v[212:215], v[2:5]
	v_mfma_f32_16x16x32_bf16 v[6:9], v[232:235], v[212:215], v[6:9]
	v_mfma_f32_16x16x32_bf16 v[10:13], v[236:239], v[212:215], v[10:13]
	v_mfma_f32_16x16x32_bf16 v[14:17], v[240:243], v[212:215], v[14:17]
	v_mfma_f32_16x16x32_bf16 v[18:21], v[228:231], v[216:219], v[18:21]
	v_mfma_f32_16x16x32_bf16 v[22:25], v[232:235], v[216:219], v[22:25]
	v_mfma_f32_16x16x32_bf16 v[26:29], v[236:239], v[216:219], v[26:29]
	v_mfma_f32_16x16x32_bf16 v[30:33], v[240:243], v[216:219], v[30:33]
	v_mfma_f32_16x16x32_bf16 v[34:37], v[228:231], v[220:223], v[34:37]
	v_mfma_f32_16x16x32_bf16 v[38:41], v[232:235], v[220:223], v[38:41]
	v_mfma_f32_16x16x32_bf16 v[42:45], v[236:239], v[220:223], v[42:45]
	v_mfma_f32_16x16x32_bf16 v[46:49], v[240:243], v[220:223], v[46:49]
	v_mfma_f32_16x16x32_bf16 v[50:53], v[228:231], v[224:227], v[50:53]
	v_mfma_f32_16x16x32_bf16 v[54:57], v[232:235], v[224:227], v[54:57]
	v_mfma_f32_16x16x32_bf16 v[58:61], v[236:239], v[224:227], v[58:61]
	v_mfma_f32_16x16x32_bf16 v[62:65], v[240:243], v[224:227], v[62:65]
	s_setprio 0
	s_waitcnt vmcnt(6)
	s_barrier
	s_add_i32 s16, s16, -1
	s_cmp_lg_u32 s16, 0
	s_cbranch_scc1 .Ldn_kloop1
	v_add_u32_e32 v204, 0x18000, v200
	v_add_u32_e32 v205, 0x18000, v202
	ds_read_b128 v[130:133], v204 offset:0
	ds_read_b128 v[134:137], v204 offset:2048
	ds_read_b128 v[138:141], v204 offset:4096
	ds_read_b128 v[142:145], v204 offset:6144
	ds_read_b128 v[146:149], v205 offset:0
	ds_read_b128 v[150:153], v205 offset:2048
	ds_read_b128 v[154:157], v205 offset:4096
	ds_read_b128 v[158:161], v205 offset:6144
	v_add_u32_e32 v204, 0x18000, v201
	v_add_u32_e32 v205, 0x18000, v203
	ds_read_b128 v[212:215], v204 offset:0
	ds_read_b128 v[216:219], v204 offset:2048
	ds_read_b128 v[220:223], v204 offset:4096
	ds_read_b128 v[224:227], v204 offset:6144
	ds_read_b128 v[228:231], v205 offset:0
	ds_read_b128 v[232:235], v205 offset:2048
	ds_read_b128 v[236:239], v205 offset:4096
	ds_read_b128 v[240:243], v205 offset:6144
	s_add_u32 m0, s76, 0xc000
	s_nop 0
	global_load_lds_dwordx4 v196, s[68:69]
	s_add_u32 m0, s76, 0xe000
	s_nop 0
	global_load_lds_dwordx4 v197, s[68:69]
	s_add_u32 m0, s76, 0x10000
	s_nop 0
	global_load_lds_dwordx4 v198, s[68:69]
	s_add_u32 m0, s76, 0x12000
	s_nop 0
	global_load_lds_dwordx4 v199, s[68:69]
	s_add_u32 m0, s76, 0x14000
	s_nop 0
	global_load_lds_dwordx4 v196, s[70:71]
	s_add_u32 m0, s76, 0x16000
	s_nop 0
	global_load_lds_dwordx4 v197, s[70:71]
	s_add_u32 s68, s68, 0x80
	s_addc_u32 s69, s69, 0
	s_add_u32 s70, s70, 0x80
	s_addc_u32 s71, s71, 0
	s_waitcnt lgkmcnt(0)
	s_barrier
	s_setprio 1
	v_mfma_f32_16x16x32_bf16 v[2:5], v[146:149], v[130:133], v[2:5]
	v_mfma_f32_16x16x32_bf16 v[6:9], v[150:153], v[130:133], v[6:9]
	v_mfma_f32_16x16x32_bf16 v[10:13], v[154:157], v[130:133], v[10:13]
	v_mfma_f32_16x16x32_bf16 v[14:17], v[158:161], v[130:133], v[14:17]
	v_mfma_f32_16x16x32_bf16 v[18:21], v[146:149], v[134:137], v[18:21]
	v_mfma_f32_16x16x32_bf16 v[22:25], v[150:153], v[134:137], v[22:25]
	v_mfma_f32_16x16x32_bf16 v[26:29], v[154:157], v[134:137], v[26:29]
	v_mfma_f32_16x16x32_bf16 v[30:33], v[158:161], v[134:137], v[30:33]
	v_mfma_f32_16x16x32_bf16 v[34:37], v[146:149], v[138:141], v[34:37]
	v_mfma_f32_16x16x32_bf16 v[38:41], v[150:153], v[138:141], v[38:41]
	v_mfma_f32_16x16x32_bf16 v[42:45], v[154:157], v[138:141], v[42:45]
	v_mfma_f32_16x16x32_bf16 v[46:49], v[158:161], v[138:141], v[46:49]
	v_mfma_f32_16x16x32_bf16 v[50:53], v[146:149], v[142:145], v[50:53]
	v_mfma_f32_16x16x32_bf16 v[54:57], v[150:153], v[142:145], v[54:57]
	v_mfma_f32_16x16x32_bf16 v[58:61], v[154:157], v[142:145], v[58:61]
	v_mfma_f32_16x16x32_bf16 v[62:65], v[158:161], v[142:145], v[62:65]
	v_mfma_f32_16x16x32_bf16 v[2:5], v[228:231], v[212:215], v[2:5]
	v_mfma_f32_16x16x32_bf16 v[6:9], v[232:235], v[212:215], v[6:9]
	v_mfma_f32_16x16x32_bf16 v[10:13], v[236:239], v[212:215], v[10:13]
	v_mfma_f32_16x16x32_bf16 v[14:17], v[240:243], v[212:215], v[14:17]
	v_mfma_f32_16x16x32_bf16 v[18:21], v[228:231], v[216:219], v[18:21]
	v_mfma_f32_16x16x32_bf16 v[22:25], v[232:235], v[216:219], v[22:25]
	v_mfma_f32_16x16x32_bf16 v[26:29], v[236:239], v[216:219], v[26:29]
	v_mfma_f32_16x16x32_bf16 v[30:33], v[240:243], v[216:219], v[30:33]
	v_mfma_f32_16x16x32_bf16 v[34:37], v[228:231], v[220:223], v[34:37]
	v_mfma_f32_16x16x32_bf16 v[38:41], v[232:235], v[220:223], v[38:41]
	v_mfma_f32_16x16x32_bf16 v[42:45], v[236:239], v[220:223], v[42:45]
	v_mfma_f32_16x16x32_bf16 v[46:49], v[240:243], v[220:223], v[46:49]
	v_mfma_f32_16x16x32_bf16 v[50:53], v[228:231], v[224:227], v[50:53]
	v_mfma_f32_16x16x32_bf16 v[54:57], v[232:235], v[224:227], v[54:57]
	v_mfma_f32_16x16x32_bf16 v[58:61], v[236:239], v[224:227], v[58:61]
	v_mfma_f32_16x16x32_bf16 v[62:65], v[240:243], v[224:227], v[62:65]
	s_setprio 0
	s_waitcnt vmcnt(6)
	s_barrier
	v_add_u32_e32 v204, 0x0, v200
	v_add_u32_e32 v205, 0x0, v202
	ds_read_b128 v[130:133], v204 offset:0
	ds_read_b128 v[134:137], v204 offset:2048
	ds_read_b128 v[138:141], v204 offset:4096
	ds_read_b128 v[142:145], v204 offset:6144
	ds_read_b128 v[146:149], v205 offset:0
	ds_read_b128 v[150:153], v205 offset:2048
	ds_read_b128 v[154:157], v205 offset:4096
	ds_read_b128 v[158:161], v205 offset:6144
	v_add_u32_e32 v204, 0x0, v201
	v_add_u32_e32 v205, 0x0, v203
	ds_read_b128 v[212:215], v204 offset:0
	ds_read_b128 v[216:219], v204 offset:2048
	ds_read_b128 v[220:223], v204 offset:4096
	ds_read_b128 v[224:227], v204 offset:6144
	ds_read_b128 v[228:231], v205 offset:0
	ds_read_b128 v[232:235], v205 offset:2048
	ds_read_b128 v[236:239], v205 offset:4096
	ds_read_b128 v[240:243], v205 offset:6144
	s_waitcnt lgkmcnt(0)
	s_barrier
	s_setprio 1
	v_mfma_f32_16x16x32_bf16 v[2:5], v[146:149], v[130:133], v[2:5]
	v_mfma_f32_16x16x32_bf16 v[6:9], v[150:153], v[130:133], v[6:9]
	v_mfma_f32_16x16x32_bf16 v[10:13], v[154:157], v[130:133], v[10:13]
	v_mfma_f32_16x16x32_bf16 v[14:17], v[158:161], v[130:133], v[14:17]
	v_mfma_f32_16x16x32_bf16 v[18:21], v[146:149], v[134:137], v[18:21]
	v_mfma_f32_16x16x32_bf16 v[22:25], v[150:153], v[134:137], v[22:25]
	v_mfma_f32_16x16x32_bf16 v[26:29], v[154:157], v[134:137], v[26:29]
	v_mfma_f32_16x16x32_bf16 v[30:33], v[158:161], v[134:137], v[30:33]
	v_mfma_f32_16x16x32_bf16 v[34:37], v[146:149], v[138:141], v[34:37]
	v_mfma_f32_16x16x32_bf16 v[38:41], v[150:153], v[138:141], v[38:41]
	v_mfma_f32_16x16x32_bf16 v[42:45], v[154:157], v[138:141], v[42:45]
	v_mfma_f32_16x16x32_bf16 v[46:49], v[158:161], v[138:141], v[46:49]
	v_mfma_f32_16x16x32_bf16 v[50:53], v[146:149], v[142:145], v[50:53]
	v_mfma_f32_16x16x32_bf16 v[54:57], v[150:153], v[142:145], v[54:57]
	v_mfma_f32_16x16x32_bf16 v[58:61], v[154:157], v[142:145], v[58:61]
	v_mfma_f32_16x16x32_bf16 v[62:65], v[158:161], v[142:145], v[62:65]
	v_mfma_f32_16x16x32_bf16 v[2:5], v[228:231], v[212:215], v[2:5]
	v_mfma_f32_16x16x32_bf16 v[6:9], v[232:235], v[212:215], v[6:9]
	v_mfma_f32_16x16x32_bf16 v[10:13], v[236:239], v[212:215], v[10:13]
	v_mfma_f32_16x16x32_bf16 v[14:17], v[240:243], v[212:215], v[14:17]
	v_mfma_f32_16x16x32_bf16 v[18:21], v[228:231], v[216:219], v[18:21]
	v_mfma_f32_16x16x32_bf16 v[22:25], v[232:235], v[216:219], v[22:25]
	v_mfma_f32_16x16x32_bf16 v[26:29], v[236:239], v[216:219], v[26:29]
	v_mfma_f32_16x16x32_bf16 v[30:33], v[240:243], v[216:219], v[30:33]
	v_mfma_f32_16x16x32_bf16 v[34:37], v[228:231], v[220:223], v[34:37]
	v_mfma_f32_16x16x32_bf16 v[38:41], v[232:235], v[220:223], v[38:41]
	v_mfma_f32_16x16x32_bf16 v[42:45], v[236:239], v[220:223], v[42:45]
	v_mfma_f32_16x16x32_bf16 v[46:49], v[240:243], v[220:223], v[46:49]
	v_mfma_f32_16x16x32_bf16 v[50:53], v[228:231], v[224:227], v[50:53]
	v_mfma_f32_16x16x32_bf16 v[54:57], v[232:235], v[224:227], v[54:57]
	v_mfma_f32_16x16x32_bf16 v[58:61], v[236:239], v[224:227], v[58:61]
	v_mfma_f32_16x16x32_bf16 v[62:65], v[240:243], v[224:227], v[62:65]
	s_setprio 0
	s_waitcnt vmcnt(0)
	s_barrier
	v_add_u32_e32 v204, 0xc000, v200
	v_add_u32_e32 v205, 0xc000, v202
	ds_read_b128 v[130:133], v204 offset:0
	ds_read_b128 v[134:137], v204 offset:2048
	ds_read_b128 v[138:141], v204 offset:4096
	ds_read_b128 v[142:145], v204 offset:6144
	ds_read_b128 v[146:149], v205 offset:0
	ds_read_b128 v[150:153], v205 offset:2048
	ds_read_b128 v[154:157], v205 offset:4096
	ds_read_b128 v[158:161], v205 offset:6144
	v_add_u32_e32 v204, 0xc000, v201
	v_add_u32_e32 v205, 0xc000, v203
	ds_read_b128 v[212:215], v204 offset:0
	ds_read_b128 v[216:219], v204 offset:2048
	ds_read_b128 v[220:223], v204 offset:4096
	ds_read_b128 v[224:227], v204 offset:6144
	ds_read_b128 v[228:231], v205 offset:0
	ds_read_b128 v[232:235], v205 offset:2048
	ds_read_b128 v[236:239], v205 offset:4096
	ds_read_b128 v[240:243], v205 offset:6144
	s_waitcnt lgkmcnt(0)
	s_barrier
	s_setprio 1
	v_mfma_f32_16x16x32_bf16 v[2:5], v[146:149], v[130:133], v[2:5]
	v_mfma_f32_16x16x32_bf16 v[6:9], v[150:153], v[130:133], v[6:9]
	v_mfma_f32_16x16x32_bf16 v[10:13], v[154:157], v[130:133], v[10:13]
	v_mfma_f32_16x16x32_bf16 v[14:17], v[158:161], v[130:133], v[14:17]
	v_mfma_f32_16x16x32_bf16 v[18:21], v[146:149], v[134:137], v[18:21]
	v_mfma_f32_16x16x32_bf16 v[22:25], v[150:153], v[134:137], v[22:25]
	v_mfma_f32_16x16x32_bf16 v[26:29], v[154:157], v[134:137], v[26:29]
	v_mfma_f32_16x16x32_bf16 v[30:33], v[158:161], v[134:137], v[30:33]
	v_mfma_f32_16x16x32_bf16 v[34:37], v[146:149], v[138:141], v[34:37]
	v_mfma_f32_16x16x32_bf16 v[38:41], v[150:153], v[138:141], v[38:41]
	v_mfma_f32_16x16x32_bf16 v[42:45], v[154:157], v[138:141], v[42:45]
	v_mfma_f32_16x16x32_bf16 v[46:49], v[158:161], v[138:141], v[46:49]
	v_mfma_f32_16x16x32_bf16 v[50:53], v[146:149], v[142:145], v[50:53]
	v_mfma_f32_16x16x32_bf16 v[54:57], v[150:153], v[142:145], v[54:57]
	v_mfma_f32_16x16x32_bf16 v[58:61], v[154:157], v[142:145], v[58:61]
	v_mfma_f32_16x16x32_bf16 v[62:65], v[158:161], v[142:145], v[62:65]
	v_mfma_f32_16x16x32_bf16 v[2:5], v[228:231], v[212:215], v[2:5]
	v_mfma_f32_16x16x32_bf16 v[6:9], v[232:235], v[212:215], v[6:9]
	v_mfma_f32_16x16x32_bf16 v[10:13], v[236:239], v[212:215], v[10:13]
	v_mfma_f32_16x16x32_bf16 v[14:17], v[240:243], v[212:215], v[14:17]
	v_mfma_f32_16x16x32_bf16 v[18:21], v[228:231], v[216:219], v[18:21]
	v_mfma_f32_16x16x32_bf16 v[22:25], v[232:235], v[216:219], v[22:25]
	v_mfma_f32_16x16x32_bf16 v[26:29], v[236:239], v[216:219], v[26:29]
	v_mfma_f32_16x16x32_bf16 v[30:33], v[240:243], v[216:219], v[30:33]
	v_mfma_f32_16x16x32_bf16 v[34:37], v[228:231], v[220:223], v[34:37]
	v_mfma_f32_16x16x32_bf16 v[38:41], v[232:235], v[220:223], v[38:41]
	v_mfma_f32_16x16x32_bf16 v[42:45], v[236:239], v[220:223], v[42:45]
	v_mfma_f32_16x16x32_bf16 v[46:49], v[240:243], v[220:223], v[46:49]
	v_mfma_f32_16x16x32_bf16 v[50:53], v[228:231], v[224:227], v[50:53]
	v_mfma_f32_16x16x32_bf16 v[54:57], v[232:235], v[224:227], v[54:57]
	v_mfma_f32_16x16x32_bf16 v[58:61], v[236:239], v[224:227], v[58:61]
	v_mfma_f32_16x16x32_bf16 v[62:65], v[240:243], v[224:227], v[62:65]
	s_setprio 0
	s_barrier
	s_branch .Ldn_join
.Ldn_streamB:
	s_barrier
	v_add_u32_e32 v204, 0x0, v200
	v_add_u32_e32 v205, 0x0, v202
	ds_read_b128 v[130:133], v204 offset:0
	ds_read_b128 v[134:137], v204 offset:2048
	ds_read_b128 v[138:141], v204 offset:4096
	ds_read_b128 v[142:145], v204 offset:6144
	ds_read_b128 v[146:149], v205 offset:0
	ds_read_b128 v[150:153], v205 offset:2048
	ds_read_b128 v[154:157], v205 offset:4096
	ds_read_b128 v[158:161], v205 offset:6144
	v_add_u32_e32 v204, 0x0, v201
	v_add_u32_e32 v205, 0x0, v203
	ds_read_b128 v[212:215], v204 offset:0
	ds_read_b128 v[216:219], v204 offset:2048
	ds_read_b128 v[220:223], v204 offset:4096
	ds_read_b128 v[224:227], v204 offset:6144
	ds_read_b128 v[228:231], v205 offset:0
	ds_read_b128 v[232:235], v205 offset:2048
	ds_read_b128 v[236:239], v205 offset:4096
	ds_read_b128 v[240:243], v205 offset:6144
	s_add_u32 m0, s76, 0x18000
	s_nop 0
	global_load_lds_dwordx4 v196, s[68:69]
	s_add_u32 m0, s76, 0x1a000
	s_nop 0
	global_load_lds_dwordx4 v197, s[68:69]
	s_add_u32 m0, s76, 0x1c000
	s_nop 0
	global_load_lds_dwordx4 v198, s[68:69]
	s_add_u32 m0, s76, 0x1e000
	s_nop 0
	global_load_lds_dwordx4 v199, s[68:69]
	s_add_u32 m0, s76, 0x20000
	s_nop 0
	global_load_lds_dwordx4 v196, s[70:71]
	s_add_u32 m0, s76, 0x22000
	s_nop 0
	global_load_lds_dwordx4 v197, s[70:71]
	s_add_u32 s68, s68, 0x80
	s_addc_u32 s69, s69, 0
	s_add_u32 s70, s70, 0x80
	s_addc_u32 s71, s71, 0
	global_load_dwordx4 v[174:177], v190, s[72:73] offset:0
	global_load_dwordx4 v[178:181], v190, s[72:73] offset:64
	global_load_dwordx4 v[182:185], v190, s[72:73] offset:128
	global_load_dwordx4 v[186:189], v190, s[72:73] offset:192
	global_load_dwordx2 v[66:67], v206, s[74:75] offset:0
	global_load_dwordx2 v[70:71], v206, s[74:75] offset:32
	global_load_dwordx2 v[74:75], v206, s[74:75] offset:64
	s_waitcnt vmcnt(13)
	s_waitcnt lgkmcnt(0)
	s_barrier
	s_setprio 1
	v_mfma_f32_16x16x32_bf16 v[2:5], v[146:149], v[130:133], 0
	v_mfma_f32_16x16x32_bf16 v[6:9], v[150:153], v[130:133], 0
	v_mfma_f32_16x16x32_bf16 v[10:13], v[154:157], v[130:133], 0
	v_mfma_f32_16x16x32_bf16 v[14:17], v[158:161], v[130:133], 0
	v_mfma_f32_16x16x32_bf16 v[18:21], v[146:149], v[134:137], 0
	v_mfma_f32_16x16x32_bf16 v[22:25], v[150:153], v[134:137], 0
	v_mfma_f32_16x16x32_bf16 v[26:29], v[154:157], v[134:137], 0
	v_mfma_f32_16x16x32_bf16 v[30:33], v[158:161], v[134:137], 0
	v_mfma_f32_16x16x32_bf16 v[34:37], v[146:149], v[138:141], 0
	v_mfma_f32_16x16x32_bf16 v[38:41], v[150:153], v[138:141], 0
	v_mfma_f32_16x16x32_bf16 v[42:45], v[154:157], v[138:141], 0
	v_mfma_f32_16x16x32_bf16 v[46:49], v[158:161], v[138:141], 0
	v_mfma_f32_16x16x32_bf16 v[50:53], v[146:149], v[142:145], 0
	v_mfma_f32_16x16x32_bf16 v[54:57], v[150:153], v[142:145], 0
	v_mfma_f32_16x16x32_bf16 v[58:61], v[154:157], v[142:145], 0
	v_mfma_f32_16x16x32_bf16 v[62:65], v[158:161], v[142:145], 0
	v_mfma_f32_16x16x32_bf16 v[2:5], v[228:231], v[212:215], v[2:5]
	v_mfma_f32_16x16x32_bf16 v[6:9], v[232:235], v[212:215], v[6:9]
	v_mfma_f32_16x16x32_bf16 v[10:13], v[236:239], v[212:215], v[10:13]
	v_mfma_f32_16x16x32_bf16 v[14:17], v[240:243], v[212:215], v[14:17]
	v_mfma_f32_16x16x32_bf16 v[18:21], v[228:231], v[216:219], v[18:21]
	v_mfma_f32_16x16x32_bf16 v[22:25], v[232:235], v[216:219], v[22:25]
	v_mfma_f32_16x16x32_bf16 v[26:29], v[236:239], v[216:219], v[26:29]
	v_mfma_f32_16x16x32_bf16 v[30:33], v[240:243], v[216:219], v[30:33]
	v_mfma_f32_16x16x32_bf16 v[34:37], v[228:231], v[220:223], v[34:37]
	v_mfma_f32_16x16x32_bf16 v[38:41], v[232:235], v[220:223], v[38:41]
	v_mfma_f32_16x16x32_bf16 v[42:45], v[236:239], v[220:223], v[42:45]
	v_mfma_f32_16x16x32_bf16 v[46:49], v[240:243], v[220:223], v[46:49]
	v_mfma_f32_16x16x32_bf16 v[50:53], v[228:231], v[224:227], v[50:53]
	v_mfma_f32_16x16x32_bf16 v[54:57], v[232:235], v[224:227], v[54:57]
	v_mfma_f32_16x16x32_bf16 v[58:61], v[236:239], v[224:227], v[58:61]
	v_mfma_f32_16x16x32_bf16 v[62:65], v[240:243], v[224:227], v[62:65]
	s_setprio 0
	s_barrier
	v_add_u32_e32 v204, 0xc000, v200
	v_add_u32_e32 v205, 0xc000, v202
	ds_read_b128 v[130:133], v204 offset:0
	ds_read_b128 v[134:137], v204 offset:2048
	ds_read_b128 v[138:141], v204 offset:4096
	ds_read_b128 v[142:145], v204 offset:6144
	ds_read_b128 v[146:149], v205 offset:0
	ds_read_b128 v[150:153], v205 offset:2048
	ds_read_b128 v[154:157], v205 offset:4096
	ds_read_b128 v[158:161], v205 offset:6144
	v_add_u32_e32 v204, 0xc000, v201
	v_add_u32_e32 v205, 0xc000, v203
	ds_read_b128 v[212:215], v204 offset:0
	ds_read_b128 v[216:219], v204 offset:2048
	ds_read_b128 v[220:223], v204 offset:4096
	ds_read_b128 v[224:227], v204 offset:6144
	ds_read_b128 v[228:231], v205 offset:0
	ds_read_b128 v[232:235], v205 offset:2048
	ds_read_b128 v[236:239], v205 offset:4096
	ds_read_b128 v[240:243], v205 offset:6144
	s_add_u32 m0, s76, 0x0
	s_nop 0
	global_load_lds_dwordx4 v196, s[68:69]
	s_add_u32 m0, s76, 0x2000
	s_nop 0
	global_load_lds_dwordx4 v197, s[68:69]
	s_add_u32 m0, s76, 0x4000
	s_nop 0
	global_load_lds_dwordx4 v198, s[68:69]
	s_add_u32 m0, s76, 0x6000
	s_nop 0
	global_load_lds_dwordx4 v199, s[68:69]
	s_add_u32 m0, s76, 0x8000
	s_nop 0
	global_load_lds_dwordx4 v196, s[70:71]
	s_add_u32 m0, s76, 0xa000
	s_nop 0
	global_load_lds_dwordx4 v197, s[70:71]
	s_add_u32 s68, s68, 0x80
	s_addc_u32 s69, s69, 0
	s_add_u32 s70, s70, 0x80
	s_addc_u32 s71, s71, 0
	global_load_dwordx2 v[78:79], v206, s[74:75] offset:96
	global_load_dwordx2 v[82:83], v207, s[74:75] offset:0
	global_load_dwordx2 v[86:87], v207, s[74:75] offset:32
	global_load_dwordx2 v[90:91], v207, s[74:75] offset:64
	global_load_dwordx2 v[94:95], v207, s[74:75] offset:96
	global_load_dwordx2 v[98:99], v208, s[74:75] offset:0
	global_load_dwordx2 v[102:103], v208, s[74:75] offset:32
	s_waitcnt vmcnt(20)
	s_waitcnt lgkmcnt(0)
	s_barrier
	s_setprio 1
	v_mfma_f32_16x16x32_bf16 v[2:5], v[146:149], v[130:133], v[2:5]
	v_mfma_f32_16x16x32_bf16 v[6:9], v[150:153], v[130:133], v[6:9]
	v_mfma_f32_16x16x32_bf16 v[10:13], v[154:157], v[130:133], v[10:13]
	v_mfma_f32_16x16x32_bf16 v[14:17], v[158:161], v[130:133], v[14:17]
	v_mfma_f32_16x16x32_bf16 v[18:21], v[146:149], v[134:137], v[18:21]
	v_mfma_f32_16x16x32_bf16 v[22:25], v[150:153], v[134:137], v[22:25]
	v_mfma_f32_16x16x32_bf16 v[26:29], v[154:157], v[134:137], v[26:29]
	v_mfma_f32_16x16x32_bf16 v[30:33], v[158:161], v[134:137], v[30:33]
	v_mfma_f32_16x16x32_bf16 v[34:37], v[146:149], v[138:141], v[34:37]
	v_mfma_f32_16x16x32_bf16 v[38:41], v[150:153], v[138:141], v[38:41]
	v_mfma_f32_16x16x32_bf16 v[42:45], v[154:157], v[138:141], v[42:45]
	v_mfma_f32_16x16x32_bf16 v[46:49], v[158:161], v[138:141], v[46:49]
	v_mfma_f32_16x16x32_bf16 v[50:53], v[146:149], v[142:145], v[50:53]
	v_mfma_f32_16x16x32_bf16 v[54:57], v[150:153], v[142:145], v[54:57]
	v_mfma_f32_16x16x32_bf16 v[58:61], v[154:157], v[142:145], v[58:61]
	v_mfma_f32_16x16x32_bf16 v[62:65], v[158:161], v[142:145], v[62:65]
	v_mfma_f32_16x16x32_bf16 v[2:5], v[228:231], v[212:215], v[2:5]
	v_mfma_f32_16x16x32_bf16 v[6:9], v[232:235], v[212:215], v[6:9]
	v_mfma_f32_16x16x32_bf16 v[10:13], v[236:239], v[212:215], v[10:13]
	v_mfma_f32_16x16x32_bf16 v[14:17], v[240:243], v[212:215], v[14:17]
	v_mfma_f32_16x16x32_bf16 v[18:21], v[228:231], v[216:219], v[18:21]
	v_mfma_f32_16x16x32_bf16 v[22:25], v[232:235], v[216:219], v[22:25]
	v_mfma_f32_16x16x32_bf16 v[26:29], v[236:239], v[216:219], v[26:29]
	v_mfma_f32_16x16x32_bf16 v[30:33], v[240:243], v[216:219], v[30:33]
	v_mfma_f32_16x16x32_bf16 v[34:37], v[228:231], v[220:223], v[34:37]
	v_mfma_f32_16x16x32_bf16 v[38:41], v[232:235], v[220:223], v[38:41]
	v_mfma_f32_16x16x32_bf16 v[42:45], v[236:239], v[220:223], v[42:45]
	v_mfma_f32_16x16x32_bf16 v[46:49], v[240:243], v[220:223], v[46:49]
	v_mfma_f32_16x16x32_bf16 v[50:53], v[228:231], v[224:227], v[50:53]
	v_mfma_f32_16x16x32_bf16 v[54:57], v[232:235], v[224:227], v[54:57]
	v_mfma_f32_16x16x32_bf16 v[58:61], v[236:239], v[224:227], v[58:61]
	v_mfma_f32_16x16x32_bf16 v[62:65], v[240:243], v[224:227], v[62:65]
	s_setprio 0
	s_barrier
	v_add_u32_e32 v204, 0x18000, v200
	v_add_u32_e32 v205, 0x18000, v202
	ds_read_b128 v[130:133], v204 offset:0
	ds_read_b128 v[134:137], v204 offset:2048
	ds_read_b128 v[138:141], v204 offset:4096
	ds_read_b128 v[142:145], v204 offset:6144
	ds_read_b128 v[146:149], v205 offset:0
	ds_read_b128 v[150:153], v205 offset:2048
	ds_read_b128 v[154:157], v205 offset:4096
	ds_read_b128 v[158:161], v205 offset:6144
	v_add_u32_e32 v204, 0x18000, v201
	v_add_u32_e32 v205, 0x18000, v203
	ds_read_b128 v[212:215], v204 offset:0
	ds_read_b128 v[216:219], v204 offset:2048
	ds_read_b128 v[220:223], v204 offset:4096
	ds_read_b128 v[224:227], v204 offset:6144
	ds_read_b128 v[228:231], v205 offset:0
	ds_read_b128 v[232:235], v205 offset:2048
	ds_read_b128 v[236:239], v205 offset:4096
	ds_read_b128 v[240:243], v205 offset:6144
	s_add_u32 m0, s76, 0xc000
	s_nop 0
	global_load_lds_dwordx4 v196, s[68:69]
	s_add_u32 m0, s76, 0xe000
	s_nop 0
	global_load_lds_dwordx4 v197, s[68:69]
	s_add_u32 m0, s76, 0x10000
	s_nop 0
	global_load_lds_dwordx4 v198, s[68:69]
	s_add_u32 m0, s76, 0x12000
	s_nop 0
	global_load_lds_dwordx4 v199, s[68:69]
	s_add_u32 m0, s76, 0x14000
	s_nop 0
	global_load_lds_dwordx4 v196, s[70:71]
	s_add_u32 m0, s76, 0x16000
	s_nop 0
	global_load_lds_dwordx4 v197, s[70:71]
	s_add_u32 s68, s68, 0x80
	s_addc_u32 s69, s69, 0
	s_add_u32 s70, s70, 0x80
	s_addc_u32 s71, s71, 0
	global_load_dwordx2 v[106:107], v208, s[74:75] offset:64
	global_load_dwordx2 v[110:111], v208, s[74:75] offset:96
	global_load_dwordx2 v[114:115], v209, s[74:75] offset:0
	global_load_dwordx2 v[118:119], v209, s[74:75] offset:32
	global_load_dwordx2 v[122:123], v209, s[74:75] offset:64
	global_load_dwordx2 v[126:127], v209, s[74:75] offset:96
	s_waitcnt vmcnt(19)
	s_waitcnt lgkmcnt(0)
	s_barrier
	s_setprio 1
	v_mfma_f32_16x16x32_bf16 v[2:5], v[146:149], v[130:133], v[2:5]
	v_mfma_f32_16x16x32_bf16 v[6:9], v[150:153], v[130:133], v[6:9]
	v_mfma_f32_16x16x32_bf16 v[10:13], v[154:157], v[130:133], v[10:13]
	v_mfma_f32_16x16x32_bf16 v[14:17], v[158:161], v[130:133], v[14:17]
	v_mfma_f32_16x16x32_bf16 v[18:21], v[146:149], v[134:137], v[18:21]
	v_mfma_f32_16x16x32_bf16 v[22:25], v[150:153], v[134:137], v[22:25]
	v_mfma_f32_16x16x32_bf16 v[26:29], v[154:157], v[134:137], v[26:29]
	v_mfma_f32_16x16x32_bf16 v[30:33], v[158:161], v[134:137], v[30:33]
	v_mfma_f32_16x16x32_bf16 v[34:37], v[146:149], v[138:141], v[34:37]
	v_mfma_f32_16x16x32_bf16 v[38:41], v[150:153], v[138:141], v[38:41]
	v_mfma_f32_16x16x32_bf16 v[42:45], v[154:157], v[138:141], v[42:45]
	v_mfma_f32_16x16x32_bf16 v[46:49], v[158:161], v[138:141], v[46:49]
	v_mfma_f32_16x16x32_bf16 v[50:53], v[146:149], v[142:145], v[50:53]
	v_mfma_f32_16x16x32_bf16 v[54:57], v[150:153], v[142:145], v[54:57]
	v_mfma_f32_16x16x32_bf16 v[58:61], v[154:157], v[142:145], v[58:61]
	v_mfma_f32_16x16x32_bf16 v[62:65], v[158:161], v[142:145], v[62:65]
	v_mfma_f32_16x16x32_bf16 v[2:5], v[228:231], v[212:215], v[2:5]
	v_mfma_f32_16x16x32_bf16 v[6:9], v[232:235], v[212:215], v[6:9]
	v_mfma_f32_16x16x32_bf16 v[10:13], v[236:239], v[212:215], v[10:13]
	v_mfma_f32_16x16x32_bf16 v[14:17], v[240:243], v[212:215], v[14:17]
	v_mfma_f32_16x16x32_bf16 v[18:21], v[228:231], v[216:219], v[18:21]
	v_mfma_f32_16x16x32_bf16 v[22:25], v[232:235], v[216:219], v[22:25]
	v_mfma_f32_16x16x32_bf16 v[26:29], v[236:239], v[216:219], v[26:29]
	v_mfma_f32_16x16x32_bf16 v[30:33], v[240:243], v[216:219], v[30:33]
	v_mfma_f32_16x16x32_bf16 v[34:37], v[228:231], v[220:223], v[34:37]
	v_mfma_f32_16x16x32_bf16 v[38:41], v[232:235], v[220:223], v[38:41]
	v_mfma_f32_16x16x32_bf16 v[42:45], v[236:239], v[220:223], v[42:45]
	v_mfma_f32_16x16x32_bf16 v[46:49], v[240:243], v[220:223], v[46:49]
	v_mfma_f32_16x16x32_bf16 v[50:53], v[228:231], v[224:227], v[50:53]
	v_mfma_f32_16x16x32_bf16 v[54:57], v[232:235], v[224:227], v[54:57]
	v_mfma_f32_16x16x32_bf16 v[58:61], v[236:239], v[224:227], v[58:61]
	v_mfma_f32_16x16x32_bf16 v[62:65], v[240:243], v[224:227], v[62:65]
	s_setprio 0
	s_barrier
	v_add_u32_e32 v204, 0x0, v200
	v_add_u32_e32 v205, 0x0, v202
	ds_read_b128 v[130:133], v204 offset:0
	ds_read_b128 v[134:137], v204 offset:2048
	ds_read_b128 v[138:141], v204 offset:4096
	ds_read_b128 v[142:145], v204 offset:6144
	ds_read_b128 v[146:149], v205 offset:0
	ds_read_b128 v[150:153], v205 offset:2048
	ds_read_b128 v[154:157], v205 offset:4096
	ds_read_b128 v[158:161], v205 offset:6144
	v_add_u32_e32 v204, 0x0, v201
	v_add_u32_e32 v205, 0x0, v203
	ds_read_b128 v[212:215], v204 offset:0
	ds_read_b128 v[216:219], v204 offset:2048
	ds_read_b128 v[220:223], v204 offset:4096
	ds_read_b128 v[224:227], v204 offset:6144
	ds_read_b128 v[228:231], v205 offset:0
	ds_read_b128 v[232:235], v205 offset:2048
	ds_read_b128 v[236:239], v205 offset:4096
	ds_read_b128 v[240:243], v205 offset:6144
	s_add_u32 m0, s76, 0x18000
	s_nop 0
	global_load_lds_dwordx4 v196, s[68:69]
	s_add_u32 m0, s76, 0x1a000
	s_nop 0
	global_load_lds_dwordx4 v197, s[68:69]
	s_add_u32 m0, s76, 0x1c000
	s_nop 0
	global_load_lds_dwordx4 v198, s[68:69]
	s_add_u32 m0, s76, 0x1e000
	s_nop 0
	global_load_lds_dwordx4 v199, s[68:69]
	s_add_u32 m0, s76, 0x20000
	s_nop 0
	global_load_lds_dwordx4 v196, s[70:71]
	s_add_u32 m0, s76, 0x22000
	s_nop 0
	global_load_lds_dwordx4 v197, s[70:71]
	s_add_u32 s68, s68, 0x80
	s_addc_u32 s69, s69, 0
	s_add_u32 s70, s70, 0x80
	s_addc_u32 s71, s71, 0
	s_waitcnt vmcnt(12)
	s_waitcnt lgkmcnt(0)
	s_barrier
	s_setprio 1
	v_mfma_f32_16x16x32_bf16 v[2:5], v[146:149], v[130:133], v[2:5]
	v_mfma_f32_16x16x32_bf16 v[6:9], v[150:153], v[130:133], v[6:9]
	v_mfma_f32_16x16x32_bf16 v[10:13], v[154:157], v[130:133], v[10:13]
	v_mfma_f32_16x16x32_bf16 v[14:17], v[158:161], v[130:133], v[14:17]
	v_mfma_f32_16x16x32_bf16 v[18:21], v[146:149], v[134:137], v[18:21]
	v_mfma_f32_16x16x32_bf16 v[22:25], v[150:153], v[134:137], v[22:25]
	v_mfma_f32_16x16x32_bf16 v[26:29], v[154:157], v[134:137], v[26:29]
	v_mfma_f32_16x16x32_bf16 v[30:33], v[158:161], v[134:137], v[30:33]
	v_mfma_f32_16x16x32_bf16 v[34:37], v[146:149], v[138:141], v[34:37]
	v_mfma_f32_16x16x32_bf16 v[38:41], v[150:153], v[138:141], v[38:41]
	v_mfma_f32_16x16x32_bf16 v[42:45], v[154:157], v[138:141], v[42:45]
	v_mfma_f32_16x16x32_bf16 v[46:49], v[158:161], v[138:141], v[46:49]
	v_mfma_f32_16x16x32_bf16 v[50:53], v[146:149], v[142:145], v[50:53]
	v_mfma_f32_16x16x32_bf16 v[54:57], v[150:153], v[142:145], v[54:57]
	v_mfma_f32_16x16x32_bf16 v[58:61], v[154:157], v[142:145], v[58:61]
	v_mfma_f32_16x16x32_bf16 v[62:65], v[158:161], v[142:145], v[62:65]
	v_mfma_f32_16x16x32_bf16 v[2:5], v[228:231], v[212:215], v[2:5]
	v_mfma_f32_16x16x32_bf16 v[6:9], v[232:235], v[212:215], v[6:9]
	v_mfma_f32_16x16x32_bf16 v[10:13], v[236:239], v[212:215], v[10:13]
	v_mfma_f32_16x16x32_bf16 v[14:17], v[240:243], v[212:215], v[14:17]
	v_mfma_f32_16x16x32_bf16 v[18:21], v[228:231], v[216:219], v[18:21]
	v_mfma_f32_16x16x32_bf16 v[22:25], v[232:235], v[216:219], v[22:25]
	v_mfma_f32_16x16x32_bf16 v[26:29], v[236:239], v[216:219], v[26:29]
	v_mfma_f32_16x16x32_bf16 v[30:33], v[240:243], v[216:219], v[30:33]
	v_mfma_f32_16x16x32_bf16 v[34:37], v[228:231], v[220:223], v[34:37]
	v_mfma_f32_16x16x32_bf16 v[38:41], v[232:235], v[220:223], v[38:41]
	v_mfma_f32_16x16x32_bf16 v[42:45], v[236:239], v[220:223], v[42:45]
	v_mfma_f32_16x16x32_bf16 v[46:49], v[240:243], v[220:223], v[46:49]
	v_mfma_f32_16x16x32_bf16 v[50:53], v[228:231], v[224:227], v[50:53]
	v_mfma_f32_16x16x32_bf16 v[54:57], v[232:235], v[224:227], v[54:57]
	v_mfma_f32_16x16x32_bf16 v[58:61], v[236:239], v[224:227], v[58:61]
	v_mfma_f32_16x16x32_bf16 v[62:65], v[240:243], v[224:227], v[62:65]
	s_setprio 0
	s_barrier
	v_add_u32_e32 v204, 0xc000, v200
	v_add_u32_e32 v205, 0xc000, v202
	ds_read_b128 v[130:133], v204 offset:0
	ds_read_b128 v[134:137], v204 offset:2048
	ds_read_b128 v[138:141], v204 offset:4096
	ds_read_b128 v[142:145], v204 offset:6144
	ds_read_b128 v[146:149], v205 offset:0
	ds_read_b128 v[150:153], v205 offset:2048
	ds_read_b128 v[154:157], v205 offset:4096
	ds_read_b128 v[158:161], v205 offset:6144
	v_add_u32_e32 v204, 0xc000, v201
	v_add_u32_e32 v205, 0xc000, v203
	ds_read_b128 v[212:215], v204 offset:0
	ds_read_b128 v[216:219], v204 offset:2048
	ds_read_b128 v[220:223], v204 offset:4096
	ds_read_b128 v[224:227], v204 offset:6144
	ds_read_b128 v[228:231], v205 offset:0
	ds_read_b128 v[232:235], v205 offset:2048
	ds_read_b128 v[236:239], v205 offset:4096
	ds_read_b128 v[240:243], v205 offset:6144
	s_add_u32 m0, s76, 0x0
	s_nop 0
	global_load_lds_dwordx4 v196, s[68:69]
	s_add_u32 m0, s76, 0x2000
	s_nop 0
	global_load_lds_dwordx4 v197, s[68:69]
	s_add_u32 m0, s76, 0x4000
	s_nop 0
	global_load_lds_dwordx4 v198, s[68:69]
	s_add_u32 m0, s76, 0x6000
	s_nop 0
	global_load_lds_dwordx4 v199, s[68:69]
	s_add_u32 m0, s76, 0x8000
	s_nop 0
	global_load_lds_dwordx4 v196, s[70:71]
	s_add_u32 m0, s76, 0xa000
	s_nop 0
	global_load_lds_dwordx4 v197, s[70:71]
	s_add_u32 s68, s68, 0x80
	s_addc_u32 s69, s69, 0
	s_add_u32 s70, s70, 0x80
	s_addc_u32 s71, s71, 0
	s_waitcnt vmcnt(6)
	s_waitcnt lgkmcnt(0)
	s_barrier
	s_setprio 1
	v_mfma_f32_16x16x32_bf16 v[2:5], v[146:149], v[130:133], v[2:5]
	v_mfma_f32_16x16x32_bf16 v[6:9], v[150:153], v[130:133], v[6:9]
	v_mfma_f32_16x16x32_bf16 v[10:13], v[154:157], v[130:133], v[10:13]
	v_mfma_f32_16x16x32_bf16 v[14:17], v[158:161], v[130:133], v[14:17]
	v_mfma_f32_16x16x32_bf16 v[18:21], v[146:149], v[134:137], v[18:21]
	v_mfma_f32_16x16x32_bf16 v[22:25], v[150:153], v[134:137], v[22:25]
	v_mfma_f32_16x16x32_bf16 v[26:29], v[154:157], v[134:137], v[26:29]
	v_mfma_f32_16x16x32_bf16 v[30:33], v[158:161], v[134:137], v[30:33]
	v_mfma_f32_16x16x32_bf16 v[34:37], v[146:149], v[138:141], v[34:37]
	v_mfma_f32_16x16x32_bf16 v[38:41], v[150:153], v[138:141], v[38:41]
	v_mfma_f32_16x16x32_bf16 v[42:45], v[154:157], v[138:141], v[42:45]
	v_mfma_f32_16x16x32_bf16 v[46:49], v[158:161], v[138:141], v[46:49]
	v_mfma_f32_16x16x32_bf16 v[50:53], v[146:149], v[142:145], v[50:53]
	v_mfma_f32_16x16x32_bf16 v[54:57], v[150:153], v[142:145], v[54:57]
	v_mfma_f32_16x16x32_bf16 v[58:61], v[154:157], v[142:145], v[58:61]
	v_mfma_f32_16x16x32_bf16 v[62:65], v[158:161], v[142:145], v[62:65]
	v_mfma_f32_16x16x32_bf16 v[2:5], v[228:231], v[212:215], v[2:5]
	v_mfma_f32_16x16x32_bf16 v[6:9], v[232:235], v[212:215], v[6:9]
	v_mfma_f32_16x16x32_bf16 v[10:13], v[236:239], v[212:215], v[10:13]
	v_mfma_f32_16x16x32_bf16 v[14:17], v[240:243], v[212:215], v[14:17]
	v_mfma_f32_16x16x32_bf16 v[18:21], v[228:231], v[216:219], v[18:21]
	v_mfma_f32_16x16x32_bf16 v[22:25], v[232:235], v[216:219], v[22:25]
	v_mfma_f32_16x16x32_bf16 v[26:29], v[236:239], v[216:219], v[26:29]
	v_mfma_f32_16x16x32_bf16 v[30:33], v[240:243], v[216:219], v[30:33]
	v_mfma_f32_16x16x32_bf16 v[34:37], v[228:231], v[220:223], v[34:37]
	v_mfma_f32_16x16x32_bf16 v[38:41], v[232:235], v[220:223], v[38:41]
	v_mfma_f32_16x16x32_bf16 v[42:45], v[236:239], v[220:223], v[42:45]
	v_mfma_f32_16x16x32_bf16 v[46:49], v[240:243], v[220:223], v[46:49]
	v_mfma_f32_16x16x32_bf16 v[50:53], v[228:231], v[224:227], v[50:53]
	v_mfma_f32_16x16x32_bf16 v[54:57], v[232:235], v[224:227], v[54:57]
	v_mfma_f32_16x16x32_bf16 v[58:61], v[236:239], v[224:227], v[58:61]
	v_mfma_f32_16x16x32_bf16 v[62:65], v[240:243], v[224:227], v[62:65]
	s_setprio 0
	s_barrier
	s_mov_b32 s16, 12
.Ldn_kloop2:
	v_add_u32_e32 v204, 0x18000, v200
	v_add_u32_e32 v205, 0x18000, v202
	ds_read_b128 v[130:133], v204 offset:0
	ds_read_b128 v[134:137], v204 offset:2048
	ds_read_b128 v[138:141], v204 offset:4096
	ds_read_b128 v[142:145], v204 offset:6144
	ds_read_b128 v[146:149], v205 offset:0
	ds_read_b128 v[150:153], v205 offset:2048
	ds_read_b128 v[154:157], v205 offset:4096
	ds_read_b128 v[158:161], v205 offset:6144
	v_add_u32_e32 v204, 0x18000, v201
	v_add_u32_e32 v205, 0x18000, v203
	ds_read_b128 v[212:215], v204 offset:0
	ds_read_b128 v[216:219], v204 offset:2048
	ds_read_b128 v[220:223], v204 offset:4096
	ds_read_b128 v[224:227], v204 offset:6144
	ds_read_b128 v[228:231], v205 offset:0
	ds_read_b128 v[232:235], v205 offset:2048
	ds_read_b128 v[236:239], v205 offset:4096
	ds_read_b128 v[240:243], v205 offset:6144
	s_add_u32 m0, s76, 0xc000
	s_nop 0
	global_load_lds_dwordx4 v196, s[68:69]
	s_add_u32 m0, s76, 0xe000
	s_nop 0
	global_load_lds_dwordx4 v197, s[68:69]
	s_add_u32 m0, s76, 0x10000
	s_nop 0
	global_load_lds_dwordx4 v198, s[68:69]
	s_add_u32 m0, s76, 0x12000
	s_nop 0
	global_load_lds_dwordx4 v199, s[68:69]
	s_add_u32 m0, s76, 0x14000
	s_nop 0
	global_load_lds_dwordx4 v196, s[70:71]
	s_add_u32 m0, s76, 0x16000
	s_nop 0
	global_load_lds_dwordx4 v197, s[70:71]
	s_add_u32 s68, s68, 0x80
	s_addc_u32 s69, s69, 0
	s_add_u32 s70, s70, 0x80
	s_addc_u32 s71, s71, 0
	s_waitcnt vmcnt(6)
	s_waitcnt lgkmcnt(0)
	s_barrier
	s_setprio 1
	v_mfma_f32_16x16x32_bf16 v[2:5], v[146:149], v[130:133], v[2:5]
	v_mfma_f32_16x16x32_bf16 v[6:9], v[150:153], v[130:133], v[6:9]
	v_mfma_f32_16x16x32_bf16 v[10:13], v[154:157], v[130:133], v[10:13]
	v_mfma_f32_16x16x32_bf16 v[14:17], v[158:161], v[130:133], v[14:17]
	v_mfma_f32_16x16x32_bf16 v[18:21], v[146:149], v[134:137], v[18:21]
	v_mfma_f32_16x16x32_bf16 v[22:25], v[150:153], v[134:137], v[22:25]
	v_mfma_f32_16x16x32_bf16 v[26:29], v[154:157], v[134:137], v[26:29]
	v_mfma_f32_16x16x32_bf16 v[30:33], v[158:161], v[134:137], v[30:33]
	v_mfma_f32_16x16x32_bf16 v[34:37], v[146:149], v[138:141], v[34:37]
	v_mfma_f32_16x16x32_bf16 v[38:41], v[150:153], v[138:141], v[38:41]
	v_mfma_f32_16x16x32_bf16 v[42:45], v[154:157], v[138:141], v[42:45]
	v_mfma_f32_16x16x32_bf16 v[46:49], v[158:161], v[138:141], v[46:49]
	v_mfma_f32_16x16x32_bf16 v[50:53], v[146:149], v[142:145], v[50:53]
	v_mfma_f32_16x16x32_bf16 v[54:57], v[150:153], v[142:145], v[54:57]
	v_mfma_f32_16x16x32_bf16 v[58:61], v[154:157], v[142:145], v[58:61]
	v_mfma_f32_16x16x32_bf16 v[62:65], v[158:161], v[142:145], v[62:65]
	v_mfma_f32_16x16x32_bf16 v[2:5], v[228:231], v[212:215], v[2:5]
	v_mfma_f32_16x16x32_bf16 v[6:9], v[232:235], v[212:215], v[6:9]
	v_mfma_f32_16x16x32_bf16 v[10:13], v[236:239], v[212:215], v[10:13]
	v_mfma_f32_16x16x32_bf16 v[14:17], v[240:243], v[212:215], v[14:17]
	v_mfma_f32_16x16x32_bf16 v[18:21], v[228:231], v[216:219], v[18:21]
	v_mfma_f32_16x16x32_bf16 v[22:25], v[232:235], v[216:219], v[22:25]
	v_mfma_f32_16x16x32_bf16 v[26:29], v[236:239], v[216:219], v[26:29]
	v_mfma_f32_16x16x32_bf16 v[30:33], v[240:243], v[216:219], v[30:33]
	v_mfma_f32_16x16x32_bf16 v[34:37], v[228:231], v[220:223], v[34:37]
	v_mfma_f32_16x16x32_bf16 v[38:41], v[232:235], v[220:223], v[38:41]
	v_mfma_f32_16x16x32_bf16 v[42:45], v[236:239], v[220:223], v[42:45]
	v_mfma_f32_16x16x32_bf16 v[46:49], v[240:243], v[220:223], v[46:49]
	v_mfma_f32_16x16x32_bf16 v[50:53], v[228:231], v[224:227], v[50:53]
	v_mfma_f32_16x16x32_bf16 v[54:57], v[232:235], v[224:227], v[54:57]
	v_mfma_f32_16x16x32_bf16 v[58:61], v[236:239], v[224:227], v[58:61]
	v_mfma_f32_16x16x32_bf16 v[62:65], v[240:243], v[224:227], v[62:65]
	s_setprio 0
	s_barrier
	v_add_u32_e32 v204, 0x0, v200
	v_add_u32_e32 v205, 0x0, v202
	ds_read_b128 v[130:133], v204 offset:0
	ds_read_b128 v[134:137], v204 offset:2048
	ds_read_b128 v[138:141], v204 offset:4096
	ds_read_b128 v[142:145], v204 offset:6144
	ds_read_b128 v[146:149], v205 offset:0
	ds_read_b128 v[150:153], v205 offset:2048
	ds_read_b128 v[154:157], v205 offset:4096
	ds_read_b128 v[158:161], v205 offset:6144
	v_add_u32_e32 v204, 0x0, v201
	v_add_u32_e32 v205, 0x0, v203
	ds_read_b128 v[212:215], v204 offset:0
	ds_read_b128 v[216:219], v204 offset:2048
	ds_read_b128 v[220:223], v204 offset:4096
	ds_read_b128 v[224:227], v204 offset:6144
	ds_read_b128 v[228:231], v205 offset:0
	ds_read_b128 v[232:235], v205 offset:2048
	ds_read_b128 v[236:239], v205 offset:4096
	ds_read_b128 v[240:243], v205 offset:6144
	s_add_u32 m0, s76, 0x18000
	s_nop 0
	global_load_lds_dwordx4 v196, s[68:69]
	s_add_u32 m0, s76, 0x1a000
	s_nop 0
	global_load_lds_dwordx4 v197, s[68:69]
	s_add_u32 m0, s76, 0x1c000
	s_nop 0
	global_load_lds_dwordx4 v198, s[68:69]
	s_add_u32 m0, s76, 0x1e000
	s_nop 0
	global_load_lds_dwordx4 v199, s[68:69]
	s_add_u32 m0, s76, 0x20000
	s_nop 0
	global_load_lds_dwordx4 v196, s[70:71]
	s_add_u32 m0, s76, 0x22000
	s_nop 0
	global_load_lds_dwordx4 v197, s[70:71]
	s_add_u32 s68, s68, 0x80
	s_addc_u32 s69, s69, 0
	s_add_u32 s70, s70, 0x80
	s_addc_u32 s71, s71, 0
	s_waitcnt vmcnt(6)
	s_waitcnt lgkmcnt(0)
	s_barrier
	s_setprio 1
	v_mfma_f32_16x16x32_bf16 v[2:5], v[146:149], v[130:133], v[2:5]
	v_mfma_f32_16x16x32_bf16 v[6:9], v[150:153], v[130:133], v[6:9]
	v_mfma_f32_16x16x32_bf16 v[10:13], v[154:157], v[130:133], v[10:13]
	v_mfma_f32_16x16x32_bf16 v[14:17], v[158:161], v[130:133], v[14:17]
	v_mfma_f32_16x16x32_bf16 v[18:21], v[146:149], v[134:137], v[18:21]
	v_mfma_f32_16x16x32_bf16 v[22:25], v[150:153], v[134:137], v[22:25]
	v_mfma_f32_16x16x32_bf16 v[26:29], v[154:157], v[134:137], v[26:29]
	v_mfma_f32_16x16x32_bf16 v[30:33], v[158:161], v[134:137], v[30:33]
	v_mfma_f32_16x16x32_bf16 v[34:37], v[146:149], v[138:141], v[34:37]
	v_mfma_f32_16x16x32_bf16 v[38:41], v[150:153], v[138:141], v[38:41]
	v_mfma_f32_16x16x32_bf16 v[42:45], v[154:157], v[138:141], v[42:45]
	v_mfma_f32_16x16x32_bf16 v[46:49], v[158:161], v[138:141], v[46:49]
	v_mfma_f32_16x16x32_bf16 v[50:53], v[146:149], v[142:145], v[50:53]
	v_mfma_f32_16x16x32_bf16 v[54:57], v[150:153], v[142:145], v[54:57]
	v_mfma_f32_16x16x32_bf16 v[58:61], v[154:157], v[142:145], v[58:61]
	v_mfma_f32_16x16x32_bf16 v[62:65], v[158:161], v[142:145], v[62:65]
	v_mfma_f32_16x16x32_bf16 v[2:5], v[228:231], v[212:215], v[2:5]
	v_mfma_f32_16x16x32_bf16 v[6:9], v[232:235], v[212:215], v[6:9]
	v_mfma_f32_16x16x32_bf16 v[10:13], v[236:239], v[212:215], v[10:13]
	v_mfma_f32_16x16x32_bf16 v[14:17], v[240:243], v[212:215], v[14:17]
	v_mfma_f32_16x16x32_bf16 v[18:21], v[228:231], v[216:219], v[18:21]
	v_mfma_f32_16x16x32_bf16 v[22:25], v[232:235], v[216:219], v[22:25]
	v_mfma_f32_16x16x32_bf16 v[26:29], v[236:239], v[216:219], v[26:29]
	v_mfma_f32_16x16x32_bf16 v[30:33], v[240:243], v[216:219], v[30:33]
	v_mfma_f32_16x16x32_bf16 v[34:37], v[228:231], v[220:223], v[34:37]
	v_mfma_f32_16x16x32_bf16 v[38:41], v[232:235], v[220:223], v[38:41]
	v_mfma_f32_16x16x32_bf16 v[42:45], v[236:239], v[220:223], v[42:45]
	v_mfma_f32_16x16x32_bf16 v[46:49], v[240:243], v[220:223], v[46:49]
	v_mfma_f32_16x16x32_bf16 v[50:53], v[228:231], v[224:227], v[50:53]
	v_mfma_f32_16x16x32_bf16 v[54:57], v[232:235], v[224:227], v[54:57]
	v_mfma_f32_16x16x32_bf16 v[58:61], v[236:239], v[224:227], v[58:61]
	v_mfma_f32_16x16x32_bf16 v[62:65], v[240:243], v[224:227], v[62:65]
	s_setprio 0
	s_barrier
	v_add_u32_e32 v204, 0xc000, v200
	v_add_u32_e32 v205, 0xc000, v202
	ds_read_b128 v[130:133], v204 offset:0
	ds_read_b128 v[134:137], v204 offset:2048
	ds_read_b128 v[138:141], v204 offset:4096
	ds_read_b128 v[142:145], v204 offset:6144
	ds_read_b128 v[146:149], v205 offset:0
	ds_read_b128 v[150:153], v205 offset:2048
	ds_read_b128 v[154:157], v205 offset:4096
	ds_read_b128 v[158:161], v205 offset:6144
	v_add_u32_e32 v204, 0xc000, v201
	v_add_u32_e32 v205, 0xc000, v203
	ds_read_b128 v[212:215], v204 offset:0
	ds_read_b128 v[216:219], v204 offset:2048
	ds_read_b128 v[220:223], v204 offset:4096
	ds_read_b128 v[224:227], v204 offset:6144
	ds_read_b128 v[228:231], v205 offset:0
	ds_read_b128 v[232:235], v205 offset:2048
	ds_read_b128 v[236:239], v205 offset:4096
	ds_read_b128 v[240:243], v205 offset:6144
	s_add_u32 m0, s76, 0x0
	s_nop 0
	global_load_lds_dwordx4 v196, s[68:69]
	s_add_u32 m0, s76, 0x2000
	s_nop 0
	global_load_lds_dwordx4 v197, s[68:69]
	s_add_u32 m0, s76, 0x4000
	s_nop 0
	global_load_lds_dwordx4 v198, s[68:69]
	s_add_u32 m0, s76, 0x6000
	s_nop 0
	global_load_lds_dwordx4 v199, s[68:69]
	s_add_u32 m0, s76, 0x8000
	s_nop 0
	global_load_lds_dwordx4 v196, s[70:71]
	s_add_u32 m0, s76, 0xa000
	s_nop 0
	global_load_lds_dwordx4 v197, s[70:71]
	s_add_u32 s68, s68, 0x80
	s_addc_u32 s69, s69, 0
	s_add_u32 s70, s70, 0x80
	s_addc_u32 s71, s71, 0
	s_waitcnt vmcnt(6)
	s_waitcnt lgkmcnt(0)
	s_barrier
	s_setprio 1
	v_mfma_f32_16x16x32_bf16 v[2:5], v[146:149], v[130:133], v[2:5]
	v_mfma_f32_16x16x32_bf16 v[6:9], v[150:153], v[130:133], v[6:9]
	v_mfma_f32_16x16x32_bf16 v[10:13], v[154:157], v[130:133], v[10:13]
	v_mfma_f32_16x16x32_bf16 v[14:17], v[158:161], v[130:133], v[14:17]
	v_mfma_f32_16x16x32_bf16 v[18:21], v[146:149], v[134:137], v[18:21]
	v_mfma_f32_16x16x32_bf16 v[22:25], v[150:153], v[134:137], v[22:25]
	v_mfma_f32_16x16x32_bf16 v[26:29], v[154:157], v[134:137], v[26:29]
	v_mfma_f32_16x16x32_bf16 v[30:33], v[158:161], v[134:137], v[30:33]
	v_mfma_f32_16x16x32_bf16 v[34:37], v[146:149], v[138:141], v[34:37]
	v_mfma_f32_16x16x32_bf16 v[38:41], v[150:153], v[138:141], v[38:41]
	v_mfma_f32_16x16x32_bf16 v[42:45], v[154:157], v[138:141], v[42:45]
	v_mfma_f32_16x16x32_bf16 v[46:49], v[158:161], v[138:141], v[46:49]
	v_mfma_f32_16x16x32_bf16 v[50:53], v[146:149], v[142:145], v[50:53]
	v_mfma_f32_16x16x32_bf16 v[54:57], v[150:153], v[142:145], v[54:57]
	v_mfma_f32_16x16x32_bf16 v[58:61], v[154:157], v[142:145], v[58:61]
	v_mfma_f32_16x16x32_bf16 v[62:65], v[158:161], v[142:145], v[62:65]
	v_mfma_f32_16x16x32_bf16 v[2:5], v[228:231], v[212:215], v[2:5]
	v_mfma_f32_16x16x32_bf16 v[6:9], v[232:235], v[212:215], v[6:9]
	v_mfma_f32_16x16x32_bf16 v[10:13], v[236:239], v[212:215], v[10:13]
	v_mfma_f32_16x16x32_bf16 v[14:17], v[240:243], v[212:215], v[14:17]
	v_mfma_f32_16x16x32_bf16 v[18:21], v[228:231], v[216:219], v[18:21]
	v_mfma_f32_16x16x32_bf16 v[22:25], v[232:235], v[216:219], v[22:25]
	v_mfma_f32_16x16x32_bf16 v[26:29], v[236:239], v[216:219], v[26:29]
	v_mfma_f32_16x16x32_bf16 v[30:33], v[240:243], v[216:219], v[30:33]
	v_mfma_f32_16x16x32_bf16 v[34:37], v[228:231], v[220:223], v[34:37]
	v_mfma_f32_16x16x32_bf16 v[38:41], v[232:235], v[220:223], v[38:41]
	v_mfma_f32_16x16x32_bf16 v[42:45], v[236:239], v[220:223], v[42:45]
	v_mfma_f32_16x16x32_bf16 v[46:49], v[240:243], v[220:223], v[46:49]
	v_mfma_f32_16x16x32_bf16 v[50:53], v[228:231], v[224:227], v[50:53]
	v_mfma_f32_16x16x32_bf16 v[54:57], v[232:235], v[224:227], v[54:57]
	v_mfma_f32_16x16x32_bf16 v[58:61], v[236:239], v[224:227], v[58:61]
	v_mfma_f32_16x16x32_bf16 v[62:65], v[240:243], v[224:227], v[62:65]
	s_setprio 0
	s_barrier
	s_add_i32 s16, s16, -1
	s_cmp_lg_u32 s16, 0
	s_cbranch_scc1 .Ldn_kloop2
	v_add_u32_e32 v204, 0x18000, v200
	v_add_u32_e32 v205, 0x18000, v202
	ds_read_b128 v[130:133], v204 offset:0
	ds_read_b128 v[134:137], v204 offset:2048
	ds_read_b128 v[138:141], v204 offset:4096
	ds_read_b128 v[142:145], v204 offset:6144
	ds_read_b128 v[146:149], v205 offset:0
	ds_read_b128 v[150:153], v205 offset:2048
	ds_read_b128 v[154:157], v205 offset:4096
	ds_read_b128 v[158:161], v205 offset:6144
	v_add_u32_e32 v204, 0x18000, v201
	v_add_u32_e32 v205, 0x18000, v203
	ds_read_b128 v[212:215], v204 offset:0
	ds_read_b128 v[216:219], v204 offset:2048
	ds_read_b128 v[220:223], v204 offset:4096
	ds_read_b128 v[224:227], v204 offset:6144
	ds_read_b128 v[228:231], v205 offset:0
	ds_read_b128 v[232:235], v205 offset:2048
	ds_read_b128 v[236:239], v205 offset:4096
	ds_read_b128 v[240:243], v205 offset:6144
	s_add_u32 m0, s76, 0xc000
	s_nop 0
	global_load_lds_dwordx4 v196, s[68:69]
	s_add_u32 m0, s76, 0xe000
	s_nop 0
	global_load_lds_dwordx4 v197, s[68:69]
	s_add_u32 m0, s76, 0x10000
	s_nop 0
	global_load_lds_dwordx4 v198, s[68:69]
	s_add_u32 m0, s76, 0x12000
	s_nop 0
	global_load_lds_dwordx4 v199, s[68:69]
	s_add_u32 m0, s76, 0x14000
	s_nop 0
	global_load_lds_dwordx4 v196, s[70:71]
	s_add_u32 m0, s76, 0x16000
	s_nop 0
	global_load_lds_dwordx4 v197, s[70:71]
	s_add_u32 s68, s68, 0x80
	s_addc_u32 s69, s69, 0
	s_add_u32 s70, s70, 0x80
	s_addc_u32 s71, s71, 0
	s_waitcnt vmcnt(6)
	s_waitcnt lgkmcnt(0)
	s_barrier
	s_setprio 1
	v_mfma_f32_16x16x32_bf16 v[2:5], v[146:149], v[130:133], v[2:5]
	v_mfma_f32_16x16x32_bf16 v[6:9], v[150:153], v[130:133], v[6:9]
	v_mfma_f32_16x16x32_bf16 v[10:13], v[154:157], v[130:133], v[10:13]
	v_mfma_f32_16x16x32_bf16 v[14:17], v[158:161], v[130:133], v[14:17]
	v_mfma_f32_16x16x32_bf16 v[18:21], v[146:149], v[134:137], v[18:21]
	v_mfma_f32_16x16x32_bf16 v[22:25], v[150:153], v[134:137], v[22:25]
	v_mfma_f32_16x16x32_bf16 v[26:29], v[154:157], v[134:137], v[26:29]
	v_mfma_f32_16x16x32_bf16 v[30:33], v[158:161], v[134:137], v[30:33]
	v_mfma_f32_16x16x32_bf16 v[34:37], v[146:149], v[138:141], v[34:37]
	v_mfma_f32_16x16x32_bf16 v[38:41], v[150:153], v[138:141], v[38:41]
	v_mfma_f32_16x16x32_bf16 v[42:45], v[154:157], v[138:141], v[42:45]
	v_mfma_f32_16x16x32_bf16 v[46:49], v[158:161], v[138:141], v[46:49]
	v_mfma_f32_16x16x32_bf16 v[50:53], v[146:149], v[142:145], v[50:53]
	v_mfma_f32_16x16x32_bf16 v[54:57], v[150:153], v[142:145], v[54:57]
	v_mfma_f32_16x16x32_bf16 v[58:61], v[154:157], v[142:145], v[58:61]
	v_mfma_f32_16x16x32_bf16 v[62:65], v[158:161], v[142:145], v[62:65]
	v_mfma_f32_16x16x32_bf16 v[2:5], v[228:231], v[212:215], v[2:5]
	v_mfma_f32_16x16x32_bf16 v[6:9], v[232:235], v[212:215], v[6:9]
	v_mfma_f32_16x16x32_bf16 v[10:13], v[236:239], v[212:215], v[10:13]
	v_mfma_f32_16x16x32_bf16 v[14:17], v[240:243], v[212:215], v[14:17]
	v_mfma_f32_16x16x32_bf16 v[18:21], v[228:231], v[216:219], v[18:21]
	v_mfma_f32_16x16x32_bf16 v[22:25], v[232:235], v[216:219], v[22:25]
	v_mfma_f32_16x16x32_bf16 v[26:29], v[236:239], v[216:219], v[26:29]
	v_mfma_f32_16x16x32_bf16 v[30:33], v[240:243], v[216:219], v[30:33]
	v_mfma_f32_16x16x32_bf16 v[34:37], v[228:231], v[220:223], v[34:37]
	v_mfma_f32_16x16x32_bf16 v[38:41], v[232:235], v[220:223], v[38:41]
	v_mfma_f32_16x16x32_bf16 v[42:45], v[236:239], v[220:223], v[42:45]
	v_mfma_f32_16x16x32_bf16 v[46:49], v[240:243], v[220:223], v[46:49]
	v_mfma_f32_16x16x32_bf16 v[50:53], v[228:231], v[224:227], v[50:53]
	v_mfma_f32_16x16x32_bf16 v[54:57], v[232:235], v[224:227], v[54:57]
	v_mfma_f32_16x16x32_bf16 v[58:61], v[236:239], v[224:227], v[58:61]
	v_mfma_f32_16x16x32_bf16 v[62:65], v[240:243], v[224:227], v[62:65]
	s_setprio 0
	s_barrier
	v_add_u32_e32 v204, 0x0, v200
	v_add_u32_e32 v205, 0x0, v202
	ds_read_b128 v[130:133], v204 offset:0
	ds_read_b128 v[134:137], v204 offset:2048
	ds_read_b128 v[138:141], v204 offset:4096
	ds_read_b128 v[142:145], v204 offset:6144
	ds_read_b128 v[146:149], v205 offset:0
	ds_read_b128 v[150:153], v205 offset:2048
	ds_read_b128 v[154:157], v205 offset:4096
	ds_read_b128 v[158:161], v205 offset:6144
	v_add_u32_e32 v204, 0x0, v201
	v_add_u32_e32 v205, 0x0, v203
	ds_read_b128 v[212:215], v204 offset:0
	ds_read_b128 v[216:219], v204 offset:2048
	ds_read_b128 v[220:223], v204 offset:4096
	ds_read_b128 v[224:227], v204 offset:6144
	ds_read_b128 v[228:231], v205 offset:0
	ds_read_b128 v[232:235], v205 offset:2048
	ds_read_b128 v[236:239], v205 offset:4096
	ds_read_b128 v[240:243], v205 offset:6144
	s_waitcnt vmcnt(0)
	s_waitcnt lgkmcnt(0)
	s_barrier
	s_setprio 1
	v_mfma_f32_16x16x32_bf16 v[2:5], v[146:149], v[130:133], v[2:5]
	v_mfma_f32_16x16x32_bf16 v[6:9], v[150:153], v[130:133], v[6:9]
	v_mfma_f32_16x16x32_bf16 v[10:13], v[154:157], v[130:133], v[10:13]
	v_mfma_f32_16x16x32_bf16 v[14:17], v[158:161], v[130:133], v[14:17]
	v_mfma_f32_16x16x32_bf16 v[18:21], v[146:149], v[134:137], v[18:21]
	v_mfma_f32_16x16x32_bf16 v[22:25], v[150:153], v[134:137], v[22:25]
	v_mfma_f32_16x16x32_bf16 v[26:29], v[154:157], v[134:137], v[26:29]
	v_mfma_f32_16x16x32_bf16 v[30:33], v[158:161], v[134:137], v[30:33]
	v_mfma_f32_16x16x32_bf16 v[34:37], v[146:149], v[138:141], v[34:37]
	v_mfma_f32_16x16x32_bf16 v[38:41], v[150:153], v[138:141], v[38:41]
	v_mfma_f32_16x16x32_bf16 v[42:45], v[154:157], v[138:141], v[42:45]
	v_mfma_f32_16x16x32_bf16 v[46:49], v[158:161], v[138:141], v[46:49]
	v_mfma_f32_16x16x32_bf16 v[50:53], v[146:149], v[142:145], v[50:53]
	v_mfma_f32_16x16x32_bf16 v[54:57], v[150:153], v[142:145], v[54:57]
	v_mfma_f32_16x16x32_bf16 v[58:61], v[154:157], v[142:145], v[58:61]
	v_mfma_f32_16x16x32_bf16 v[62:65], v[158:161], v[142:145], v[62:65]
	v_mfma_f32_16x16x32_bf16 v[2:5], v[228:231], v[212:215], v[2:5]
	v_mfma_f32_16x16x32_bf16 v[6:9], v[232:235], v[212:215], v[6:9]
	v_mfma_f32_16x16x32_bf16 v[10:13], v[236:239], v[212:215], v[10:13]
	v_mfma_f32_16x16x32_bf16 v[14:17], v[240:243], v[212:215], v[14:17]
	v_mfma_f32_16x16x32_bf16 v[18:21], v[228:231], v[216:219], v[18:21]
	v_mfma_f32_16x16x32_bf16 v[22:25], v[232:235], v[216:219], v[22:25]
	v_mfma_f32_16x16x32_bf16 v[26:29], v[236:239], v[216:219], v[26:29]
	v_mfma_f32_16x16x32_bf16 v[30:33], v[240:243], v[216:219], v[30:33]
	v_mfma_f32_16x16x32_bf16 v[34:37], v[228:231], v[220:223], v[34:37]
	v_mfma_f32_16x16x32_bf16 v[38:41], v[232:235], v[220:223], v[38:41]
	v_mfma_f32_16x16x32_bf16 v[42:45], v[236:239], v[220:223], v[42:45]
	v_mfma_f32_16x16x32_bf16 v[46:49], v[240:243], v[220:223], v[46:49]
	v_mfma_f32_16x16x32_bf16 v[50:53], v[228:231], v[224:227], v[50:53]
	v_mfma_f32_16x16x32_bf16 v[54:57], v[232:235], v[224:227], v[54:57]
	v_mfma_f32_16x16x32_bf16 v[58:61], v[236:239], v[224:227], v[58:61]
	v_mfma_f32_16x16x32_bf16 v[62:65], v[240:243], v[224:227], v[62:65]
	s_setprio 0
	s_barrier
	v_add_u32_e32 v204, 0xc000, v200
	v_add_u32_e32 v205, 0xc000, v202
	ds_read_b128 v[130:133], v204 offset:0
	ds_read_b128 v[134:137], v204 offset:2048
	ds_read_b128 v[138:141], v204 offset:4096
	ds_read_b128 v[142:145], v204 offset:6144
	ds_read_b128 v[146:149], v205 offset:0
	ds_read_b128 v[150:153], v205 offset:2048
	ds_read_b128 v[154:157], v205 offset:4096
	ds_read_b128 v[158:161], v205 offset:6144
	v_add_u32_e32 v204, 0xc000, v201
	v_add_u32_e32 v205, 0xc000, v203
	ds_read_b128 v[212:215], v204 offset:0
	ds_read_b128 v[216:219], v204 offset:2048
	ds_read_b128 v[220:223], v204 offset:4096
	ds_read_b128 v[224:227], v204 offset:6144
	ds_read_b128 v[228:231], v205 offset:0
	ds_read_b128 v[232:235], v205 offset:2048
	ds_read_b128 v[236:239], v205 offset:4096
	ds_read_b128 v[240:243], v205 offset:6144
	s_waitcnt lgkmcnt(0)
	s_barrier
	s_setprio 1
	v_mfma_f32_16x16x32_bf16 v[2:5], v[146:149], v[130:133], v[2:5]
	v_mfma_f32_16x16x32_bf16 v[6:9], v[150:153], v[130:133], v[6:9]
	v_mfma_f32_16x16x32_bf16 v[10:13], v[154:157], v[130:133], v[10:13]
	v_mfma_f32_16x16x32_bf16 v[14:17], v[158:161], v[130:133], v[14:17]
	v_mfma_f32_16x16x32_bf16 v[18:21], v[146:149], v[134:137], v[18:21]
	v_mfma_f32_16x16x32_bf16 v[22:25], v[150:153], v[134:137], v[22:25]
	v_mfma_f32_16x16x32_bf16 v[26:29], v[154:157], v[134:137], v[26:29]
	v_mfma_f32_16x16x32_bf16 v[30:33], v[158:161], v[134:137], v[30:33]
	v_mfma_f32_16x16x32_bf16 v[34:37], v[146:149], v[138:141], v[34:37]
	v_mfma_f32_16x16x32_bf16 v[38:41], v[150:153], v[138:141], v[38:41]
	v_mfma_f32_16x16x32_bf16 v[42:45], v[154:157], v[138:141], v[42:45]
	v_mfma_f32_16x16x32_bf16 v[46:49], v[158:161], v[138:141], v[46:49]
	v_mfma_f32_16x16x32_bf16 v[50:53], v[146:149], v[142:145], v[50:53]
	v_mfma_f32_16x16x32_bf16 v[54:57], v[150:153], v[142:145], v[54:57]
	v_mfma_f32_16x16x32_bf16 v[58:61], v[154:157], v[142:145], v[58:61]
	v_mfma_f32_16x16x32_bf16 v[62:65], v[158:161], v[142:145], v[62:65]
	v_mfma_f32_16x16x32_bf16 v[2:5], v[228:231], v[212:215], v[2:5]
	v_mfma_f32_16x16x32_bf16 v[6:9], v[232:235], v[212:215], v[6:9]
	v_mfma_f32_16x16x32_bf16 v[10:13], v[236:239], v[212:215], v[10:13]
	v_mfma_f32_16x16x32_bf16 v[14:17], v[240:243], v[212:215], v[14:17]
	v_mfma_f32_16x16x32_bf16 v[18:21], v[228:231], v[216:219], v[18:21]
	v_mfma_f32_16x16x32_bf16 v[22:25], v[232:235], v[216:219], v[22:25]
	v_mfma_f32_16x16x32_bf16 v[26:29], v[236:239], v[216:219], v[26:29]
	v_mfma_f32_16x16x32_bf16 v[30:33], v[240:243], v[216:219], v[30:33]
	v_mfma_f32_16x16x32_bf16 v[34:37], v[228:231], v[220:223], v[34:37]
	v_mfma_f32_16x16x32_bf16 v[38:41], v[232:235], v[220:223], v[38:41]
	v_mfma_f32_16x16x32_bf16 v[42:45], v[236:239], v[220:223], v[42:45]
	v_mfma_f32_16x16x32_bf16 v[46:49], v[240:243], v[220:223], v[46:49]
	v_mfma_f32_16x16x32_bf16 v[50:53], v[228:231], v[224:227], v[50:53]
	v_mfma_f32_16x16x32_bf16 v[54:57], v[232:235], v[224:227], v[54:57]
	v_mfma_f32_16x16x32_bf16 v[58:61], v[236:239], v[224:227], v[58:61]
	v_mfma_f32_16x16x32_bf16 v[62:65], v[240:243], v[224:227], v[62:65]
	s_setprio 0

.Lop_tile:
	s_and_b32 s0, s78, 3
	s_or_b32 s0, s0, s77
	s_lshr_b32 s1, s78, 2
	s_lshl_b32 s1, s1, 7
	s_lshl_b32 s2, s0, 8
	s_mul_i32 s3, s2, 0x800
	s_add_u32 s68, s18, s3
	s_addc_u32 s69, s19, 0
	s_mul_i32 s3, s1, 0x800
	s_add_u32 s70, s80, s3
	s_addc_u32 s71, s81, 0
	s_lshl_b32 s3, s2, 11
	s_lshl_b32 s12, s1, 1
	s_add_u32 s3, s3, s12
	s_add_u32 s74, s24, s3
	s_addc_u32 s75, s25, 0
	s_add_i32 s12, s0, -12
	s_lshr_b32 s12, s12, 2
	s_cmp_lt_u32 s0, 16
	s_cselect_b32 s12, 0, s12
	s_cselect_b32 s14, s52, s54
	s_cselect_b32 s15, s53, s55
	s_mul_i32 s13, s82, 5
	s_add_i32 s12, s12, s13
	s_mul_i32 s12, s12, 0x6000
	s_add_u32 s12, s12, 0x2000
	s_lshl_b32 s13, s1, 2
	s_add_u32 s12, s12, s13
	s_add_u32 s72, s30, s12
	s_addc_u32 s73, s31, 0
	s_and_b32 s12, s0, 15
	s_lshl_b32 s12, s12, 20
	s_add_u32 s12, s12, s13
	s_add_u32 s14, s14, s12
	s_addc_u32 s15, s15, 0
	s_cmp_eq_u32 s82, 0
	s_cselect_b32 s14, s14, s74
	s_cselect_b32 s15, s15, s75
	s_cselect_b32 s38, 64, 32
	s_cselect_b64 vcc, -1, 0
	s_lshl_b32 s39, s38, 1
	s_add_u32 s40, s39, s38
	v_cndmask_b32_e32 v191, v206, v210, vcc
	v_cndmask_b32_e32 v192, v207, v211, vcc
	v_cndmask_b32_e32 v193, v208, v168, vcc
	v_cndmask_b32_e32 v244, v209, v169, vcc
	s_add_u32 m0, s76, 0x0
	s_nop 0
	global_load_lds_dwordx4 v196, s[68:69]
	s_add_u32 m0, s76, 0x2000
	s_nop 0
	global_load_lds_dwordx4 v197, s[68:69]
	s_add_u32 m0, s76, 0x4000
	s_nop 0
	global_load_lds_dwordx4 v198, s[68:69]
	s_add_u32 m0, s76, 0x6000
	s_nop 0
	global_load_lds_dwordx4 v199, s[68:69]
	s_add_u32 m0, s76, 0x8000
	s_nop 0
	global_load_lds_dwordx4 v196, s[70:71]
	s_add_u32 m0, s76, 0xa000
	s_nop 0
	global_load_lds_dwordx4 v197, s[70:71]
	s_add_u32 s68, s68, 0x80
	s_addc_u32 s69, s69, 0
	s_add_u32 s70, s70, 0x80
	s_addc_u32 s71, s71, 0
	s_add_u32 m0, s76, 0xc000
	s_nop 0
	global_load_lds_dwordx4 v196, s[68:69]
	s_add_u32 m0, s76, 0xe000
	s_nop 0
	global_load_lds_dwordx4 v197, s[68:69]
	s_add_u32 m0, s76, 0x10000
	s_nop 0
	global_load_lds_dwordx4 v198, s[68:69]
	s_add_u32 m0, s76, 0x12000
	s_nop 0
	global_load_lds_dwordx4 v199, s[68:69]
	s_add_u32 m0, s76, 0x14000
	s_nop 0
	global_load_lds_dwordx4 v196, s[70:71]
	s_add_u32 m0, s76, 0x16000
	s_nop 0
	global_load_lds_dwordx4 v197, s[70:71]
	s_add_u32 s68, s68, 0x80
	s_addc_u32 s69, s69, 0
	s_add_u32 s70, s70, 0x80
	s_addc_u32 s71, s71, 0
	s_waitcnt vmcnt(6)
	s_barrier
	s_cmp_ge_u32 s76, 0x1000
	s_cbranch_scc1 .Lop_streamB
	v_add_u32_e32 v204, 0x0, v200
	v_add_u32_e32 v205, 0x0, v202
	ds_read_b128 v[130:133], v204 offset:0
	ds_read_b128 v[134:137], v204 offset:2048
	ds_read_b128 v[138:141], v204 offset:4096
	ds_read_b128 v[142:145], v204 offset:6144
	ds_read_b128 v[146:149], v205 offset:0
	ds_read_b128 v[150:153], v205 offset:2048
	ds_read_b128 v[154:157], v205 offset:4096
	ds_read_b128 v[158:161], v205 offset:6144
	v_add_u32_e32 v204, 0x0, v201
	v_add_u32_e32 v205, 0x0, v203
	ds_read_b128 v[212:215], v204 offset:0
	ds_read_b128 v[216:219], v204 offset:2048
	ds_read_b128 v[220:223], v204 offset:4096
	ds_read_b128 v[224:227], v204 offset:6144
	ds_read_b128 v[228:231], v205 offset:0
	ds_read_b128 v[232:235], v205 offset:2048
	ds_read_b128 v[236:239], v205 offset:4096
	ds_read_b128 v[240:243], v205 offset:6144
	s_add_u32 m0, s76, 0x18000
	s_nop 0
	global_load_lds_dwordx4 v196, s[68:69]
	s_add_u32 m0, s76, 0x1a000
	s_nop 0
	global_load_lds_dwordx4 v197, s[68:69]
	s_add_u32 m0, s76, 0x1c000
	s_nop 0
	global_load_lds_dwordx4 v198, s[68:69]
	s_add_u32 m0, s76, 0x1e000
	s_nop 0
	global_load_lds_dwordx4 v199, s[68:69]
	s_add_u32 m0, s76, 0x20000
	s_nop 0
	global_load_lds_dwordx4 v196, s[70:71]
	s_add_u32 m0, s76, 0x22000
	s_nop 0
	global_load_lds_dwordx4 v197, s[70:71]
	s_add_u32 s68, s68, 0x80
	s_addc_u32 s69, s69, 0
	s_add_u32 s70, s70, 0x80
	s_addc_u32 s71, s71, 0
	global_load_dwordx4 v[174:177], v190, s[72:73] offset:0
	global_load_dwordx4 v[178:181], v190, s[72:73] offset:64
	s_waitcnt lgkmcnt(0)
	s_barrier
	s_setprio 1
	v_mfma_f32_16x16x32_bf16 v[2:5], v[146:149], v[130:133], 0
	v_mfma_f32_16x16x32_bf16 v[6:9], v[150:153], v[130:133], 0
	v_mfma_f32_16x16x32_bf16 v[10:13], v[154:157], v[130:133], 0
	v_mfma_f32_16x16x32_bf16 v[14:17], v[158:161], v[130:133], 0
	v_mfma_f32_16x16x32_bf16 v[18:21], v[146:149], v[134:137], 0
	v_mfma_f32_16x16x32_bf16 v[22:25], v[150:153], v[134:137], 0
	v_mfma_f32_16x16x32_bf16 v[26:29], v[154:157], v[134:137], 0
	v_mfma_f32_16x16x32_bf16 v[30:33], v[158:161], v[134:137], 0
	v_mfma_f32_16x16x32_bf16 v[34:37], v[146:149], v[138:141], 0
	v_mfma_f32_16x16x32_bf16 v[38:41], v[150:153], v[138:141], 0
	v_mfma_f32_16x16x32_bf16 v[42:45], v[154:157], v[138:141], 0
	v_mfma_f32_16x16x32_bf16 v[46:49], v[158:161], v[138:141], 0
	v_mfma_f32_16x16x32_bf16 v[50:53], v[146:149], v[142:145], 0
	v_mfma_f32_16x16x32_bf16 v[54:57], v[150:153], v[142:145], 0
	v_mfma_f32_16x16x32_bf16 v[58:61], v[154:157], v[142:145], 0
	v_mfma_f32_16x16x32_bf16 v[62:65], v[158:161], v[142:145], 0
	v_mfma_f32_16x16x32_bf16 v[2:5], v[228:231], v[212:215], v[2:5]
	v_mfma_f32_16x16x32_bf16 v[6:9], v[232:235], v[212:215], v[6:9]
	v_mfma_f32_16x16x32_bf16 v[10:13], v[236:239], v[212:215], v[10:13]
	v_mfma_f32_16x16x32_bf16 v[14:17], v[240:243], v[212:215], v[14:17]
	v_mfma_f32_16x16x32_bf16 v[18:21], v[228:231], v[216:219], v[18:21]
	v_mfma_f32_16x16x32_bf16 v[22:25], v[232:235], v[216:219], v[22:25]
	v_mfma_f32_16x16x32_bf16 v[26:29], v[236:239], v[216:219], v[26:29]
	v_mfma_f32_16x16x32_bf16 v[30:33], v[240:243], v[216:219], v[30:33]
	v_mfma_f32_16x16x32_bf16 v[34:37], v[228:231], v[220:223], v[34:37]
	v_mfma_f32_16x16x32_bf16 v[38:41], v[232:235], v[220:223], v[38:41]
	v_mfma_f32_16x16x32_bf16 v[42:45], v[236:239], v[220:223], v[42:45]
	v_mfma_f32_16x16x32_bf16 v[46:49], v[240:243], v[220:223], v[46:49]
	v_mfma_f32_16x16x32_bf16 v[50:53], v[228:231], v[224:227], v[50:53]
	v_mfma_f32_16x16x32_bf16 v[54:57], v[232:235], v[224:227], v[54:57]
	v_mfma_f32_16x16x32_bf16 v[58:61], v[236:239], v[224:227], v[58:61]
	v_mfma_f32_16x16x32_bf16 v[62:65], v[240:243], v[224:227], v[62:65]
	s_setprio 0
	s_waitcnt vmcnt(8)
	s_barrier
	v_add_u32_e32 v204, 0xc000, v200
	v_add_u32_e32 v205, 0xc000, v202
	ds_read_b128 v[130:133], v204 offset:0
	ds_read_b128 v[134:137], v204 offset:2048
	ds_read_b128 v[138:141], v204 offset:4096
	ds_read_b128 v[142:145], v204 offset:6144
	ds_read_b128 v[146:149], v205 offset:0
	ds_read_b128 v[150:153], v205 offset:2048
	ds_read_b128 v[154:157], v205 offset:4096
	ds_read_b128 v[158:161], v205 offset:6144
	v_add_u32_e32 v204, 0xc000, v201
	v_add_u32_e32 v205, 0xc000, v203
	ds_read_b128 v[212:215], v204 offset:0
	ds_read_b128 v[216:219], v204 offset:2048
	ds_read_b128 v[220:223], v204 offset:4096
	ds_read_b128 v[224:227], v204 offset:6144
	ds_read_b128 v[228:231], v205 offset:0
	ds_read_b128 v[232:235], v205 offset:2048
	ds_read_b128 v[236:239], v205 offset:4096
	ds_read_b128 v[240:243], v205 offset:6144
	s_add_u32 m0, s76, 0x0
	s_nop 0
	global_load_lds_dwordx4 v196, s[68:69]
	s_add_u32 m0, s76, 0x2000
	s_nop 0
	global_load_lds_dwordx4 v197, s[68:69]
	s_add_u32 m0, s76, 0x4000
	s_nop 0
	global_load_lds_dwordx4 v198, s[68:69]
	s_add_u32 m0, s76, 0x6000
	s_nop 0
	global_load_lds_dwordx4 v199, s[68:69]
	s_add_u32 m0, s76, 0x8000
	s_nop 0
	global_load_lds_dwordx4 v196, s[70:71]
	s_add_u32 m0, s76, 0xa000
	s_nop 0
	global_load_lds_dwordx4 v197, s[70:71]
	s_add_u32 s68, s68, 0x80
	s_addc_u32 s69, s69, 0
	s_add_u32 s70, s70, 0x80
	s_addc_u32 s71, s71, 0
	global_load_dwordx4 v[182:185], v190, s[72:73] offset:128
	global_load_dwordx4 v[186:189], v190, s[72:73] offset:192
	s_waitcnt lgkmcnt(0)
	s_barrier
	s_setprio 1
	v_mfma_f32_16x16x32_bf16 v[2:5], v[146:149], v[130:133], v[2:5]
	v_mfma_f32_16x16x32_bf16 v[6:9], v[150:153], v[130:133], v[6:9]
	v_mfma_f32_16x16x32_bf16 v[10:13], v[154:157], v[130:133], v[10:13]
	v_mfma_f32_16x16x32_bf16 v[14:17], v[158:161], v[130:133], v[14:17]
	v_mfma_f32_16x16x32_bf16 v[18:21], v[146:149], v[134:137], v[18:21]
	v_mfma_f32_16x16x32_bf16 v[22:25], v[150:153], v[134:137], v[22:25]
	v_mfma_f32_16x16x32_bf16 v[26:29], v[154:157], v[134:137], v[26:29]
	v_mfma_f32_16x16x32_bf16 v[30:33], v[158:161], v[134:137], v[30:33]
	v_mfma_f32_16x16x32_bf16 v[34:37], v[146:149], v[138:141], v[34:37]
	v_mfma_f32_16x16x32_bf16 v[38:41], v[150:153], v[138:141], v[38:41]
	v_mfma_f32_16x16x32_bf16 v[42:45], v[154:157], v[138:141], v[42:45]
	v_mfma_f32_16x16x32_bf16 v[46:49], v[158:161], v[138:141], v[46:49]
	v_mfma_f32_16x16x32_bf16 v[50:53], v[146:149], v[142:145], v[50:53]
	v_mfma_f32_16x16x32_bf16 v[54:57], v[150:153], v[142:145], v[54:57]
	v_mfma_f32_16x16x32_bf16 v[58:61], v[154:157], v[142:145], v[58:61]
	v_mfma_f32_16x16x32_bf16 v[62:65], v[158:161], v[142:145], v[62:65]
	v_mfma_f32_16x16x32_bf16 v[2:5], v[228:231], v[212:215], v[2:5]
	v_mfma_f32_16x16x32_bf16 v[6:9], v[232:235], v[212:215], v[6:9]
	v_mfma_f32_16x16x32_bf16 v[10:13], v[236:239], v[212:215], v[10:13]
	v_mfma_f32_16x16x32_bf16 v[14:17], v[240:243], v[212:215], v[14:17]
	v_mfma_f32_16x16x32_bf16 v[18:21], v[228:231], v[216:219], v[18:21]
	v_mfma_f32_16x16x32_bf16 v[22:25], v[232:235], v[216:219], v[22:25]
	v_mfma_f32_16x16x32_bf16 v[26:29], v[236:239], v[216:219], v[26:29]
	v_mfma_f32_16x16x32_bf16 v[30:33], v[240:243], v[216:219], v[30:33]
	v_mfma_f32_16x16x32_bf16 v[34:37], v[228:231], v[220:223], v[34:37]
	v_mfma_f32_16x16x32_bf16 v[38:41], v[232:235], v[220:223], v[38:41]
	v_mfma_f32_16x16x32_bf16 v[42:45], v[236:239], v[220:223], v[42:45]
	v_mfma_f32_16x16x32_bf16 v[46:49], v[240:243], v[220:223], v[46:49]
	v_mfma_f32_16x16x32_bf16 v[50:53], v[228:231], v[224:227], v[50:53]
	v_mfma_f32_16x16x32_bf16 v[54:57], v[232:235], v[224:227], v[54:57]
	v_mfma_f32_16x16x32_bf16 v[58:61], v[236:239], v[224:227], v[58:61]
	v_mfma_f32_16x16x32_bf16 v[62:65], v[240:243], v[224:227], v[62:65]
	s_setprio 0
	s_waitcnt vmcnt(10)
	s_barrier
	v_add_u32_e32 v204, 0x18000, v200
	v_add_u32_e32 v205, 0x18000, v202
	ds_read_b128 v[130:133], v204 offset:0
	ds_read_b128 v[134:137], v204 offset:2048
	ds_read_b128 v[138:141], v204 offset:4096
	ds_read_b128 v[142:145], v204 offset:6144
	ds_read_b128 v[146:149], v205 offset:0
	ds_read_b128 v[150:153], v205 offset:2048
	ds_read_b128 v[154:157], v205 offset:4096
	ds_read_b128 v[158:161], v205 offset:6144
	v_add_u32_e32 v204, 0x18000, v201
	v_add_u32_e32 v205, 0x18000, v203
	ds_read_b128 v[212:215], v204 offset:0
	ds_read_b128 v[216:219], v204 offset:2048
	ds_read_b128 v[220:223], v204 offset:4096
	ds_read_b128 v[224:227], v204 offset:6144
	ds_read_b128 v[228:231], v205 offset:0
	ds_read_b128 v[232:235], v205 offset:2048
	ds_read_b128 v[236:239], v205 offset:4096
	ds_read_b128 v[240:243], v205 offset:6144
	s_add_u32 m0, s76, 0xc000
	s_nop 0
	global_load_lds_dwordx4 v196, s[68:69]
	s_add_u32 m0, s76, 0xe000
	s_nop 0
	global_load_lds_dwordx4 v197, s[68:69]
	s_add_u32 m0, s76, 0x10000
	s_nop 0
	global_load_lds_dwordx4 v198, s[68:69]
	s_add_u32 m0, s76, 0x12000
	s_nop 0
	global_load_lds_dwordx4 v199, s[68:69]
	s_add_u32 m0, s76, 0x14000
	s_nop 0
	global_load_lds_dwordx4 v196, s[70:71]
	s_add_u32 m0, s76, 0x16000
	s_nop 0
	global_load_lds_dwordx4 v197, s[70:71]
	s_add_u32 s68, s68, 0x80
	s_addc_u32 s69, s69, 0
	s_add_u32 s70, s70, 0x80
	s_addc_u32 s71, s71, 0
	global_load_dwordx4 v[66:69], v191, s[14:15]
	v_add_u32_e32 v170, s38, v191
	global_load_dwordx4 v[70:73], v170, s[14:15]
	s_waitcnt lgkmcnt(0)
	s_barrier
	s_setprio 1
	v_mfma_f32_16x16x32_bf16 v[2:5], v[146:149], v[130:133], v[2:5]
	v_mfma_f32_16x16x32_bf16 v[6:9], v[150:153], v[130:133], v[6:9]
	v_mfma_f32_16x16x32_bf16 v[10:13], v[154:157], v[130:133], v[10:13]
	v_mfma_f32_16x16x32_bf16 v[14:17], v[158:161], v[130:133], v[14:17]
	v_mfma_f32_16x16x32_bf16 v[18:21], v[146:149], v[134:137], v[18:21]
	v_mfma_f32_16x16x32_bf16 v[22:25], v[150:153], v[134:137], v[22:25]
	v_mfma_f32_16x16x32_bf16 v[26:29], v[154:157], v[134:137], v[26:29]
	v_mfma_f32_16x16x32_bf16 v[30:33], v[158:161], v[134:137], v[30:33]
	v_mfma_f32_16x16x32_bf16 v[34:37], v[146:149], v[138:141], v[34:37]
	v_mfma_f32_16x16x32_bf16 v[38:41], v[150:153], v[138:141], v[38:41]
	v_mfma_f32_16x16x32_bf16 v[42:45], v[154:157], v[138:141], v[42:45]
	v_mfma_f32_16x16x32_bf16 v[46:49], v[158:161], v[138:141], v[46:49]
	v_mfma_f32_16x16x32_bf16 v[50:53], v[146:149], v[142:145], v[50:53]
	v_mfma_f32_16x16x32_bf16 v[54:57], v[150:153], v[142:145], v[54:57]
	v_mfma_f32_16x16x32_bf16 v[58:61], v[154:157], v[142:145], v[58:61]
	v_mfma_f32_16x16x32_bf16 v[62:65], v[158:161], v[142:145], v[62:65]
	v_mfma_f32_16x16x32_bf16 v[2:5], v[228:231], v[212:215], v[2:5]
	v_mfma_f32_16x16x32_bf16 v[6:9], v[232:235], v[212:215], v[6:9]
	v_mfma_f32_16x16x32_bf16 v[10:13], v[236:239], v[212:215], v[10:13]
	v_mfma_f32_16x16x32_bf16 v[14:17], v[240:243], v[212:215], v[14:17]
	v_mfma_f32_16x16x32_bf16 v[18:21], v[228:231], v[216:219], v[18:21]
	v_mfma_f32_16x16x32_bf16 v[22:25], v[232:235], v[216:219], v[22:25]
	v_mfma_f32_16x16x32_bf16 v[26:29], v[236:239], v[216:219], v[26:29]
	v_mfma_f32_16x16x32_bf16 v[30:33], v[240:243], v[216:219], v[30:33]
	v_mfma_f32_16x16x32_bf16 v[34:37], v[228:231], v[220:223], v[34:37]
	v_mfma_f32_16x16x32_bf16 v[38:41], v[232:235], v[220:223], v[38:41]
	v_mfma_f32_16x16x32_bf16 v[42:45], v[236:239], v[220:223], v[42:45]
	v_mfma_f32_16x16x32_bf16 v[46:49], v[240:243], v[220:223], v[46:49]
	v_mfma_f32_16x16x32_bf16 v[50:53], v[228:231], v[224:227], v[50:53]
	v_mfma_f32_16x16x32_bf16 v[54:57], v[232:235], v[224:227], v[54:57]
	v_mfma_f32_16x16x32_bf16 v[58:61], v[236:239], v[224:227], v[58:61]
	v_mfma_f32_16x16x32_bf16 v[62:65], v[240:243], v[224:227], v[62:65]
	s_setprio 0
	s_waitcnt vmcnt(10)
	s_barrier
	v_add_u32_e32 v204, 0x0, v200
	v_add_u32_e32 v205, 0x0, v202
	ds_read_b128 v[130:133], v204 offset:0
	ds_read_b128 v[134:137], v204 offset:2048
	ds_read_b128 v[138:141], v204 offset:4096
	ds_read_b128 v[142:145], v204 offset:6144
	ds_read_b128 v[146:149], v205 offset:0
	ds_read_b128 v[150:153], v205 offset:2048
	ds_read_b128 v[154:157], v205 offset:4096
	ds_read_b128 v[158:161], v205 offset:6144
	v_add_u32_e32 v204, 0x0, v201
	v_add_u32_e32 v205, 0x0, v203
	ds_read_b128 v[212:215], v204 offset:0
	ds_read_b128 v[216:219], v204 offset:2048
	ds_read_b128 v[220:223], v204 offset:4096
	ds_read_b128 v[224:227], v204 offset:6144
	ds_read_b128 v[228:231], v205 offset:0
	ds_read_b128 v[232:235], v205 offset:2048
	ds_read_b128 v[236:239], v205 offset:4096
	ds_read_b128 v[240:243], v205 offset:6144
	s_add_u32 m0, s76, 0x18000
	s_nop 0
	global_load_lds_dwordx4 v196, s[68:69]
	s_add_u32 m0, s76, 0x1a000
	s_nop 0
	global_load_lds_dwordx4 v197, s[68:69]
	s_add_u32 m0, s76, 0x1c000
	s_nop 0
	global_load_lds_dwordx4 v198, s[68:69]
	s_add_u32 m0, s76, 0x1e000
	s_nop 0
	global_load_lds_dwordx4 v199, s[68:69]
	s_add_u32 m0, s76, 0x20000
	s_nop 0
	global_load_lds_dwordx4 v196, s[70:71]
	s_add_u32 m0, s76, 0x22000
	s_nop 0
	global_load_lds_dwordx4 v197, s[70:71]
	s_add_u32 s68, s68, 0x80
	s_addc_u32 s69, s69, 0
	s_add_u32 s70, s70, 0x80
	s_addc_u32 s71, s71, 0
	v_add_u32_e32 v170, s39, v191
	global_load_dwordx4 v[74:77], v170, s[14:15]
	v_add_u32_e32 v170, s40, v191
	global_load_dwordx4 v[78:81], v170, s[14:15]
	s_waitcnt lgkmcnt(0)
	s_barrier
	s_setprio 1
	v_mfma_f32_16x16x32_bf16 v[2:5], v[146:149], v[130:133], v[2:5]
	v_mfma_f32_16x16x32_bf16 v[6:9], v[150:153], v[130:133], v[6:9]
	v_mfma_f32_16x16x32_bf16 v[10:13], v[154:157], v[130:133], v[10:13]
	v_mfma_f32_16x16x32_bf16 v[14:17], v[158:161], v[130:133], v[14:17]
	v_mfma_f32_16x16x32_bf16 v[18:21], v[146:149], v[134:137], v[18:21]
	v_mfma_f32_16x16x32_bf16 v[22:25], v[150:153], v[134:137], v[22:25]
	v_mfma_f32_16x16x32_bf16 v[26:29], v[154:157], v[134:137], v[26:29]
	v_mfma_f32_16x16x32_bf16 v[30:33], v[158:161], v[134:137], v[30:33]
	v_mfma_f32_16x16x32_bf16 v[34:37], v[146:149], v[138:141], v[34:37]
	v_mfma_f32_16x16x32_bf16 v[38:41], v[150:153], v[138:141], v[38:41]
	v_mfma_f32_16x16x32_bf16 v[42:45], v[154:157], v[138:141], v[42:45]
	v_mfma_f32_16x16x32_bf16 v[46:49], v[158:161], v[138:141], v[46:49]
	v_mfma_f32_16x16x32_bf16 v[50:53], v[146:149], v[142:145], v[50:53]
	v_mfma_f32_16x16x32_bf16 v[54:57], v[150:153], v[142:145], v[54:57]
	v_mfma_f32_16x16x32_bf16 v[58:61], v[154:157], v[142:145], v[58:61]
	v_mfma_f32_16x16x32_bf16 v[62:65], v[158:161], v[142:145], v[62:65]
	v_mfma_f32_16x16x32_bf16 v[2:5], v[228:231], v[212:215], v[2:5]
	v_mfma_f32_16x16x32_bf16 v[6:9], v[232:235], v[212:215], v[6:9]
	v_mfma_f32_16x16x32_bf16 v[10:13], v[236:239], v[212:215], v[10:13]
	v_mfma_f32_16x16x32_bf16 v[14:17], v[240:243], v[212:215], v[14:17]
	v_mfma_f32_16x16x32_bf16 v[18:21], v[228:231], v[216:219], v[18:21]
	v_mfma_f32_16x16x32_bf16 v[22:25], v[232:235], v[216:219], v[22:25]
	v_mfma_f32_16x16x32_bf16 v[26:29], v[236:239], v[216:219], v[26:29]
	v_mfma_f32_16x16x32_bf16 v[30:33], v[240:243], v[216:219], v[30:33]
	v_mfma_f32_16x16x32_bf16 v[34:37], v[228:231], v[220:223], v[34:37]
	v_mfma_f32_16x16x32_bf16 v[38:41], v[232:235], v[220:223], v[38:41]
	v_mfma_f32_16x16x32_bf16 v[42:45], v[236:239], v[220:223], v[42:45]
	v_mfma_f32_16x16x32_bf16 v[46:49], v[240:243], v[220:223], v[46:49]
	v_mfma_f32_16x16x32_bf16 v[50:53], v[228:231], v[224:227], v[50:53]
	v_mfma_f32_16x16x32_bf16 v[54:57], v[232:235], v[224:227], v[54:57]
	v_mfma_f32_16x16x32_bf16 v[58:61], v[236:239], v[224:227], v[58:61]
	v_mfma_f32_16x16x32_bf16 v[62:65], v[240:243], v[224:227], v[62:65]
	s_setprio 0
	s_waitcnt vmcnt(10)
	s_barrier
	v_add_u32_e32 v204, 0xc000, v200
	v_add_u32_e32 v205, 0xc000, v202
	ds_read_b128 v[130:133], v204 offset:0
	ds_read_b128 v[134:137], v204 offset:2048
	ds_read_b128 v[138:141], v204 offset:4096
	ds_read_b128 v[142:145], v204 offset:6144
	ds_read_b128 v[146:149], v205 offset:0
	ds_read_b128 v[150:153], v205 offset:2048
	ds_read_b128 v[154:157], v205 offset:4096
	ds_read_b128 v[158:161], v205 offset:6144
	v_add_u32_e32 v204, 0xc000, v201
	v_add_u32_e32 v205, 0xc000, v203
	ds_read_b128 v[212:215], v204 offset:0
	ds_read_b128 v[216:219], v204 offset:2048
	ds_read_b128 v[220:223], v204 offset:4096
	ds_read_b128 v[224:227], v204 offset:6144
	ds_read_b128 v[228:231], v205 offset:0
	ds_read_b128 v[232:235], v205 offset:2048
	ds_read_b128 v[236:239], v205 offset:4096
	ds_read_b128 v[240:243], v205 offset:6144
	s_add_u32 m0, s76, 0x0
	s_nop 0
	global_load_lds_dwordx4 v196, s[68:69]
	s_add_u32 m0, s76, 0x2000
	s_nop 0
	global_load_lds_dwordx4 v197, s[68:69]
	s_add_u32 m0, s76, 0x4000
	s_nop 0
	global_load_lds_dwordx4 v198, s[68:69]
	s_add_u32 m0, s76, 0x6000
	s_nop 0
	global_load_lds_dwordx4 v199, s[68:69]
	s_add_u32 m0, s76, 0x8000
	s_nop 0
	global_load_lds_dwordx4 v196, s[70:71]
	s_add_u32 m0, s76, 0xa000
	s_nop 0
	global_load_lds_dwordx4 v197, s[70:71]
	s_add_u32 s68, s68, 0x80
	s_addc_u32 s69, s69, 0
	s_add_u32 s70, s70, 0x80
	s_addc_u32 s71, s71, 0
	global_load_dwordx4 v[82:85], v192, s[14:15]
	v_add_u32_e32 v170, s38, v192
	global_load_dwordx4 v[86:89], v170, s[14:15]
	s_waitcnt lgkmcnt(0)
	s_barrier
	s_setprio 1
	v_mfma_f32_16x16x32_bf16 v[2:5], v[146:149], v[130:133], v[2:5]
	v_mfma_f32_16x16x32_bf16 v[6:9], v[150:153], v[130:133], v[6:9]
	v_mfma_f32_16x16x32_bf16 v[10:13], v[154:157], v[130:133], v[10:13]
	v_mfma_f32_16x16x32_bf16 v[14:17], v[158:161], v[130:133], v[14:17]
	v_mfma_f32_16x16x32_bf16 v[18:21], v[146:149], v[134:137], v[18:21]
	v_mfma_f32_16x16x32_bf16 v[22:25], v[150:153], v[134:137], v[22:25]
	v_mfma_f32_16x16x32_bf16 v[26:29], v[154:157], v[134:137], v[26:29]
	v_mfma_f32_16x16x32_bf16 v[30:33], v[158:161], v[134:137], v[30:33]
	v_mfma_f32_16x16x32_bf16 v[34:37], v[146:149], v[138:141], v[34:37]
	v_mfma_f32_16x16x32_bf16 v[38:41], v[150:153], v[138:141], v[38:41]
	v_mfma_f32_16x16x32_bf16 v[42:45], v[154:157], v[138:141], v[42:45]
	v_mfma_f32_16x16x32_bf16 v[46:49], v[158:161], v[138:141], v[46:49]
	v_mfma_f32_16x16x32_bf16 v[50:53], v[146:149], v[142:145], v[50:53]
	v_mfma_f32_16x16x32_bf16 v[54:57], v[150:153], v[142:145], v[54:57]
	v_mfma_f32_16x16x32_bf16 v[58:61], v[154:157], v[142:145], v[58:61]
	v_mfma_f32_16x16x32_bf16 v[62:65], v[158:161], v[142:145], v[62:65]
	v_mfma_f32_16x16x32_bf16 v[2:5], v[228:231], v[212:215], v[2:5]
	v_mfma_f32_16x16x32_bf16 v[6:9], v[232:235], v[212:215], v[6:9]
	v_mfma_f32_16x16x32_bf16 v[10:13], v[236:239], v[212:215], v[10:13]
	v_mfma_f32_16x16x32_bf16 v[14:17], v[240:243], v[212:215], v[14:17]
	v_mfma_f32_16x16x32_bf16 v[18:21], v[228:231], v[216:219], v[18:21]
	v_mfma_f32_16x16x32_bf16 v[22:25], v[232:235], v[216:219], v[22:25]
	v_mfma_f32_16x16x32_bf16 v[26:29], v[236:239], v[216:219], v[26:29]
	v_mfma_f32_16x16x32_bf16 v[30:33], v[240:243], v[216:219], v[30:33]
	v_mfma_f32_16x16x32_bf16 v[34:37], v[228:231], v[220:223], v[34:37]
	v_mfma_f32_16x16x32_bf16 v[38:41], v[232:235], v[220:223], v[38:41]
	v_mfma_f32_16x16x32_bf16 v[42:45], v[236:239], v[220:223], v[42:45]
	v_mfma_f32_16x16x32_bf16 v[46:49], v[240:243], v[220:223], v[46:49]
	v_mfma_f32_16x16x32_bf16 v[50:53], v[228:231], v[224:227], v[50:53]
	v_mfma_f32_16x16x32_bf16 v[54:57], v[232:235], v[224:227], v[54:57]
	v_mfma_f32_16x16x32_bf16 v[58:61], v[236:239], v[224:227], v[58:61]
	v_mfma_f32_16x16x32_bf16 v[62:65], v[240:243], v[224:227], v[62:65]
	s_setprio 0
	s_waitcnt vmcnt(10)
	s_barrier
	v_add_u32_e32 v204, 0x18000, v200
	v_add_u32_e32 v205, 0x18000, v202
	ds_read_b128 v[130:133], v204 offset:0
	ds_read_b128 v[134:137], v204 offset:2048
	ds_read_b128 v[138:141], v204 offset:4096
	ds_read_b128 v[142:145], v204 offset:6144
	ds_read_b128 v[146:149], v205 offset:0
	ds_read_b128 v[150:153], v205 offset:2048
	ds_read_b128 v[154:157], v205 offset:4096
	ds_read_b128 v[158:161], v205 offset:6144
	v_add_u32_e32 v204, 0x18000, v201
	v_add_u32_e32 v205, 0x18000, v203
	ds_read_b128 v[212:215], v204 offset:0
	ds_read_b128 v[216:219], v204 offset:2048
	ds_read_b128 v[220:223], v204 offset:4096
	ds_read_b128 v[224:227], v204 offset:6144
	ds_read_b128 v[228:231], v205 offset:0
	ds_read_b128 v[232:235], v205 offset:2048
	ds_read_b128 v[236:239], v205 offset:4096
	ds_read_b128 v[240:243], v205 offset:6144
	s_add_u32 m0, s76, 0xc000
	s_nop 0
	global_load_lds_dwordx4 v196, s[68:69]
	s_add_u32 m0, s76, 0xe000
	s_nop 0
	global_load_lds_dwordx4 v197, s[68:69]
	s_add_u32 m0, s76, 0x10000
	s_nop 0
	global_load_lds_dwordx4 v198, s[68:69]
	s_add_u32 m0, s76, 0x12000
	s_nop 0
	global_load_lds_dwordx4 v199, s[68:69]
	s_add_u32 m0, s76, 0x14000
	s_nop 0
	global_load_lds_dwordx4 v196, s[70:71]
	s_add_u32 m0, s76, 0x16000
	s_nop 0
	global_load_lds_dwordx4 v197, s[70:71]
	s_add_u32 s68, s68, 0x80
	s_addc_u32 s69, s69, 0
	s_add_u32 s70, s70, 0x80
	s_addc_u32 s71, s71, 0
	v_add_u32_e32 v170, s39, v192
	global_load_dwordx4 v[90:93], v170, s[14:15]
	v_add_u32_e32 v170, s40, v192
	global_load_dwordx4 v[94:97], v170, s[14:15]
	s_waitcnt lgkmcnt(0)
	s_barrier
	s_setprio 1
	v_mfma_f32_16x16x32_bf16 v[2:5], v[146:149], v[130:133], v[2:5]
	v_mfma_f32_16x16x32_bf16 v[6:9], v[150:153], v[130:133], v[6:9]
	v_mfma_f32_16x16x32_bf16 v[10:13], v[154:157], v[130:133], v[10:13]
	v_mfma_f32_16x16x32_bf16 v[14:17], v[158:161], v[130:133], v[14:17]
	v_mfma_f32_16x16x32_bf16 v[18:21], v[146:149], v[134:137], v[18:21]
	v_mfma_f32_16x16x32_bf16 v[22:25], v[150:153], v[134:137], v[22:25]
	v_mfma_f32_16x16x32_bf16 v[26:29], v[154:157], v[134:137], v[26:29]
	v_mfma_f32_16x16x32_bf16 v[30:33], v[158:161], v[134:137], v[30:33]
	v_mfma_f32_16x16x32_bf16 v[34:37], v[146:149], v[138:141], v[34:37]
	v_mfma_f32_16x16x32_bf16 v[38:41], v[150:153], v[138:141], v[38:41]
	v_mfma_f32_16x16x32_bf16 v[42:45], v[154:157], v[138:141], v[42:45]
	v_mfma_f32_16x16x32_bf16 v[46:49], v[158:161], v[138:141], v[46:49]
	v_mfma_f32_16x16x32_bf16 v[50:53], v[146:149], v[142:145], v[50:53]
	v_mfma_f32_16x16x32_bf16 v[54:57], v[150:153], v[142:145], v[54:57]
	v_mfma_f32_16x16x32_bf16 v[58:61], v[154:157], v[142:145], v[58:61]
	v_mfma_f32_16x16x32_bf16 v[62:65], v[158:161], v[142:145], v[62:65]
	v_mfma_f32_16x16x32_bf16 v[2:5], v[228:231], v[212:215], v[2:5]
	v_mfma_f32_16x16x32_bf16 v[6:9], v[232:235], v[212:215], v[6:9]
	v_mfma_f32_16x16x32_bf16 v[10:13], v[236:239], v[212:215], v[10:13]
	v_mfma_f32_16x16x32_bf16 v[14:17], v[240:243], v[212:215], v[14:17]
	v_mfma_f32_16x16x32_bf16 v[18:21], v[228:231], v[216:219], v[18:21]
	v_mfma_f32_16x16x32_bf16 v[22:25], v[232:235], v[216:219], v[22:25]
	v_mfma_f32_16x16x32_bf16 v[26:29], v[236:239], v[216:219], v[26:29]
	v_mfma_f32_16x16x32_bf16 v[30:33], v[240:243], v[216:219], v[30:33]
	v_mfma_f32_16x16x32_bf16 v[34:37], v[228:231], v[220:223], v[34:37]
	v_mfma_f32_16x16x32_bf16 v[38:41], v[232:235], v[220:223], v[38:41]
	v_mfma_f32_16x16x32_bf16 v[42:45], v[236:239], v[220:223], v[42:45]
	v_mfma_f32_16x16x32_bf16 v[46:49], v[240:243], v[220:223], v[46:49]
	v_mfma_f32_16x16x32_bf16 v[50:53], v[228:231], v[224:227], v[50:53]
	v_mfma_f32_16x16x32_bf16 v[54:57], v[232:235], v[224:227], v[54:57]
	v_mfma_f32_16x16x32_bf16 v[58:61], v[236:239], v[224:227], v[58:61]
	v_mfma_f32_16x16x32_bf16 v[62:65], v[240:243], v[224:227], v[62:65]
	s_setprio 0
	s_waitcnt vmcnt(10)
	s_barrier
	v_add_u32_e32 v204, 0x0, v200
	v_add_u32_e32 v205, 0x0, v202
	ds_read_b128 v[130:133], v204 offset:0
	ds_read_b128 v[134:137], v204 offset:2048
	ds_read_b128 v[138:141], v204 offset:4096
	ds_read_b128 v[142:145], v204 offset:6144
	ds_read_b128 v[146:149], v205 offset:0
	ds_read_b128 v[150:153], v205 offset:2048
	ds_read_b128 v[154:157], v205 offset:4096
	ds_read_b128 v[158:161], v205 offset:6144
	v_add_u32_e32 v204, 0x0, v201
	v_add_u32_e32 v205, 0x0, v203
	ds_read_b128 v[212:215], v204 offset:0
	ds_read_b128 v[216:219], v204 offset:2048
	ds_read_b128 v[220:223], v204 offset:4096
	ds_read_b128 v[224:227], v204 offset:6144
	ds_read_b128 v[228:231], v205 offset:0
	ds_read_b128 v[232:235], v205 offset:2048
	ds_read_b128 v[236:239], v205 offset:4096
	ds_read_b128 v[240:243], v205 offset:6144
	s_add_u32 m0, s76, 0x18000
	s_nop 0
	global_load_lds_dwordx4 v196, s[68:69]
	s_add_u32 m0, s76, 0x1a000
	s_nop 0
	global_load_lds_dwordx4 v197, s[68:69]
	s_add_u32 m0, s76, 0x1c000
	s_nop 0
	global_load_lds_dwordx4 v198, s[68:69]
	s_add_u32 m0, s76, 0x1e000
	s_nop 0
	global_load_lds_dwordx4 v199, s[68:69]
	s_add_u32 m0, s76, 0x20000
	s_nop 0
	global_load_lds_dwordx4 v196, s[70:71]
	s_add_u32 m0, s76, 0x22000
	s_nop 0
	global_load_lds_dwordx4 v197, s[70:71]
	s_add_u32 s68, s68, 0x80
	s_addc_u32 s69, s69, 0
	s_add_u32 s70, s70, 0x80
	s_addc_u32 s71, s71, 0
	global_load_dwordx4 v[98:101], v193, s[14:15]
	v_add_u32_e32 v170, s38, v193
	global_load_dwordx4 v[102:105], v170, s[14:15]
	s_waitcnt lgkmcnt(0)
	s_barrier
	s_setprio 1
	v_mfma_f32_16x16x32_bf16 v[2:5], v[146:149], v[130:133], v[2:5]
	v_mfma_f32_16x16x32_bf16 v[6:9], v[150:153], v[130:133], v[6:9]
	v_mfma_f32_16x16x32_bf16 v[10:13], v[154:157], v[130:133], v[10:13]
	v_mfma_f32_16x16x32_bf16 v[14:17], v[158:161], v[130:133], v[14:17]
	v_mfma_f32_16x16x32_bf16 v[18:21], v[146:149], v[134:137], v[18:21]
	v_mfma_f32_16x16x32_bf16 v[22:25], v[150:153], v[134:137], v[22:25]
	v_mfma_f32_16x16x32_bf16 v[26:29], v[154:157], v[134:137], v[26:29]
	v_mfma_f32_16x16x32_bf16 v[30:33], v[158:161], v[134:137], v[30:33]
	v_mfma_f32_16x16x32_bf16 v[34:37], v[146:149], v[138:141], v[34:37]
	v_mfma_f32_16x16x32_bf16 v[38:41], v[150:153], v[138:141], v[38:41]
	v_mfma_f32_16x16x32_bf16 v[42:45], v[154:157], v[138:141], v[42:45]
	v_mfma_f32_16x16x32_bf16 v[46:49], v[158:161], v[138:141], v[46:49]
	v_mfma_f32_16x16x32_bf16 v[50:53], v[146:149], v[142:145], v[50:53]
	v_mfma_f32_16x16x32_bf16 v[54:57], v[150:153], v[142:145], v[54:57]
	v_mfma_f32_16x16x32_bf16 v[58:61], v[154:157], v[142:145], v[58:61]
	v_mfma_f32_16x16x32_bf16 v[62:65], v[158:161], v[142:145], v[62:65]
	v_mfma_f32_16x16x32_bf16 v[2:5], v[228:231], v[212:215], v[2:5]
	v_mfma_f32_16x16x32_bf16 v[6:9], v[232:235], v[212:215], v[6:9]
	v_mfma_f32_16x16x32_bf16 v[10:13], v[236:239], v[212:215], v[10:13]
	v_mfma_f32_16x16x32_bf16 v[14:17], v[240:243], v[212:215], v[14:17]
	v_mfma_f32_16x16x32_bf16 v[18:21], v[228:231], v[216:219], v[18:21]
	v_mfma_f32_16x16x32_bf16 v[22:25], v[232:235], v[216:219], v[22:25]
	v_mfma_f32_16x16x32_bf16 v[26:29], v[236:239], v[216:219], v[26:29]
	v_mfma_f32_16x16x32_bf16 v[30:33], v[240:243], v[216:219], v[30:33]
	v_mfma_f32_16x16x32_bf16 v[34:37], v[228:231], v[220:223], v[34:37]
	v_mfma_f32_16x16x32_bf16 v[38:41], v[232:235], v[220:223], v[38:41]
	v_mfma_f32_16x16x32_bf16 v[42:45], v[236:239], v[220:223], v[42:45]
	v_mfma_f32_16x16x32_bf16 v[46:49], v[240:243], v[220:223], v[46:49]
	v_mfma_f32_16x16x32_bf16 v[50:53], v[228:231], v[224:227], v[50:53]
	v_mfma_f32_16x16x32_bf16 v[54:57], v[232:235], v[224:227], v[54:57]
	v_mfma_f32_16x16x32_bf16 v[58:61], v[236:239], v[224:227], v[58:61]
	v_mfma_f32_16x16x32_bf16 v[62:65], v[240:243], v[224:227], v[62:65]
	s_setprio 0
	s_waitcnt vmcnt(10)
	s_barrier
	v_add_u32_e32 v204, 0xc000, v200
	v_add_u32_e32 v205, 0xc000, v202
	ds_read_b128 v[130:133], v204 offset:0
	ds_read_b128 v[134:137], v204 offset:2048
	ds_read_b128 v[138:141], v204 offset:4096
	ds_read_b128 v[142:145], v204 offset:6144
	ds_read_b128 v[146:149], v205 offset:0
	ds_read_b128 v[150:153], v205 offset:2048
	ds_read_b128 v[154:157], v205 offset:4096
	ds_read_b128 v[158:161], v205 offset:6144
	v_add_u32_e32 v204, 0xc000, v201
	v_add_u32_e32 v205, 0xc000, v203
	ds_read_b128 v[212:215], v204 offset:0
	ds_read_b128 v[216:219], v204 offset:2048
	ds_read_b128 v[220:223], v204 offset:4096
	ds_read_b128 v[224:227], v204 offset:6144
	ds_read_b128 v[228:231], v205 offset:0
	ds_read_b128 v[232:235], v205 offset:2048
	ds_read_b128 v[236:239], v205 offset:4096
	ds_read_b128 v[240:243], v205 offset:6144
	s_add_u32 m0, s76, 0x0
	s_nop 0
	global_load_lds_dwordx4 v196, s[68:69]
	s_add_u32 m0, s76, 0x2000
	s_nop 0
	global_load_lds_dwordx4 v197, s[68:69]
	s_add_u32 m0, s76, 0x4000
	s_nop 0
	global_load_lds_dwordx4 v198, s[68:69]
	s_add_u32 m0, s76, 0x6000
	s_nop 0
	global_load_lds_dwordx4 v199, s[68:69]
	s_add_u32 m0, s76, 0x8000
	s_nop 0
	global_load_lds_dwordx4 v196, s[70:71]
	s_add_u32 m0, s76, 0xa000
	s_nop 0
	global_load_lds_dwordx4 v197, s[70:71]
	s_add_u32 s68, s68, 0x80
	s_addc_u32 s69, s69, 0
	s_add_u32 s70, s70, 0x80
	s_addc_u32 s71, s71, 0
	v_add_u32_e32 v170, s39, v193
	global_load_dwordx4 v[106:109], v170, s[14:15]
	v_add_u32_e32 v170, s40, v193
	global_load_dwordx4 v[110:113], v170, s[14:15]
	s_waitcnt lgkmcnt(0)
	s_barrier
	s_setprio 1
	v_mfma_f32_16x16x32_bf16 v[2:5], v[146:149], v[130:133], v[2:5]
	v_mfma_f32_16x16x32_bf16 v[6:9], v[150:153], v[130:133], v[6:9]
	v_mfma_f32_16x16x32_bf16 v[10:13], v[154:157], v[130:133], v[10:13]
	v_mfma_f32_16x16x32_bf16 v[14:17], v[158:161], v[130:133], v[14:17]
	v_mfma_f32_16x16x32_bf16 v[18:21], v[146:149], v[134:137], v[18:21]
	v_mfma_f32_16x16x32_bf16 v[22:25], v[150:153], v[134:137], v[22:25]
	v_mfma_f32_16x16x32_bf16 v[26:29], v[154:157], v[134:137], v[26:29]
	v_mfma_f32_16x16x32_bf16 v[30:33], v[158:161], v[134:137], v[30:33]
	v_mfma_f32_16x16x32_bf16 v[34:37], v[146:149], v[138:141], v[34:37]
	v_mfma_f32_16x16x32_bf16 v[38:41], v[150:153], v[138:141], v[38:41]
	v_mfma_f32_16x16x32_bf16 v[42:45], v[154:157], v[138:141], v[42:45]
	v_mfma_f32_16x16x32_bf16 v[46:49], v[158:161], v[138:141], v[46:49]
	v_mfma_f32_16x16x32_bf16 v[50:53], v[146:149], v[142:145], v[50:53]
	v_mfma_f32_16x16x32_bf16 v[54:57], v[150:153], v[142:145], v[54:57]
	v_mfma_f32_16x16x32_bf16 v[58:61], v[154:157], v[142:145], v[58:61]
	v_mfma_f32_16x16x32_bf16 v[62:65], v[158:161], v[142:145], v[62:65]
	v_mfma_f32_16x16x32_bf16 v[2:5], v[228:231], v[212:215], v[2:5]
	v_mfma_f32_16x16x32_bf16 v[6:9], v[232:235], v[212:215], v[6:9]
	v_mfma_f32_16x16x32_bf16 v[10:13], v[236:239], v[212:215], v[10:13]
	v_mfma_f32_16x16x32_bf16 v[14:17], v[240:243], v[212:215], v[14:17]
	v_mfma_f32_16x16x32_bf16 v[18:21], v[228:231], v[216:219], v[18:21]
	v_mfma_f32_16x16x32_bf16 v[22:25], v[232:235], v[216:219], v[22:25]
	v_mfma_f32_16x16x32_bf16 v[26:29], v[236:239], v[216:219], v[26:29]
	v_mfma_f32_16x16x32_bf16 v[30:33], v[240:243], v[216:219], v[30:33]
	v_mfma_f32_16x16x32_bf16 v[34:37], v[228:231], v[220:223], v[34:37]
	v_mfma_f32_16x16x32_bf16 v[38:41], v[232:235], v[220:223], v[38:41]
	v_mfma_f32_16x16x32_bf16 v[42:45], v[236:239], v[220:223], v[42:45]
	v_mfma_f32_16x16x32_bf16 v[46:49], v[240:243], v[220:223], v[46:49]
	v_mfma_f32_16x16x32_bf16 v[50:53], v[228:231], v[224:227], v[50:53]
	v_mfma_f32_16x16x32_bf16 v[54:57], v[232:235], v[224:227], v[54:57]
	v_mfma_f32_16x16x32_bf16 v[58:61], v[236:239], v[224:227], v[58:61]
	v_mfma_f32_16x16x32_bf16 v[62:65], v[240:243], v[224:227], v[62:65]
	s_setprio 0
	s_waitcnt vmcnt(10)
	s_barrier
	v_add_u32_e32 v204, 0x18000, v200
	v_add_u32_e32 v205, 0x18000, v202
	ds_read_b128 v[130:133], v204 offset:0
	ds_read_b128 v[134:137], v204 offset:2048
	ds_read_b128 v[138:141], v204 offset:4096
	ds_read_b128 v[142:145], v204 offset:6144
	ds_read_b128 v[146:149], v205 offset:0
	ds_read_b128 v[150:153], v205 offset:2048
	ds_read_b128 v[154:157], v205 offset:4096
	ds_read_b128 v[158:161], v205 offset:6144
	v_add_u32_e32 v204, 0x18000, v201
	v_add_u32_e32 v205, 0x18000, v203
	ds_read_b128 v[212:215], v204 offset:0
	ds_read_b128 v[216:219], v204 offset:2048
	ds_read_b128 v[220:223], v204 offset:4096
	ds_read_b128 v[224:227], v204 offset:6144
	ds_read_b128 v[228:231], v205 offset:0
	ds_read_b128 v[232:235], v205 offset:2048
	ds_read_b128 v[236:239], v205 offset:4096
	ds_read_b128 v[240:243], v205 offset:6144
	s_add_u32 m0, s76, 0xc000
	s_nop 0
	global_load_lds_dwordx4 v196, s[68:69]
	s_add_u32 m0, s76, 0xe000
	s_nop 0
	global_load_lds_dwordx4 v197, s[68:69]
	s_add_u32 m0, s76, 0x10000
	s_nop 0
	global_load_lds_dwordx4 v198, s[68:69]
	s_add_u32 m0, s76, 0x12000
	s_nop 0
	global_load_lds_dwordx4 v199, s[68:69]
	s_add_u32 m0, s76, 0x14000
	s_nop 0
	global_load_lds_dwordx4 v196, s[70:71]
	s_add_u32 m0, s76, 0x16000
	s_nop 0
	global_load_lds_dwordx4 v197, s[70:71]
	s_add_u32 s68, s68, 0x80
	s_addc_u32 s69, s69, 0
	s_add_u32 s70, s70, 0x80
	s_addc_u32 s71, s71, 0
	global_load_dwordx4 v[114:117], v244, s[14:15]
	v_add_u32_e32 v170, s38, v244
	global_load_dwordx4 v[118:121], v170, s[14:15]
	s_waitcnt lgkmcnt(0)
	s_barrier
	s_setprio 1
	v_mfma_f32_16x16x32_bf16 v[2:5], v[146:149], v[130:133], v[2:5]
	v_mfma_f32_16x16x32_bf16 v[6:9], v[150:153], v[130:133], v[6:9]
	v_mfma_f32_16x16x32_bf16 v[10:13], v[154:157], v[130:133], v[10:13]
	v_mfma_f32_16x16x32_bf16 v[14:17], v[158:161], v[130:133], v[14:17]
	v_mfma_f32_16x16x32_bf16 v[18:21], v[146:149], v[134:137], v[18:21]
	v_mfma_f32_16x16x32_bf16 v[22:25], v[150:153], v[134:137], v[22:25]
	v_mfma_f32_16x16x32_bf16 v[26:29], v[154:157], v[134:137], v[26:29]
	v_mfma_f32_16x16x32_bf16 v[30:33], v[158:161], v[134:137], v[30:33]
	v_mfma_f32_16x16x32_bf16 v[34:37], v[146:149], v[138:141], v[34:37]
	v_mfma_f32_16x16x32_bf16 v[38:41], v[150:153], v[138:141], v[38:41]
	v_mfma_f32_16x16x32_bf16 v[42:45], v[154:157], v[138:141], v[42:45]
	v_mfma_f32_16x16x32_bf16 v[46:49], v[158:161], v[138:141], v[46:49]
	v_mfma_f32_16x16x32_bf16 v[50:53], v[146:149], v[142:145], v[50:53]
	v_mfma_f32_16x16x32_bf16 v[54:57], v[150:153], v[142:145], v[54:57]
	v_mfma_f32_16x16x32_bf16 v[58:61], v[154:157], v[142:145], v[58:61]
	v_mfma_f32_16x16x32_bf16 v[62:65], v[158:161], v[142:145], v[62:65]
	v_mfma_f32_16x16x32_bf16 v[2:5], v[228:231], v[212:215], v[2:5]
	v_mfma_f32_16x16x32_bf16 v[6:9], v[232:235], v[212:215], v[6:9]
	v_mfma_f32_16x16x32_bf16 v[10:13], v[236:239], v[212:215], v[10:13]
	v_mfma_f32_16x16x32_bf16 v[14:17], v[240:243], v[212:215], v[14:17]
	v_mfma_f32_16x16x32_bf16 v[18:21], v[228:231], v[216:219], v[18:21]
	v_mfma_f32_16x16x32_bf16 v[22:25], v[232:235], v[216:219], v[22:25]
	v_mfma_f32_16x16x32_bf16 v[26:29], v[236:239], v[216:219], v[26:29]
	v_mfma_f32_16x16x32_bf16 v[30:33], v[240:243], v[216:219], v[30:33]
	v_mfma_f32_16x16x32_bf16 v[34:37], v[228:231], v[220:223], v[34:37]
	v_mfma_f32_16x16x32_bf16 v[38:41], v[232:235], v[220:223], v[38:41]
	v_mfma_f32_16x16x32_bf16 v[42:45], v[236:239], v[220:223], v[42:45]
	v_mfma_f32_16x16x32_bf16 v[46:49], v[240:243], v[220:223], v[46:49]
	v_mfma_f32_16x16x32_bf16 v[50:53], v[228:231], v[224:227], v[50:53]
	v_mfma_f32_16x16x32_bf16 v[54:57], v[232:235], v[224:227], v[54:57]
	v_mfma_f32_16x16x32_bf16 v[58:61], v[236:239], v[224:227], v[58:61]
	v_mfma_f32_16x16x32_bf16 v[62:65], v[240:243], v[224:227], v[62:65]
	s_setprio 0
	s_waitcnt vmcnt(10)
	s_barrier
	v_add_u32_e32 v204, 0x0, v200
	v_add_u32_e32 v205, 0x0, v202
	ds_read_b128 v[130:133], v204 offset:0
	ds_read_b128 v[134:137], v204 offset:2048
	ds_read_b128 v[138:141], v204 offset:4096
	ds_read_b128 v[142:145], v204 offset:6144
	ds_read_b128 v[146:149], v205 offset:0
	ds_read_b128 v[150:153], v205 offset:2048
	ds_read_b128 v[154:157], v205 offset:4096
	ds_read_b128 v[158:161], v205 offset:6144
	v_add_u32_e32 v204, 0x0, v201
	v_add_u32_e32 v205, 0x0, v203
	ds_read_b128 v[212:215], v204 offset:0
	ds_read_b128 v[216:219], v204 offset:2048
	ds_read_b128 v[220:223], v204 offset:4096
	ds_read_b128 v[224:227], v204 offset:6144
	ds_read_b128 v[228:231], v205 offset:0
	ds_read_b128 v[232:235], v205 offset:2048
	ds_read_b128 v[236:239], v205 offset:4096
	ds_read_b128 v[240:243], v205 offset:6144
	s_add_u32 m0, s76, 0x18000
	s_nop 0
	global_load_lds_dwordx4 v196, s[68:69]
	s_add_u32 m0, s76, 0x1a000
	s_nop 0
	global_load_lds_dwordx4 v197, s[68:69]
	s_add_u32 m0, s76, 0x1c000
	s_nop 0
	global_load_lds_dwordx4 v198, s[68:69]
	s_add_u32 m0, s76, 0x1e000
	s_nop 0
	global_load_lds_dwordx4 v199, s[68:69]
	s_add_u32 m0, s76, 0x20000
	s_nop 0
	global_load_lds_dwordx4 v196, s[70:71]
	s_add_u32 m0, s76, 0x22000
	s_nop 0
	global_load_lds_dwordx4 v197, s[70:71]
	s_add_u32 s68, s68, 0x80
	s_addc_u32 s69, s69, 0
	s_add_u32 s70, s70, 0x80
	s_addc_u32 s71, s71, 0
	v_add_u32_e32 v170, s39, v244
	global_load_dwordx4 v[122:125], v170, s[14:15]
	v_add_u32_e32 v170, s40, v244
	global_load_dwordx4 v[126:129], v170, s[14:15]
	s_waitcnt lgkmcnt(0)
	s_barrier
	s_setprio 1
	v_mfma_f32_16x16x32_bf16 v[2:5], v[146:149], v[130:133], v[2:5]
	v_mfma_f32_16x16x32_bf16 v[6:9], v[150:153], v[130:133], v[6:9]
	v_mfma_f32_16x16x32_bf16 v[10:13], v[154:157], v[130:133], v[10:13]
	v_mfma_f32_16x16x32_bf16 v[14:17], v[158:161], v[130:133], v[14:17]
	v_mfma_f32_16x16x32_bf16 v[18:21], v[146:149], v[134:137], v[18:21]
	v_mfma_f32_16x16x32_bf16 v[22:25], v[150:153], v[134:137], v[22:25]
	v_mfma_f32_16x16x32_bf16 v[26:29], v[154:157], v[134:137], v[26:29]
	v_mfma_f32_16x16x32_bf16 v[30:33], v[158:161], v[134:137], v[30:33]
	v_mfma_f32_16x16x32_bf16 v[34:37], v[146:149], v[138:141], v[34:37]
	v_mfma_f32_16x16x32_bf16 v[38:41], v[150:153], v[138:141], v[38:41]
	v_mfma_f32_16x16x32_bf16 v[42:45], v[154:157], v[138:141], v[42:45]
	v_mfma_f32_16x16x32_bf16 v[46:49], v[158:161], v[138:141], v[46:49]
	v_mfma_f32_16x16x32_bf16 v[50:53], v[146:149], v[142:145], v[50:53]
	v_mfma_f32_16x16x32_bf16 v[54:57], v[150:153], v[142:145], v[54:57]
	v_mfma_f32_16x16x32_bf16 v[58:61], v[154:157], v[142:145], v[58:61]
	v_mfma_f32_16x16x32_bf16 v[62:65], v[158:161], v[142:145], v[62:65]
	v_mfma_f32_16x16x32_bf16 v[2:5], v[228:231], v[212:215], v[2:5]
	v_mfma_f32_16x16x32_bf16 v[6:9], v[232:235], v[212:215], v[6:9]
	v_mfma_f32_16x16x32_bf16 v[10:13], v[236:239], v[212:215], v[10:13]
	v_mfma_f32_16x16x32_bf16 v[14:17], v[240:243], v[212:215], v[14:17]
	v_mfma_f32_16x16x32_bf16 v[18:21], v[228:231], v[216:219], v[18:21]
	v_mfma_f32_16x16x32_bf16 v[22:25], v[232:235], v[216:219], v[22:25]
	v_mfma_f32_16x16x32_bf16 v[26:29], v[236:239], v[216:219], v[26:29]
	v_mfma_f32_16x16x32_bf16 v[30:33], v[240:243], v[216:219], v[30:33]
	v_mfma_f32_16x16x32_bf16 v[34:37], v[228:231], v[220:223], v[34:37]
	v_mfma_f32_16x16x32_bf16 v[38:41], v[232:235], v[220:223], v[38:41]
	v_mfma_f32_16x16x32_bf16 v[42:45], v[236:239], v[220:223], v[42:45]
	v_mfma_f32_16x16x32_bf16 v[46:49], v[240:243], v[220:223], v[46:49]
	v_mfma_f32_16x16x32_bf16 v[50:53], v[228:231], v[224:227], v[50:53]
	v_mfma_f32_16x16x32_bf16 v[54:57], v[232:235], v[224:227], v[54:57]
	v_mfma_f32_16x16x32_bf16 v[58:61], v[236:239], v[224:227], v[58:61]
	v_mfma_f32_16x16x32_bf16 v[62:65], v[240:243], v[224:227], v[62:65]
	s_setprio 0
	s_waitcnt vmcnt(10)
	s_barrier
	v_add_u32_e32 v204, 0xc000, v200
	v_add_u32_e32 v205, 0xc000, v202
	ds_read_b128 v[130:133], v204 offset:0
	ds_read_b128 v[134:137], v204 offset:2048
	ds_read_b128 v[138:141], v204 offset:4096
	ds_read_b128 v[142:145], v204 offset:6144
	ds_read_b128 v[146:149], v205 offset:0
	ds_read_b128 v[150:153], v205 offset:2048
	ds_read_b128 v[154:157], v205 offset:4096
	ds_read_b128 v[158:161], v205 offset:6144
	v_add_u32_e32 v204, 0xc000, v201
	v_add_u32_e32 v205, 0xc000, v203
	ds_read_b128 v[212:215], v204 offset:0
	ds_read_b128 v[216:219], v204 offset:2048
	ds_read_b128 v[220:223], v204 offset:4096
	ds_read_b128 v[224:227], v204 offset:6144
	ds_read_b128 v[228:231], v205 offset:0
	ds_read_b128 v[232:235], v205 offset:2048
	ds_read_b128 v[236:239], v205 offset:4096
	ds_read_b128 v[240:243], v205 offset:6144
	s_add_u32 m0, s76, 0x0
	s_nop 0
	global_load_lds_dwordx4 v196, s[68:69]
	s_add_u32 m0, s76, 0x2000
	s_nop 0
	global_load_lds_dwordx4 v197, s[68:69]
	s_add_u32 m0, s76, 0x4000
	s_nop 0
	global_load_lds_dwordx4 v198, s[68:69]
	s_add_u32 m0, s76, 0x6000
	s_nop 0
	global_load_lds_dwordx4 v199, s[68:69]
	s_add_u32 m0, s76, 0x8000
	s_nop 0
	global_load_lds_dwordx4 v196, s[70:71]
	s_add_u32 m0, s76, 0xa000
	s_nop 0
	global_load_lds_dwordx4 v197, s[70:71]
	s_add_u32 s68, s68, 0x80
	s_addc_u32 s69, s69, 0
	s_add_u32 s70, s70, 0x80
	s_addc_u32 s71, s71, 0
	s_waitcnt lgkmcnt(0)
	s_barrier
	s_setprio 1
	v_mfma_f32_16x16x32_bf16 v[2:5], v[146:149], v[130:133], v[2:5]
	v_mfma_f32_16x16x32_bf16 v[6:9], v[150:153], v[130:133], v[6:9]
	v_mfma_f32_16x16x32_bf16 v[10:13], v[154:157], v[130:133], v[10:13]
	v_mfma_f32_16x16x32_bf16 v[14:17], v[158:161], v[130:133], v[14:17]
	v_mfma_f32_16x16x32_bf16 v[18:21], v[146:149], v[134:137], v[18:21]
	v_mfma_f32_16x16x32_bf16 v[22:25], v[150:153], v[134:137], v[22:25]
	v_mfma_f32_16x16x32_bf16 v[26:29], v[154:157], v[134:137], v[26:29]
	v_mfma_f32_16x16x32_bf16 v[30:33], v[158:161], v[134:137], v[30:33]
	v_mfma_f32_16x16x32_bf16 v[34:37], v[146:149], v[138:141], v[34:37]
	v_mfma_f32_16x16x32_bf16 v[38:41], v[150:153], v[138:141], v[38:41]
	v_mfma_f32_16x16x32_bf16 v[42:45], v[154:157], v[138:141], v[42:45]
	v_mfma_f32_16x16x32_bf16 v[46:49], v[158:161], v[138:141], v[46:49]
	v_mfma_f32_16x16x32_bf16 v[50:53], v[146:149], v[142:145], v[50:53]
	v_mfma_f32_16x16x32_bf16 v[54:57], v[150:153], v[142:145], v[54:57]
	v_mfma_f32_16x16x32_bf16 v[58:61], v[154:157], v[142:145], v[58:61]
	v_mfma_f32_16x16x32_bf16 v[62:65], v[158:161], v[142:145], v[62:65]
	v_mfma_f32_16x16x32_bf16 v[2:5], v[228:231], v[212:215], v[2:5]
	v_mfma_f32_16x16x32_bf16 v[6:9], v[232:235], v[212:215], v[6:9]
	v_mfma_f32_16x16x32_bf16 v[10:13], v[236:239], v[212:215], v[10:13]
	v_mfma_f32_16x16x32_bf16 v[14:17], v[240:243], v[212:215], v[14:17]
	v_mfma_f32_16x16x32_bf16 v[18:21], v[228:231], v[216:219], v[18:21]
	v_mfma_f32_16x16x32_bf16 v[22:25], v[232:235], v[216:219], v[22:25]
	v_mfma_f32_16x16x32_bf16 v[26:29], v[236:239], v[216:219], v[26:29]
	v_mfma_f32_16x16x32_bf16 v[30:33], v[240:243], v[216:219], v[30:33]
	v_mfma_f32_16x16x32_bf16 v[34:37], v[228:231], v[220:223], v[34:37]
	v_mfma_f32_16x16x32_bf16 v[38:41], v[232:235], v[220:223], v[38:41]
	v_mfma_f32_16x16x32_bf16 v[42:45], v[236:239], v[220:223], v[42:45]
	v_mfma_f32_16x16x32_bf16 v[46:49], v[240:243], v[220:223], v[46:49]
	v_mfma_f32_16x16x32_bf16 v[50:53], v[228:231], v[224:227], v[50:53]
	v_mfma_f32_16x16x32_bf16 v[54:57], v[232:235], v[224:227], v[54:57]
	v_mfma_f32_16x16x32_bf16 v[58:61], v[236:239], v[224:227], v[58:61]
	v_mfma_f32_16x16x32_bf16 v[62:65], v[240:243], v[224:227], v[62:65]
	s_setprio 0
	s_waitcnt vmcnt(8)
	s_barrier
	v_add_u32_e32 v204, 0x18000, v200
	v_add_u32_e32 v205, 0x18000, v202
	ds_read_b128 v[130:133], v204 offset:0
	ds_read_b128 v[134:137], v204 offset:2048
	ds_read_b128 v[138:141], v204 offset:4096
	ds_read_b128 v[142:145], v204 offset:6144
	ds_read_b128 v[146:149], v205 offset:0
	ds_read_b128 v[150:153], v205 offset:2048
	ds_read_b128 v[154:157], v205 offset:4096
	ds_read_b128 v[158:161], v205 offset:6144
	v_add_u32_e32 v204, 0x18000, v201
	v_add_u32_e32 v205, 0x18000, v203
	ds_read_b128 v[212:215], v204 offset:0
	ds_read_b128 v[216:219], v204 offset:2048
	ds_read_b128 v[220:223], v204 offset:4096
	ds_read_b128 v[224:227], v204 offset:6144
	ds_read_b128 v[228:231], v205 offset:0
	ds_read_b128 v[232:235], v205 offset:2048
	ds_read_b128 v[236:239], v205 offset:4096
	ds_read_b128 v[240:243], v205 offset:6144
	s_add_u32 m0, s76, 0xc000
	s_nop 0
	global_load_lds_dwordx4 v196, s[68:69]
	s_add_u32 m0, s76, 0xe000
	s_nop 0
	global_load_lds_dwordx4 v197, s[68:69]
	s_add_u32 m0, s76, 0x10000
	s_nop 0
	global_load_lds_dwordx4 v198, s[68:69]
	s_add_u32 m0, s76, 0x12000
	s_nop 0
	global_load_lds_dwordx4 v199, s[68:69]
	s_add_u32 m0, s76, 0x14000
	s_nop 0
	global_load_lds_dwordx4 v196, s[70:71]
	s_add_u32 m0, s76, 0x16000
	s_nop 0
	global_load_lds_dwordx4 v197, s[70:71]
	s_add_u32 s68, s68, 0x80
	s_addc_u32 s69, s69, 0
	s_add_u32 s70, s70, 0x80
	s_addc_u32 s71, s71, 0
	s_waitcnt lgkmcnt(0)
	s_barrier
	s_setprio 1
	v_mfma_f32_16x16x32_bf16 v[2:5], v[146:149], v[130:133], v[2:5]
	v_mfma_f32_16x16x32_bf16 v[6:9], v[150:153], v[130:133], v[6:9]
	v_mfma_f32_16x16x32_bf16 v[10:13], v[154:157], v[130:133], v[10:13]
	v_mfma_f32_16x16x32_bf16 v[14:17], v[158:161], v[130:133], v[14:17]
	v_mfma_f32_16x16x32_bf16 v[18:21], v[146:149], v[134:137], v[18:21]
	v_mfma_f32_16x16x32_bf16 v[22:25], v[150:153], v[134:137], v[22:25]
	v_mfma_f32_16x16x32_bf16 v[26:29], v[154:157], v[134:137], v[26:29]
	v_mfma_f32_16x16x32_bf16 v[30:33], v[158:161], v[134:137], v[30:33]
	v_mfma_f32_16x16x32_bf16 v[34:37], v[146:149], v[138:141], v[34:37]
	v_mfma_f32_16x16x32_bf16 v[38:41], v[150:153], v[138:141], v[38:41]
	v_mfma_f32_16x16x32_bf16 v[42:45], v[154:157], v[138:141], v[42:45]
	v_mfma_f32_16x16x32_bf16 v[46:49], v[158:161], v[138:141], v[46:49]
	v_mfma_f32_16x16x32_bf16 v[50:53], v[146:149], v[142:145], v[50:53]
	v_mfma_f32_16x16x32_bf16 v[54:57], v[150:153], v[142:145], v[54:57]
	v_mfma_f32_16x16x32_bf16 v[58:61], v[154:157], v[142:145], v[58:61]
	v_mfma_f32_16x16x32_bf16 v[62:65], v[158:161], v[142:145], v[62:65]
	v_mfma_f32_16x16x32_bf16 v[2:5], v[228:231], v[212:215], v[2:5]
	v_mfma_f32_16x16x32_bf16 v[6:9], v[232:235], v[212:215], v[6:9]
	v_mfma_f32_16x16x32_bf16 v[10:13], v[236:239], v[212:215], v[10:13]
	v_mfma_f32_16x16x32_bf16 v[14:17], v[240:243], v[212:215], v[14:17]
	v_mfma_f32_16x16x32_bf16 v[18:21], v[228:231], v[216:219], v[18:21]
	v_mfma_f32_16x16x32_bf16 v[22:25], v[232:235], v[216:219], v[22:25]
	v_mfma_f32_16x16x32_bf16 v[26:29], v[236:239], v[216:219], v[26:29]
	v_mfma_f32_16x16x32_bf16 v[30:33], v[240:243], v[216:219], v[30:33]
	v_mfma_f32_16x16x32_bf16 v[34:37], v[228:231], v[220:223], v[34:37]
	v_mfma_f32_16x16x32_bf16 v[38:41], v[232:235], v[220:223], v[38:41]
	v_mfma_f32_16x16x32_bf16 v[42:45], v[236:239], v[220:223], v[42:45]
	v_mfma_f32_16x16x32_bf16 v[46:49], v[240:243], v[220:223], v[46:49]
	v_mfma_f32_16x16x32_bf16 v[50:53], v[228:231], v[224:227], v[50:53]
	v_mfma_f32_16x16x32_bf16 v[54:57], v[232:235], v[224:227], v[54:57]
	v_mfma_f32_16x16x32_bf16 v[58:61], v[236:239], v[224:227], v[58:61]
	v_mfma_f32_16x16x32_bf16 v[62:65], v[240:243], v[224:227], v[62:65]
	s_setprio 0
	s_waitcnt vmcnt(6)
	s_barrier
	v_add_u32_e32 v204, 0x0, v200
	v_add_u32_e32 v205, 0x0, v202
	ds_read_b128 v[130:133], v204 offset:0
	ds_read_b128 v[134:137], v204 offset:2048
	ds_read_b128 v[138:141], v204 offset:4096
	ds_read_b128 v[142:145], v204 offset:6144
	ds_read_b128 v[146:149], v205 offset:0
	ds_read_b128 v[150:153], v205 offset:2048
	ds_read_b128 v[154:157], v205 offset:4096
	ds_read_b128 v[158:161], v205 offset:6144
	v_add_u32_e32 v204, 0x0, v201
	v_add_u32_e32 v205, 0x0, v203
	ds_read_b128 v[212:215], v204 offset:0
	ds_read_b128 v[216:219], v204 offset:2048
	ds_read_b128 v[220:223], v204 offset:4096
	ds_read_b128 v[224:227], v204 offset:6144
	ds_read_b128 v[228:231], v205 offset:0
	ds_read_b128 v[232:235], v205 offset:2048
	ds_read_b128 v[236:239], v205 offset:4096
	ds_read_b128 v[240:243], v205 offset:6144
	s_add_u32 m0, s76, 0x18000
	s_nop 0
	global_load_lds_dwordx4 v196, s[68:69]
	s_add_u32 m0, s76, 0x1a000
	s_nop 0
	global_load_lds_dwordx4 v197, s[68:69]
	s_add_u32 m0, s76, 0x1c000
	s_nop 0
	global_load_lds_dwordx4 v198, s[68:69]
	s_add_u32 m0, s76, 0x1e000
	s_nop 0
	global_load_lds_dwordx4 v199, s[68:69]
	s_add_u32 m0, s76, 0x20000
	s_nop 0
	global_load_lds_dwordx4 v196, s[70:71]
	s_add_u32 m0, s76, 0x22000
	s_nop 0
	global_load_lds_dwordx4 v197, s[70:71]
	s_add_u32 s68, s68, 0x80
	s_addc_u32 s69, s69, 0
	s_add_u32 s70, s70, 0x80
	s_addc_u32 s71, s71, 0
	s_waitcnt lgkmcnt(0)
	s_barrier
	s_setprio 1
	v_mfma_f32_16x16x32_bf16 v[2:5], v[146:149], v[130:133], v[2:5]
	v_mfma_f32_16x16x32_bf16 v[6:9], v[150:153], v[130:133], v[6:9]
	v_mfma_f32_16x16x32_bf16 v[10:13], v[154:157], v[130:133], v[10:13]
	v_mfma_f32_16x16x32_bf16 v[14:17], v[158:161], v[130:133], v[14:17]
	v_mfma_f32_16x16x32_bf16 v[18:21], v[146:149], v[134:137], v[18:21]
	v_mfma_f32_16x16x32_bf16 v[22:25], v[150:153], v[134:137], v[22:25]
	v_mfma_f32_16x16x32_bf16 v[26:29], v[154:157], v[134:137], v[26:29]
	v_mfma_f32_16x16x32_bf16 v[30:33], v[158:161], v[134:137], v[30:33]
	v_mfma_f32_16x16x32_bf16 v[34:37], v[146:149], v[138:141], v[34:37]
	v_mfma_f32_16x16x32_bf16 v[38:41], v[150:153], v[138:141], v[38:41]
	v_mfma_f32_16x16x32_bf16 v[42:45], v[154:157], v[138:141], v[42:45]
	v_mfma_f32_16x16x32_bf16 v[46:49], v[158:161], v[138:141], v[46:49]
	v_mfma_f32_16x16x32_bf16 v[50:53], v[146:149], v[142:145], v[50:53]
	v_mfma_f32_16x16x32_bf16 v[54:57], v[150:153], v[142:145], v[54:57]
	v_mfma_f32_16x16x32_bf16 v[58:61], v[154:157], v[142:145], v[58:61]
	v_mfma_f32_16x16x32_bf16 v[62:65], v[158:161], v[142:145], v[62:65]
	v_mfma_f32_16x16x32_bf16 v[2:5], v[228:231], v[212:215], v[2:5]
	v_mfma_f32_16x16x32_bf16 v[6:9], v[232:235], v[212:215], v[6:9]
	v_mfma_f32_16x16x32_bf16 v[10:13], v[236:239], v[212:215], v[10:13]
	v_mfma_f32_16x16x32_bf16 v[14:17], v[240:243], v[212:215], v[14:17]
	v_mfma_f32_16x16x32_bf16 v[18:21], v[228:231], v[216:219], v[18:21]
	v_mfma_f32_16x16x32_bf16 v[22:25], v[232:235], v[216:219], v[22:25]
	v_mfma_f32_16x16x32_bf16 v[26:29], v[236:239], v[216:219], v[26:29]
	v_mfma_f32_16x16x32_bf16 v[30:33], v[240:243], v[216:219], v[30:33]
	v_mfma_f32_16x16x32_bf16 v[34:37], v[228:231], v[220:223], v[34:37]
	v_mfma_f32_16x16x32_bf16 v[38:41], v[232:235], v[220:223], v[38:41]
	v_mfma_f32_16x16x32_bf16 v[42:45], v[236:239], v[220:223], v[42:45]
	v_mfma_f32_16x16x32_bf16 v[46:49], v[240:243], v[220:223], v[46:49]
	v_mfma_f32_16x16x32_bf16 v[50:53], v[228:231], v[224:227], v[50:53]
	v_mfma_f32_16x16x32_bf16 v[54:57], v[232:235], v[224:227], v[54:57]
	v_mfma_f32_16x16x32_bf16 v[58:61], v[236:239], v[224:227], v[58:61]
	v_mfma_f32_16x16x32_bf16 v[62:65], v[240:243], v[224:227], v[62:65]
	s_setprio 0
	s_waitcnt vmcnt(6)
	s_barrier
	v_add_u32_e32 v204, 0xc000, v200
	v_add_u32_e32 v205, 0xc000, v202
	ds_read_b128 v[130:133], v204 offset:0
	ds_read_b128 v[134:137], v204 offset:2048
	ds_read_b128 v[138:141], v204 offset:4096
	ds_read_b128 v[142:145], v204 offset:6144
	ds_read_b128 v[146:149], v205 offset:0
	ds_read_b128 v[150:153], v205 offset:2048
	ds_read_b128 v[154:157], v205 offset:4096
	ds_read_b128 v[158:161], v205 offset:6144
	v_add_u32_e32 v204, 0xc000, v201
	v_add_u32_e32 v205, 0xc000, v203
	ds_read_b128 v[212:215], v204 offset:0
	ds_read_b128 v[216:219], v204 offset:2048
	ds_read_b128 v[220:223], v204 offset:4096
	ds_read_b128 v[224:227], v204 offset:6144
	ds_read_b128 v[228:231], v205 offset:0
	ds_read_b128 v[232:235], v205 offset:2048
	ds_read_b128 v[236:239], v205 offset:4096
	ds_read_b128 v[240:243], v205 offset:6144
	s_add_u32 m0, s76, 0x0
	s_nop 0
	global_load_lds_dwordx4 v196, s[68:69]
	s_add_u32 m0, s76, 0x2000
	s_nop 0
	global_load_lds_dwordx4 v197, s[68:69]
	s_add_u32 m0, s76, 0x4000
	s_nop 0
	global_load_lds_dwordx4 v198, s[68:69]
	s_add_u32 m0, s76, 0x6000
	s_nop 0
	global_load_lds_dwordx4 v199, s[68:69]
	s_add_u32 m0, s76, 0x8000
	s_nop 0
	global_load_lds_dwordx4 v196, s[70:71]
	s_add_u32 m0, s76, 0xa000
	s_nop 0
	global_load_lds_dwordx4 v197, s[70:71]
	s_add_u32 s68, s68, 0x80
	s_addc_u32 s69, s69, 0
	s_add_u32 s70, s70, 0x80
	s_addc_u32 s71, s71, 0
	s_waitcnt lgkmcnt(0)
	s_barrier
	s_setprio 1
	v_mfma_f32_16x16x32_bf16 v[2:5], v[146:149], v[130:133], v[2:5]
	v_mfma_f32_16x16x32_bf16 v[6:9], v[150:153], v[130:133], v[6:9]
	v_mfma_f32_16x16x32_bf16 v[10:13], v[154:157], v[130:133], v[10:13]
	v_mfma_f32_16x16x32_bf16 v[14:17], v[158:161], v[130:133], v[14:17]
	v_mfma_f32_16x16x32_bf16 v[18:21], v[146:149], v[134:137], v[18:21]
	v_mfma_f32_16x16x32_bf16 v[22:25], v[150:153], v[134:137], v[22:25]
	v_mfma_f32_16x16x32_bf16 v[26:29], v[154:157], v[134:137], v[26:29]
	v_mfma_f32_16x16x32_bf16 v[30:33], v[158:161], v[134:137], v[30:33]
	v_mfma_f32_16x16x32_bf16 v[34:37], v[146:149], v[138:141], v[34:37]
	v_mfma_f32_16x16x32_bf16 v[38:41], v[150:153], v[138:141], v[38:41]
	v_mfma_f32_16x16x32_bf16 v[42:45], v[154:157], v[138:141], v[42:45]
	v_mfma_f32_16x16x32_bf16 v[46:49], v[158:161], v[138:141], v[46:49]
	v_mfma_f32_16x16x32_bf16 v[50:53], v[146:149], v[142:145], v[50:53]
	v_mfma_f32_16x16x32_bf16 v[54:57], v[150:153], v[142:145], v[54:57]
	v_mfma_f32_16x16x32_bf16 v[58:61], v[154:157], v[142:145], v[58:61]
	v_mfma_f32_16x16x32_bf16 v[62:65], v[158:161], v[142:145], v[62:65]
	v_mfma_f32_16x16x32_bf16 v[2:5], v[228:231], v[212:215], v[2:5]
	v_mfma_f32_16x16x32_bf16 v[6:9], v[232:235], v[212:215], v[6:9]
	v_mfma_f32_16x16x32_bf16 v[10:13], v[236:239], v[212:215], v[10:13]
	v_mfma_f32_16x16x32_bf16 v[14:17], v[240:243], v[212:215], v[14:17]
	v_mfma_f32_16x16x32_bf16 v[18:21], v[228:231], v[216:219], v[18:21]
	v_mfma_f32_16x16x32_bf16 v[22:25], v[232:235], v[216:219], v[22:25]
	v_mfma_f32_16x16x32_bf16 v[26:29], v[236:239], v[216:219], v[26:29]
	v_mfma_f32_16x16x32_bf16 v[30:33], v[240:243], v[216:219], v[30:33]
	v_mfma_f32_16x16x32_bf16 v[34:37], v[228:231], v[220:223], v[34:37]
	v_mfma_f32_16x16x32_bf16 v[38:41], v[232:235], v[220:223], v[38:41]
	v_mfma_f32_16x16x32_bf16 v[42:45], v[236:239], v[220:223], v[42:45]
	v_mfma_f32_16x16x32_bf16 v[46:49], v[240:243], v[220:223], v[46:49]
	v_mfma_f32_16x16x32_bf16 v[50:53], v[228:231], v[224:227], v[50:53]
	v_mfma_f32_16x16x32_bf16 v[54:57], v[232:235], v[224:227], v[54:57]
	v_mfma_f32_16x16x32_bf16 v[58:61], v[236:239], v[224:227], v[58:61]
	v_mfma_f32_16x16x32_bf16 v[62:65], v[240:243], v[224:227], v[62:65]
	s_setprio 0
	s_waitcnt vmcnt(6)
	s_barrier
	v_add_u32_e32 v204, 0x18000, v200
	v_add_u32_e32 v205, 0x18000, v202
	ds_read_b128 v[130:133], v204 offset:0
	ds_read_b128 v[134:137], v204 offset:2048
	ds_read_b128 v[138:141], v204 offset:4096
	ds_read_b128 v[142:145], v204 offset:6144
	ds_read_b128 v[146:149], v205 offset:0
	ds_read_b128 v[150:153], v205 offset:2048
	ds_read_b128 v[154:157], v205 offset:4096
	ds_read_b128 v[158:161], v205 offset:6144
	v_add_u32_e32 v204, 0x18000, v201
	v_add_u32_e32 v205, 0x18000, v203
	ds_read_b128 v[212:215], v204 offset:0
	ds_read_b128 v[216:219], v204 offset:2048
	ds_read_b128 v[220:223], v204 offset:4096
	ds_read_b128 v[224:227], v204 offset:6144
	ds_read_b128 v[228:231], v205 offset:0
	ds_read_b128 v[232:235], v205 offset:2048
	ds_read_b128 v[236:239], v205 offset:4096
	ds_read_b128 v[240:243], v205 offset:6144
	s_waitcnt lgkmcnt(0)
	s_barrier
	s_setprio 1
	v_mfma_f32_16x16x32_bf16 v[2:5], v[146:149], v[130:133], v[2:5]
	v_mfma_f32_16x16x32_bf16 v[6:9], v[150:153], v[130:133], v[6:9]
	v_mfma_f32_16x16x32_bf16 v[10:13], v[154:157], v[130:133], v[10:13]
	v_mfma_f32_16x16x32_bf16 v[14:17], v[158:161], v[130:133], v[14:17]
	v_mfma_f32_16x16x32_bf16 v[18:21], v[146:149], v[134:137], v[18:21]
	v_mfma_f32_16x16x32_bf16 v[22:25], v[150:153], v[134:137], v[22:25]
	v_mfma_f32_16x16x32_bf16 v[26:29], v[154:157], v[134:137], v[26:29]
	v_mfma_f32_16x16x32_bf16 v[30:33], v[158:161], v[134:137], v[30:33]
	v_mfma_f32_16x16x32_bf16 v[34:37], v[146:149], v[138:141], v[34:37]
	v_mfma_f32_16x16x32_bf16 v[38:41], v[150:153], v[138:141], v[38:41]
	v_mfma_f32_16x16x32_bf16 v[42:45], v[154:157], v[138:141], v[42:45]
	v_mfma_f32_16x16x32_bf16 v[46:49], v[158:161], v[138:141], v[46:49]
	v_mfma_f32_16x16x32_bf16 v[50:53], v[146:149], v[142:145], v[50:53]
	v_mfma_f32_16x16x32_bf16 v[54:57], v[150:153], v[142:145], v[54:57]
	v_mfma_f32_16x16x32_bf16 v[58:61], v[154:157], v[142:145], v[58:61]
	v_mfma_f32_16x16x32_bf16 v[62:65], v[158:161], v[142:145], v[62:65]
	v_mfma_f32_16x16x32_bf16 v[2:5], v[228:231], v[212:215], v[2:5]
	v_mfma_f32_16x16x32_bf16 v[6:9], v[232:235], v[212:215], v[6:9]
	v_mfma_f32_16x16x32_bf16 v[10:13], v[236:239], v[212:215], v[10:13]
	v_mfma_f32_16x16x32_bf16 v[14:17], v[240:243], v[212:215], v[14:17]
	v_mfma_f32_16x16x32_bf16 v[18:21], v[228:231], v[216:219], v[18:21]
	v_mfma_f32_16x16x32_bf16 v[22:25], v[232:235], v[216:219], v[22:25]
	v_mfma_f32_16x16x32_bf16 v[26:29], v[236:239], v[216:219], v[26:29]
	v_mfma_f32_16x16x32_bf16 v[30:33], v[240:243], v[216:219], v[30:33]
	v_mfma_f32_16x16x32_bf16 v[34:37], v[228:231], v[220:223], v[34:37]
	v_mfma_f32_16x16x32_bf16 v[38:41], v[232:235], v[220:223], v[38:41]
	v_mfma_f32_16x16x32_bf16 v[42:45], v[236:239], v[220:223], v[42:45]
	v_mfma_f32_16x16x32_bf16 v[46:49], v[240:243], v[220:223], v[46:49]
	v_mfma_f32_16x16x32_bf16 v[50:53], v[228:231], v[224:227], v[50:53]
	v_mfma_f32_16x16x32_bf16 v[54:57], v[232:235], v[224:227], v[54:57]
	v_mfma_f32_16x16x32_bf16 v[58:61], v[236:239], v[224:227], v[58:61]
	v_mfma_f32_16x16x32_bf16 v[62:65], v[240:243], v[224:227], v[62:65]
	s_setprio 0
	s_waitcnt vmcnt(0)
	s_barrier
	v_add_u32_e32 v204, 0x0, v200
	v_add_u32_e32 v205, 0x0, v202
	ds_read_b128 v[130:133], v204 offset:0
	ds_read_b128 v[134:137], v204 offset:2048
	ds_read_b128 v[138:141], v204 offset:4096
	ds_read_b128 v[142:145], v204 offset:6144
	ds_read_b128 v[146:149], v205 offset:0
	ds_read_b128 v[150:153], v205 offset:2048
	ds_read_b128 v[154:157], v205 offset:4096
	ds_read_b128 v[158:161], v205 offset:6144
	v_add_u32_e32 v204, 0x0, v201
	v_add_u32_e32 v205, 0x0, v203
	ds_read_b128 v[212:215], v204 offset:0
	ds_read_b128 v[216:219], v204 offset:2048
	ds_read_b128 v[220:223], v204 offset:4096
	ds_read_b128 v[224:227], v204 offset:6144
	ds_read_b128 v[228:231], v205 offset:0
	ds_read_b128 v[232:235], v205 offset:2048
	ds_read_b128 v[236:239], v205 offset:4096
	ds_read_b128 v[240:243], v205 offset:6144
	s_waitcnt lgkmcnt(0)
	s_barrier
	s_setprio 1
	v_mfma_f32_16x16x32_bf16 v[2:5], v[146:149], v[130:133], v[2:5]
	v_mfma_f32_16x16x32_bf16 v[6:9], v[150:153], v[130:133], v[6:9]
	v_mfma_f32_16x16x32_bf16 v[10:13], v[154:157], v[130:133], v[10:13]
	v_mfma_f32_16x16x32_bf16 v[14:17], v[158:161], v[130:133], v[14:17]
	v_mfma_f32_16x16x32_bf16 v[18:21], v[146:149], v[134:137], v[18:21]
	v_mfma_f32_16x16x32_bf16 v[22:25], v[150:153], v[134:137], v[22:25]
	v_mfma_f32_16x16x32_bf16 v[26:29], v[154:157], v[134:137], v[26:29]
	v_mfma_f32_16x16x32_bf16 v[30:33], v[158:161], v[134:137], v[30:33]
	v_mfma_f32_16x16x32_bf16 v[34:37], v[146:149], v[138:141], v[34:37]
	v_mfma_f32_16x16x32_bf16 v[38:41], v[150:153], v[138:141], v[38:41]
	v_mfma_f32_16x16x32_bf16 v[42:45], v[154:157], v[138:141], v[42:45]
	v_mfma_f32_16x16x32_bf16 v[46:49], v[158:161], v[138:141], v[46:49]
	v_mfma_f32_16x16x32_bf16 v[50:53], v[146:149], v[142:145], v[50:53]
	v_mfma_f32_16x16x32_bf16 v[54:57], v[150:153], v[142:145], v[54:57]
	v_mfma_f32_16x16x32_bf16 v[58:61], v[154:157], v[142:145], v[58:61]
	v_mfma_f32_16x16x32_bf16 v[62:65], v[158:161], v[142:145], v[62:65]
	v_mfma_f32_16x16x32_bf16 v[2:5], v[228:231], v[212:215], v[2:5]
	v_mfma_f32_16x16x32_bf16 v[6:9], v[232:235], v[212:215], v[6:9]
	v_mfma_f32_16x16x32_bf16 v[10:13], v[236:239], v[212:215], v[10:13]
	v_mfma_f32_16x16x32_bf16 v[14:17], v[240:243], v[212:215], v[14:17]
	v_mfma_f32_16x16x32_bf16 v[18:21], v[228:231], v[216:219], v[18:21]
	v_mfma_f32_16x16x32_bf16 v[22:25], v[232:235], v[216:219], v[22:25]
	v_mfma_f32_16x16x32_bf16 v[26:29], v[236:239], v[216:219], v[26:29]
	v_mfma_f32_16x16x32_bf16 v[30:33], v[240:243], v[216:219], v[30:33]
	v_mfma_f32_16x16x32_bf16 v[34:37], v[228:231], v[220:223], v[34:37]
	v_mfma_f32_16x16x32_bf16 v[38:41], v[232:235], v[220:223], v[38:41]
	v_mfma_f32_16x16x32_bf16 v[42:45], v[236:239], v[220:223], v[42:45]
	v_mfma_f32_16x16x32_bf16 v[46:49], v[240:243], v[220:223], v[46:49]
	v_mfma_f32_16x16x32_bf16 v[50:53], v[228:231], v[224:227], v[50:53]
	v_mfma_f32_16x16x32_bf16 v[54:57], v[232:235], v[224:227], v[54:57]
	v_mfma_f32_16x16x32_bf16 v[58:61], v[236:239], v[224:227], v[58:61]
	v_mfma_f32_16x16x32_bf16 v[62:65], v[240:243], v[224:227], v[62:65]
	s_setprio 0
	s_barrier
	s_branch .Lop_join
.Lop_streamB:
	s_barrier
	v_add_u32_e32 v204, 0x0, v200
	v_add_u32_e32 v205, 0x0, v202
	ds_read_b128 v[130:133], v204 offset:0
	ds_read_b128 v[134:137], v204 offset:2048
	ds_read_b128 v[138:141], v204 offset:4096
	ds_read_b128 v[142:145], v204 offset:6144
	ds_read_b128 v[146:149], v205 offset:0
	ds_read_b128 v[150:153], v205 offset:2048
	ds_read_b128 v[154:157], v205 offset:4096
	ds_read_b128 v[158:161], v205 offset:6144
	v_add_u32_e32 v204, 0x0, v201
	v_add_u32_e32 v205, 0x0, v203
	ds_read_b128 v[212:215], v204 offset:0
	ds_read_b128 v[216:219], v204 offset:2048
	ds_read_b128 v[220:223], v204 offset:4096
	ds_read_b128 v[224:227], v204 offset:6144
	ds_read_b128 v[228:231], v205 offset:0
	ds_read_b128 v[232:235], v205 offset:2048
	ds_read_b128 v[236:239], v205 offset:4096
	ds_read_b128 v[240:243], v205 offset:6144
	s_add_u32 m0, s76, 0x18000
	s_nop 0
	global_load_lds_dwordx4 v196, s[68:69]
	s_add_u32 m0, s76, 0x1a000
	s_nop 0
	global_load_lds_dwordx4 v197, s[68:69]
	s_add_u32 m0, s76, 0x1c000
	s_nop 0
	global_load_lds_dwordx4 v198, s[68:69]
	s_add_u32 m0, s76, 0x1e000
	s_nop 0
	global_load_lds_dwordx4 v199, s[68:69]
	s_add_u32 m0, s76, 0x20000
	s_nop 0
	global_load_lds_dwordx4 v196, s[70:71]
	s_add_u32 m0, s76, 0x22000
	s_nop 0
	global_load_lds_dwordx4 v197, s[70:71]
	s_add_u32 s68, s68, 0x80
	s_addc_u32 s69, s69, 0
	s_add_u32 s70, s70, 0x80
	s_addc_u32 s71, s71, 0
	global_load_dwordx4 v[174:177], v190, s[72:73] offset:0
	global_load_dwordx4 v[178:181], v190, s[72:73] offset:64
	s_waitcnt vmcnt(8)
	s_waitcnt lgkmcnt(0)
	s_barrier
	s_setprio 1
	v_mfma_f32_16x16x32_bf16 v[2:5], v[146:149], v[130:133], 0
	v_mfma_f32_16x16x32_bf16 v[6:9], v[150:153], v[130:133], 0
	v_mfma_f32_16x16x32_bf16 v[10:13], v[154:157], v[130:133], 0
	v_mfma_f32_16x16x32_bf16 v[14:17], v[158:161], v[130:133], 0
	v_mfma_f32_16x16x32_bf16 v[18:21], v[146:149], v[134:137], 0
	v_mfma_f32_16x16x32_bf16 v[22:25], v[150:153], v[134:137], 0
	v_mfma_f32_16x16x32_bf16 v[26:29], v[154:157], v[134:137], 0
	v_mfma_f32_16x16x32_bf16 v[30:33], v[158:161], v[134:137], 0
	v_mfma_f32_16x16x32_bf16 v[34:37], v[146:149], v[138:141], 0
	v_mfma_f32_16x16x32_bf16 v[38:41], v[150:153], v[138:141], 0
	v_mfma_f32_16x16x32_bf16 v[42:45], v[154:157], v[138:141], 0
	v_mfma_f32_16x16x32_bf16 v[46:49], v[158:161], v[138:141], 0
	v_mfma_f32_16x16x32_bf16 v[50:53], v[146:149], v[142:145], 0
	v_mfma_f32_16x16x32_bf16 v[54:57], v[150:153], v[142:145], 0
	v_mfma_f32_16x16x32_bf16 v[58:61], v[154:157], v[142:145], 0
	v_mfma_f32_16x16x32_bf16 v[62:65], v[158:161], v[142:145], 0
	v_mfma_f32_16x16x32_bf16 v[2:5], v[228:231], v[212:215], v[2:5]
	v_mfma_f32_16x16x32_bf16 v[6:9], v[232:235], v[212:215], v[6:9]
	v_mfma_f32_16x16x32_bf16 v[10:13], v[236:239], v[212:215], v[10:13]
	v_mfma_f32_16x16x32_bf16 v[14:17], v[240:243], v[212:215], v[14:17]
	v_mfma_f32_16x16x32_bf16 v[18:21], v[228:231], v[216:219], v[18:21]
	v_mfma_f32_16x16x32_bf16 v[22:25], v[232:235], v[216:219], v[22:25]
	v_mfma_f32_16x16x32_bf16 v[26:29], v[236:239], v[216:219], v[26:29]
	v_mfma_f32_16x16x32_bf16 v[30:33], v[240:243], v[216:219], v[30:33]
	v_mfma_f32_16x16x32_bf16 v[34:37], v[228:231], v[220:223], v[34:37]
	v_mfma_f32_16x16x32_bf16 v[38:41], v[232:235], v[220:223], v[38:41]
	v_mfma_f32_16x16x32_bf16 v[42:45], v[236:239], v[220:223], v[42:45]
	v_mfma_f32_16x16x32_bf16 v[46:49], v[240:243], v[220:223], v[46:49]
	v_mfma_f32_16x16x32_bf16 v[50:53], v[228:231], v[224:227], v[50:53]
	v_mfma_f32_16x16x32_bf16 v[54:57], v[232:235], v[224:227], v[54:57]
	v_mfma_f32_16x16x32_bf16 v[58:61], v[236:239], v[224:227], v[58:61]
	v_mfma_f32_16x16x32_bf16 v[62:65], v[240:243], v[224:227], v[62:65]
	s_setprio 0
	s_barrier
	v_add_u32_e32 v204, 0xc000, v200
	v_add_u32_e32 v205, 0xc000, v202
	ds_read_b128 v[130:133], v204 offset:0
	ds_read_b128 v[134:137], v204 offset:2048
	ds_read_b128 v[138:141], v204 offset:4096
	ds_read_b128 v[142:145], v204 offset:6144
	ds_read_b128 v[146:149], v205 offset:0
	ds_read_b128 v[150:153], v205 offset:2048
	ds_read_b128 v[154:157], v205 offset:4096
	ds_read_b128 v[158:161], v205 offset:6144
	v_add_u32_e32 v204, 0xc000, v201
	v_add_u32_e32 v205, 0xc000, v203
	ds_read_b128 v[212:215], v204 offset:0
	ds_read_b128 v[216:219], v204 offset:2048
	ds_read_b128 v[220:223], v204 offset:4096
	ds_read_b128 v[224:227], v204 offset:6144
	ds_read_b128 v[228:231], v205 offset:0
	ds_read_b128 v[232:235], v205 offset:2048
	ds_read_b128 v[236:239], v205 offset:4096
	ds_read_b128 v[240:243], v205 offset:6144
	s_add_u32 m0, s76, 0x0
	s_nop 0
	global_load_lds_dwordx4 v196, s[68:69]
	s_add_u32 m0, s76, 0x2000
	s_nop 0
	global_load_lds_dwordx4 v197, s[68:69]
	s_add_u32 m0, s76, 0x4000
	s_nop 0
	global_load_lds_dwordx4 v198, s[68:69]
	s_add_u32 m0, s76, 0x6000
	s_nop 0
	global_load_lds_dwordx4 v199, s[68:69]
	s_add_u32 m0, s76, 0x8000
	s_nop 0
	global_load_lds_dwordx4 v196, s[70:71]
	s_add_u32 m0, s76, 0xa000
	s_nop 0
	global_load_lds_dwordx4 v197, s[70:71]
	s_add_u32 s68, s68, 0x80
	s_addc_u32 s69, s69, 0
	s_add_u32 s70, s70, 0x80
	s_addc_u32 s71, s71, 0
	global_load_dwordx4 v[182:185], v190, s[72:73] offset:128
	global_load_dwordx4 v[186:189], v190, s[72:73] offset:192
	s_waitcnt vmcnt(10)
	s_waitcnt lgkmcnt(0)
	s_barrier
	s_setprio 1
	v_mfma_f32_16x16x32_bf16 v[2:5], v[146:149], v[130:133], v[2:5]
	v_mfma_f32_16x16x32_bf16 v[6:9], v[150:153], v[130:133], v[6:9]
	v_mfma_f32_16x16x32_bf16 v[10:13], v[154:157], v[130:133], v[10:13]
	v_mfma_f32_16x16x32_bf16 v[14:17], v[158:161], v[130:133], v[14:17]
	v_mfma_f32_16x16x32_bf16 v[18:21], v[146:149], v[134:137], v[18:21]
	v_mfma_f32_16x16x32_bf16 v[22:25], v[150:153], v[134:137], v[22:25]
	v_mfma_f32_16x16x32_bf16 v[26:29], v[154:157], v[134:137], v[26:29]
	v_mfma_f32_16x16x32_bf16 v[30:33], v[158:161], v[134:137], v[30:33]
	v_mfma_f32_16x16x32_bf16 v[34:37], v[146:149], v[138:141], v[34:37]
	v_mfma_f32_16x16x32_bf16 v[38:41], v[150:153], v[138:141], v[38:41]
	v_mfma_f32_16x16x32_bf16 v[42:45], v[154:157], v[138:141], v[42:45]
	v_mfma_f32_16x16x32_bf16 v[46:49], v[158:161], v[138:141], v[46:49]
	v_mfma_f32_16x16x32_bf16 v[50:53], v[146:149], v[142:145], v[50:53]
	v_mfma_f32_16x16x32_bf16 v[54:57], v[150:153], v[142:145], v[54:57]
	v_mfma_f32_16x16x32_bf16 v[58:61], v[154:157], v[142:145], v[58:61]
	v_mfma_f32_16x16x32_bf16 v[62:65], v[158:161], v[142:145], v[62:65]
	v_mfma_f32_16x16x32_bf16 v[2:5], v[228:231], v[212:215], v[2:5]
	v_mfma_f32_16x16x32_bf16 v[6:9], v[232:235], v[212:215], v[6:9]
	v_mfma_f32_16x16x32_bf16 v[10:13], v[236:239], v[212:215], v[10:13]
	v_mfma_f32_16x16x32_bf16 v[14:17], v[240:243], v[212:215], v[14:17]
	v_mfma_f32_16x16x32_bf16 v[18:21], v[228:231], v[216:219], v[18:21]
	v_mfma_f32_16x16x32_bf16 v[22:25], v[232:235], v[216:219], v[22:25]
	v_mfma_f32_16x16x32_bf16 v[26:29], v[236:239], v[216:219], v[26:29]
	v_mfma_f32_16x16x32_bf16 v[30:33], v[240:243], v[216:219], v[30:33]
	v_mfma_f32_16x16x32_bf16 v[34:37], v[228:231], v[220:223], v[34:37]
	v_mfma_f32_16x16x32_bf16 v[38:41], v[232:235], v[220:223], v[38:41]
	v_mfma_f32_16x16x32_bf16 v[42:45], v[236:239], v[220:223], v[42:45]
	v_mfma_f32_16x16x32_bf16 v[46:49], v[240:243], v[220:223], v[46:49]
	v_mfma_f32_16x16x32_bf16 v[50:53], v[228:231], v[224:227], v[50:53]
	v_mfma_f32_16x16x32_bf16 v[54:57], v[232:235], v[224:227], v[54:57]
	v_mfma_f32_16x16x32_bf16 v[58:61], v[236:239], v[224:227], v[58:61]
	v_mfma_f32_16x16x32_bf16 v[62:65], v[240:243], v[224:227], v[62:65]
	s_setprio 0
	s_barrier
	v_add_u32_e32 v204, 0x18000, v200
	v_add_u32_e32 v205, 0x18000, v202
	ds_read_b128 v[130:133], v204 offset:0
	ds_read_b128 v[134:137], v204 offset:2048
	ds_read_b128 v[138:141], v204 offset:4096
	ds_read_b128 v[142:145], v204 offset:6144
	ds_read_b128 v[146:149], v205 offset:0
	ds_read_b128 v[150:153], v205 offset:2048
	ds_read_b128 v[154:157], v205 offset:4096
	ds_read_b128 v[158:161], v205 offset:6144
	v_add_u32_e32 v204, 0x18000, v201
	v_add_u32_e32 v205, 0x18000, v203
	ds_read_b128 v[212:215], v204 offset:0
	ds_read_b128 v[216:219], v204 offset:2048
	ds_read_b128 v[220:223], v204 offset:4096
	ds_read_b128 v[224:227], v204 offset:6144
	ds_read_b128 v[228:231], v205 offset:0
	ds_read_b128 v[232:235], v205 offset:2048
	ds_read_b128 v[236:239], v205 offset:4096
	ds_read_b128 v[240:243], v205 offset:6144
	s_add_u32 m0, s76, 0xc000
	s_nop 0
	global_load_lds_dwordx4 v196, s[68:69]
	s_add_u32 m0, s76, 0xe000
	s_nop 0
	global_load_lds_dwordx4 v197, s[68:69]
	s_add_u32 m0, s76, 0x10000
	s_nop 0
	global_load_lds_dwordx4 v198, s[68:69]
	s_add_u32 m0, s76, 0x12000
	s_nop 0
	global_load_lds_dwordx4 v199, s[68:69]
	s_add_u32 m0, s76, 0x14000
	s_nop 0
	global_load_lds_dwordx4 v196, s[70:71]
	s_add_u32 m0, s76, 0x16000
	s_nop 0
	global_load_lds_dwordx4 v197, s[70:71]
	s_add_u32 s68, s68, 0x80
	s_addc_u32 s69, s69, 0
	s_add_u32 s70, s70, 0x80
	s_addc_u32 s71, s71, 0
	global_load_dwordx4 v[66:69], v191, s[14:15]
	v_add_u32_e32 v170, s38, v191
	global_load_dwordx4 v[70:73], v170, s[14:15]
	s_waitcnt vmcnt(10)
	s_waitcnt lgkmcnt(0)
	s_barrier
	s_setprio 1
	v_mfma_f32_16x16x32_bf16 v[2:5], v[146:149], v[130:133], v[2:5]
	v_mfma_f32_16x16x32_bf16 v[6:9], v[150:153], v[130:133], v[6:9]
	v_mfma_f32_16x16x32_bf16 v[10:13], v[154:157], v[130:133], v[10:13]
	v_mfma_f32_16x16x32_bf16 v[14:17], v[158:161], v[130:133], v[14:17]
	v_mfma_f32_16x16x32_bf16 v[18:21], v[146:149], v[134:137], v[18:21]
	v_mfma_f32_16x16x32_bf16 v[22:25], v[150:153], v[134:137], v[22:25]
	v_mfma_f32_16x16x32_bf16 v[26:29], v[154:157], v[134:137], v[26:29]
	v_mfma_f32_16x16x32_bf16 v[30:33], v[158:161], v[134:137], v[30:33]
	v_mfma_f32_16x16x32_bf16 v[34:37], v[146:149], v[138:141], v[34:37]
	v_mfma_f32_16x16x32_bf16 v[38:41], v[150:153], v[138:141], v[38:41]
	v_mfma_f32_16x16x32_bf16 v[42:45], v[154:157], v[138:141], v[42:45]
	v_mfma_f32_16x16x32_bf16 v[46:49], v[158:161], v[138:141], v[46:49]
	v_mfma_f32_16x16x32_bf16 v[50:53], v[146:149], v[142:145], v[50:53]
	v_mfma_f32_16x16x32_bf16 v[54:57], v[150:153], v[142:145], v[54:57]
	v_mfma_f32_16x16x32_bf16 v[58:61], v[154:157], v[142:145], v[58:61]
	v_mfma_f32_16x16x32_bf16 v[62:65], v[158:161], v[142:145], v[62:65]
	v_mfma_f32_16x16x32_bf16 v[2:5], v[228:231], v[212:215], v[2:5]
	v_mfma_f32_16x16x32_bf16 v[6:9], v[232:235], v[212:215], v[6:9]
	v_mfma_f32_16x16x32_bf16 v[10:13], v[236:239], v[212:215], v[10:13]
	v_mfma_f32_16x16x32_bf16 v[14:17], v[240:243], v[212:215], v[14:17]
	v_mfma_f32_16x16x32_bf16 v[18:21], v[228:231], v[216:219], v[18:21]
	v_mfma_f32_16x16x32_bf16 v[22:25], v[232:235], v[216:219], v[22:25]
	v_mfma_f32_16x16x32_bf16 v[26:29], v[236:239], v[216:219], v[26:29]
	v_mfma_f32_16x16x32_bf16 v[30:33], v[240:243], v[216:219], v[30:33]
	v_mfma_f32_16x16x32_bf16 v[34:37], v[228:231], v[220:223], v[34:37]
	v_mfma_f32_16x16x32_bf16 v[38:41], v[232:235], v[220:223], v[38:41]
	v_mfma_f32_16x16x32_bf16 v[42:45], v[236:239], v[220:223], v[42:45]
	v_mfma_f32_16x16x32_bf16 v[46:49], v[240:243], v[220:223], v[46:49]
	v_mfma_f32_16x16x32_bf16 v[50:53], v[228:231], v[224:227], v[50:53]
	v_mfma_f32_16x16x32_bf16 v[54:57], v[232:235], v[224:227], v[54:57]
	v_mfma_f32_16x16x32_bf16 v[58:61], v[236:239], v[224:227], v[58:61]
	v_mfma_f32_16x16x32_bf16 v[62:65], v[240:243], v[224:227], v[62:65]
	s_setprio 0
	s_barrier
	v_add_u32_e32 v204, 0x0, v200
	v_add_u32_e32 v205, 0x0, v202
	ds_read_b128 v[130:133], v204 offset:0
	ds_read_b128 v[134:137], v204 offset:2048
	ds_read_b128 v[138:141], v204 offset:4096
	ds_read_b128 v[142:145], v204 offset:6144
	ds_read_b128 v[146:149], v205 offset:0
	ds_read_b128 v[150:153], v205 offset:2048
	ds_read_b128 v[154:157], v205 offset:4096
	ds_read_b128 v[158:161], v205 offset:6144
	v_add_u32_e32 v204, 0x0, v201
	v_add_u32_e32 v205, 0x0, v203
	ds_read_b128 v[212:215], v204 offset:0
	ds_read_b128 v[216:219], v204 offset:2048
	ds_read_b128 v[220:223], v204 offset:4096
	ds_read_b128 v[224:227], v204 offset:6144
	ds_read_b128 v[228:231], v205 offset:0
	ds_read_b128 v[232:235], v205 offset:2048
	ds_read_b128 v[236:239], v205 offset:4096
	ds_read_b128 v[240:243], v205 offset:6144
	s_add_u32 m0, s76, 0x18000
	s_nop 0
	global_load_lds_dwordx4 v196, s[68:69]
	s_add_u32 m0, s76, 0x1a000
	s_nop 0
	global_load_lds_dwordx4 v197, s[68:69]
	s_add_u32 m0, s76, 0x1c000
	s_nop 0
	global_load_lds_dwordx4 v198, s[68:69]
	s_add_u32 m0, s76, 0x1e000
	s_nop 0
	global_load_lds_dwordx4 v199, s[68:69]
	s_add_u32 m0, s76, 0x20000
	s_nop 0
	global_load_lds_dwordx4 v196, s[70:71]
	s_add_u32 m0, s76, 0x22000
	s_nop 0
	global_load_lds_dwordx4 v197, s[70:71]
	s_add_u32 s68, s68, 0x80
	s_addc_u32 s69, s69, 0
	s_add_u32 s70, s70, 0x80
	s_addc_u32 s71, s71, 0
	v_add_u32_e32 v170, s39, v191
	global_load_dwordx4 v[74:77], v170, s[14:15]
	v_add_u32_e32 v170, s40, v191
	global_load_dwordx4 v[78:81], v170, s[14:15]
	s_waitcnt vmcnt(10)
	s_waitcnt lgkmcnt(0)
	s_barrier
	s_setprio 1
	v_mfma_f32_16x16x32_bf16 v[2:5], v[146:149], v[130:133], v[2:5]
	v_mfma_f32_16x16x32_bf16 v[6:9], v[150:153], v[130:133], v[6:9]
	v_mfma_f32_16x16x32_bf16 v[10:13], v[154:157], v[130:133], v[10:13]
	v_mfma_f32_16x16x32_bf16 v[14:17], v[158:161], v[130:133], v[14:17]
	v_mfma_f32_16x16x32_bf16 v[18:21], v[146:149], v[134:137], v[18:21]
	v_mfma_f32_16x16x32_bf16 v[22:25], v[150:153], v[134:137], v[22:25]
	v_mfma_f32_16x16x32_bf16 v[26:29], v[154:157], v[134:137], v[26:29]
	v_mfma_f32_16x16x32_bf16 v[30:33], v[158:161], v[134:137], v[30:33]
	v_mfma_f32_16x16x32_bf16 v[34:37], v[146:149], v[138:141], v[34:37]
	v_mfma_f32_16x16x32_bf16 v[38:41], v[150:153], v[138:141], v[38:41]
	v_mfma_f32_16x16x32_bf16 v[42:45], v[154:157], v[138:141], v[42:45]
	v_mfma_f32_16x16x32_bf16 v[46:49], v[158:161], v[138:141], v[46:49]
	v_mfma_f32_16x16x32_bf16 v[50:53], v[146:149], v[142:145], v[50:53]
	v_mfma_f32_16x16x32_bf16 v[54:57], v[150:153], v[142:145], v[54:57]
	v_mfma_f32_16x16x32_bf16 v[58:61], v[154:157], v[142:145], v[58:61]
	v_mfma_f32_16x16x32_bf16 v[62:65], v[158:161], v[142:145], v[62:65]
	v_mfma_f32_16x16x32_bf16 v[2:5], v[228:231], v[212:215], v[2:5]
	v_mfma_f32_16x16x32_bf16 v[6:9], v[232:235], v[212:215], v[6:9]
	v_mfma_f32_16x16x32_bf16 v[10:13], v[236:239], v[212:215], v[10:13]
	v_mfma_f32_16x16x32_bf16 v[14:17], v[240:243], v[212:215], v[14:17]
	v_mfma_f32_16x16x32_bf16 v[18:21], v[228:231], v[216:219], v[18:21]
	v_mfma_f32_16x16x32_bf16 v[22:25], v[232:235], v[216:219], v[22:25]
	v_mfma_f32_16x16x32_bf16 v[26:29], v[236:239], v[216:219], v[26:29]
	v_mfma_f32_16x16x32_bf16 v[30:33], v[240:243], v[216:219], v[30:33]
	v_mfma_f32_16x16x32_bf16 v[34:37], v[228:231], v[220:223], v[34:37]
	v_mfma_f32_16x16x32_bf16 v[38:41], v[232:235], v[220:223], v[38:41]
	v_mfma_f32_16x16x32_bf16 v[42:45], v[236:239], v[220:223], v[42:45]
	v_mfma_f32_16x16x32_bf16 v[46:49], v[240:243], v[220:223], v[46:49]
	v_mfma_f32_16x16x32_bf16 v[50:53], v[228:231], v[224:227], v[50:53]
	v_mfma_f32_16x16x32_bf16 v[54:57], v[232:235], v[224:227], v[54:57]
	v_mfma_f32_16x16x32_bf16 v[58:61], v[236:239], v[224:227], v[58:61]
	v_mfma_f32_16x16x32_bf16 v[62:65], v[240:243], v[224:227], v[62:65]
	s_setprio 0
	s_barrier
	v_add_u32_e32 v204, 0xc000, v200
	v_add_u32_e32 v205, 0xc000, v202
	ds_read_b128 v[130:133], v204 offset:0
	ds_read_b128 v[134:137], v204 offset:2048
	ds_read_b128 v[138:141], v204 offset:4096
	ds_read_b128 v[142:145], v204 offset:6144
	ds_read_b128 v[146:149], v205 offset:0
	ds_read_b128 v[150:153], v205 offset:2048
	ds_read_b128 v[154:157], v205 offset:4096
	ds_read_b128 v[158:161], v205 offset:6144
	v_add_u32_e32 v204, 0xc000, v201
	v_add_u32_e32 v205, 0xc000, v203
	ds_read_b128 v[212:215], v204 offset:0
	ds_read_b128 v[216:219], v204 offset:2048
	ds_read_b128 v[220:223], v204 offset:4096
	ds_read_b128 v[224:227], v204 offset:6144
	ds_read_b128 v[228:231], v205 offset:0
	ds_read_b128 v[232:235], v205 offset:2048
	ds_read_b128 v[236:239], v205 offset:4096
	ds_read_b128 v[240:243], v205 offset:6144
	s_add_u32 m0, s76, 0x0
	s_nop 0
	global_load_lds_dwordx4 v196, s[68:69]
	s_add_u32 m0, s76, 0x2000
	s_nop 0
	global_load_lds_dwordx4 v197, s[68:69]
	s_add_u32 m0, s76, 0x4000
	s_nop 0
	global_load_lds_dwordx4 v198, s[68:69]
	s_add_u32 m0, s76, 0x6000
	s_nop 0
	global_load_lds_dwordx4 v199, s[68:69]
	s_add_u32 m0, s76, 0x8000
	s_nop 0
	global_load_lds_dwordx4 v196, s[70:71]
	s_add_u32 m0, s76, 0xa000
	s_nop 0
	global_load_lds_dwordx4 v197, s[70:71]
	s_add_u32 s68, s68, 0x80
	s_addc_u32 s69, s69, 0
	s_add_u32 s70, s70, 0x80
	s_addc_u32 s71, s71, 0
	global_load_dwordx4 v[82:85], v192, s[14:15]
	v_add_u32_e32 v170, s38, v192
	global_load_dwordx4 v[86:89], v170, s[14:15]
	s_waitcnt vmcnt(10)
	s_waitcnt lgkmcnt(0)
	s_barrier
	s_setprio 1
	v_mfma_f32_16x16x32_bf16 v[2:5], v[146:149], v[130:133], v[2:5]
	v_mfma_f32_16x16x32_bf16 v[6:9], v[150:153], v[130:133], v[6:9]
	v_mfma_f32_16x16x32_bf16 v[10:13], v[154:157], v[130:133], v[10:13]
	v_mfma_f32_16x16x32_bf16 v[14:17], v[158:161], v[130:133], v[14:17]
	v_mfma_f32_16x16x32_bf16 v[18:21], v[146:149], v[134:137], v[18:21]
	v_mfma_f32_16x16x32_bf16 v[22:25], v[150:153], v[134:137], v[22:25]
	v_mfma_f32_16x16x32_bf16 v[26:29], v[154:157], v[134:137], v[26:29]
	v_mfma_f32_16x16x32_bf16 v[30:33], v[158:161], v[134:137], v[30:33]
	v_mfma_f32_16x16x32_bf16 v[34:37], v[146:149], v[138:141], v[34:37]
	v_mfma_f32_16x16x32_bf16 v[38:41], v[150:153], v[138:141], v[38:41]
	v_mfma_f32_16x16x32_bf16 v[42:45], v[154:157], v[138:141], v[42:45]
	v_mfma_f32_16x16x32_bf16 v[46:49], v[158:161], v[138:141], v[46:49]
	v_mfma_f32_16x16x32_bf16 v[50:53], v[146:149], v[142:145], v[50:53]
	v_mfma_f32_16x16x32_bf16 v[54:57], v[150:153], v[142:145], v[54:57]
	v_mfma_f32_16x16x32_bf16 v[58:61], v[154:157], v[142:145], v[58:61]
	v_mfma_f32_16x16x32_bf16 v[62:65], v[158:161], v[142:145], v[62:65]
	v_mfma_f32_16x16x32_bf16 v[2:5], v[228:231], v[212:215], v[2:5]
	v_mfma_f32_16x16x32_bf16 v[6:9], v[232:235], v[212:215], v[6:9]
	v_mfma_f32_16x16x32_bf16 v[10:13], v[236:239], v[212:215], v[10:13]
	v_mfma_f32_16x16x32_bf16 v[14:17], v[240:243], v[212:215], v[14:17]
	v_mfma_f32_16x16x32_bf16 v[18:21], v[228:231], v[216:219], v[18:21]
	v_mfma_f32_16x16x32_bf16 v[22:25], v[232:235], v[216:219], v[22:25]
	v_mfma_f32_16x16x32_bf16 v[26:29], v[236:239], v[216:219], v[26:29]
	v_mfma_f32_16x16x32_bf16 v[30:33], v[240:243], v[216:219], v[30:33]
	v_mfma_f32_16x16x32_bf16 v[34:37], v[228:231], v[220:223], v[34:37]
	v_mfma_f32_16x16x32_bf16 v[38:41], v[232:235], v[220:223], v[38:41]
	v_mfma_f32_16x16x32_bf16 v[42:45], v[236:239], v[220:223], v[42:45]
	v_mfma_f32_16x16x32_bf16 v[46:49], v[240:243], v[220:223], v[46:49]
	v_mfma_f32_16x16x32_bf16 v[50:53], v[228:231], v[224:227], v[50:53]
	v_mfma_f32_16x16x32_bf16 v[54:57], v[232:235], v[224:227], v[54:57]
	v_mfma_f32_16x16x32_bf16 v[58:61], v[236:239], v[224:227], v[58:61]
	v_mfma_f32_16x16x32_bf16 v[62:65], v[240:243], v[224:227], v[62:65]
	s_setprio 0
	s_barrier
	v_add_u32_e32 v204, 0x18000, v200
	v_add_u32_e32 v205, 0x18000, v202
	ds_read_b128 v[130:133], v204 offset:0
	ds_read_b128 v[134:137], v204 offset:2048
	ds_read_b128 v[138:141], v204 offset:4096
	ds_read_b128 v[142:145], v204 offset:6144
	ds_read_b128 v[146:149], v205 offset:0
	ds_read_b128 v[150:153], v205 offset:2048
	ds_read_b128 v[154:157], v205 offset:4096
	ds_read_b128 v[158:161], v205 offset:6144
	v_add_u32_e32 v204, 0x18000, v201
	v_add_u32_e32 v205, 0x18000, v203
	ds_read_b128 v[212:215], v204 offset:0
	ds_read_b128 v[216:219], v204 offset:2048
	ds_read_b128 v[220:223], v204 offset:4096
	ds_read_b128 v[224:227], v204 offset:6144
	ds_read_b128 v[228:231], v205 offset:0
	ds_read_b128 v[232:235], v205 offset:2048
	ds_read_b128 v[236:239], v205 offset:4096
	ds_read_b128 v[240:243], v205 offset:6144
	s_add_u32 m0, s76, 0xc000
	s_nop 0
	global_load_lds_dwordx4 v196, s[68:69]
	s_add_u32 m0, s76, 0xe000
	s_nop 0
	global_load_lds_dwordx4 v197, s[68:69]
	s_add_u32 m0, s76, 0x10000
	s_nop 0
	global_load_lds_dwordx4 v198, s[68:69]
	s_add_u32 m0, s76, 0x12000
	s_nop 0
	global_load_lds_dwordx4 v199, s[68:69]
	s_add_u32 m0, s76, 0x14000
	s_nop 0
	global_load_lds_dwordx4 v196, s[70:71]
	s_add_u32 m0, s76, 0x16000
	s_nop 0
	global_load_lds_dwordx4 v197, s[70:71]
	s_add_u32 s68, s68, 0x80
	s_addc_u32 s69, s69, 0
	s_add_u32 s70, s70, 0x80
	s_addc_u32 s71, s71, 0
	v_add_u32_e32 v170, s39, v192
	global_load_dwordx4 v[90:93], v170, s[14:15]
	v_add_u32_e32 v170, s40, v192
	global_load_dwordx4 v[94:97], v170, s[14:15]
	s_waitcnt vmcnt(10)
	s_waitcnt lgkmcnt(0)
	s_barrier
	s_setprio 1
	v_mfma_f32_16x16x32_bf16 v[2:5], v[146:149], v[130:133], v[2:5]
	v_mfma_f32_16x16x32_bf16 v[6:9], v[150:153], v[130:133], v[6:9]
	v_mfma_f32_16x16x32_bf16 v[10:13], v[154:157], v[130:133], v[10:13]
	v_mfma_f32_16x16x32_bf16 v[14:17], v[158:161], v[130:133], v[14:17]
	v_mfma_f32_16x16x32_bf16 v[18:21], v[146:149], v[134:137], v[18:21]
	v_mfma_f32_16x16x32_bf16 v[22:25], v[150:153], v[134:137], v[22:25]
	v_mfma_f32_16x16x32_bf16 v[26:29], v[154:157], v[134:137], v[26:29]
	v_mfma_f32_16x16x32_bf16 v[30:33], v[158:161], v[134:137], v[30:33]
	v_mfma_f32_16x16x32_bf16 v[34:37], v[146:149], v[138:141], v[34:37]
	v_mfma_f32_16x16x32_bf16 v[38:41], v[150:153], v[138:141], v[38:41]
	v_mfma_f32_16x16x32_bf16 v[42:45], v[154:157], v[138:141], v[42:45]
	v_mfma_f32_16x16x32_bf16 v[46:49], v[158:161], v[138:141], v[46:49]
	v_mfma_f32_16x16x32_bf16 v[50:53], v[146:149], v[142:145], v[50:53]
	v_mfma_f32_16x16x32_bf16 v[54:57], v[150:153], v[142:145], v[54:57]
	v_mfma_f32_16x16x32_bf16 v[58:61], v[154:157], v[142:145], v[58:61]
	v_mfma_f32_16x16x32_bf16 v[62:65], v[158:161], v[142:145], v[62:65]
	v_mfma_f32_16x16x32_bf16 v[2:5], v[228:231], v[212:215], v[2:5]
	v_mfma_f32_16x16x32_bf16 v[6:9], v[232:235], v[212:215], v[6:9]
	v_mfma_f32_16x16x32_bf16 v[10:13], v[236:239], v[212:215], v[10:13]
	v_mfma_f32_16x16x32_bf16 v[14:17], v[240:243], v[212:215], v[14:17]
	v_mfma_f32_16x16x32_bf16 v[18:21], v[228:231], v[216:219], v[18:21]
	v_mfma_f32_16x16x32_bf16 v[22:25], v[232:235], v[216:219], v[22:25]
	v_mfma_f32_16x16x32_bf16 v[26:29], v[236:239], v[216:219], v[26:29]
	v_mfma_f32_16x16x32_bf16 v[30:33], v[240:243], v[216:219], v[30:33]
	v_mfma_f32_16x16x32_bf16 v[34:37], v[228:231], v[220:223], v[34:37]
	v_mfma_f32_16x16x32_bf16 v[38:41], v[232:235], v[220:223], v[38:41]
	v_mfma_f32_16x16x32_bf16 v[42:45], v[236:239], v[220:223], v[42:45]
	v_mfma_f32_16x16x32_bf16 v[46:49], v[240:243], v[220:223], v[46:49]
	v_mfma_f32_16x16x32_bf16 v[50:53], v[228:231], v[224:227], v[50:53]
	v_mfma_f32_16x16x32_bf16 v[54:57], v[232:235], v[224:227], v[54:57]
	v_mfma_f32_16x16x32_bf16 v[58:61], v[236:239], v[224:227], v[58:61]
	v_mfma_f32_16x16x32_bf16 v[62:65], v[240:243], v[224:227], v[62:65]
	s_setprio 0
	s_barrier
	v_add_u32_e32 v204, 0x0, v200
	v_add_u32_e32 v205, 0x0, v202
	ds_read_b128 v[130:133], v204 offset:0
	ds_read_b128 v[134:137], v204 offset:2048
	ds_read_b128 v[138:141], v204 offset:4096
	ds_read_b128 v[142:145], v204 offset:6144
	ds_read_b128 v[146:149], v205 offset:0
	ds_read_b128 v[150:153], v205 offset:2048
	ds_read_b128 v[154:157], v205 offset:4096
	ds_read_b128 v[158:161], v205 offset:6144
	v_add_u32_e32 v204, 0x0, v201
	v_add_u32_e32 v205, 0x0, v203
	ds_read_b128 v[212:215], v204 offset:0
	ds_read_b128 v[216:219], v204 offset:2048
	ds_read_b128 v[220:223], v204 offset:4096
	ds_read_b128 v[224:227], v204 offset:6144
	ds_read_b128 v[228:231], v205 offset:0
	ds_read_b128 v[232:235], v205 offset:2048
	ds_read_b128 v[236:239], v205 offset:4096
	ds_read_b128 v[240:243], v205 offset:6144
	s_add_u32 m0, s76, 0x18000
	s_nop 0
	global_load_lds_dwordx4 v196, s[68:69]
	s_add_u32 m0, s76, 0x1a000
	s_nop 0
	global_load_lds_dwordx4 v197, s[68:69]
	s_add_u32 m0, s76, 0x1c000
	s_nop 0
	global_load_lds_dwordx4 v198, s[68:69]
	s_add_u32 m0, s76, 0x1e000
	s_nop 0
	global_load_lds_dwordx4 v199, s[68:69]
	s_add_u32 m0, s76, 0x20000
	s_nop 0
	global_load_lds_dwordx4 v196, s[70:71]
	s_add_u32 m0, s76, 0x22000
	s_nop 0
	global_load_lds_dwordx4 v197, s[70:71]
	s_add_u32 s68, s68, 0x80
	s_addc_u32 s69, s69, 0
	s_add_u32 s70, s70, 0x80
	s_addc_u32 s71, s71, 0
	global_load_dwordx4 v[98:101], v193, s[14:15]
	v_add_u32_e32 v170, s38, v193
	global_load_dwordx4 v[102:105], v170, s[14:15]
	s_waitcnt vmcnt(10)
	s_waitcnt lgkmcnt(0)
	s_barrier
	s_setprio 1
	v_mfma_f32_16x16x32_bf16 v[2:5], v[146:149], v[130:133], v[2:5]
	v_mfma_f32_16x16x32_bf16 v[6:9], v[150:153], v[130:133], v[6:9]
	v_mfma_f32_16x16x32_bf16 v[10:13], v[154:157], v[130:133], v[10:13]
	v_mfma_f32_16x16x32_bf16 v[14:17], v[158:161], v[130:133], v[14:17]
	v_mfma_f32_16x16x32_bf16 v[18:21], v[146:149], v[134:137], v[18:21]
	v_mfma_f32_16x16x32_bf16 v[22:25], v[150:153], v[134:137], v[22:25]
	v_mfma_f32_16x16x32_bf16 v[26:29], v[154:157], v[134:137], v[26:29]
	v_mfma_f32_16x16x32_bf16 v[30:33], v[158:161], v[134:137], v[30:33]
	v_mfma_f32_16x16x32_bf16 v[34:37], v[146:149], v[138:141], v[34:37]
	v_mfma_f32_16x16x32_bf16 v[38:41], v[150:153], v[138:141], v[38:41]
	v_mfma_f32_16x16x32_bf16 v[42:45], v[154:157], v[138:141], v[42:45]
	v_mfma_f32_16x16x32_bf16 v[46:49], v[158:161], v[138:141], v[46:49]
	v_mfma_f32_16x16x32_bf16 v[50:53], v[146:149], v[142:145], v[50:53]
	v_mfma_f32_16x16x32_bf16 v[54:57], v[150:153], v[142:145], v[54:57]
	v_mfma_f32_16x16x32_bf16 v[58:61], v[154:157], v[142:145], v[58:61]
	v_mfma_f32_16x16x32_bf16 v[62:65], v[158:161], v[142:145], v[62:65]
	v_mfma_f32_16x16x32_bf16 v[2:5], v[228:231], v[212:215], v[2:5]
	v_mfma_f32_16x16x32_bf16 v[6:9], v[232:235], v[212:215], v[6:9]
	v_mfma_f32_16x16x32_bf16 v[10:13], v[236:239], v[212:215], v[10:13]
	v_mfma_f32_16x16x32_bf16 v[14:17], v[240:243], v[212:215], v[14:17]
	v_mfma_f32_16x16x32_bf16 v[18:21], v[228:231], v[216:219], v[18:21]
	v_mfma_f32_16x16x32_bf16 v[22:25], v[232:235], v[216:219], v[22:25]
	v_mfma_f32_16x16x32_bf16 v[26:29], v[236:239], v[216:219], v[26:29]
	v_mfma_f32_16x16x32_bf16 v[30:33], v[240:243], v[216:219], v[30:33]
	v_mfma_f32_16x16x32_bf16 v[34:37], v[228:231], v[220:223], v[34:37]
	v_mfma_f32_16x16x32_bf16 v[38:41], v[232:235], v[220:223], v[38:41]
	v_mfma_f32_16x16x32_bf16 v[42:45], v[236:239], v[220:223], v[42:45]
	v_mfma_f32_16x16x32_bf16 v[46:49], v[240:243], v[220:223], v[46:49]
	v_mfma_f32_16x16x32_bf16 v[50:53], v[228:231], v[224:227], v[50:53]
	v_mfma_f32_16x16x32_bf16 v[54:57], v[232:235], v[224:227], v[54:57]
	v_mfma_f32_16x16x32_bf16 v[58:61], v[236:239], v[224:227], v[58:61]
	v_mfma_f32_16x16x32_bf16 v[62:65], v[240:243], v[224:227], v[62:65]
	s_setprio 0
	s_barrier
	v_add_u32_e32 v204, 0xc000, v200
	v_add_u32_e32 v205, 0xc000, v202
	ds_read_b128 v[130:133], v204 offset:0
	ds_read_b128 v[134:137], v204 offset:2048
	ds_read_b128 v[138:141], v204 offset:4096
	ds_read_b128 v[142:145], v204 offset:6144
	ds_read_b128 v[146:149], v205 offset:0
	ds_read_b128 v[150:153], v205 offset:2048
	ds_read_b128 v[154:157], v205 offset:4096
	ds_read_b128 v[158:161], v205 offset:6144
	v_add_u32_e32 v204, 0xc000, v201
	v_add_u32_e32 v205, 0xc000, v203
	ds_read_b128 v[212:215], v204 offset:0
	ds_read_b128 v[216:219], v204 offset:2048
	ds_read_b128 v[220:223], v204 offset:4096
	ds_read_b128 v[224:227], v204 offset:6144
	ds_read_b128 v[228:231], v205 offset:0
	ds_read_b128 v[232:235], v205 offset:2048
	ds_read_b128 v[236:239], v205 offset:4096
	ds_read_b128 v[240:243], v205 offset:6144
	s_add_u32 m0, s76, 0x0
	s_nop 0
	global_load_lds_dwordx4 v196, s[68:69]
	s_add_u32 m0, s76, 0x2000
	s_nop 0
	global_load_lds_dwordx4 v197, s[68:69]
	s_add_u32 m0, s76, 0x4000
	s_nop 0
	global_load_lds_dwordx4 v198, s[68:69]
	s_add_u32 m0, s76, 0x6000
	s_nop 0
	global_load_lds_dwordx4 v199, s[68:69]
	s_add_u32 m0, s76, 0x8000
	s_nop 0
	global_load_lds_dwordx4 v196, s[70:71]
	s_add_u32 m0, s76, 0xa000
	s_nop 0
	global_load_lds_dwordx4 v197, s[70:71]
	s_add_u32 s68, s68, 0x80
	s_addc_u32 s69, s69, 0
	s_add_u32 s70, s70, 0x80
	s_addc_u32 s71, s71, 0
	v_add_u32_e32 v170, s39, v193
	global_load_dwordx4 v[106:109], v170, s[14:15]
	v_add_u32_e32 v170, s40, v193
	global_load_dwordx4 v[110:113], v170, s[14:15]
	s_waitcnt vmcnt(10)
	s_waitcnt lgkmcnt(0)
	s_barrier
	s_setprio 1
	v_mfma_f32_16x16x32_bf16 v[2:5], v[146:149], v[130:133], v[2:5]
	v_mfma_f32_16x16x32_bf16 v[6:9], v[150:153], v[130:133], v[6:9]
	v_mfma_f32_16x16x32_bf16 v[10:13], v[154:157], v[130:133], v[10:13]
	v_mfma_f32_16x16x32_bf16 v[14:17], v[158:161], v[130:133], v[14:17]
	v_mfma_f32_16x16x32_bf16 v[18:21], v[146:149], v[134:137], v[18:21]
	v_mfma_f32_16x16x32_bf16 v[22:25], v[150:153], v[134:137], v[22:25]
	v_mfma_f32_16x16x32_bf16 v[26:29], v[154:157], v[134:137], v[26:29]
	v_mfma_f32_16x16x32_bf16 v[30:33], v[158:161], v[134:137], v[30:33]
	v_mfma_f32_16x16x32_bf16 v[34:37], v[146:149], v[138:141], v[34:37]
	v_mfma_f32_16x16x32_bf16 v[38:41], v[150:153], v[138:141], v[38:41]
	v_mfma_f32_16x16x32_bf16 v[42:45], v[154:157], v[138:141], v[42:45]
	v_mfma_f32_16x16x32_bf16 v[46:49], v[158:161], v[138:141], v[46:49]
	v_mfma_f32_16x16x32_bf16 v[50:53], v[146:149], v[142:145], v[50:53]
	v_mfma_f32_16x16x32_bf16 v[54:57], v[150:153], v[142:145], v[54:57]
	v_mfma_f32_16x16x32_bf16 v[58:61], v[154:157], v[142:145], v[58:61]
	v_mfma_f32_16x16x32_bf16 v[62:65], v[158:161], v[142:145], v[62:65]
	v_mfma_f32_16x16x32_bf16 v[2:5], v[228:231], v[212:215], v[2:5]
	v_mfma_f32_16x16x32_bf16 v[6:9], v[232:235], v[212:215], v[6:9]
	v_mfma_f32_16x16x32_bf16 v[10:13], v[236:239], v[212:215], v[10:13]
	v_mfma_f32_16x16x32_bf16 v[14:17], v[240:243], v[212:215], v[14:17]
	v_mfma_f32_16x16x32_bf16 v[18:21], v[228:231], v[216:219], v[18:21]
	v_mfma_f32_16x16x32_bf16 v[22:25], v[232:235], v[216:219], v[22:25]
	v_mfma_f32_16x16x32_bf16 v[26:29], v[236:239], v[216:219], v[26:29]
	v_mfma_f32_16x16x32_bf16 v[30:33], v[240:243], v[216:219], v[30:33]
	v_mfma_f32_16x16x32_bf16 v[34:37], v[228:231], v[220:223], v[34:37]
	v_mfma_f32_16x16x32_bf16 v[38:41], v[232:235], v[220:223], v[38:41]
	v_mfma_f32_16x16x32_bf16 v[42:45], v[236:239], v[220:223], v[42:45]
	v_mfma_f32_16x16x32_bf16 v[46:49], v[240:243], v[220:223], v[46:49]
	v_mfma_f32_16x16x32_bf16 v[50:53], v[228:231], v[224:227], v[50:53]
	v_mfma_f32_16x16x32_bf16 v[54:57], v[232:235], v[224:227], v[54:57]
	v_mfma_f32_16x16x32_bf16 v[58:61], v[236:239], v[224:227], v[58:61]
	v_mfma_f32_16x16x32_bf16 v[62:65], v[240:243], v[224:227], v[62:65]
	s_setprio 0
	s_barrier
	v_add_u32_e32 v204, 0x18000, v200
	v_add_u32_e32 v205, 0x18000, v202
	ds_read_b128 v[130:133], v204 offset:0
	ds_read_b128 v[134:137], v204 offset:2048
	ds_read_b128 v[138:141], v204 offset:4096
	ds_read_b128 v[142:145], v204 offset:6144
	ds_read_b128 v[146:149], v205 offset:0
	ds_read_b128 v[150:153], v205 offset:2048
	ds_read_b128 v[154:157], v205 offset:4096
	ds_read_b128 v[158:161], v205 offset:6144
	v_add_u32_e32 v204, 0x18000, v201
	v_add_u32_e32 v205, 0x18000, v203
	ds_read_b128 v[212:215], v204 offset:0
	ds_read_b128 v[216:219], v204 offset:2048
	ds_read_b128 v[220:223], v204 offset:4096
	ds_read_b128 v[224:227], v204 offset:6144
	ds_read_b128 v[228:231], v205 offset:0
	ds_read_b128 v[232:235], v205 offset:2048
	ds_read_b128 v[236:239], v205 offset:4096
	ds_read_b128 v[240:243], v205 offset:6144
	s_add_u32 m0, s76, 0xc000
	s_nop 0
	global_load_lds_dwordx4 v196, s[68:69]
	s_add_u32 m0, s76, 0xe000
	s_nop 0
	global_load_lds_dwordx4 v197, s[68:69]
	s_add_u32 m0, s76, 0x10000
	s_nop 0
	global_load_lds_dwordx4 v198, s[68:69]
	s_add_u32 m0, s76, 0x12000
	s_nop 0
	global_load_lds_dwordx4 v199, s[68:69]
	s_add_u32 m0, s76, 0x14000
	s_nop 0
	global_load_lds_dwordx4 v196, s[70:71]
	s_add_u32 m0, s76, 0x16000
	s_nop 0
	global_load_lds_dwordx4 v197, s[70:71]
	s_add_u32 s68, s68, 0x80
	s_addc_u32 s69, s69, 0
	s_add_u32 s70, s70, 0x80
	s_addc_u32 s71, s71, 0
	global_load_dwordx4 v[114:117], v244, s[14:15]
	v_add_u32_e32 v170, s38, v244
	global_load_dwordx4 v[118:121], v170, s[14:15]
	s_waitcnt vmcnt(10)
	s_waitcnt lgkmcnt(0)
	s_barrier
	s_setprio 1
	v_mfma_f32_16x16x32_bf16 v[2:5], v[146:149], v[130:133], v[2:5]
	v_mfma_f32_16x16x32_bf16 v[6:9], v[150:153], v[130:133], v[6:9]
	v_mfma_f32_16x16x32_bf16 v[10:13], v[154:157], v[130:133], v[10:13]
	v_mfma_f32_16x16x32_bf16 v[14:17], v[158:161], v[130:133], v[14:17]
	v_mfma_f32_16x16x32_bf16 v[18:21], v[146:149], v[134:137], v[18:21]
	v_mfma_f32_16x16x32_bf16 v[22:25], v[150:153], v[134:137], v[22:25]
	v_mfma_f32_16x16x32_bf16 v[26:29], v[154:157], v[134:137], v[26:29]
	v_mfma_f32_16x16x32_bf16 v[30:33], v[158:161], v[134:137], v[30:33]
	v_mfma_f32_16x16x32_bf16 v[34:37], v[146:149], v[138:141], v[34:37]
	v_mfma_f32_16x16x32_bf16 v[38:41], v[150:153], v[138:141], v[38:41]
	v_mfma_f32_16x16x32_bf16 v[42:45], v[154:157], v[138:141], v[42:45]
	v_mfma_f32_16x16x32_bf16 v[46:49], v[158:161], v[138:141], v[46:49]
	v_mfma_f32_16x16x32_bf16 v[50:53], v[146:149], v[142:145], v[50:53]
	v_mfma_f32_16x16x32_bf16 v[54:57], v[150:153], v[142:145], v[54:57]
	v_mfma_f32_16x16x32_bf16 v[58:61], v[154:157], v[142:145], v[58:61]
	v_mfma_f32_16x16x32_bf16 v[62:65], v[158:161], v[142:145], v[62:65]
	v_mfma_f32_16x16x32_bf16 v[2:5], v[228:231], v[212:215], v[2:5]
	v_mfma_f32_16x16x32_bf16 v[6:9], v[232:235], v[212:215], v[6:9]
	v_mfma_f32_16x16x32_bf16 v[10:13], v[236:239], v[212:215], v[10:13]
	v_mfma_f32_16x16x32_bf16 v[14:17], v[240:243], v[212:215], v[14:17]
	v_mfma_f32_16x16x32_bf16 v[18:21], v[228:231], v[216:219], v[18:21]
	v_mfma_f32_16x16x32_bf16 v[22:25], v[232:235], v[216:219], v[22:25]
	v_mfma_f32_16x16x32_bf16 v[26:29], v[236:239], v[216:219], v[26:29]
	v_mfma_f32_16x16x32_bf16 v[30:33], v[240:243], v[216:219], v[30:33]
	v_mfma_f32_16x16x32_bf16 v[34:37], v[228:231], v[220:223], v[34:37]
	v_mfma_f32_16x16x32_bf16 v[38:41], v[232:235], v[220:223], v[38:41]
	v_mfma_f32_16x16x32_bf16 v[42:45], v[236:239], v[220:223], v[42:45]
	v_mfma_f32_16x16x32_bf16 v[46:49], v[240:243], v[220:223], v[46:49]
	v_mfma_f32_16x16x32_bf16 v[50:53], v[228:231], v[224:227], v[50:53]
	v_mfma_f32_16x16x32_bf16 v[54:57], v[232:235], v[224:227], v[54:57]
	v_mfma_f32_16x16x32_bf16 v[58:61], v[236:239], v[224:227], v[58:61]
	v_mfma_f32_16x16x32_bf16 v[62:65], v[240:243], v[224:227], v[62:65]
	s_setprio 0
	s_barrier
	v_add_u32_e32 v204, 0x0, v200
	v_add_u32_e32 v205, 0x0, v202
	ds_read_b128 v[130:133], v204 offset:0
	ds_read_b128 v[134:137], v204 offset:2048
	ds_read_b128 v[138:141], v204 offset:4096
	ds_read_b128 v[142:145], v204 offset:6144
	ds_read_b128 v[146:149], v205 offset:0
	ds_read_b128 v[150:153], v205 offset:2048
	ds_read_b128 v[154:157], v205 offset:4096
	ds_read_b128 v[158:161], v205 offset:6144
	v_add_u32_e32 v204, 0x0, v201
	v_add_u32_e32 v205, 0x0, v203
	ds_read_b128 v[212:215], v204 offset:0
	ds_read_b128 v[216:219], v204 offset:2048
	ds_read_b128 v[220:223], v204 offset:4096
	ds_read_b128 v[224:227], v204 offset:6144
	ds_read_b128 v[228:231], v205 offset:0
	ds_read_b128 v[232:235], v205 offset:2048
	ds_read_b128 v[236:239], v205 offset:4096
	ds_read_b128 v[240:243], v205 offset:6144
	s_add_u32 m0, s76, 0x18000
	s_nop 0
	global_load_lds_dwordx4 v196, s[68:69]
	s_add_u32 m0, s76, 0x1a000
	s_nop 0
	global_load_lds_dwordx4 v197, s[68:69]
	s_add_u32 m0, s76, 0x1c000
	s_nop 0
	global_load_lds_dwordx4 v198, s[68:69]
	s_add_u32 m0, s76, 0x1e000
	s_nop 0
	global_load_lds_dwordx4 v199, s[68:69]
	s_add_u32 m0, s76, 0x20000
	s_nop 0
	global_load_lds_dwordx4 v196, s[70:71]
	s_add_u32 m0, s76, 0x22000
	s_nop 0
	global_load_lds_dwordx4 v197, s[70:71]
	s_add_u32 s68, s68, 0x80
	s_addc_u32 s69, s69, 0
	s_add_u32 s70, s70, 0x80
	s_addc_u32 s71, s71, 0
	v_add_u32_e32 v170, s39, v244
	global_load_dwordx4 v[122:125], v170, s[14:15]
	v_add_u32_e32 v170, s40, v244
	global_load_dwordx4 v[126:129], v170, s[14:15]
	s_waitcnt vmcnt(10)
	s_waitcnt lgkmcnt(0)
	s_barrier
	s_setprio 1
	v_mfma_f32_16x16x32_bf16 v[2:5], v[146:149], v[130:133], v[2:5]
	v_mfma_f32_16x16x32_bf16 v[6:9], v[150:153], v[130:133], v[6:9]
	v_mfma_f32_16x16x32_bf16 v[10:13], v[154:157], v[130:133], v[10:13]
	v_mfma_f32_16x16x32_bf16 v[14:17], v[158:161], v[130:133], v[14:17]
	v_mfma_f32_16x16x32_bf16 v[18:21], v[146:149], v[134:137], v[18:21]
	v_mfma_f32_16x16x32_bf16 v[22:25], v[150:153], v[134:137], v[22:25]
	v_mfma_f32_16x16x32_bf16 v[26:29], v[154:157], v[134:137], v[26:29]
	v_mfma_f32_16x16x32_bf16 v[30:33], v[158:161], v[134:137], v[30:33]
	v_mfma_f32_16x16x32_bf16 v[34:37], v[146:149], v[138:141], v[34:37]
	v_mfma_f32_16x16x32_bf16 v[38:41], v[150:153], v[138:141], v[38:41]
	v_mfma_f32_16x16x32_bf16 v[42:45], v[154:157], v[138:141], v[42:45]
	v_mfma_f32_16x16x32_bf16 v[46:49], v[158:161], v[138:141], v[46:49]
	v_mfma_f32_16x16x32_bf16 v[50:53], v[146:149], v[142:145], v[50:53]
	v_mfma_f32_16x16x32_bf16 v[54:57], v[150:153], v[142:145], v[54:57]
	v_mfma_f32_16x16x32_bf16 v[58:61], v[154:157], v[142:145], v[58:61]
	v_mfma_f32_16x16x32_bf16 v[62:65], v[158:161], v[142:145], v[62:65]
	v_mfma_f32_16x16x32_bf16 v[2:5], v[228:231], v[212:215], v[2:5]
	v_mfma_f32_16x16x32_bf16 v[6:9], v[232:235], v[212:215], v[6:9]
	v_mfma_f32_16x16x32_bf16 v[10:13], v[236:239], v[212:215], v[10:13]
	v_mfma_f32_16x16x32_bf16 v[14:17], v[240:243], v[212:215], v[14:17]
	v_mfma_f32_16x16x32_bf16 v[18:21], v[228:231], v[216:219], v[18:21]
	v_mfma_f32_16x16x32_bf16 v[22:25], v[232:235], v[216:219], v[22:25]
	v_mfma_f32_16x16x32_bf16 v[26:29], v[236:239], v[216:219], v[26:29]
	v_mfma_f32_16x16x32_bf16 v[30:33], v[240:243], v[216:219], v[30:33]
	v_mfma_f32_16x16x32_bf16 v[34:37], v[228:231], v[220:223], v[34:37]
	v_mfma_f32_16x16x32_bf16 v[38:41], v[232:235], v[220:223], v[38:41]
	v_mfma_f32_16x16x32_bf16 v[42:45], v[236:239], v[220:223], v[42:45]
	v_mfma_f32_16x16x32_bf16 v[46:49], v[240:243], v[220:223], v[46:49]
	v_mfma_f32_16x16x32_bf16 v[50:53], v[228:231], v[224:227], v[50:53]
	v_mfma_f32_16x16x32_bf16 v[54:57], v[232:235], v[224:227], v[54:57]
	v_mfma_f32_16x16x32_bf16 v[58:61], v[236:239], v[224:227], v[58:61]
	v_mfma_f32_16x16x32_bf16 v[62:65], v[240:243], v[224:227], v[62:65]
	s_setprio 0
	s_barrier
	v_add_u32_e32 v204, 0xc000, v200
	v_add_u32_e32 v205, 0xc000, v202
	ds_read_b128 v[130:133], v204 offset:0
	ds_read_b128 v[134:137], v204 offset:2048
	ds_read_b128 v[138:141], v204 offset:4096
	ds_read_b128 v[142:145], v204 offset:6144
	ds_read_b128 v[146:149], v205 offset:0
	ds_read_b128 v[150:153], v205 offset:2048
	ds_read_b128 v[154:157], v205 offset:4096
	ds_read_b128 v[158:161], v205 offset:6144
	v_add_u32_e32 v204, 0xc000, v201
	v_add_u32_e32 v205, 0xc000, v203
	ds_read_b128 v[212:215], v204 offset:0
	ds_read_b128 v[216:219], v204 offset:2048
	ds_read_b128 v[220:223], v204 offset:4096
	ds_read_b128 v[224:227], v204 offset:6144
	ds_read_b128 v[228:231], v205 offset:0
	ds_read_b128 v[232:235], v205 offset:2048
	ds_read_b128 v[236:239], v205 offset:4096
	ds_read_b128 v[240:243], v205 offset:6144
	s_add_u32 m0, s76, 0x0
	s_nop 0
	global_load_lds_dwordx4 v196, s[68:69]
	s_add_u32 m0, s76, 0x2000
	s_nop 0
	global_load_lds_dwordx4 v197, s[68:69]
	s_add_u32 m0, s76, 0x4000
	s_nop 0
	global_load_lds_dwordx4 v198, s[68:69]
	s_add_u32 m0, s76, 0x6000
	s_nop 0
	global_load_lds_dwordx4 v199, s[68:69]
	s_add_u32 m0, s76, 0x8000
	s_nop 0
	global_load_lds_dwordx4 v196, s[70:71]
	s_add_u32 m0, s76, 0xa000
	s_nop 0
	global_load_lds_dwordx4 v197, s[70:71]
	s_add_u32 s68, s68, 0x80
	s_addc_u32 s69, s69, 0
	s_add_u32 s70, s70, 0x80
	s_addc_u32 s71, s71, 0
	s_waitcnt vmcnt(8)
	s_waitcnt lgkmcnt(0)
	s_barrier
	s_setprio 1
	v_mfma_f32_16x16x32_bf16 v[2:5], v[146:149], v[130:133], v[2:5]
	v_mfma_f32_16x16x32_bf16 v[6:9], v[150:153], v[130:133], v[6:9]
	v_mfma_f32_16x16x32_bf16 v[10:13], v[154:157], v[130:133], v[10:13]
	v_mfma_f32_16x16x32_bf16 v[14:17], v[158:161], v[130:133], v[14:17]
	v_mfma_f32_16x16x32_bf16 v[18:21], v[146:149], v[134:137], v[18:21]
	v_mfma_f32_16x16x32_bf16 v[22:25], v[150:153], v[134:137], v[22:25]
	v_mfma_f32_16x16x32_bf16 v[26:29], v[154:157], v[134:137], v[26:29]
	v_mfma_f32_16x16x32_bf16 v[30:33], v[158:161], v[134:137], v[30:33]
	v_mfma_f32_16x16x32_bf16 v[34:37], v[146:149], v[138:141], v[34:37]
	v_mfma_f32_16x16x32_bf16 v[38:41], v[150:153], v[138:141], v[38:41]
	v_mfma_f32_16x16x32_bf16 v[42:45], v[154:157], v[138:141], v[42:45]
	v_mfma_f32_16x16x32_bf16 v[46:49], v[158:161], v[138:141], v[46:49]
	v_mfma_f32_16x16x32_bf16 v[50:53], v[146:149], v[142:145], v[50:53]
	v_mfma_f32_16x16x32_bf16 v[54:57], v[150:153], v[142:145], v[54:57]
	v_mfma_f32_16x16x32_bf16 v[58:61], v[154:157], v[142:145], v[58:61]
	v_mfma_f32_16x16x32_bf16 v[62:65], v[158:161], v[142:145], v[62:65]
	v_mfma_f32_16x16x32_bf16 v[2:5], v[228:231], v[212:215], v[2:5]
	v_mfma_f32_16x16x32_bf16 v[6:9], v[232:235], v[212:215], v[6:9]
	v_mfma_f32_16x16x32_bf16 v[10:13], v[236:239], v[212:215], v[10:13]
	v_mfma_f32_16x16x32_bf16 v[14:17], v[240:243], v[212:215], v[14:17]
	v_mfma_f32_16x16x32_bf16 v[18:21], v[228:231], v[216:219], v[18:21]
	v_mfma_f32_16x16x32_bf16 v[22:25], v[232:235], v[216:219], v[22:25]
	v_mfma_f32_16x16x32_bf16 v[26:29], v[236:239], v[216:219], v[26:29]
	v_mfma_f32_16x16x32_bf16 v[30:33], v[240:243], v[216:219], v[30:33]
	v_mfma_f32_16x16x32_bf16 v[34:37], v[228:231], v[220:223], v[34:37]
	v_mfma_f32_16x16x32_bf16 v[38:41], v[232:235], v[220:223], v[38:41]
	v_mfma_f32_16x16x32_bf16 v[42:45], v[236:239], v[220:223], v[42:45]
	v_mfma_f32_16x16x32_bf16 v[46:49], v[240:243], v[220:223], v[46:49]
	v_mfma_f32_16x16x32_bf16 v[50:53], v[228:231], v[224:227], v[50:53]
	v_mfma_f32_16x16x32_bf16 v[54:57], v[232:235], v[224:227], v[54:57]
	v_mfma_f32_16x16x32_bf16 v[58:61], v[236:239], v[224:227], v[58:61]
	v_mfma_f32_16x16x32_bf16 v[62:65], v[240:243], v[224:227], v[62:65]
	s_setprio 0
	s_barrier
	v_add_u32_e32 v204, 0x18000, v200
	v_add_u32_e32 v205, 0x18000, v202
	ds_read_b128 v[130:133], v204 offset:0
	ds_read_b128 v[134:137], v204 offset:2048
	ds_read_b128 v[138:141], v204 offset:4096
	ds_read_b128 v[142:145], v204 offset:6144
	ds_read_b128 v[146:149], v205 offset:0
	ds_read_b128 v[150:153], v205 offset:2048
	ds_read_b128 v[154:157], v205 offset:4096
	ds_read_b128 v[158:161], v205 offset:6144
	v_add_u32_e32 v204, 0x18000, v201
	v_add_u32_e32 v205, 0x18000, v203
	ds_read_b128 v[212:215], v204 offset:0
	ds_read_b128 v[216:219], v204 offset:2048
	ds_read_b128 v[220:223], v204 offset:4096
	ds_read_b128 v[224:227], v204 offset:6144
	ds_read_b128 v[228:231], v205 offset:0
	ds_read_b128 v[232:235], v205 offset:2048
	ds_read_b128 v[236:239], v205 offset:4096
	ds_read_b128 v[240:243], v205 offset:6144
	s_add_u32 m0, s76, 0xc000
	s_nop 0
	global_load_lds_dwordx4 v196, s[68:69]
	s_add_u32 m0, s76, 0xe000
	s_nop 0
	global_load_lds_dwordx4 v197, s[68:69]
	s_add_u32 m0, s76, 0x10000
	s_nop 0
	global_load_lds_dwordx4 v198, s[68:69]
	s_add_u32 m0, s76, 0x12000
	s_nop 0
	global_load_lds_dwordx4 v199, s[68:69]
	s_add_u32 m0, s76, 0x14000
	s_nop 0
	global_load_lds_dwordx4 v196, s[70:71]
	s_add_u32 m0, s76, 0x16000
	s_nop 0
	global_load_lds_dwordx4 v197, s[70:71]
	s_add_u32 s68, s68, 0x80
	s_addc_u32 s69, s69, 0
	s_add_u32 s70, s70, 0x80
	s_addc_u32 s71, s71, 0
	s_waitcnt vmcnt(6)
	s_waitcnt lgkmcnt(0)
	s_barrier
	s_setprio 1
	v_mfma_f32_16x16x32_bf16 v[2:5], v[146:149], v[130:133], v[2:5]
	v_mfma_f32_16x16x32_bf16 v[6:9], v[150:153], v[130:133], v[6:9]
	v_mfma_f32_16x16x32_bf16 v[10:13], v[154:157], v[130:133], v[10:13]
	v_mfma_f32_16x16x32_bf16 v[14:17], v[158:161], v[130:133], v[14:17]
	v_mfma_f32_16x16x32_bf16 v[18:21], v[146:149], v[134:137], v[18:21]
	v_mfma_f32_16x16x32_bf16 v[22:25], v[150:153], v[134:137], v[22:25]
	v_mfma_f32_16x16x32_bf16 v[26:29], v[154:157], v[134:137], v[26:29]
	v_mfma_f32_16x16x32_bf16 v[30:33], v[158:161], v[134:137], v[30:33]
	v_mfma_f32_16x16x32_bf16 v[34:37], v[146:149], v[138:141], v[34:37]
	v_mfma_f32_16x16x32_bf16 v[38:41], v[150:153], v[138:141], v[38:41]
	v_mfma_f32_16x16x32_bf16 v[42:45], v[154:157], v[138:141], v[42:45]
	v_mfma_f32_16x16x32_bf16 v[46:49], v[158:161], v[138:141], v[46:49]
	v_mfma_f32_16x16x32_bf16 v[50:53], v[146:149], v[142:145], v[50:53]
	v_mfma_f32_16x16x32_bf16 v[54:57], v[150:153], v[142:145], v[54:57]
	v_mfma_f32_16x16x32_bf16 v[58:61], v[154:157], v[142:145], v[58:61]
	v_mfma_f32_16x16x32_bf16 v[62:65], v[158:161], v[142:145], v[62:65]
	v_mfma_f32_16x16x32_bf16 v[2:5], v[228:231], v[212:215], v[2:5]
	v_mfma_f32_16x16x32_bf16 v[6:9], v[232:235], v[212:215], v[6:9]
	v_mfma_f32_16x16x32_bf16 v[10:13], v[236:239], v[212:215], v[10:13]
	v_mfma_f32_16x16x32_bf16 v[14:17], v[240:243], v[212:215], v[14:17]
	v_mfma_f32_16x16x32_bf16 v[18:21], v[228:231], v[216:219], v[18:21]
	v_mfma_f32_16x16x32_bf16 v[22:25], v[232:235], v[216:219], v[22:25]
	v_mfma_f32_16x16x32_bf16 v[26:29], v[236:239], v[216:219], v[26:29]
	v_mfma_f32_16x16x32_bf16 v[30:33], v[240:243], v[216:219], v[30:33]
	v_mfma_f32_16x16x32_bf16 v[34:37], v[228:231], v[220:223], v[34:37]
	v_mfma_f32_16x16x32_bf16 v[38:41], v[232:235], v[220:223], v[38:41]
	v_mfma_f32_16x16x32_bf16 v[42:45], v[236:239], v[220:223], v[42:45]
	v_mfma_f32_16x16x32_bf16 v[46:49], v[240:243], v[220:223], v[46:49]
	v_mfma_f32_16x16x32_bf16 v[50:53], v[228:231], v[224:227], v[50:53]
	v_mfma_f32_16x16x32_bf16 v[54:57], v[232:235], v[224:227], v[54:57]
	v_mfma_f32_16x16x32_bf16 v[58:61], v[236:239], v[224:227], v[58:61]
	v_mfma_f32_16x16x32_bf16 v[62:65], v[240:243], v[224:227], v[62:65]
	s_setprio 0
	s_barrier
	v_add_u32_e32 v204, 0x0, v200
	v_add_u32_e32 v205, 0x0, v202
	ds_read_b128 v[130:133], v204 offset:0
	ds_read_b128 v[134:137], v204 offset:2048
	ds_read_b128 v[138:141], v204 offset:4096
	ds_read_b128 v[142:145], v204 offset:6144
	ds_read_b128 v[146:149], v205 offset:0
	ds_read_b128 v[150:153], v205 offset:2048
	ds_read_b128 v[154:157], v205 offset:4096
	ds_read_b128 v[158:161], v205 offset:6144
	v_add_u32_e32 v204, 0x0, v201
	v_add_u32_e32 v205, 0x0, v203
	ds_read_b128 v[212:215], v204 offset:0
	ds_read_b128 v[216:219], v204 offset:2048
	ds_read_b128 v[220:223], v204 offset:4096
	ds_read_b128 v[224:227], v204 offset:6144
	ds_read_b128 v[228:231], v205 offset:0
	ds_read_b128 v[232:235], v205 offset:2048
	ds_read_b128 v[236:239], v205 offset:4096
	ds_read_b128 v[240:243], v205 offset:6144
	s_add_u32 m0, s76, 0x18000
	s_nop 0
	global_load_lds_dwordx4 v196, s[68:69]
	s_add_u32 m0, s76, 0x1a000
	s_nop 0
	global_load_lds_dwordx4 v197, s[68:69]
	s_add_u32 m0, s76, 0x1c000
	s_nop 0
	global_load_lds_dwordx4 v198, s[68:69]
	s_add_u32 m0, s76, 0x1e000
	s_nop 0
	global_load_lds_dwordx4 v199, s[68:69]
	s_add_u32 m0, s76, 0x20000
	s_nop 0
	global_load_lds_dwordx4 v196, s[70:71]
	s_add_u32 m0, s76, 0x22000
	s_nop 0
	global_load_lds_dwordx4 v197, s[70:71]
	s_add_u32 s68, s68, 0x80
	s_addc_u32 s69, s69, 0
	s_add_u32 s70, s70, 0x80
	s_addc_u32 s71, s71, 0
	s_waitcnt vmcnt(6)
	s_waitcnt lgkmcnt(0)
	s_barrier
	s_setprio 1
	v_mfma_f32_16x16x32_bf16 v[2:5], v[146:149], v[130:133], v[2:5]
	v_mfma_f32_16x16x32_bf16 v[6:9], v[150:153], v[130:133], v[6:9]
	v_mfma_f32_16x16x32_bf16 v[10:13], v[154:157], v[130:133], v[10:13]
	v_mfma_f32_16x16x32_bf16 v[14:17], v[158:161], v[130:133], v[14:17]
	v_mfma_f32_16x16x32_bf16 v[18:21], v[146:149], v[134:137], v[18:21]
	v_mfma_f32_16x16x32_bf16 v[22:25], v[150:153], v[134:137], v[22:25]
	v_mfma_f32_16x16x32_bf16 v[26:29], v[154:157], v[134:137], v[26:29]
	v_mfma_f32_16x16x32_bf16 v[30:33], v[158:161], v[134:137], v[30:33]
	v_mfma_f32_16x16x32_bf16 v[34:37], v[146:149], v[138:141], v[34:37]
	v_mfma_f32_16x16x32_bf16 v[38:41], v[150:153], v[138:141], v[38:41]
	v_mfma_f32_16x16x32_bf16 v[42:45], v[154:157], v[138:141], v[42:45]
	v_mfma_f32_16x16x32_bf16 v[46:49], v[158:161], v[138:141], v[46:49]
	v_mfma_f32_16x16x32_bf16 v[50:53], v[146:149], v[142:145], v[50:53]
	v_mfma_f32_16x16x32_bf16 v[54:57], v[150:153], v[142:145], v[54:57]
	v_mfma_f32_16x16x32_bf16 v[58:61], v[154:157], v[142:145], v[58:61]
	v_mfma_f32_16x16x32_bf16 v[62:65], v[158:161], v[142:145], v[62:65]
	v_mfma_f32_16x16x32_bf16 v[2:5], v[228:231], v[212:215], v[2:5]
	v_mfma_f32_16x16x32_bf16 v[6:9], v[232:235], v[212:215], v[6:9]
	v_mfma_f32_16x16x32_bf16 v[10:13], v[236:239], v[212:215], v[10:13]
	v_mfma_f32_16x16x32_bf16 v[14:17], v[240:243], v[212:215], v[14:17]
	v_mfma_f32_16x16x32_bf16 v[18:21], v[228:231], v[216:219], v[18:21]
	v_mfma_f32_16x16x32_bf16 v[22:25], v[232:235], v[216:219], v[22:25]
	v_mfma_f32_16x16x32_bf16 v[26:29], v[236:239], v[216:219], v[26:29]
	v_mfma_f32_16x16x32_bf16 v[30:33], v[240:243], v[216:219], v[30:33]
	v_mfma_f32_16x16x32_bf16 v[34:37], v[228:231], v[220:223], v[34:37]
	v_mfma_f32_16x16x32_bf16 v[38:41], v[232:235], v[220:223], v[38:41]
	v_mfma_f32_16x16x32_bf16 v[42:45], v[236:239], v[220:223], v[42:45]
	v_mfma_f32_16x16x32_bf16 v[46:49], v[240:243], v[220:223], v[46:49]
	v_mfma_f32_16x16x32_bf16 v[50:53], v[228:231], v[224:227], v[50:53]
	v_mfma_f32_16x16x32_bf16 v[54:57], v[232:235], v[224:227], v[54:57]
	v_mfma_f32_16x16x32_bf16 v[58:61], v[236:239], v[224:227], v[58:61]
	v_mfma_f32_16x16x32_bf16 v[62:65], v[240:243], v[224:227], v[62:65]
	s_setprio 0
	s_barrier
	v_add_u32_e32 v204, 0xc000, v200
	v_add_u32_e32 v205, 0xc000, v202
	ds_read_b128 v[130:133], v204 offset:0
	ds_read_b128 v[134:137], v204 offset:2048
	ds_read_b128 v[138:141], v204 offset:4096
	ds_read_b128 v[142:145], v204 offset:6144
	ds_read_b128 v[146:149], v205 offset:0
	ds_read_b128 v[150:153], v205 offset:2048
	ds_read_b128 v[154:157], v205 offset:4096
	ds_read_b128 v[158:161], v205 offset:6144
	v_add_u32_e32 v204, 0xc000, v201
	v_add_u32_e32 v205, 0xc000, v203
	ds_read_b128 v[212:215], v204 offset:0
	ds_read_b128 v[216:219], v204 offset:2048
	ds_read_b128 v[220:223], v204 offset:4096
	ds_read_b128 v[224:227], v204 offset:6144
	ds_read_b128 v[228:231], v205 offset:0
	ds_read_b128 v[232:235], v205 offset:2048
	ds_read_b128 v[236:239], v205 offset:4096
	ds_read_b128 v[240:243], v205 offset:6144
	s_add_u32 m0, s76, 0x0
	s_nop 0
	global_load_lds_dwordx4 v196, s[68:69]
	s_add_u32 m0, s76, 0x2000
	s_nop 0
	global_load_lds_dwordx4 v197, s[68:69]
	s_add_u32 m0, s76, 0x4000
	s_nop 0
	global_load_lds_dwordx4 v198, s[68:69]
	s_add_u32 m0, s76, 0x6000
	s_nop 0
	global_load_lds_dwordx4 v199, s[68:69]
	s_add_u32 m0, s76, 0x8000
	s_nop 0
	global_load_lds_dwordx4 v196, s[70:71]
	s_add_u32 m0, s76, 0xa000
	s_nop 0
	global_load_lds_dwordx4 v197, s[70:71]
	s_add_u32 s68, s68, 0x80
	s_addc_u32 s69, s69, 0
	s_add_u32 s70, s70, 0x80
	s_addc_u32 s71, s71, 0
	s_waitcnt vmcnt(6)
	s_waitcnt lgkmcnt(0)
	s_barrier
	s_setprio 1
	v_mfma_f32_16x16x32_bf16 v[2:5], v[146:149], v[130:133], v[2:5]
	v_mfma_f32_16x16x32_bf16 v[6:9], v[150:153], v[130:133], v[6:9]
	v_mfma_f32_16x16x32_bf16 v[10:13], v[154:157], v[130:133], v[10:13]
	v_mfma_f32_16x16x32_bf16 v[14:17], v[158:161], v[130:133], v[14:17]
	v_mfma_f32_16x16x32_bf16 v[18:21], v[146:149], v[134:137], v[18:21]
	v_mfma_f32_16x16x32_bf16 v[22:25], v[150:153], v[134:137], v[22:25]
	v_mfma_f32_16x16x32_bf16 v[26:29], v[154:157], v[134:137], v[26:29]
	v_mfma_f32_16x16x32_bf16 v[30:33], v[158:161], v[134:137], v[30:33]
	v_mfma_f32_16x16x32_bf16 v[34:37], v[146:149], v[138:141], v[34:37]
	v_mfma_f32_16x16x32_bf16 v[38:41], v[150:153], v[138:141], v[38:41]
	v_mfma_f32_16x16x32_bf16 v[42:45], v[154:157], v[138:141], v[42:45]
	v_mfma_f32_16x16x32_bf16 v[46:49], v[158:161], v[138:141], v[46:49]
	v_mfma_f32_16x16x32_bf16 v[50:53], v[146:149], v[142:145], v[50:53]
	v_mfma_f32_16x16x32_bf16 v[54:57], v[150:153], v[142:145], v[54:57]
	v_mfma_f32_16x16x32_bf16 v[58:61], v[154:157], v[142:145], v[58:61]
	v_mfma_f32_16x16x32_bf16 v[62:65], v[158:161], v[142:145], v[62:65]
	v_mfma_f32_16x16x32_bf16 v[2:5], v[228:231], v[212:215], v[2:5]
	v_mfma_f32_16x16x32_bf16 v[6:9], v[232:235], v[212:215], v[6:9]
	v_mfma_f32_16x16x32_bf16 v[10:13], v[236:239], v[212:215], v[10:13]
	v_mfma_f32_16x16x32_bf16 v[14:17], v[240:243], v[212:215], v[14:17]
	v_mfma_f32_16x16x32_bf16 v[18:21], v[228:231], v[216:219], v[18:21]
	v_mfma_f32_16x16x32_bf16 v[22:25], v[232:235], v[216:219], v[22:25]
	v_mfma_f32_16x16x32_bf16 v[26:29], v[236:239], v[216:219], v[26:29]
	v_mfma_f32_16x16x32_bf16 v[30:33], v[240:243], v[216:219], v[30:33]
	v_mfma_f32_16x16x32_bf16 v[34:37], v[228:231], v[220:223], v[34:37]
	v_mfma_f32_16x16x32_bf16 v[38:41], v[232:235], v[220:223], v[38:41]
	v_mfma_f32_16x16x32_bf16 v[42:45], v[236:239], v[220:223], v[42:45]
	v_mfma_f32_16x16x32_bf16 v[46:49], v[240:243], v[220:223], v[46:49]
	v_mfma_f32_16x16x32_bf16 v[50:53], v[228:231], v[224:227], v[50:53]
	v_mfma_f32_16x16x32_bf16 v[54:57], v[232:235], v[224:227], v[54:57]
	v_mfma_f32_16x16x32_bf16 v[58:61], v[236:239], v[224:227], v[58:61]
	v_mfma_f32_16x16x32_bf16 v[62:65], v[240:243], v[224:227], v[62:65]
	s_setprio 0
	s_barrier
	v_add_u32_e32 v204, 0x18000, v200
	v_add_u32_e32 v205, 0x18000, v202
	ds_read_b128 v[130:133], v204 offset:0
	ds_read_b128 v[134:137], v204 offset:2048
	ds_read_b128 v[138:141], v204 offset:4096
	ds_read_b128 v[142:145], v204 offset:6144
	ds_read_b128 v[146:149], v205 offset:0
	ds_read_b128 v[150:153], v205 offset:2048
	ds_read_b128 v[154:157], v205 offset:4096
	ds_read_b128 v[158:161], v205 offset:6144
	v_add_u32_e32 v204, 0x18000, v201
	v_add_u32_e32 v205, 0x18000, v203
	ds_read_b128 v[212:215], v204 offset:0
	ds_read_b128 v[216:219], v204 offset:2048
	ds_read_b128 v[220:223], v204 offset:4096
	ds_read_b128 v[224:227], v204 offset:6144
	ds_read_b128 v[228:231], v205 offset:0
	ds_read_b128 v[232:235], v205 offset:2048
	ds_read_b128 v[236:239], v205 offset:4096
	ds_read_b128 v[240:243], v205 offset:6144
	s_waitcnt vmcnt(0)
	s_waitcnt lgkmcnt(0)
	s_barrier
	s_setprio 1
	v_mfma_f32_16x16x32_bf16 v[2:5], v[146:149], v[130:133], v[2:5]
	v_mfma_f32_16x16x32_bf16 v[6:9], v[150:153], v[130:133], v[6:9]
	v_mfma_f32_16x16x32_bf16 v[10:13], v[154:157], v[130:133], v[10:13]
	v_mfma_f32_16x16x32_bf16 v[14:17], v[158:161], v[130:133], v[14:17]
	v_mfma_f32_16x16x32_bf16 v[18:21], v[146:149], v[134:137], v[18:21]
	v_mfma_f32_16x16x32_bf16 v[22:25], v[150:153], v[134:137], v[22:25]
	v_mfma_f32_16x16x32_bf16 v[26:29], v[154:157], v[134:137], v[26:29]
	v_mfma_f32_16x16x32_bf16 v[30:33], v[158:161], v[134:137], v[30:33]
	v_mfma_f32_16x16x32_bf16 v[34:37], v[146:149], v[138:141], v[34:37]
	v_mfma_f32_16x16x32_bf16 v[38:41], v[150:153], v[138:141], v[38:41]
	v_mfma_f32_16x16x32_bf16 v[42:45], v[154:157], v[138:141], v[42:45]
	v_mfma_f32_16x16x32_bf16 v[46:49], v[158:161], v[138:141], v[46:49]
	v_mfma_f32_16x16x32_bf16 v[50:53], v[146:149], v[142:145], v[50:53]
	v_mfma_f32_16x16x32_bf16 v[54:57], v[150:153], v[142:145], v[54:57]
	v_mfma_f32_16x16x32_bf16 v[58:61], v[154:157], v[142:145], v[58:61]
	v_mfma_f32_16x16x32_bf16 v[62:65], v[158:161], v[142:145], v[62:65]
	v_mfma_f32_16x16x32_bf16 v[2:5], v[228:231], v[212:215], v[2:5]
	v_mfma_f32_16x16x32_bf16 v[6:9], v[232:235], v[212:215], v[6:9]
	v_mfma_f32_16x16x32_bf16 v[10:13], v[236:239], v[212:215], v[10:13]
	v_mfma_f32_16x16x32_bf16 v[14:17], v[240:243], v[212:215], v[14:17]
	v_mfma_f32_16x16x32_bf16 v[18:21], v[228:231], v[216:219], v[18:21]
	v_mfma_f32_16x16x32_bf16 v[22:25], v[232:235], v[216:219], v[22:25]
	v_mfma_f32_16x16x32_bf16 v[26:29], v[236:239], v[216:219], v[26:29]
	v_mfma_f32_16x16x32_bf16 v[30:33], v[240:243], v[216:219], v[30:33]
	v_mfma_f32_16x16x32_bf16 v[34:37], v[228:231], v[220:223], v[34:37]
	v_mfma_f32_16x16x32_bf16 v[38:41], v[232:235], v[220:223], v[38:41]
	v_mfma_f32_16x16x32_bf16 v[42:45], v[236:239], v[220:223], v[42:45]
	v_mfma_f32_16x16x32_bf16 v[46:49], v[240:243], v[220:223], v[46:49]
	v_mfma_f32_16x16x32_bf16 v[50:53], v[228:231], v[224:227], v[50:53]
	v_mfma_f32_16x16x32_bf16 v[54:57], v[232:235], v[224:227], v[54:57]
	v_mfma_f32_16x16x32_bf16 v[58:61], v[236:239], v[224:227], v[58:61]
	v_mfma_f32_16x16x32_bf16 v[62:65], v[240:243], v[224:227], v[62:65]
	s_setprio 0
	s_barrier
	v_add_u32_e32 v204, 0x0, v200
	v_add_u32_e32 v205, 0x0, v202
	ds_read_b128 v[130:133], v204 offset:0
	ds_read_b128 v[134:137], v204 offset:2048
	ds_read_b128 v[138:141], v204 offset:4096
	ds_read_b128 v[142:145], v204 offset:6144
	ds_read_b128 v[146:149], v205 offset:0
	ds_read_b128 v[150:153], v205 offset:2048
	ds_read_b128 v[154:157], v205 offset:4096
	ds_read_b128 v[158:161], v205 offset:6144
	v_add_u32_e32 v204, 0x0, v201
	v_add_u32_e32 v205, 0x0, v203
	ds_read_b128 v[212:215], v204 offset:0
	ds_read_b128 v[216:219], v204 offset:2048
	ds_read_b128 v[220:223], v204 offset:4096
	ds_read_b128 v[224:227], v204 offset:6144
	ds_read_b128 v[228:231], v205 offset:0
	ds_read_b128 v[232:235], v205 offset:2048
	ds_read_b128 v[236:239], v205 offset:4096
	ds_read_b128 v[240:243], v205 offset:6144
	s_waitcnt lgkmcnt(0)
	s_barrier
	s_setprio 1
	v_mfma_f32_16x16x32_bf16 v[2:5], v[146:149], v[130:133], v[2:5]
	v_mfma_f32_16x16x32_bf16 v[6:9], v[150:153], v[130:133], v[6:9]
	v_mfma_f32_16x16x32_bf16 v[10:13], v[154:157], v[130:133], v[10:13]
	v_mfma_f32_16x16x32_bf16 v[14:17], v[158:161], v[130:133], v[14:17]
	v_mfma_f32_16x16x32_bf16 v[18:21], v[146:149], v[134:137], v[18:21]
	v_mfma_f32_16x16x32_bf16 v[22:25], v[150:153], v[134:137], v[22:25]
	v_mfma_f32_16x16x32_bf16 v[26:29], v[154:157], v[134:137], v[26:29]
	v_mfma_f32_16x16x32_bf16 v[30:33], v[158:161], v[134:137], v[30:33]
	v_mfma_f32_16x16x32_bf16 v[34:37], v[146:149], v[138:141], v[34:37]
	v_mfma_f32_16x16x32_bf16 v[38:41], v[150:153], v[138:141], v[38:41]
	v_mfma_f32_16x16x32_bf16 v[42:45], v[154:157], v[138:141], v[42:45]
	v_mfma_f32_16x16x32_bf16 v[46:49], v[158:161], v[138:141], v[46:49]
	v_mfma_f32_16x16x32_bf16 v[50:53], v[146:149], v[142:145], v[50:53]
	v_mfma_f32_16x16x32_bf16 v[54:57], v[150:153], v[142:145], v[54:57]
	v_mfma_f32_16x16x32_bf16 v[58:61], v[154:157], v[142:145], v[58:61]
	v_mfma_f32_16x16x32_bf16 v[62:65], v[158:161], v[142:145], v[62:65]
	v_mfma_f32_16x16x32_bf16 v[2:5], v[228:231], v[212:215], v[2:5]
	v_mfma_f32_16x16x32_bf16 v[6:9], v[232:235], v[212:215], v[6:9]
	v_mfma_f32_16x16x32_bf16 v[10:13], v[236:239], v[212:215], v[10:13]
	v_mfma_f32_16x16x32_bf16 v[14:17], v[240:243], v[212:215], v[14:17]
	v_mfma_f32_16x16x32_bf16 v[18:21], v[228:231], v[216:219], v[18:21]
	v_mfma_f32_16x16x32_bf16 v[22:25], v[232:235], v[216:219], v[22:25]
	v_mfma_f32_16x16x32_bf16 v[26:29], v[236:239], v[216:219], v[26:29]
	v_mfma_f32_16x16x32_bf16 v[30:33], v[240:243], v[216:219], v[30:33]
	v_mfma_f32_16x16x32_bf16 v[34:37], v[228:231], v[220:223], v[34:37]
	v_mfma_f32_16x16x32_bf16 v[38:41], v[232:235], v[220:223], v[38:41]
	v_mfma_f32_16x16x32_bf16 v[42:45], v[236:239], v[220:223], v[42:45]
	v_mfma_f32_16x16x32_bf16 v[46:49], v[240:243], v[220:223], v[46:49]
	v_mfma_f32_16x16x32_bf16 v[50:53], v[228:231], v[224:227], v[50:53]
	v_mfma_f32_16x16x32_bf16 v[54:57], v[232:235], v[224:227], v[54:57]
	v_mfma_f32_16x16x32_bf16 v[58:61], v[236:239], v[224:227], v[58:61]
	v_mfma_f32_16x16x32_bf16 v[62:65], v[240:243], v[224:227], v[62:65]
	s_setprio 0

.Lbr_tile:
	s_and_b32 s0, s78, 3
	s_or_b32 s0, s0, s77
	s_lshl_b32 s0, s0, 8
	s_lshr_b32 s1, s78, 2
	s_lshl_b32 s1, s1, 7
	s_mul_i32 s2, s0, 0xc00
	s_add_u32 s68, s8, s2
	s_addc_u32 s69, s9, 0
	s_mul_i32 s2, s1, 0xc00
	s_add_u32 s70, s80, s2
	s_addc_u32 s71, s81, 0
	s_mul_i32 s2, s0, 0x3400
	s_lshl_b32 s3, s1, 1
	s_add_u32 s2, s2, s3
	s_add_u32 s2, s2, 0x1c00
	s_add_u32 s72, s4, s2
	s_addc_u32 s73, s5, 0
	s_lshl_b32 s2, s0, 11
	s_add_u32 s2, s2, s3
	s_add_u32 s74, s10, s2
	s_addc_u32 s75, s11, 0
	s_add_u32 m0, s76, 0x0
	s_nop 0
	global_load_lds_dwordx4 v196, s[68:69]
	s_add_u32 m0, s76, 0x2000
	s_nop 0
	global_load_lds_dwordx4 v197, s[68:69]
	s_add_u32 m0, s76, 0x4000
	s_nop 0
	global_load_lds_dwordx4 v198, s[68:69]
	s_add_u32 m0, s76, 0x6000
	s_nop 0
	global_load_lds_dwordx4 v199, s[68:69]
	s_add_u32 m0, s76, 0x8000
	s_nop 0
	global_load_lds_dwordx4 v196, s[70:71]
	s_add_u32 m0, s76, 0xa000
	s_nop 0
	global_load_lds_dwordx4 v197, s[70:71]
	s_add_u32 s68, s68, 0x80
	s_addc_u32 s69, s69, 0
	s_add_u32 s70, s70, 0x80
	s_addc_u32 s71, s71, 0
	s_add_u32 m0, s76, 0xc000
	s_nop 0
	global_load_lds_dwordx4 v196, s[68:69]
	s_add_u32 m0, s76, 0xe000
	s_nop 0
	global_load_lds_dwordx4 v197, s[68:69]
	s_add_u32 m0, s76, 0x10000
	s_nop 0
	global_load_lds_dwordx4 v198, s[68:69]
	s_add_u32 m0, s76, 0x12000
	s_nop 0
	global_load_lds_dwordx4 v199, s[68:69]
	s_add_u32 m0, s76, 0x14000
	s_nop 0
	global_load_lds_dwordx4 v196, s[70:71]
	s_add_u32 m0, s76, 0x16000
	s_nop 0
	global_load_lds_dwordx4 v197, s[70:71]
	s_add_u32 s68, s68, 0x80
	s_addc_u32 s69, s69, 0
	s_add_u32 s70, s70, 0x80
	s_addc_u32 s71, s71, 0
	v_mov_b32_e32 v66, 0
	v_mov_b32_e32 v67, 0
	v_mov_b32_e32 v68, 0
	v_mov_b32_e32 v69, 0
	v_mov_b32_e32 v70, 0
	v_mov_b32_e32 v71, 0
	v_mov_b32_e32 v72, 0
	v_mov_b32_e32 v73, 0
	v_mov_b32_e32 v74, 0
	v_mov_b32_e32 v75, 0
	v_mov_b32_e32 v76, 0
	v_mov_b32_e32 v77, 0
	v_mov_b32_e32 v78, 0
	v_mov_b32_e32 v79, 0
	v_mov_b32_e32 v80, 0
	v_mov_b32_e32 v81, 0
	v_mov_b32_e32 v82, 0
	v_mov_b32_e32 v83, 0
	v_mov_b32_e32 v84, 0
	v_mov_b32_e32 v85, 0
	v_mov_b32_e32 v86, 0
	v_mov_b32_e32 v87, 0
	v_mov_b32_e32 v88, 0
	v_mov_b32_e32 v89, 0
	v_mov_b32_e32 v90, 0
	v_mov_b32_e32 v91, 0
	v_mov_b32_e32 v92, 0
	v_mov_b32_e32 v93, 0
	v_mov_b32_e32 v94, 0
	v_mov_b32_e32 v95, 0
	v_mov_b32_e32 v96, 0
	v_mov_b32_e32 v97, 0
	v_mov_b32_e32 v98, 0
	v_mov_b32_e32 v99, 0
	v_mov_b32_e32 v100, 0
	v_mov_b32_e32 v101, 0
	v_mov_b32_e32 v102, 0
	v_mov_b32_e32 v103, 0
	v_mov_b32_e32 v104, 0
	v_mov_b32_e32 v105, 0
	v_mov_b32_e32 v106, 0
	v_mov_b32_e32 v107, 0
	v_mov_b32_e32 v108, 0
	v_mov_b32_e32 v109, 0
	v_mov_b32_e32 v110, 0
	v_mov_b32_e32 v111, 0
	v_mov_b32_e32 v112, 0
	v_mov_b32_e32 v113, 0
	v_mov_b32_e32 v114, 0
	v_mov_b32_e32 v115, 0
	v_mov_b32_e32 v116, 0
	v_mov_b32_e32 v117, 0
	v_mov_b32_e32 v118, 0
	v_mov_b32_e32 v119, 0
	v_mov_b32_e32 v120, 0
	v_mov_b32_e32 v121, 0
	v_mov_b32_e32 v122, 0
	v_mov_b32_e32 v123, 0
	v_mov_b32_e32 v124, 0
	v_mov_b32_e32 v125, 0
	v_mov_b32_e32 v126, 0
	v_mov_b32_e32 v127, 0
	v_mov_b32_e32 v128, 0
	v_mov_b32_e32 v129, 0
	s_waitcnt vmcnt(6)
	s_barrier
	s_cmp_ge_u32 s76, 0x1000
	s_cbranch_scc1 .Lbr_streamB
	v_add_u32_e32 v204, 0x0, v200
	v_add_u32_e32 v205, 0x0, v202
	ds_read_b128 v[130:133], v204 offset:0
	ds_read_b128 v[134:137], v204 offset:2048
	ds_read_b128 v[138:141], v204 offset:4096
	ds_read_b128 v[142:145], v204 offset:6144
	ds_read_b128 v[146:149], v205 offset:0
	ds_read_b128 v[150:153], v205 offset:2048
	ds_read_b128 v[154:157], v205 offset:4096
	ds_read_b128 v[158:161], v205 offset:6144
	v_add_u32_e32 v204, 0x0, v201
	v_add_u32_e32 v205, 0x0, v203
	ds_read_b128 v[212:215], v204 offset:0
	ds_read_b128 v[216:219], v204 offset:2048
	ds_read_b128 v[220:223], v204 offset:4096
	ds_read_b128 v[224:227], v204 offset:6144
	ds_read_b128 v[228:231], v205 offset:0
	ds_read_b128 v[232:235], v205 offset:2048
	ds_read_b128 v[236:239], v205 offset:4096
	ds_read_b128 v[240:243], v205 offset:6144
	s_add_u32 m0, s76, 0x18000
	s_nop 0
	global_load_lds_dwordx4 v196, s[68:69]
	s_add_u32 m0, s76, 0x1a000
	s_nop 0
	global_load_lds_dwordx4 v197, s[68:69]
	s_add_u32 m0, s76, 0x1c000
	s_nop 0
	global_load_lds_dwordx4 v198, s[68:69]
	s_add_u32 m0, s76, 0x1e000
	s_nop 0
	global_load_lds_dwordx4 v199, s[68:69]
	s_add_u32 m0, s76, 0x20000
	s_nop 0
	global_load_lds_dwordx4 v196, s[70:71]
	s_add_u32 m0, s76, 0x22000
	s_nop 0
	global_load_lds_dwordx4 v197, s[70:71]
	s_add_u32 s68, s68, 0x80
	s_addc_u32 s69, s69, 0
	s_add_u32 s70, s70, 0x80
	s_addc_u32 s71, s71, 0
	global_load_dwordx2 v[174:175], v206, s[72:73] offset:0
	global_load_dwordx2 v[176:177], v206, s[72:73] offset:32
	global_load_dwordx2 v[178:179], v206, s[72:73] offset:64
	global_load_dwordx2 v[180:181], v206, s[72:73] offset:96
	global_load_dwordx2 v[182:183], v207, s[72:73] offset:0
	global_load_dwordx2 v[184:185], v207, s[72:73] offset:32
	s_waitcnt lgkmcnt(0)
	s_barrier
	s_setprio 1
	v_mfma_f32_16x16x32_bf16 v[2:5], v[146:149], v[130:133], 0
	v_mfma_f32_16x16x32_bf16 v[6:9], v[150:153], v[130:133], 0
	v_mfma_f32_16x16x32_bf16 v[10:13], v[154:157], v[130:133], 0
	v_mfma_f32_16x16x32_bf16 v[14:17], v[158:161], v[130:133], 0
	v_mfma_f32_16x16x32_bf16 v[18:21], v[146:149], v[134:137], 0
	v_mfma_f32_16x16x32_bf16 v[22:25], v[150:153], v[134:137], 0
	v_mfma_f32_16x16x32_bf16 v[26:29], v[154:157], v[134:137], 0
	v_mfma_f32_16x16x32_bf16 v[30:33], v[158:161], v[134:137], 0
	v_mfma_f32_16x16x32_bf16 v[34:37], v[146:149], v[138:141], 0
	v_mfma_f32_16x16x32_bf16 v[38:41], v[150:153], v[138:141], 0
	v_mfma_f32_16x16x32_bf16 v[42:45], v[154:157], v[138:141], 0
	v_mfma_f32_16x16x32_bf16 v[46:49], v[158:161], v[138:141], 0
	v_mfma_f32_16x16x32_bf16 v[50:53], v[146:149], v[142:145], 0
	v_mfma_f32_16x16x32_bf16 v[54:57], v[150:153], v[142:145], 0
	v_mfma_f32_16x16x32_bf16 v[58:61], v[154:157], v[142:145], 0
	v_mfma_f32_16x16x32_bf16 v[62:65], v[158:161], v[142:145], 0
	v_mfma_f32_16x16x32_bf16 v[2:5], v[228:231], v[212:215], v[2:5]
	v_mfma_f32_16x16x32_bf16 v[6:9], v[232:235], v[212:215], v[6:9]
	v_mfma_f32_16x16x32_bf16 v[10:13], v[236:239], v[212:215], v[10:13]
	v_mfma_f32_16x16x32_bf16 v[14:17], v[240:243], v[212:215], v[14:17]
	v_mfma_f32_16x16x32_bf16 v[18:21], v[228:231], v[216:219], v[18:21]
	v_mfma_f32_16x16x32_bf16 v[22:25], v[232:235], v[216:219], v[22:25]
	v_mfma_f32_16x16x32_bf16 v[26:29], v[236:239], v[216:219], v[26:29]
	v_mfma_f32_16x16x32_bf16 v[30:33], v[240:243], v[216:219], v[30:33]
	v_mfma_f32_16x16x32_bf16 v[34:37], v[228:231], v[220:223], v[34:37]
	v_mfma_f32_16x16x32_bf16 v[38:41], v[232:235], v[220:223], v[38:41]
	v_mfma_f32_16x16x32_bf16 v[42:45], v[236:239], v[220:223], v[42:45]
	v_mfma_f32_16x16x32_bf16 v[46:49], v[240:243], v[220:223], v[46:49]
	v_mfma_f32_16x16x32_bf16 v[50:53], v[228:231], v[224:227], v[50:53]
	v_mfma_f32_16x16x32_bf16 v[54:57], v[232:235], v[224:227], v[54:57]
	v_mfma_f32_16x16x32_bf16 v[58:61], v[236:239], v[224:227], v[58:61]
	v_mfma_f32_16x16x32_bf16 v[62:65], v[240:243], v[224:227], v[62:65]
	s_setprio 0
	s_waitcnt vmcnt(12)
	s_barrier
	v_add_u32_e32 v204, 0xc000, v200
	v_add_u32_e32 v205, 0xc000, v202
	ds_read_b128 v[130:133], v204 offset:0
	ds_read_b128 v[134:137], v204 offset:2048
	ds_read_b128 v[138:141], v204 offset:4096
	ds_read_b128 v[142:145], v204 offset:6144
	ds_read_b128 v[146:149], v205 offset:0
	ds_read_b128 v[150:153], v205 offset:2048
	ds_read_b128 v[154:157], v205 offset:4096
	ds_read_b128 v[158:161], v205 offset:6144
	v_add_u32_e32 v204, 0xc000, v201
	v_add_u32_e32 v205, 0xc000, v203
	ds_read_b128 v[212:215], v204 offset:0
	ds_read_b128 v[216:219], v204 offset:2048
	ds_read_b128 v[220:223], v204 offset:4096
	ds_read_b128 v[224:227], v204 offset:6144
	ds_read_b128 v[228:231], v205 offset:0
	ds_read_b128 v[232:235], v205 offset:2048
	ds_read_b128 v[236:239], v205 offset:4096
	ds_read_b128 v[240:243], v205 offset:6144
	s_add_u32 m0, s76, 0x0
	s_nop 0
	global_load_lds_dwordx4 v196, s[68:69]
	s_add_u32 m0, s76, 0x2000
	s_nop 0
	global_load_lds_dwordx4 v197, s[68:69]
	s_add_u32 m0, s76, 0x4000
	s_nop 0
	global_load_lds_dwordx4 v198, s[68:69]
	s_add_u32 m0, s76, 0x6000
	s_nop 0
	global_load_lds_dwordx4 v199, s[68:69]
	s_add_u32 m0, s76, 0x8000
	s_nop 0
	global_load_lds_dwordx4 v196, s[70:71]
	s_add_u32 m0, s76, 0xa000
	s_nop 0
	global_load_lds_dwordx4 v197, s[70:71]
	s_add_u32 s68, s68, 0x80
	s_addc_u32 s69, s69, 0
	s_add_u32 s70, s70, 0x80
	s_addc_u32 s71, s71, 0
	global_load_dwordx2 v[186:187], v207, s[72:73] offset:64
	global_load_dwordx2 v[188:189], v207, s[72:73] offset:96
	global_load_dwordx2 v[190:191], v208, s[72:73] offset:0
	global_load_dwordx2 v[192:193], v208, s[72:73] offset:32
	global_load_dwordx2 v[244:245], v208, s[72:73] offset:64
	global_load_dwordx2 v[246:247], v208, s[72:73] offset:96
	s_waitcnt lgkmcnt(0)
	s_barrier
	s_setprio 1
	v_mfma_f32_16x16x32_bf16 v[2:5], v[146:149], v[130:133], v[2:5]
	v_mfma_f32_16x16x32_bf16 v[6:9], v[150:153], v[130:133], v[6:9]
	v_mfma_f32_16x16x32_bf16 v[10:13], v[154:157], v[130:133], v[10:13]
	v_mfma_f32_16x16x32_bf16 v[14:17], v[158:161], v[130:133], v[14:17]
	v_mfma_f32_16x16x32_bf16 v[18:21], v[146:149], v[134:137], v[18:21]
	v_mfma_f32_16x16x32_bf16 v[22:25], v[150:153], v[134:137], v[22:25]
	v_mfma_f32_16x16x32_bf16 v[26:29], v[154:157], v[134:137], v[26:29]
	v_mfma_f32_16x16x32_bf16 v[30:33], v[158:161], v[134:137], v[30:33]
	v_mfma_f32_16x16x32_bf16 v[34:37], v[146:149], v[138:141], v[34:37]
	v_mfma_f32_16x16x32_bf16 v[38:41], v[150:153], v[138:141], v[38:41]
	v_mfma_f32_16x16x32_bf16 v[42:45], v[154:157], v[138:141], v[42:45]
	v_mfma_f32_16x16x32_bf16 v[46:49], v[158:161], v[138:141], v[46:49]
	v_mfma_f32_16x16x32_bf16 v[50:53], v[146:149], v[142:145], v[50:53]
	v_mfma_f32_16x16x32_bf16 v[54:57], v[150:153], v[142:145], v[54:57]
	v_mfma_f32_16x16x32_bf16 v[58:61], v[154:157], v[142:145], v[58:61]
	v_mfma_f32_16x16x32_bf16 v[62:65], v[158:161], v[142:145], v[62:65]
	v_mfma_f32_16x16x32_bf16 v[2:5], v[228:231], v[212:215], v[2:5]
	v_mfma_f32_16x16x32_bf16 v[6:9], v[232:235], v[212:215], v[6:9]
	v_mfma_f32_16x16x32_bf16 v[10:13], v[236:239], v[212:215], v[10:13]
	v_mfma_f32_16x16x32_bf16 v[14:17], v[240:243], v[212:215], v[14:17]
	v_mfma_f32_16x16x32_bf16 v[18:21], v[228:231], v[216:219], v[18:21]
	v_mfma_f32_16x16x32_bf16 v[22:25], v[232:235], v[216:219], v[22:25]
	v_mfma_f32_16x16x32_bf16 v[26:29], v[236:239], v[216:219], v[26:29]
	v_mfma_f32_16x16x32_bf16 v[30:33], v[240:243], v[216:219], v[30:33]
	v_mfma_f32_16x16x32_bf16 v[34:37], v[228:231], v[220:223], v[34:37]
	v_mfma_f32_16x16x32_bf16 v[38:41], v[232:235], v[220:223], v[38:41]
	v_mfma_f32_16x16x32_bf16 v[42:45], v[236:239], v[220:223], v[42:45]
	v_mfma_f32_16x16x32_bf16 v[46:49], v[240:243], v[220:223], v[46:49]
	v_mfma_f32_16x16x32_bf16 v[50:53], v[228:231], v[224:227], v[50:53]
	v_mfma_f32_16x16x32_bf16 v[54:57], v[232:235], v[224:227], v[54:57]
	v_mfma_f32_16x16x32_bf16 v[58:61], v[236:239], v[224:227], v[58:61]
	v_mfma_f32_16x16x32_bf16 v[62:65], v[240:243], v[224:227], v[62:65]
	s_setprio 0
	s_waitcnt vmcnt(18)
	s_barrier
	v_add_u32_e32 v204, 0x18000, v200
	v_add_u32_e32 v205, 0x18000, v202
	ds_read_b128 v[130:133], v204 offset:0
	ds_read_b128 v[134:137], v204 offset:2048
	ds_read_b128 v[138:141], v204 offset:4096
	ds_read_b128 v[142:145], v204 offset:6144
	ds_read_b128 v[146:149], v205 offset:0
	ds_read_b128 v[150:153], v205 offset:2048
	ds_read_b128 v[154:157], v205 offset:4096
	ds_read_b128 v[158:161], v205 offset:6144
	v_add_u32_e32 v204, 0x18000, v201
	v_add_u32_e32 v205, 0x18000, v203
	ds_read_b128 v[212:215], v204 offset:0
	ds_read_b128 v[216:219], v204 offset:2048
	ds_read_b128 v[220:223], v204 offset:4096
	ds_read_b128 v[224:227], v204 offset:6144
	ds_read_b128 v[228:231], v205 offset:0
	ds_read_b128 v[232:235], v205 offset:2048
	ds_read_b128 v[236:239], v205 offset:4096
	ds_read_b128 v[240:243], v205 offset:6144
	s_add_u32 m0, s76, 0xc000
	s_nop 0
	global_load_lds_dwordx4 v196, s[68:69]
	s_add_u32 m0, s76, 0xe000
	s_nop 0
	global_load_lds_dwordx4 v197, s[68:69]
	s_add_u32 m0, s76, 0x10000
	s_nop 0
	global_load_lds_dwordx4 v198, s[68:69]
	s_add_u32 m0, s76, 0x12000
	s_nop 0
	global_load_lds_dwordx4 v199, s[68:69]
	s_add_u32 m0, s76, 0x14000
	s_nop 0
	global_load_lds_dwordx4 v196, s[70:71]
	s_add_u32 m0, s76, 0x16000
	s_nop 0
	global_load_lds_dwordx4 v197, s[70:71]
	s_add_u32 s68, s68, 0x80
	s_addc_u32 s69, s69, 0
	s_add_u32 s70, s70, 0x80
	s_addc_u32 s71, s71, 0
	global_load_dwordx2 v[248:249], v209, s[72:73] offset:0
	global_load_dwordx2 v[250:251], v209, s[72:73] offset:32
	global_load_dwordx2 v[166:167], v209, s[72:73] offset:64
	global_load_dwordx2 v[194:195], v209, s[72:73] offset:96
	s_add_u32 s72, s72, 0x800
	s_addc_u32 s73, s73, 0
	s_waitcnt lgkmcnt(0)
	s_barrier
	s_setprio 1
	v_mfma_f32_16x16x32_bf16 v[2:5], v[146:149], v[130:133], v[2:5]
	v_mfma_f32_16x16x32_bf16 v[6:9], v[150:153], v[130:133], v[6:9]
	v_mfma_f32_16x16x32_bf16 v[10:13], v[154:157], v[130:133], v[10:13]
	v_mfma_f32_16x16x32_bf16 v[14:17], v[158:161], v[130:133], v[14:17]
	v_mfma_f32_16x16x32_bf16 v[18:21], v[146:149], v[134:137], v[18:21]
	v_mfma_f32_16x16x32_bf16 v[22:25], v[150:153], v[134:137], v[22:25]
	v_mfma_f32_16x16x32_bf16 v[26:29], v[154:157], v[134:137], v[26:29]
	v_mfma_f32_16x16x32_bf16 v[30:33], v[158:161], v[134:137], v[30:33]
	v_mfma_f32_16x16x32_bf16 v[34:37], v[146:149], v[138:141], v[34:37]
	v_mfma_f32_16x16x32_bf16 v[38:41], v[150:153], v[138:141], v[38:41]
	v_mfma_f32_16x16x32_bf16 v[42:45], v[154:157], v[138:141], v[42:45]
	v_mfma_f32_16x16x32_bf16 v[46:49], v[158:161], v[138:141], v[46:49]
	v_mfma_f32_16x16x32_bf16 v[50:53], v[146:149], v[142:145], v[50:53]
	v_mfma_f32_16x16x32_bf16 v[54:57], v[150:153], v[142:145], v[54:57]
	v_mfma_f32_16x16x32_bf16 v[58:61], v[154:157], v[142:145], v[58:61]
	v_mfma_f32_16x16x32_bf16 v[62:65], v[158:161], v[142:145], v[62:65]
	v_mfma_f32_16x16x32_bf16 v[2:5], v[228:231], v[212:215], v[2:5]
	v_mfma_f32_16x16x32_bf16 v[6:9], v[232:235], v[212:215], v[6:9]
	v_mfma_f32_16x16x32_bf16 v[10:13], v[236:239], v[212:215], v[10:13]
	v_mfma_f32_16x16x32_bf16 v[14:17], v[240:243], v[212:215], v[14:17]
	v_mfma_f32_16x16x32_bf16 v[18:21], v[228:231], v[216:219], v[18:21]
	v_mfma_f32_16x16x32_bf16 v[22:25], v[232:235], v[216:219], v[22:25]
	v_mfma_f32_16x16x32_bf16 v[26:29], v[236:239], v[216:219], v[26:29]
	v_mfma_f32_16x16x32_bf16 v[30:33], v[240:243], v[216:219], v[30:33]
	v_mfma_f32_16x16x32_bf16 v[34:37], v[228:231], v[220:223], v[34:37]
	v_mfma_f32_16x16x32_bf16 v[38:41], v[232:235], v[220:223], v[38:41]
	v_mfma_f32_16x16x32_bf16 v[42:45], v[236:239], v[220:223], v[42:45]
	v_mfma_f32_16x16x32_bf16 v[46:49], v[240:243], v[220:223], v[46:49]
	v_mfma_f32_16x16x32_bf16 v[50:53], v[228:231], v[224:227], v[50:53]
	v_mfma_f32_16x16x32_bf16 v[54:57], v[232:235], v[224:227], v[54:57]
	v_mfma_f32_16x16x32_bf16 v[58:61], v[236:239], v[224:227], v[58:61]
	v_mfma_f32_16x16x32_bf16 v[62:65], v[240:243], v[224:227], v[62:65]
	s_setprio 0
	s_waitcnt vmcnt(16)
	s_barrier
	v_add_u32_e32 v204, 0x0, v200
	v_add_u32_e32 v205, 0x0, v202
	ds_read_b128 v[130:133], v204 offset:0
	ds_read_b128 v[134:137], v204 offset:2048
	ds_read_b128 v[138:141], v204 offset:4096
	ds_read_b128 v[142:145], v204 offset:6144
	ds_read_b128 v[146:149], v205 offset:0
	ds_read_b128 v[150:153], v205 offset:2048
	ds_read_b128 v[154:157], v205 offset:4096
	ds_read_b128 v[158:161], v205 offset:6144
	v_add_u32_e32 v204, 0x0, v201
	v_add_u32_e32 v205, 0x0, v203
	ds_read_b128 v[212:215], v204 offset:0
	ds_read_b128 v[216:219], v204 offset:2048
	ds_read_b128 v[220:223], v204 offset:4096
	ds_read_b128 v[224:227], v204 offset:6144
	ds_read_b128 v[228:231], v205 offset:0
	ds_read_b128 v[232:235], v205 offset:2048
	ds_read_b128 v[236:239], v205 offset:4096
	ds_read_b128 v[240:243], v205 offset:6144
	s_add_u32 m0, s76, 0x18000
	s_nop 0
	global_load_lds_dwordx4 v196, s[68:69]
	s_add_u32 m0, s76, 0x1a000
	s_nop 0
	global_load_lds_dwordx4 v197, s[68:69]
	s_add_u32 m0, s76, 0x1c000
	s_nop 0
	global_load_lds_dwordx4 v198, s[68:69]
	s_add_u32 m0, s76, 0x1e000
	s_nop 0
	global_load_lds_dwordx4 v199, s[68:69]
	s_add_u32 m0, s76, 0x20000
	s_nop 0
	global_load_lds_dwordx4 v196, s[70:71]
	s_add_u32 m0, s76, 0x22000
	s_nop 0
	global_load_lds_dwordx4 v197, s[70:71]
	s_add_u32 s68, s68, 0x80
	s_addc_u32 s69, s69, 0
	s_add_u32 s70, s70, 0x80
	s_addc_u32 s71, s71, 0
	s_waitcnt lgkmcnt(0)
	s_barrier
	s_setprio 1
	v_mfma_f32_16x16x32_bf16 v[2:5], v[146:149], v[130:133], v[2:5]
	v_mfma_f32_16x16x32_bf16 v[6:9], v[150:153], v[130:133], v[6:9]
	v_mfma_f32_16x16x32_bf16 v[10:13], v[154:157], v[130:133], v[10:13]
	v_mfma_f32_16x16x32_bf16 v[14:17], v[158:161], v[130:133], v[14:17]
	v_mfma_f32_16x16x32_bf16 v[18:21], v[146:149], v[134:137], v[18:21]
	v_mfma_f32_16x16x32_bf16 v[22:25], v[150:153], v[134:137], v[22:25]
	v_mfma_f32_16x16x32_bf16 v[26:29], v[154:157], v[134:137], v[26:29]
	v_mfma_f32_16x16x32_bf16 v[30:33], v[158:161], v[134:137], v[30:33]
	v_mfma_f32_16x16x32_bf16 v[34:37], v[146:149], v[138:141], v[34:37]
	v_mfma_f32_16x16x32_bf16 v[38:41], v[150:153], v[138:141], v[38:41]
	v_mfma_f32_16x16x32_bf16 v[42:45], v[154:157], v[138:141], v[42:45]
	v_mfma_f32_16x16x32_bf16 v[46:49], v[158:161], v[138:141], v[46:49]
	v_mfma_f32_16x16x32_bf16 v[50:53], v[146:149], v[142:145], v[50:53]
	v_mfma_f32_16x16x32_bf16 v[54:57], v[150:153], v[142:145], v[54:57]
	v_mfma_f32_16x16x32_bf16 v[58:61], v[154:157], v[142:145], v[58:61]
	v_mfma_f32_16x16x32_bf16 v[62:65], v[158:161], v[142:145], v[62:65]
	v_mfma_f32_16x16x32_bf16 v[2:5], v[228:231], v[212:215], v[2:5]
	v_mfma_f32_16x16x32_bf16 v[6:9], v[232:235], v[212:215], v[6:9]
	v_mfma_f32_16x16x32_bf16 v[10:13], v[236:239], v[212:215], v[10:13]
	v_mfma_f32_16x16x32_bf16 v[14:17], v[240:243], v[212:215], v[14:17]
	v_mfma_f32_16x16x32_bf16 v[18:21], v[228:231], v[216:219], v[18:21]
	v_mfma_f32_16x16x32_bf16 v[22:25], v[232:235], v[216:219], v[22:25]
	v_mfma_f32_16x16x32_bf16 v[26:29], v[236:239], v[216:219], v[26:29]
	v_mfma_f32_16x16x32_bf16 v[30:33], v[240:243], v[216:219], v[30:33]
	v_mfma_f32_16x16x32_bf16 v[34:37], v[228:231], v[220:223], v[34:37]
	v_mfma_f32_16x16x32_bf16 v[38:41], v[232:235], v[220:223], v[38:41]
	v_mfma_f32_16x16x32_bf16 v[42:45], v[236:239], v[220:223], v[42:45]
	v_mfma_f32_16x16x32_bf16 v[46:49], v[240:243], v[220:223], v[46:49]
	v_mfma_f32_16x16x32_bf16 v[50:53], v[228:231], v[224:227], v[50:53]
	v_mfma_f32_16x16x32_bf16 v[54:57], v[232:235], v[224:227], v[54:57]
	v_mfma_f32_16x16x32_bf16 v[58:61], v[236:239], v[224:227], v[58:61]
	v_mfma_f32_16x16x32_bf16 v[62:65], v[240:243], v[224:227], v[62:65]
	s_setprio 0
	s_waitcnt vmcnt(10)
	s_barrier
	v_add_u32_e32 v204, 0xc000, v200
	v_add_u32_e32 v205, 0xc000, v202
	ds_read_b128 v[130:133], v204 offset:0
	ds_read_b128 v[134:137], v204 offset:2048
	ds_read_b128 v[138:141], v204 offset:4096
	ds_read_b128 v[142:145], v204 offset:6144
	ds_read_b128 v[146:149], v205 offset:0
	ds_read_b128 v[150:153], v205 offset:2048
	ds_read_b128 v[154:157], v205 offset:4096
	ds_read_b128 v[158:161], v205 offset:6144
	v_add_u32_e32 v204, 0xc000, v201
	v_add_u32_e32 v205, 0xc000, v203
	ds_read_b128 v[212:215], v204 offset:0
	ds_read_b128 v[216:219], v204 offset:2048
	ds_read_b128 v[220:223], v204 offset:4096
	ds_read_b128 v[224:227], v204 offset:6144
	ds_read_b128 v[228:231], v205 offset:0
	ds_read_b128 v[232:235], v205 offset:2048
	ds_read_b128 v[236:239], v205 offset:4096
	ds_read_b128 v[240:243], v205 offset:6144
	s_add_u32 m0, s76, 0x0
	s_nop 0
	global_load_lds_dwordx4 v196, s[68:69]
	s_add_u32 m0, s76, 0x2000
	s_nop 0
	global_load_lds_dwordx4 v197, s[68:69]
	s_add_u32 m0, s76, 0x4000
	s_nop 0
	global_load_lds_dwordx4 v198, s[68:69]
	s_add_u32 m0, s76, 0x6000
	s_nop 0
	global_load_lds_dwordx4 v199, s[68:69]
	s_add_u32 m0, s76, 0x8000
	s_nop 0
	global_load_lds_dwordx4 v196, s[70:71]
	s_add_u32 m0, s76, 0xa000
	s_nop 0
	global_load_lds_dwordx4 v197, s[70:71]
	s_add_u32 s68, s68, 0x80
	s_addc_u32 s69, s69, 0
	s_add_u32 s70, s70, 0x80
	s_addc_u32 s71, s71, 0
	s_waitcnt lgkmcnt(0)
	s_barrier
	s_setprio 1
	v_mfma_f32_16x16x32_bf16 v[2:5], v[146:149], v[130:133], v[2:5]
	v_mfma_f32_16x16x32_bf16 v[6:9], v[150:153], v[130:133], v[6:9]
	v_mfma_f32_16x16x32_bf16 v[10:13], v[154:157], v[130:133], v[10:13]
	v_mfma_f32_16x16x32_bf16 v[14:17], v[158:161], v[130:133], v[14:17]
	v_mfma_f32_16x16x32_bf16 v[18:21], v[146:149], v[134:137], v[18:21]
	v_mfma_f32_16x16x32_bf16 v[22:25], v[150:153], v[134:137], v[22:25]
	v_mfma_f32_16x16x32_bf16 v[26:29], v[154:157], v[134:137], v[26:29]
	v_mfma_f32_16x16x32_bf16 v[30:33], v[158:161], v[134:137], v[30:33]
	v_mfma_f32_16x16x32_bf16 v[34:37], v[146:149], v[138:141], v[34:37]
	v_mfma_f32_16x16x32_bf16 v[38:41], v[150:153], v[138:141], v[38:41]
	v_mfma_f32_16x16x32_bf16 v[42:45], v[154:157], v[138:141], v[42:45]
	v_mfma_f32_16x16x32_bf16 v[46:49], v[158:161], v[138:141], v[46:49]
	v_mfma_f32_16x16x32_bf16 v[50:53], v[146:149], v[142:145], v[50:53]
	v_mfma_f32_16x16x32_bf16 v[54:57], v[150:153], v[142:145], v[54:57]
	v_mfma_f32_16x16x32_bf16 v[58:61], v[154:157], v[142:145], v[58:61]
	v_mfma_f32_16x16x32_bf16 v[62:65], v[158:161], v[142:145], v[62:65]
	v_mfma_f32_16x16x32_bf16 v[2:5], v[228:231], v[212:215], v[2:5]
	v_mfma_f32_16x16x32_bf16 v[6:9], v[232:235], v[212:215], v[6:9]
	v_mfma_f32_16x16x32_bf16 v[10:13], v[236:239], v[212:215], v[10:13]
	v_mfma_f32_16x16x32_bf16 v[14:17], v[240:243], v[212:215], v[14:17]
	v_mfma_f32_16x16x32_bf16 v[18:21], v[228:231], v[216:219], v[18:21]
	v_mfma_f32_16x16x32_bf16 v[22:25], v[232:235], v[216:219], v[22:25]
	v_mfma_f32_16x16x32_bf16 v[26:29], v[236:239], v[216:219], v[26:29]
	v_mfma_f32_16x16x32_bf16 v[30:33], v[240:243], v[216:219], v[30:33]
	v_mfma_f32_16x16x32_bf16 v[34:37], v[228:231], v[220:223], v[34:37]
	v_mfma_f32_16x16x32_bf16 v[38:41], v[232:235], v[220:223], v[38:41]
	v_mfma_f32_16x16x32_bf16 v[42:45], v[236:239], v[220:223], v[42:45]
	v_mfma_f32_16x16x32_bf16 v[46:49], v[240:243], v[220:223], v[46:49]
	v_mfma_f32_16x16x32_bf16 v[50:53], v[228:231], v[224:227], v[50:53]
	v_mfma_f32_16x16x32_bf16 v[54:57], v[232:235], v[224:227], v[54:57]
	v_mfma_f32_16x16x32_bf16 v[58:61], v[236:239], v[224:227], v[58:61]
	v_mfma_f32_16x16x32_bf16 v[62:65], v[240:243], v[224:227], v[62:65]
	s_setprio 0
	s_waitcnt vmcnt(6)
	s_barrier
	v_add_u32_e32 v204, 0x18000, v200
	v_add_u32_e32 v205, 0x18000, v202
	ds_read_b128 v[130:133], v204 offset:0
	ds_read_b128 v[134:137], v204 offset:2048
	ds_read_b128 v[138:141], v204 offset:4096
	ds_read_b128 v[142:145], v204 offset:6144
	ds_read_b128 v[146:149], v205 offset:0
	ds_read_b128 v[150:153], v205 offset:2048
	ds_read_b128 v[154:157], v205 offset:4096
	ds_read_b128 v[158:161], v205 offset:6144
	v_add_u32_e32 v204, 0x18000, v201
	v_add_u32_e32 v205, 0x18000, v203
	ds_read_b128 v[212:215], v204 offset:0
	ds_read_b128 v[216:219], v204 offset:2048
	ds_read_b128 v[220:223], v204 offset:4096
	ds_read_b128 v[224:227], v204 offset:6144
	ds_read_b128 v[228:231], v205 offset:0
	ds_read_b128 v[232:235], v205 offset:2048
	ds_read_b128 v[236:239], v205 offset:4096
	ds_read_b128 v[240:243], v205 offset:6144
	s_add_u32 m0, s76, 0xc000
	s_nop 0
	global_load_lds_dwordx4 v196, s[68:69]
	s_add_u32 m0, s76, 0xe000
	s_nop 0
	global_load_lds_dwordx4 v197, s[68:69]
	s_add_u32 m0, s76, 0x10000
	s_nop 0
	global_load_lds_dwordx4 v198, s[68:69]
	s_add_u32 m0, s76, 0x12000
	s_nop 0
	global_load_lds_dwordx4 v199, s[68:69]
	s_add_u32 m0, s76, 0x14000
	s_nop 0
	global_load_lds_dwordx4 v196, s[70:71]
	s_add_u32 m0, s76, 0x16000
	s_nop 0
	global_load_lds_dwordx4 v197, s[70:71]
	s_add_u32 s68, s68, 0x80
	s_addc_u32 s69, s69, 0
	s_add_u32 s70, s70, 0x80
	s_addc_u32 s71, s71, 0
	s_waitcnt lgkmcnt(0)
	s_barrier
	s_setprio 1
	v_mfma_f32_16x16x32_bf16 v[2:5], v[146:149], v[130:133], v[2:5]
	v_mfma_f32_16x16x32_bf16 v[6:9], v[150:153], v[130:133], v[6:9]
	v_mfma_f32_16x16x32_bf16 v[10:13], v[154:157], v[130:133], v[10:13]
	v_mfma_f32_16x16x32_bf16 v[14:17], v[158:161], v[130:133], v[14:17]
	v_mfma_f32_16x16x32_bf16 v[18:21], v[146:149], v[134:137], v[18:21]
	v_mfma_f32_16x16x32_bf16 v[22:25], v[150:153], v[134:137], v[22:25]
	v_mfma_f32_16x16x32_bf16 v[26:29], v[154:157], v[134:137], v[26:29]
	v_mfma_f32_16x16x32_bf16 v[30:33], v[158:161], v[134:137], v[30:33]
	v_mfma_f32_16x16x32_bf16 v[34:37], v[146:149], v[138:141], v[34:37]
	v_mfma_f32_16x16x32_bf16 v[38:41], v[150:153], v[138:141], v[38:41]
	v_mfma_f32_16x16x32_bf16 v[42:45], v[154:157], v[138:141], v[42:45]
	v_mfma_f32_16x16x32_bf16 v[46:49], v[158:161], v[138:141], v[46:49]
	v_mfma_f32_16x16x32_bf16 v[50:53], v[146:149], v[142:145], v[50:53]
	v_mfma_f32_16x16x32_bf16 v[54:57], v[150:153], v[142:145], v[54:57]
	v_mfma_f32_16x16x32_bf16 v[58:61], v[154:157], v[142:145], v[58:61]
	v_mfma_f32_16x16x32_bf16 v[62:65], v[158:161], v[142:145], v[62:65]
	v_mfma_f32_16x16x32_bf16 v[2:5], v[228:231], v[212:215], v[2:5]
	v_mfma_f32_16x16x32_bf16 v[6:9], v[232:235], v[212:215], v[6:9]
	v_mfma_f32_16x16x32_bf16 v[10:13], v[236:239], v[212:215], v[10:13]
	v_mfma_f32_16x16x32_bf16 v[14:17], v[240:243], v[212:215], v[14:17]
	v_mfma_f32_16x16x32_bf16 v[18:21], v[228:231], v[216:219], v[18:21]
	v_mfma_f32_16x16x32_bf16 v[22:25], v[232:235], v[216:219], v[22:25]
	v_mfma_f32_16x16x32_bf16 v[26:29], v[236:239], v[216:219], v[26:29]
	v_mfma_f32_16x16x32_bf16 v[30:33], v[240:243], v[216:219], v[30:33]
	v_mfma_f32_16x16x32_bf16 v[34:37], v[228:231], v[220:223], v[34:37]
	v_mfma_f32_16x16x32_bf16 v[38:41], v[232:235], v[220:223], v[38:41]
	v_mfma_f32_16x16x32_bf16 v[42:45], v[236:239], v[220:223], v[42:45]
	v_mfma_f32_16x16x32_bf16 v[46:49], v[240:243], v[220:223], v[46:49]
	v_mfma_f32_16x16x32_bf16 v[50:53], v[228:231], v[224:227], v[50:53]
	v_mfma_f32_16x16x32_bf16 v[54:57], v[232:235], v[224:227], v[54:57]
	v_mfma_f32_16x16x32_bf16 v[58:61], v[236:239], v[224:227], v[58:61]
	v_mfma_f32_16x16x32_bf16 v[62:65], v[240:243], v[224:227], v[62:65]
	s_setprio 0
	s_waitcnt vmcnt(6)
	s_barrier
	v_add_u32_e32 v204, 0x0, v200
	v_add_u32_e32 v205, 0x0, v202
	ds_read_b128 v[130:133], v204 offset:0
	ds_read_b128 v[134:137], v204 offset:2048
	ds_read_b128 v[138:141], v204 offset:4096
	ds_read_b128 v[142:145], v204 offset:6144
	ds_read_b128 v[146:149], v205 offset:0
	ds_read_b128 v[150:153], v205 offset:2048
	ds_read_b128 v[154:157], v205 offset:4096
	ds_read_b128 v[158:161], v205 offset:6144
	v_add_u32_e32 v204, 0x0, v201
	v_add_u32_e32 v205, 0x0, v203
	ds_read_b128 v[212:215], v204 offset:0
	ds_read_b128 v[216:219], v204 offset:2048
	ds_read_b128 v[220:223], v204 offset:4096
	ds_read_b128 v[224:227], v204 offset:6144
	ds_read_b128 v[228:231], v205 offset:0
	ds_read_b128 v[232:235], v205 offset:2048
	ds_read_b128 v[236:239], v205 offset:4096
	ds_read_b128 v[240:243], v205 offset:6144
	s_add_u32 m0, s76, 0x18000
	s_nop 0
	global_load_lds_dwordx4 v196, s[68:69]
	s_add_u32 m0, s76, 0x1a000
	s_nop 0
	global_load_lds_dwordx4 v197, s[68:69]
	s_add_u32 m0, s76, 0x1c000
	s_nop 0
	global_load_lds_dwordx4 v198, s[68:69]
	s_add_u32 m0, s76, 0x1e000
	s_nop 0
	global_load_lds_dwordx4 v199, s[68:69]
	s_add_u32 m0, s76, 0x20000
	s_nop 0
	global_load_lds_dwordx4 v196, s[70:71]
	s_add_u32 m0, s76, 0x22000
	s_nop 0
	global_load_lds_dwordx4 v197, s[70:71]
	s_add_u32 s68, s68, 0x80
	s_addc_u32 s69, s69, 0
	s_add_u32 s70, s70, 0x80
	s_addc_u32 s71, s71, 0
	s_waitcnt lgkmcnt(0)
	s_barrier
	s_setprio 1
	v_mfma_f32_16x16x32_bf16 v[2:5], v[146:149], v[130:133], v[2:5]
	v_mfma_f32_16x16x32_bf16 v[6:9], v[150:153], v[130:133], v[6:9]
	v_mfma_f32_16x16x32_bf16 v[10:13], v[154:157], v[130:133], v[10:13]
	v_mfma_f32_16x16x32_bf16 v[14:17], v[158:161], v[130:133], v[14:17]
	v_mfma_f32_16x16x32_bf16 v[18:21], v[146:149], v[134:137], v[18:21]
	v_mfma_f32_16x16x32_bf16 v[22:25], v[150:153], v[134:137], v[22:25]
	v_mfma_f32_16x16x32_bf16 v[26:29], v[154:157], v[134:137], v[26:29]
	v_mfma_f32_16x16x32_bf16 v[30:33], v[158:161], v[134:137], v[30:33]
	v_mfma_f32_16x16x32_bf16 v[34:37], v[146:149], v[138:141], v[34:37]
	v_mfma_f32_16x16x32_bf16 v[38:41], v[150:153], v[138:141], v[38:41]
	v_mfma_f32_16x16x32_bf16 v[42:45], v[154:157], v[138:141], v[42:45]
	v_mfma_f32_16x16x32_bf16 v[46:49], v[158:161], v[138:141], v[46:49]
	v_mfma_f32_16x16x32_bf16 v[50:53], v[146:149], v[142:145], v[50:53]
	v_mfma_f32_16x16x32_bf16 v[54:57], v[150:153], v[142:145], v[54:57]
	v_mfma_f32_16x16x32_bf16 v[58:61], v[154:157], v[142:145], v[58:61]
	v_mfma_f32_16x16x32_bf16 v[62:65], v[158:161], v[142:145], v[62:65]
	v_mfma_f32_16x16x32_bf16 v[2:5], v[228:231], v[212:215], v[2:5]
	v_mfma_f32_16x16x32_bf16 v[6:9], v[232:235], v[212:215], v[6:9]
	v_mfma_f32_16x16x32_bf16 v[10:13], v[236:239], v[212:215], v[10:13]
	v_mfma_f32_16x16x32_bf16 v[14:17], v[240:243], v[212:215], v[14:17]
	v_mfma_f32_16x16x32_bf16 v[18:21], v[228:231], v[216:219], v[18:21]
	v_mfma_f32_16x16x32_bf16 v[22:25], v[232:235], v[216:219], v[22:25]
	v_mfma_f32_16x16x32_bf16 v[26:29], v[236:239], v[216:219], v[26:29]
	v_mfma_f32_16x16x32_bf16 v[30:33], v[240:243], v[216:219], v[30:33]
	v_mfma_f32_16x16x32_bf16 v[34:37], v[228:231], v[220:223], v[34:37]
	v_mfma_f32_16x16x32_bf16 v[38:41], v[232:235], v[220:223], v[38:41]
	v_mfma_f32_16x16x32_bf16 v[42:45], v[236:239], v[220:223], v[42:45]
	v_mfma_f32_16x16x32_bf16 v[46:49], v[240:243], v[220:223], v[46:49]
	v_mfma_f32_16x16x32_bf16 v[50:53], v[228:231], v[224:227], v[50:53]
	v_mfma_f32_16x16x32_bf16 v[54:57], v[232:235], v[224:227], v[54:57]
	v_mfma_f32_16x16x32_bf16 v[58:61], v[236:239], v[224:227], v[58:61]
	v_mfma_f32_16x16x32_bf16 v[62:65], v[240:243], v[224:227], v[62:65]
	s_setprio 0
	s_waitcnt vmcnt(6)
	s_barrier
	v_add_u32_e32 v204, 0xc000, v200
	v_add_u32_e32 v205, 0xc000, v202
	ds_read_b128 v[130:133], v204 offset:0
	ds_read_b128 v[134:137], v204 offset:2048
	ds_read_b128 v[138:141], v204 offset:4096
	ds_read_b128 v[142:145], v204 offset:6144
	ds_read_b128 v[146:149], v205 offset:0
	ds_read_b128 v[150:153], v205 offset:2048
	ds_read_b128 v[154:157], v205 offset:4096
	ds_read_b128 v[158:161], v205 offset:6144
	v_add_u32_e32 v204, 0xc000, v201
	v_add_u32_e32 v205, 0xc000, v203
	ds_read_b128 v[212:215], v204 offset:0
	ds_read_b128 v[216:219], v204 offset:2048
	ds_read_b128 v[220:223], v204 offset:4096
	ds_read_b128 v[224:227], v204 offset:6144
	ds_read_b128 v[228:231], v205 offset:0
	ds_read_b128 v[232:235], v205 offset:2048
	ds_read_b128 v[236:239], v205 offset:4096
	ds_read_b128 v[240:243], v205 offset:6144
	s_add_u32 m0, s76, 0x0
	s_nop 0
	global_load_lds_dwordx4 v196, s[68:69]
	s_add_u32 m0, s76, 0x2000
	s_nop 0
	global_load_lds_dwordx4 v197, s[68:69]
	s_add_u32 m0, s76, 0x4000
	s_nop 0
	global_load_lds_dwordx4 v198, s[68:69]
	s_add_u32 m0, s76, 0x6000
	s_nop 0
	global_load_lds_dwordx4 v199, s[68:69]
	s_add_u32 m0, s76, 0x8000
	s_nop 0
	global_load_lds_dwordx4 v196, s[70:71]
	s_add_u32 m0, s76, 0xa000
	s_nop 0
	global_load_lds_dwordx4 v197, s[70:71]
	s_add_u32 s68, s68, 0x80
	s_addc_u32 s69, s69, 0
	s_add_u32 s70, s70, 0x80
	s_addc_u32 s71, s71, 0
	s_waitcnt lgkmcnt(0)
	s_barrier
	s_setprio 1
	v_mfma_f32_16x16x32_bf16 v[2:5], v[146:149], v[130:133], v[2:5]
	v_mfma_f32_16x16x32_bf16 v[6:9], v[150:153], v[130:133], v[6:9]
	v_mfma_f32_16x16x32_bf16 v[10:13], v[154:157], v[130:133], v[10:13]
	v_mfma_f32_16x16x32_bf16 v[14:17], v[158:161], v[130:133], v[14:17]
	v_mfma_f32_16x16x32_bf16 v[18:21], v[146:149], v[134:137], v[18:21]
	v_mfma_f32_16x16x32_bf16 v[22:25], v[150:153], v[134:137], v[22:25]
	v_mfma_f32_16x16x32_bf16 v[26:29], v[154:157], v[134:137], v[26:29]
	v_mfma_f32_16x16x32_bf16 v[30:33], v[158:161], v[134:137], v[30:33]
	v_mfma_f32_16x16x32_bf16 v[34:37], v[146:149], v[138:141], v[34:37]
	v_mfma_f32_16x16x32_bf16 v[38:41], v[150:153], v[138:141], v[38:41]
	v_mfma_f32_16x16x32_bf16 v[42:45], v[154:157], v[138:141], v[42:45]
	v_mfma_f32_16x16x32_bf16 v[46:49], v[158:161], v[138:141], v[46:49]
	v_mfma_f32_16x16x32_bf16 v[50:53], v[146:149], v[142:145], v[50:53]
	v_mfma_f32_16x16x32_bf16 v[54:57], v[150:153], v[142:145], v[54:57]
	v_mfma_f32_16x16x32_bf16 v[58:61], v[154:157], v[142:145], v[58:61]
	v_mfma_f32_16x16x32_bf16 v[62:65], v[158:161], v[142:145], v[62:65]
	v_mfma_f32_16x16x32_bf16 v[2:5], v[228:231], v[212:215], v[2:5]
	v_mfma_f32_16x16x32_bf16 v[6:9], v[232:235], v[212:215], v[6:9]
	v_mfma_f32_16x16x32_bf16 v[10:13], v[236:239], v[212:215], v[10:13]
	v_mfma_f32_16x16x32_bf16 v[14:17], v[240:243], v[212:215], v[14:17]
	v_mfma_f32_16x16x32_bf16 v[18:21], v[228:231], v[216:219], v[18:21]
	v_mfma_f32_16x16x32_bf16 v[22:25], v[232:235], v[216:219], v[22:25]
	v_mfma_f32_16x16x32_bf16 v[26:29], v[236:239], v[216:219], v[26:29]
	v_mfma_f32_16x16x32_bf16 v[30:33], v[240:243], v[216:219], v[30:33]
	v_mfma_f32_16x16x32_bf16 v[34:37], v[228:231], v[220:223], v[34:37]
	v_mfma_f32_16x16x32_bf16 v[38:41], v[232:235], v[220:223], v[38:41]
	v_mfma_f32_16x16x32_bf16 v[42:45], v[236:239], v[220:223], v[42:45]
	v_mfma_f32_16x16x32_bf16 v[46:49], v[240:243], v[220:223], v[46:49]
	v_mfma_f32_16x16x32_bf16 v[50:53], v[228:231], v[224:227], v[50:53]
	v_mfma_f32_16x16x32_bf16 v[54:57], v[232:235], v[224:227], v[54:57]
	v_mfma_f32_16x16x32_bf16 v[58:61], v[236:239], v[224:227], v[58:61]
	v_mfma_f32_16x16x32_bf16 v[62:65], v[240:243], v[224:227], v[62:65]
	s_setprio 0
	s_nop 7
	v_lshlrev_b32_e32 v212, 16, v174
	v_and_b32_e32 v213, 0xffff0000, v174
	v_lshlrev_b32_e32 v214, 16, v175
	v_and_b32_e32 v215, 0xffff0000, v175
	v_pk_fma_f32 v[66:67], v[2:3], v[212:213], v[66:67]
	v_pk_fma_f32 v[68:69], v[4:5], v[214:215], v[68:69]
	v_lshlrev_b32_e32 v216, 16, v176
	v_and_b32_e32 v217, 0xffff0000, v176
	v_lshlrev_b32_e32 v218, 16, v177
	v_and_b32_e32 v219, 0xffff0000, v177
	v_pk_fma_f32 v[70:71], v[6:7], v[216:217], v[70:71]
	v_pk_fma_f32 v[72:73], v[8:9], v[218:219], v[72:73]
	v_lshlrev_b32_e32 v220, 16, v178
	v_and_b32_e32 v221, 0xffff0000, v178
	v_lshlrev_b32_e32 v222, 16, v179
	v_and_b32_e32 v223, 0xffff0000, v179
	v_pk_fma_f32 v[74:75], v[10:11], v[220:221], v[74:75]
	v_pk_fma_f32 v[76:77], v[12:13], v[222:223], v[76:77]
	v_lshlrev_b32_e32 v224, 16, v180
	v_and_b32_e32 v225, 0xffff0000, v180
	v_lshlrev_b32_e32 v226, 16, v181
	v_and_b32_e32 v227, 0xffff0000, v181
	v_pk_fma_f32 v[78:79], v[14:15], v[224:225], v[78:79]
	v_pk_fma_f32 v[80:81], v[16:17], v[226:227], v[80:81]
	v_lshlrev_b32_e32 v228, 16, v182
	v_and_b32_e32 v229, 0xffff0000, v182
	v_lshlrev_b32_e32 v230, 16, v183
	v_and_b32_e32 v231, 0xffff0000, v183
	v_pk_fma_f32 v[82:83], v[18:19], v[228:229], v[82:83]
	v_pk_fma_f32 v[84:85], v[20:21], v[230:231], v[84:85]
	v_lshlrev_b32_e32 v232, 16, v184
	v_and_b32_e32 v233, 0xffff0000, v184
	v_lshlrev_b32_e32 v234, 16, v185
	v_and_b32_e32 v235, 0xffff0000, v185
	v_pk_fma_f32 v[86:87], v[22:23], v[232:233], v[86:87]
	v_pk_fma_f32 v[88:89], v[24:25], v[234:235], v[88:89]
	v_lshlrev_b32_e32 v236, 16, v186
	v_and_b32_e32 v237, 0xffff0000, v186
	v_lshlrev_b32_e32 v238, 16, v187
	v_and_b32_e32 v239, 0xffff0000, v187
	v_pk_fma_f32 v[90:91], v[26:27], v[236:237], v[90:91]
	v_pk_fma_f32 v[92:93], v[28:29], v[238:239], v[92:93]
	v_lshlrev_b32_e32 v240, 16, v188
	v_and_b32_e32 v241, 0xffff0000, v188
	v_lshlrev_b32_e32 v242, 16, v189
	v_and_b32_e32 v243, 0xffff0000, v189
	v_pk_fma_f32 v[94:95], v[30:31], v[240:241], v[94:95]
	v_pk_fma_f32 v[96:97], v[32:33], v[242:243], v[96:97]
	v_lshlrev_b32_e32 v212, 16, v190
	v_and_b32_e32 v213, 0xffff0000, v190
	v_lshlrev_b32_e32 v214, 16, v191
	v_and_b32_e32 v215, 0xffff0000, v191
	v_pk_fma_f32 v[98:99], v[34:35], v[212:213], v[98:99]
	v_pk_fma_f32 v[100:101], v[36:37], v[214:215], v[100:101]
	v_lshlrev_b32_e32 v216, 16, v192
	v_and_b32_e32 v217, 0xffff0000, v192
	v_lshlrev_b32_e32 v218, 16, v193
	v_and_b32_e32 v219, 0xffff0000, v193
	v_pk_fma_f32 v[102:103], v[38:39], v[216:217], v[102:103]
	v_pk_fma_f32 v[104:105], v[40:41], v[218:219], v[104:105]
	v_lshlrev_b32_e32 v220, 16, v244
	v_and_b32_e32 v221, 0xffff0000, v244
	v_lshlrev_b32_e32 v222, 16, v245
	v_and_b32_e32 v223, 0xffff0000, v245
	v_pk_fma_f32 v[106:107], v[42:43], v[220:221], v[106:107]
	v_pk_fma_f32 v[108:109], v[44:45], v[222:223], v[108:109]
	v_lshlrev_b32_e32 v224, 16, v246
	v_and_b32_e32 v225, 0xffff0000, v246
	v_lshlrev_b32_e32 v226, 16, v247
	v_and_b32_e32 v227, 0xffff0000, v247
	v_pk_fma_f32 v[110:111], v[46:47], v[224:225], v[110:111]
	v_pk_fma_f32 v[112:113], v[48:49], v[226:227], v[112:113]
	v_lshlrev_b32_e32 v228, 16, v248
	v_and_b32_e32 v229, 0xffff0000, v248
	v_lshlrev_b32_e32 v230, 16, v249
	v_and_b32_e32 v231, 0xffff0000, v249
	v_pk_fma_f32 v[114:115], v[50:51], v[228:229], v[114:115]
	v_pk_fma_f32 v[116:117], v[52:53], v[230:231], v[116:117]
	v_lshlrev_b32_e32 v232, 16, v250
	v_and_b32_e32 v233, 0xffff0000, v250
	v_lshlrev_b32_e32 v234, 16, v251
	v_and_b32_e32 v235, 0xffff0000, v251
	v_pk_fma_f32 v[118:119], v[54:55], v[232:233], v[118:119]
	v_pk_fma_f32 v[120:121], v[56:57], v[234:235], v[120:121]
	v_lshlrev_b32_e32 v236, 16, v166
	v_and_b32_e32 v237, 0xffff0000, v166
	v_lshlrev_b32_e32 v238, 16, v167
	v_and_b32_e32 v239, 0xffff0000, v167
	v_pk_fma_f32 v[122:123], v[58:59], v[236:237], v[122:123]
	v_pk_fma_f32 v[124:125], v[60:61], v[238:239], v[124:125]
	v_lshlrev_b32_e32 v240, 16, v194
	v_and_b32_e32 v241, 0xffff0000, v194
	v_lshlrev_b32_e32 v242, 16, v195
	v_and_b32_e32 v243, 0xffff0000, v195
	v_pk_fma_f32 v[126:127], v[62:63], v[240:241], v[126:127]
	v_pk_fma_f32 v[128:129], v[64:65], v[242:243], v[128:129]
	s_waitcnt vmcnt(6)
	s_barrier
	v_add_u32_e32 v204, 0x18000, v200
	v_add_u32_e32 v205, 0x18000, v202
	ds_read_b128 v[130:133], v204 offset:0
	ds_read_b128 v[134:137], v204 offset:2048
	ds_read_b128 v[138:141], v204 offset:4096
	ds_read_b128 v[142:145], v204 offset:6144
	ds_read_b128 v[146:149], v205 offset:0
	ds_read_b128 v[150:153], v205 offset:2048
	ds_read_b128 v[154:157], v205 offset:4096
	ds_read_b128 v[158:161], v205 offset:6144
	v_add_u32_e32 v204, 0x18000, v201
	v_add_u32_e32 v205, 0x18000, v203
	ds_read_b128 v[212:215], v204 offset:0
	ds_read_b128 v[216:219], v204 offset:2048
	ds_read_b128 v[220:223], v204 offset:4096
	ds_read_b128 v[224:227], v204 offset:6144
	ds_read_b128 v[228:231], v205 offset:0
	ds_read_b128 v[232:235], v205 offset:2048
	ds_read_b128 v[236:239], v205 offset:4096
	ds_read_b128 v[240:243], v205 offset:6144
	s_add_u32 m0, s76, 0xc000
	s_nop 0
	global_load_lds_dwordx4 v196, s[68:69]
	s_add_u32 m0, s76, 0xe000
	s_nop 0
	global_load_lds_dwordx4 v197, s[68:69]
	s_add_u32 m0, s76, 0x10000
	s_nop 0
	global_load_lds_dwordx4 v198, s[68:69]
	s_add_u32 m0, s76, 0x12000
	s_nop 0
	global_load_lds_dwordx4 v199, s[68:69]
	s_add_u32 m0, s76, 0x14000
	s_nop 0
	global_load_lds_dwordx4 v196, s[70:71]
	s_add_u32 m0, s76, 0x16000
	s_nop 0
	global_load_lds_dwordx4 v197, s[70:71]
	s_add_u32 s68, s68, 0x80
	s_addc_u32 s69, s69, 0
	s_add_u32 s70, s70, 0x80
	s_addc_u32 s71, s71, 0
	global_load_dwordx2 v[174:175], v206, s[72:73] offset:0
	global_load_dwordx2 v[176:177], v206, s[72:73] offset:32
	global_load_dwordx2 v[178:179], v206, s[72:73] offset:64
	global_load_dwordx2 v[180:181], v206, s[72:73] offset:96
	global_load_dwordx2 v[182:183], v207, s[72:73] offset:0
	global_load_dwordx2 v[184:185], v207, s[72:73] offset:32
	s_waitcnt lgkmcnt(0)
	s_barrier
	s_setprio 1
	v_mfma_f32_16x16x32_bf16 v[2:5], v[146:149], v[130:133], 0
	v_mfma_f32_16x16x32_bf16 v[6:9], v[150:153], v[130:133], 0
	v_mfma_f32_16x16x32_bf16 v[10:13], v[154:157], v[130:133], 0
	v_mfma_f32_16x16x32_bf16 v[14:17], v[158:161], v[130:133], 0
	v_mfma_f32_16x16x32_bf16 v[18:21], v[146:149], v[134:137], 0
	v_mfma_f32_16x16x32_bf16 v[22:25], v[150:153], v[134:137], 0
	v_mfma_f32_16x16x32_bf16 v[26:29], v[154:157], v[134:137], 0
	v_mfma_f32_16x16x32_bf16 v[30:33], v[158:161], v[134:137], 0
	v_mfma_f32_16x16x32_bf16 v[34:37], v[146:149], v[138:141], 0
	v_mfma_f32_16x16x32_bf16 v[38:41], v[150:153], v[138:141], 0
	v_mfma_f32_16x16x32_bf16 v[42:45], v[154:157], v[138:141], 0
	v_mfma_f32_16x16x32_bf16 v[46:49], v[158:161], v[138:141], 0
	v_mfma_f32_16x16x32_bf16 v[50:53], v[146:149], v[142:145], 0
	v_mfma_f32_16x16x32_bf16 v[54:57], v[150:153], v[142:145], 0
	v_mfma_f32_16x16x32_bf16 v[58:61], v[154:157], v[142:145], 0
	v_mfma_f32_16x16x32_bf16 v[62:65], v[158:161], v[142:145], 0
	v_mfma_f32_16x16x32_bf16 v[2:5], v[228:231], v[212:215], v[2:5]
	v_mfma_f32_16x16x32_bf16 v[6:9], v[232:235], v[212:215], v[6:9]
	v_mfma_f32_16x16x32_bf16 v[10:13], v[236:239], v[212:215], v[10:13]
	v_mfma_f32_16x16x32_bf16 v[14:17], v[240:243], v[212:215], v[14:17]
	v_mfma_f32_16x16x32_bf16 v[18:21], v[228:231], v[216:219], v[18:21]
	v_mfma_f32_16x16x32_bf16 v[22:25], v[232:235], v[216:219], v[22:25]
	v_mfma_f32_16x16x32_bf16 v[26:29], v[236:239], v[216:219], v[26:29]
	v_mfma_f32_16x16x32_bf16 v[30:33], v[240:243], v[216:219], v[30:33]
	v_mfma_f32_16x16x32_bf16 v[34:37], v[228:231], v[220:223], v[34:37]
	v_mfma_f32_16x16x32_bf16 v[38:41], v[232:235], v[220:223], v[38:41]
	v_mfma_f32_16x16x32_bf16 v[42:45], v[236:239], v[220:223], v[42:45]
	v_mfma_f32_16x16x32_bf16 v[46:49], v[240:243], v[220:223], v[46:49]
	v_mfma_f32_16x16x32_bf16 v[50:53], v[228:231], v[224:227], v[50:53]
	v_mfma_f32_16x16x32_bf16 v[54:57], v[232:235], v[224:227], v[54:57]
	v_mfma_f32_16x16x32_bf16 v[58:61], v[236:239], v[224:227], v[58:61]
	v_mfma_f32_16x16x32_bf16 v[62:65], v[240:243], v[224:227], v[62:65]
	s_setprio 0
	s_waitcnt vmcnt(12)
	s_barrier
	v_add_u32_e32 v204, 0x0, v200
	v_add_u32_e32 v205, 0x0, v202
	ds_read_b128 v[130:133], v204 offset:0
	ds_read_b128 v[134:137], v204 offset:2048
	ds_read_b128 v[138:141], v204 offset:4096
	ds_read_b128 v[142:145], v204 offset:6144
	ds_read_b128 v[146:149], v205 offset:0
	ds_read_b128 v[150:153], v205 offset:2048
	ds_read_b128 v[154:157], v205 offset:4096
	ds_read_b128 v[158:161], v205 offset:6144
	v_add_u32_e32 v204, 0x0, v201
	v_add_u32_e32 v205, 0x0, v203
	ds_read_b128 v[212:215], v204 offset:0
	ds_read_b128 v[216:219], v204 offset:2048
	ds_read_b128 v[220:223], v204 offset:4096
	ds_read_b128 v[224:227], v204 offset:6144
	ds_read_b128 v[228:231], v205 offset:0
	ds_read_b128 v[232:235], v205 offset:2048
	ds_read_b128 v[236:239], v205 offset:4096
	ds_read_b128 v[240:243], v205 offset:6144
	s_add_u32 m0, s76, 0x18000
	s_nop 0
	global_load_lds_dwordx4 v196, s[68:69]
	s_add_u32 m0, s76, 0x1a000
	s_nop 0
	global_load_lds_dwordx4 v197, s[68:69]
	s_add_u32 m0, s76, 0x1c000
	s_nop 0
	global_load_lds_dwordx4 v198, s[68:69]
	s_add_u32 m0, s76, 0x1e000
	s_nop 0
	global_load_lds_dwordx4 v199, s[68:69]
	s_add_u32 m0, s76, 0x20000
	s_nop 0
	global_load_lds_dwordx4 v196, s[70:71]
	s_add_u32 m0, s76, 0x22000
	s_nop 0
	global_load_lds_dwordx4 v197, s[70:71]
	s_add_u32 s68, s68, 0x80
	s_addc_u32 s69, s69, 0
	s_add_u32 s70, s70, 0x80
	s_addc_u32 s71, s71, 0
	global_load_dwordx2 v[186:187], v207, s[72:73] offset:64
	global_load_dwordx2 v[188:189], v207, s[72:73] offset:96
	global_load_dwordx2 v[190:191], v208, s[72:73] offset:0
	global_load_dwordx2 v[192:193], v208, s[72:73] offset:32
	global_load_dwordx2 v[244:245], v208, s[72:73] offset:64
	global_load_dwordx2 v[246:247], v208, s[72:73] offset:96
	s_waitcnt lgkmcnt(0)
	s_barrier
	s_setprio 1
	v_mfma_f32_16x16x32_bf16 v[2:5], v[146:149], v[130:133], v[2:5]
	v_mfma_f32_16x16x32_bf16 v[6:9], v[150:153], v[130:133], v[6:9]
	v_mfma_f32_16x16x32_bf16 v[10:13], v[154:157], v[130:133], v[10:13]
	v_mfma_f32_16x16x32_bf16 v[14:17], v[158:161], v[130:133], v[14:17]
	v_mfma_f32_16x16x32_bf16 v[18:21], v[146:149], v[134:137], v[18:21]
	v_mfma_f32_16x16x32_bf16 v[22:25], v[150:153], v[134:137], v[22:25]
	v_mfma_f32_16x16x32_bf16 v[26:29], v[154:157], v[134:137], v[26:29]
	v_mfma_f32_16x16x32_bf16 v[30:33], v[158:161], v[134:137], v[30:33]
	v_mfma_f32_16x16x32_bf16 v[34:37], v[146:149], v[138:141], v[34:37]
	v_mfma_f32_16x16x32_bf16 v[38:41], v[150:153], v[138:141], v[38:41]
	v_mfma_f32_16x16x32_bf16 v[42:45], v[154:157], v[138:141], v[42:45]
	v_mfma_f32_16x16x32_bf16 v[46:49], v[158:161], v[138:141], v[46:49]
	v_mfma_f32_16x16x32_bf16 v[50:53], v[146:149], v[142:145], v[50:53]
	v_mfma_f32_16x16x32_bf16 v[54:57], v[150:153], v[142:145], v[54:57]
	v_mfma_f32_16x16x32_bf16 v[58:61], v[154:157], v[142:145], v[58:61]
	v_mfma_f32_16x16x32_bf16 v[62:65], v[158:161], v[142:145], v[62:65]
	v_mfma_f32_16x16x32_bf16 v[2:5], v[228:231], v[212:215], v[2:5]
	v_mfma_f32_16x16x32_bf16 v[6:9], v[232:235], v[212:215], v[6:9]
	v_mfma_f32_16x16x32_bf16 v[10:13], v[236:239], v[212:215], v[10:13]
	v_mfma_f32_16x16x32_bf16 v[14:17], v[240:243], v[212:215], v[14:17]
	v_mfma_f32_16x16x32_bf16 v[18:21], v[228:231], v[216:219], v[18:21]
	v_mfma_f32_16x16x32_bf16 v[22:25], v[232:235], v[216:219], v[22:25]
	v_mfma_f32_16x16x32_bf16 v[26:29], v[236:239], v[216:219], v[26:29]
	v_mfma_f32_16x16x32_bf16 v[30:33], v[240:243], v[216:219], v[30:33]
	v_mfma_f32_16x16x32_bf16 v[34:37], v[228:231], v[220:223], v[34:37]
	v_mfma_f32_16x16x32_bf16 v[38:41], v[232:235], v[220:223], v[38:41]
	v_mfma_f32_16x16x32_bf16 v[42:45], v[236:239], v[220:223], v[42:45]
	v_mfma_f32_16x16x32_bf16 v[46:49], v[240:243], v[220:223], v[46:49]
	v_mfma_f32_16x16x32_bf16 v[50:53], v[228:231], v[224:227], v[50:53]
	v_mfma_f32_16x16x32_bf16 v[54:57], v[232:235], v[224:227], v[54:57]
	v_mfma_f32_16x16x32_bf16 v[58:61], v[236:239], v[224:227], v[58:61]
	v_mfma_f32_16x16x32_bf16 v[62:65], v[240:243], v[224:227], v[62:65]
	s_setprio 0
	s_waitcnt vmcnt(18)
	s_barrier
	v_add_u32_e32 v204, 0xc000, v200
	v_add_u32_e32 v205, 0xc000, v202
	ds_read_b128 v[130:133], v204 offset:0
	ds_read_b128 v[134:137], v204 offset:2048
	ds_read_b128 v[138:141], v204 offset:4096
	ds_read_b128 v[142:145], v204 offset:6144
	ds_read_b128 v[146:149], v205 offset:0
	ds_read_b128 v[150:153], v205 offset:2048
	ds_read_b128 v[154:157], v205 offset:4096
	ds_read_b128 v[158:161], v205 offset:6144
	v_add_u32_e32 v204, 0xc000, v201
	v_add_u32_e32 v205, 0xc000, v203
	ds_read_b128 v[212:215], v204 offset:0
	ds_read_b128 v[216:219], v204 offset:2048
	ds_read_b128 v[220:223], v204 offset:4096
	ds_read_b128 v[224:227], v204 offset:6144
	ds_read_b128 v[228:231], v205 offset:0
	ds_read_b128 v[232:235], v205 offset:2048
	ds_read_b128 v[236:239], v205 offset:4096
	ds_read_b128 v[240:243], v205 offset:6144
	s_add_u32 m0, s76, 0x0
	s_nop 0
	global_load_lds_dwordx4 v196, s[68:69]
	s_add_u32 m0, s76, 0x2000
	s_nop 0
	global_load_lds_dwordx4 v197, s[68:69]
	s_add_u32 m0, s76, 0x4000
	s_nop 0
	global_load_lds_dwordx4 v198, s[68:69]
	s_add_u32 m0, s76, 0x6000
	s_nop 0
	global_load_lds_dwordx4 v199, s[68:69]
	s_add_u32 m0, s76, 0x8000
	s_nop 0
	global_load_lds_dwordx4 v196, s[70:71]
	s_add_u32 m0, s76, 0xa000
	s_nop 0
	global_load_lds_dwordx4 v197, s[70:71]
	s_add_u32 s68, s68, 0x80
	s_addc_u32 s69, s69, 0
	s_add_u32 s70, s70, 0x80
	s_addc_u32 s71, s71, 0
	global_load_dwordx2 v[248:249], v209, s[72:73] offset:0
	global_load_dwordx2 v[250:251], v209, s[72:73] offset:32
	global_load_dwordx2 v[166:167], v209, s[72:73] offset:64
	global_load_dwordx2 v[194:195], v209, s[72:73] offset:96
	s_add_u32 s72, s72, 0x800
	s_addc_u32 s73, s73, 0
	s_waitcnt lgkmcnt(0)
	s_barrier
	s_setprio 1
	v_mfma_f32_16x16x32_bf16 v[2:5], v[146:149], v[130:133], v[2:5]
	v_mfma_f32_16x16x32_bf16 v[6:9], v[150:153], v[130:133], v[6:9]
	v_mfma_f32_16x16x32_bf16 v[10:13], v[154:157], v[130:133], v[10:13]
	v_mfma_f32_16x16x32_bf16 v[14:17], v[158:161], v[130:133], v[14:17]
	v_mfma_f32_16x16x32_bf16 v[18:21], v[146:149], v[134:137], v[18:21]
	v_mfma_f32_16x16x32_bf16 v[22:25], v[150:153], v[134:137], v[22:25]
	v_mfma_f32_16x16x32_bf16 v[26:29], v[154:157], v[134:137], v[26:29]
	v_mfma_f32_16x16x32_bf16 v[30:33], v[158:161], v[134:137], v[30:33]
	v_mfma_f32_16x16x32_bf16 v[34:37], v[146:149], v[138:141], v[34:37]
	v_mfma_f32_16x16x32_bf16 v[38:41], v[150:153], v[138:141], v[38:41]
	v_mfma_f32_16x16x32_bf16 v[42:45], v[154:157], v[138:141], v[42:45]
	v_mfma_f32_16x16x32_bf16 v[46:49], v[158:161], v[138:141], v[46:49]
	v_mfma_f32_16x16x32_bf16 v[50:53], v[146:149], v[142:145], v[50:53]
	v_mfma_f32_16x16x32_bf16 v[54:57], v[150:153], v[142:145], v[54:57]
	v_mfma_f32_16x16x32_bf16 v[58:61], v[154:157], v[142:145], v[58:61]
	v_mfma_f32_16x16x32_bf16 v[62:65], v[158:161], v[142:145], v[62:65]
	v_mfma_f32_16x16x32_bf16 v[2:5], v[228:231], v[212:215], v[2:5]
	v_mfma_f32_16x16x32_bf16 v[6:9], v[232:235], v[212:215], v[6:9]
	v_mfma_f32_16x16x32_bf16 v[10:13], v[236:239], v[212:215], v[10:13]
	v_mfma_f32_16x16x32_bf16 v[14:17], v[240:243], v[212:215], v[14:17]
	v_mfma_f32_16x16x32_bf16 v[18:21], v[228:231], v[216:219], v[18:21]
	v_mfma_f32_16x16x32_bf16 v[22:25], v[232:235], v[216:219], v[22:25]
	v_mfma_f32_16x16x32_bf16 v[26:29], v[236:239], v[216:219], v[26:29]
	v_mfma_f32_16x16x32_bf16 v[30:33], v[240:243], v[216:219], v[30:33]
	v_mfma_f32_16x16x32_bf16 v[34:37], v[228:231], v[220:223], v[34:37]
	v_mfma_f32_16x16x32_bf16 v[38:41], v[232:235], v[220:223], v[38:41]
	v_mfma_f32_16x16x32_bf16 v[42:45], v[236:239], v[220:223], v[42:45]
	v_mfma_f32_16x16x32_bf16 v[46:49], v[240:243], v[220:223], v[46:49]
	v_mfma_f32_16x16x32_bf16 v[50:53], v[228:231], v[224:227], v[50:53]
	v_mfma_f32_16x16x32_bf16 v[54:57], v[232:235], v[224:227], v[54:57]
	v_mfma_f32_16x16x32_bf16 v[58:61], v[236:239], v[224:227], v[58:61]
	v_mfma_f32_16x16x32_bf16 v[62:65], v[240:243], v[224:227], v[62:65]
	s_setprio 0
	s_waitcnt vmcnt(16)
	s_barrier
	v_add_u32_e32 v204, 0x18000, v200
	v_add_u32_e32 v205, 0x18000, v202
	ds_read_b128 v[130:133], v204 offset:0
	ds_read_b128 v[134:137], v204 offset:2048
	ds_read_b128 v[138:141], v204 offset:4096
	ds_read_b128 v[142:145], v204 offset:6144
	ds_read_b128 v[146:149], v205 offset:0
	ds_read_b128 v[150:153], v205 offset:2048
	ds_read_b128 v[154:157], v205 offset:4096
	ds_read_b128 v[158:161], v205 offset:6144
	v_add_u32_e32 v204, 0x18000, v201
	v_add_u32_e32 v205, 0x18000, v203
	ds_read_b128 v[212:215], v204 offset:0
	ds_read_b128 v[216:219], v204 offset:2048
	ds_read_b128 v[220:223], v204 offset:4096
	ds_read_b128 v[224:227], v204 offset:6144
	ds_read_b128 v[228:231], v205 offset:0
	ds_read_b128 v[232:235], v205 offset:2048
	ds_read_b128 v[236:239], v205 offset:4096
	ds_read_b128 v[240:243], v205 offset:6144
	s_add_u32 m0, s76, 0xc000
	s_nop 0
	global_load_lds_dwordx4 v196, s[68:69]
	s_add_u32 m0, s76, 0xe000
	s_nop 0
	global_load_lds_dwordx4 v197, s[68:69]
	s_add_u32 m0, s76, 0x10000
	s_nop 0
	global_load_lds_dwordx4 v198, s[68:69]
	s_add_u32 m0, s76, 0x12000
	s_nop 0
	global_load_lds_dwordx4 v199, s[68:69]
	s_add_u32 m0, s76, 0x14000
	s_nop 0
	global_load_lds_dwordx4 v196, s[70:71]
	s_add_u32 m0, s76, 0x16000
	s_nop 0
	global_load_lds_dwordx4 v197, s[70:71]
	s_add_u32 s68, s68, 0x80
	s_addc_u32 s69, s69, 0
	s_add_u32 s70, s70, 0x80
	s_addc_u32 s71, s71, 0
	s_waitcnt lgkmcnt(0)
	s_barrier
	s_setprio 1
	v_mfma_f32_16x16x32_bf16 v[2:5], v[146:149], v[130:133], v[2:5]
	v_mfma_f32_16x16x32_bf16 v[6:9], v[150:153], v[130:133], v[6:9]
	v_mfma_f32_16x16x32_bf16 v[10:13], v[154:157], v[130:133], v[10:13]
	v_mfma_f32_16x16x32_bf16 v[14:17], v[158:161], v[130:133], v[14:17]
	v_mfma_f32_16x16x32_bf16 v[18:21], v[146:149], v[134:137], v[18:21]
	v_mfma_f32_16x16x32_bf16 v[22:25], v[150:153], v[134:137], v[22:25]
	v_mfma_f32_16x16x32_bf16 v[26:29], v[154:157], v[134:137], v[26:29]
	v_mfma_f32_16x16x32_bf16 v[30:33], v[158:161], v[134:137], v[30:33]
	v_mfma_f32_16x16x32_bf16 v[34:37], v[146:149], v[138:141], v[34:37]
	v_mfma_f32_16x16x32_bf16 v[38:41], v[150:153], v[138:141], v[38:41]
	v_mfma_f32_16x16x32_bf16 v[42:45], v[154:157], v[138:141], v[42:45]
	v_mfma_f32_16x16x32_bf16 v[46:49], v[158:161], v[138:141], v[46:49]
	v_mfma_f32_16x16x32_bf16 v[50:53], v[146:149], v[142:145], v[50:53]
	v_mfma_f32_16x16x32_bf16 v[54:57], v[150:153], v[142:145], v[54:57]
	v_mfma_f32_16x16x32_bf16 v[58:61], v[154:157], v[142:145], v[58:61]
	v_mfma_f32_16x16x32_bf16 v[62:65], v[158:161], v[142:145], v[62:65]
	v_mfma_f32_16x16x32_bf16 v[2:5], v[228:231], v[212:215], v[2:5]
	v_mfma_f32_16x16x32_bf16 v[6:9], v[232:235], v[212:215], v[6:9]
	v_mfma_f32_16x16x32_bf16 v[10:13], v[236:239], v[212:215], v[10:13]
	v_mfma_f32_16x16x32_bf16 v[14:17], v[240:243], v[212:215], v[14:17]
	v_mfma_f32_16x16x32_bf16 v[18:21], v[228:231], v[216:219], v[18:21]
	v_mfma_f32_16x16x32_bf16 v[22:25], v[232:235], v[216:219], v[22:25]
	v_mfma_f32_16x16x32_bf16 v[26:29], v[236:239], v[216:219], v[26:29]
	v_mfma_f32_16x16x32_bf16 v[30:33], v[240:243], v[216:219], v[30:33]
	v_mfma_f32_16x16x32_bf16 v[34:37], v[228:231], v[220:223], v[34:37]
	v_mfma_f32_16x16x32_bf16 v[38:41], v[232:235], v[220:223], v[38:41]
	v_mfma_f32_16x16x32_bf16 v[42:45], v[236:239], v[220:223], v[42:45]
	v_mfma_f32_16x16x32_bf16 v[46:49], v[240:243], v[220:223], v[46:49]
	v_mfma_f32_16x16x32_bf16 v[50:53], v[228:231], v[224:227], v[50:53]
	v_mfma_f32_16x16x32_bf16 v[54:57], v[232:235], v[224:227], v[54:57]
	v_mfma_f32_16x16x32_bf16 v[58:61], v[236:239], v[224:227], v[58:61]
	v_mfma_f32_16x16x32_bf16 v[62:65], v[240:243], v[224:227], v[62:65]
	s_setprio 0
	s_waitcnt vmcnt(10)
	s_barrier
	v_add_u32_e32 v204, 0x0, v200
	v_add_u32_e32 v205, 0x0, v202
	ds_read_b128 v[130:133], v204 offset:0
	ds_read_b128 v[134:137], v204 offset:2048
	ds_read_b128 v[138:141], v204 offset:4096
	ds_read_b128 v[142:145], v204 offset:6144
	ds_read_b128 v[146:149], v205 offset:0
	ds_read_b128 v[150:153], v205 offset:2048
	ds_read_b128 v[154:157], v205 offset:4096
	ds_read_b128 v[158:161], v205 offset:6144
	v_add_u32_e32 v204, 0x0, v201
	v_add_u32_e32 v205, 0x0, v203
	ds_read_b128 v[212:215], v204 offset:0
	ds_read_b128 v[216:219], v204 offset:2048
	ds_read_b128 v[220:223], v204 offset:4096
	ds_read_b128 v[224:227], v204 offset:6144
	ds_read_b128 v[228:231], v205 offset:0
	ds_read_b128 v[232:235], v205 offset:2048
	ds_read_b128 v[236:239], v205 offset:4096
	ds_read_b128 v[240:243], v205 offset:6144
	s_add_u32 m0, s76, 0x18000
	s_nop 0
	global_load_lds_dwordx4 v196, s[68:69]
	s_add_u32 m0, s76, 0x1a000
	s_nop 0
	global_load_lds_dwordx4 v197, s[68:69]
	s_add_u32 m0, s76, 0x1c000
	s_nop 0
	global_load_lds_dwordx4 v198, s[68:69]
	s_add_u32 m0, s76, 0x1e000
	s_nop 0
	global_load_lds_dwordx4 v199, s[68:69]
	s_add_u32 m0, s76, 0x20000
	s_nop 0
	global_load_lds_dwordx4 v196, s[70:71]
	s_add_u32 m0, s76, 0x22000
	s_nop 0
	global_load_lds_dwordx4 v197, s[70:71]
	s_add_u32 s68, s68, 0x80
	s_addc_u32 s69, s69, 0
	s_add_u32 s70, s70, 0x80
	s_addc_u32 s71, s71, 0
	s_waitcnt lgkmcnt(0)
	s_barrier
	s_setprio 1
	v_mfma_f32_16x16x32_bf16 v[2:5], v[146:149], v[130:133], v[2:5]
	v_mfma_f32_16x16x32_bf16 v[6:9], v[150:153], v[130:133], v[6:9]
	v_mfma_f32_16x16x32_bf16 v[10:13], v[154:157], v[130:133], v[10:13]
	v_mfma_f32_16x16x32_bf16 v[14:17], v[158:161], v[130:133], v[14:17]
	v_mfma_f32_16x16x32_bf16 v[18:21], v[146:149], v[134:137], v[18:21]
	v_mfma_f32_16x16x32_bf16 v[22:25], v[150:153], v[134:137], v[22:25]
	v_mfma_f32_16x16x32_bf16 v[26:29], v[154:157], v[134:137], v[26:29]
	v_mfma_f32_16x16x32_bf16 v[30:33], v[158:161], v[134:137], v[30:33]
	v_mfma_f32_16x16x32_bf16 v[34:37], v[146:149], v[138:141], v[34:37]
	v_mfma_f32_16x16x32_bf16 v[38:41], v[150:153], v[138:141], v[38:41]
	v_mfma_f32_16x16x32_bf16 v[42:45], v[154:157], v[138:141], v[42:45]
	v_mfma_f32_16x16x32_bf16 v[46:49], v[158:161], v[138:141], v[46:49]
	v_mfma_f32_16x16x32_bf16 v[50:53], v[146:149], v[142:145], v[50:53]
	v_mfma_f32_16x16x32_bf16 v[54:57], v[150:153], v[142:145], v[54:57]
	v_mfma_f32_16x16x32_bf16 v[58:61], v[154:157], v[142:145], v[58:61]
	v_mfma_f32_16x16x32_bf16 v[62:65], v[158:161], v[142:145], v[62:65]
	v_mfma_f32_16x16x32_bf16 v[2:5], v[228:231], v[212:215], v[2:5]
	v_mfma_f32_16x16x32_bf16 v[6:9], v[232:235], v[212:215], v[6:9]
	v_mfma_f32_16x16x32_bf16 v[10:13], v[236:239], v[212:215], v[10:13]
	v_mfma_f32_16x16x32_bf16 v[14:17], v[240:243], v[212:215], v[14:17]
	v_mfma_f32_16x16x32_bf16 v[18:21], v[228:231], v[216:219], v[18:21]
	v_mfma_f32_16x16x32_bf16 v[22:25], v[232:235], v[216:219], v[22:25]
	v_mfma_f32_16x16x32_bf16 v[26:29], v[236:239], v[216:219], v[26:29]
	v_mfma_f32_16x16x32_bf16 v[30:33], v[240:243], v[216:219], v[30:33]
	v_mfma_f32_16x16x32_bf16 v[34:37], v[228:231], v[220:223], v[34:37]
	v_mfma_f32_16x16x32_bf16 v[38:41], v[232:235], v[220:223], v[38:41]
	v_mfma_f32_16x16x32_bf16 v[42:45], v[236:239], v[220:223], v[42:45]
	v_mfma_f32_16x16x32_bf16 v[46:49], v[240:243], v[220:223], v[46:49]
	v_mfma_f32_16x16x32_bf16 v[50:53], v[228:231], v[224:227], v[50:53]
	v_mfma_f32_16x16x32_bf16 v[54:57], v[232:235], v[224:227], v[54:57]
	v_mfma_f32_16x16x32_bf16 v[58:61], v[236:239], v[224:227], v[58:61]
	v_mfma_f32_16x16x32_bf16 v[62:65], v[240:243], v[224:227], v[62:65]
	s_setprio 0
	s_waitcnt vmcnt(6)
	s_barrier
	v_add_u32_e32 v204, 0xc000, v200
	v_add_u32_e32 v205, 0xc000, v202
	ds_read_b128 v[130:133], v204 offset:0
	ds_read_b128 v[134:137], v204 offset:2048
	ds_read_b128 v[138:141], v204 offset:4096
	ds_read_b128 v[142:145], v204 offset:6144
	ds_read_b128 v[146:149], v205 offset:0
	ds_read_b128 v[150:153], v205 offset:2048
	ds_read_b128 v[154:157], v205 offset:4096
	ds_read_b128 v[158:161], v205 offset:6144
	v_add_u32_e32 v204, 0xc000, v201
	v_add_u32_e32 v205, 0xc000, v203
	ds_read_b128 v[212:215], v204 offset:0
	ds_read_b128 v[216:219], v204 offset:2048
	ds_read_b128 v[220:223], v204 offset:4096
	ds_read_b128 v[224:227], v204 offset:6144
	ds_read_b128 v[228:231], v205 offset:0
	ds_read_b128 v[232:235], v205 offset:2048
	ds_read_b128 v[236:239], v205 offset:4096
	ds_read_b128 v[240:243], v205 offset:6144
	s_add_u32 m0, s76, 0x0
	s_nop 0
	global_load_lds_dwordx4 v196, s[68:69]
	s_add_u32 m0, s76, 0x2000
	s_nop 0
	global_load_lds_dwordx4 v197, s[68:69]
	s_add_u32 m0, s76, 0x4000
	s_nop 0
	global_load_lds_dwordx4 v198, s[68:69]
	s_add_u32 m0, s76, 0x6000
	s_nop 0
	global_load_lds_dwordx4 v199, s[68:69]
	s_add_u32 m0, s76, 0x8000
	s_nop 0
	global_load_lds_dwordx4 v196, s[70:71]
	s_add_u32 m0, s76, 0xa000
	s_nop 0
	global_load_lds_dwordx4 v197, s[70:71]
	s_add_u32 s68, s68, 0x80
	s_addc_u32 s69, s69, 0
	s_add_u32 s70, s70, 0x80
	s_addc_u32 s71, s71, 0
	s_waitcnt lgkmcnt(0)
	s_barrier
	s_setprio 1
	v_mfma_f32_16x16x32_bf16 v[2:5], v[146:149], v[130:133], v[2:5]
	v_mfma_f32_16x16x32_bf16 v[6:9], v[150:153], v[130:133], v[6:9]
	v_mfma_f32_16x16x32_bf16 v[10:13], v[154:157], v[130:133], v[10:13]
	v_mfma_f32_16x16x32_bf16 v[14:17], v[158:161], v[130:133], v[14:17]
	v_mfma_f32_16x16x32_bf16 v[18:21], v[146:149], v[134:137], v[18:21]
	v_mfma_f32_16x16x32_bf16 v[22:25], v[150:153], v[134:137], v[22:25]
	v_mfma_f32_16x16x32_bf16 v[26:29], v[154:157], v[134:137], v[26:29]
	v_mfma_f32_16x16x32_bf16 v[30:33], v[158:161], v[134:137], v[30:33]
	v_mfma_f32_16x16x32_bf16 v[34:37], v[146:149], v[138:141], v[34:37]
	v_mfma_f32_16x16x32_bf16 v[38:41], v[150:153], v[138:141], v[38:41]
	v_mfma_f32_16x16x32_bf16 v[42:45], v[154:157], v[138:141], v[42:45]
	v_mfma_f32_16x16x32_bf16 v[46:49], v[158:161], v[138:141], v[46:49]
	v_mfma_f32_16x16x32_bf16 v[50:53], v[146:149], v[142:145], v[50:53]
	v_mfma_f32_16x16x32_bf16 v[54:57], v[150:153], v[142:145], v[54:57]
	v_mfma_f32_16x16x32_bf16 v[58:61], v[154:157], v[142:145], v[58:61]
	v_mfma_f32_16x16x32_bf16 v[62:65], v[158:161], v[142:145], v[62:65]
	v_mfma_f32_16x16x32_bf16 v[2:5], v[228:231], v[212:215], v[2:5]
	v_mfma_f32_16x16x32_bf16 v[6:9], v[232:235], v[212:215], v[6:9]
	v_mfma_f32_16x16x32_bf16 v[10:13], v[236:239], v[212:215], v[10:13]
	v_mfma_f32_16x16x32_bf16 v[14:17], v[240:243], v[212:215], v[14:17]
	v_mfma_f32_16x16x32_bf16 v[18:21], v[228:231], v[216:219], v[18:21]
	v_mfma_f32_16x16x32_bf16 v[22:25], v[232:235], v[216:219], v[22:25]
	v_mfma_f32_16x16x32_bf16 v[26:29], v[236:239], v[216:219], v[26:29]
	v_mfma_f32_16x16x32_bf16 v[30:33], v[240:243], v[216:219], v[30:33]
	v_mfma_f32_16x16x32_bf16 v[34:37], v[228:231], v[220:223], v[34:37]
	v_mfma_f32_16x16x32_bf16 v[38:41], v[232:235], v[220:223], v[38:41]
	v_mfma_f32_16x16x32_bf16 v[42:45], v[236:239], v[220:223], v[42:45]
	v_mfma_f32_16x16x32_bf16 v[46:49], v[240:243], v[220:223], v[46:49]
	v_mfma_f32_16x16x32_bf16 v[50:53], v[228:231], v[224:227], v[50:53]
	v_mfma_f32_16x16x32_bf16 v[54:57], v[232:235], v[224:227], v[54:57]
	v_mfma_f32_16x16x32_bf16 v[58:61], v[236:239], v[224:227], v[58:61]
	v_mfma_f32_16x16x32_bf16 v[62:65], v[240:243], v[224:227], v[62:65]
	s_setprio 0
	s_waitcnt vmcnt(6)
	s_barrier
	v_add_u32_e32 v204, 0x18000, v200
	v_add_u32_e32 v205, 0x18000, v202
	ds_read_b128 v[130:133], v204 offset:0
	ds_read_b128 v[134:137], v204 offset:2048
	ds_read_b128 v[138:141], v204 offset:4096
	ds_read_b128 v[142:145], v204 offset:6144
	ds_read_b128 v[146:149], v205 offset:0
	ds_read_b128 v[150:153], v205 offset:2048
	ds_read_b128 v[154:157], v205 offset:4096
	ds_read_b128 v[158:161], v205 offset:6144
	v_add_u32_e32 v204, 0x18000, v201
	v_add_u32_e32 v205, 0x18000, v203
	ds_read_b128 v[212:215], v204 offset:0
	ds_read_b128 v[216:219], v204 offset:2048
	ds_read_b128 v[220:223], v204 offset:4096
	ds_read_b128 v[224:227], v204 offset:6144
	ds_read_b128 v[228:231], v205 offset:0
	ds_read_b128 v[232:235], v205 offset:2048
	ds_read_b128 v[236:239], v205 offset:4096
	ds_read_b128 v[240:243], v205 offset:6144
	s_add_u32 m0, s76, 0xc000
	s_nop 0
	global_load_lds_dwordx4 v196, s[68:69]
	s_add_u32 m0, s76, 0xe000
	s_nop 0
	global_load_lds_dwordx4 v197, s[68:69]
	s_add_u32 m0, s76, 0x10000
	s_nop 0
	global_load_lds_dwordx4 v198, s[68:69]
	s_add_u32 m0, s76, 0x12000
	s_nop 0
	global_load_lds_dwordx4 v199, s[68:69]
	s_add_u32 m0, s76, 0x14000
	s_nop 0
	global_load_lds_dwordx4 v196, s[70:71]
	s_add_u32 m0, s76, 0x16000
	s_nop 0
	global_load_lds_dwordx4 v197, s[70:71]
	s_add_u32 s68, s68, 0x80
	s_addc_u32 s69, s69, 0
	s_add_u32 s70, s70, 0x80
	s_addc_u32 s71, s71, 0
	s_waitcnt lgkmcnt(0)
	s_barrier
	s_setprio 1
	v_mfma_f32_16x16x32_bf16 v[2:5], v[146:149], v[130:133], v[2:5]
	v_mfma_f32_16x16x32_bf16 v[6:9], v[150:153], v[130:133], v[6:9]
	v_mfma_f32_16x16x32_bf16 v[10:13], v[154:157], v[130:133], v[10:13]
	v_mfma_f32_16x16x32_bf16 v[14:17], v[158:161], v[130:133], v[14:17]
	v_mfma_f32_16x16x32_bf16 v[18:21], v[146:149], v[134:137], v[18:21]
	v_mfma_f32_16x16x32_bf16 v[22:25], v[150:153], v[134:137], v[22:25]
	v_mfma_f32_16x16x32_bf16 v[26:29], v[154:157], v[134:137], v[26:29]
	v_mfma_f32_16x16x32_bf16 v[30:33], v[158:161], v[134:137], v[30:33]
	v_mfma_f32_16x16x32_bf16 v[34:37], v[146:149], v[138:141], v[34:37]
	v_mfma_f32_16x16x32_bf16 v[38:41], v[150:153], v[138:141], v[38:41]
	v_mfma_f32_16x16x32_bf16 v[42:45], v[154:157], v[138:141], v[42:45]
	v_mfma_f32_16x16x32_bf16 v[46:49], v[158:161], v[138:141], v[46:49]
	v_mfma_f32_16x16x32_bf16 v[50:53], v[146:149], v[142:145], v[50:53]
	v_mfma_f32_16x16x32_bf16 v[54:57], v[150:153], v[142:145], v[54:57]
	v_mfma_f32_16x16x32_bf16 v[58:61], v[154:157], v[142:145], v[58:61]
	v_mfma_f32_16x16x32_bf16 v[62:65], v[158:161], v[142:145], v[62:65]
	v_mfma_f32_16x16x32_bf16 v[2:5], v[228:231], v[212:215], v[2:5]
	v_mfma_f32_16x16x32_bf16 v[6:9], v[232:235], v[212:215], v[6:9]
	v_mfma_f32_16x16x32_bf16 v[10:13], v[236:239], v[212:215], v[10:13]
	v_mfma_f32_16x16x32_bf16 v[14:17], v[240:243], v[212:215], v[14:17]
	v_mfma_f32_16x16x32_bf16 v[18:21], v[228:231], v[216:219], v[18:21]
	v_mfma_f32_16x16x32_bf16 v[22:25], v[232:235], v[216:219], v[22:25]
	v_mfma_f32_16x16x32_bf16 v[26:29], v[236:239], v[216:219], v[26:29]
	v_mfma_f32_16x16x32_bf16 v[30:33], v[240:243], v[216:219], v[30:33]
	v_mfma_f32_16x16x32_bf16 v[34:37], v[228:231], v[220:223], v[34:37]
	v_mfma_f32_16x16x32_bf16 v[38:41], v[232:235], v[220:223], v[38:41]
	v_mfma_f32_16x16x32_bf16 v[42:45], v[236:239], v[220:223], v[42:45]
	v_mfma_f32_16x16x32_bf16 v[46:49], v[240:243], v[220:223], v[46:49]
	v_mfma_f32_16x16x32_bf16 v[50:53], v[228:231], v[224:227], v[50:53]
	v_mfma_f32_16x16x32_bf16 v[54:57], v[232:235], v[224:227], v[54:57]
	v_mfma_f32_16x16x32_bf16 v[58:61], v[236:239], v[224:227], v[58:61]
	v_mfma_f32_16x16x32_bf16 v[62:65], v[240:243], v[224:227], v[62:65]
	s_setprio 0
	s_waitcnt vmcnt(6)
	s_barrier
	v_add_u32_e32 v204, 0x0, v200
	v_add_u32_e32 v205, 0x0, v202
	ds_read_b128 v[130:133], v204 offset:0
	ds_read_b128 v[134:137], v204 offset:2048
	ds_read_b128 v[138:141], v204 offset:4096
	ds_read_b128 v[142:145], v204 offset:6144
	ds_read_b128 v[146:149], v205 offset:0
	ds_read_b128 v[150:153], v205 offset:2048
	ds_read_b128 v[154:157], v205 offset:4096
	ds_read_b128 v[158:161], v205 offset:6144
	v_add_u32_e32 v204, 0x0, v201
	v_add_u32_e32 v205, 0x0, v203
	ds_read_b128 v[212:215], v204 offset:0
	ds_read_b128 v[216:219], v204 offset:2048
	ds_read_b128 v[220:223], v204 offset:4096
	ds_read_b128 v[224:227], v204 offset:6144
	ds_read_b128 v[228:231], v205 offset:0
	ds_read_b128 v[232:235], v205 offset:2048
	ds_read_b128 v[236:239], v205 offset:4096
	ds_read_b128 v[240:243], v205 offset:6144
	s_add_u32 m0, s76, 0x18000
	s_nop 0
	global_load_lds_dwordx4 v196, s[68:69]
	s_add_u32 m0, s76, 0x1a000
	s_nop 0
	global_load_lds_dwordx4 v197, s[68:69]
	s_add_u32 m0, s76, 0x1c000
	s_nop 0
	global_load_lds_dwordx4 v198, s[68:69]
	s_add_u32 m0, s76, 0x1e000
	s_nop 0
	global_load_lds_dwordx4 v199, s[68:69]
	s_add_u32 m0, s76, 0x20000
	s_nop 0
	global_load_lds_dwordx4 v196, s[70:71]
	s_add_u32 m0, s76, 0x22000
	s_nop 0
	global_load_lds_dwordx4 v197, s[70:71]
	s_add_u32 s68, s68, 0x80
	s_addc_u32 s69, s69, 0
	s_add_u32 s70, s70, 0x80
	s_addc_u32 s71, s71, 0
	s_waitcnt lgkmcnt(0)
	s_barrier
	s_setprio 1
	v_mfma_f32_16x16x32_bf16 v[2:5], v[146:149], v[130:133], v[2:5]
	v_mfma_f32_16x16x32_bf16 v[6:9], v[150:153], v[130:133], v[6:9]
	v_mfma_f32_16x16x32_bf16 v[10:13], v[154:157], v[130:133], v[10:13]
	v_mfma_f32_16x16x32_bf16 v[14:17], v[158:161], v[130:133], v[14:17]
	v_mfma_f32_16x16x32_bf16 v[18:21], v[146:149], v[134:137], v[18:21]
	v_mfma_f32_16x16x32_bf16 v[22:25], v[150:153], v[134:137], v[22:25]
	v_mfma_f32_16x16x32_bf16 v[26:29], v[154:157], v[134:137], v[26:29]
	v_mfma_f32_16x16x32_bf16 v[30:33], v[158:161], v[134:137], v[30:33]
	v_mfma_f32_16x16x32_bf16 v[34:37], v[146:149], v[138:141], v[34:37]
	v_mfma_f32_16x16x32_bf16 v[38:41], v[150:153], v[138:141], v[38:41]
	v_mfma_f32_16x16x32_bf16 v[42:45], v[154:157], v[138:141], v[42:45]
	v_mfma_f32_16x16x32_bf16 v[46:49], v[158:161], v[138:141], v[46:49]
	v_mfma_f32_16x16x32_bf16 v[50:53], v[146:149], v[142:145], v[50:53]
	v_mfma_f32_16x16x32_bf16 v[54:57], v[150:153], v[142:145], v[54:57]
	v_mfma_f32_16x16x32_bf16 v[58:61], v[154:157], v[142:145], v[58:61]
	v_mfma_f32_16x16x32_bf16 v[62:65], v[158:161], v[142:145], v[62:65]
	v_mfma_f32_16x16x32_bf16 v[2:5], v[228:231], v[212:215], v[2:5]
	v_mfma_f32_16x16x32_bf16 v[6:9], v[232:235], v[212:215], v[6:9]
	v_mfma_f32_16x16x32_bf16 v[10:13], v[236:239], v[212:215], v[10:13]
	v_mfma_f32_16x16x32_bf16 v[14:17], v[240:243], v[212:215], v[14:17]
	v_mfma_f32_16x16x32_bf16 v[18:21], v[228:231], v[216:219], v[18:21]
	v_mfma_f32_16x16x32_bf16 v[22:25], v[232:235], v[216:219], v[22:25]
	v_mfma_f32_16x16x32_bf16 v[26:29], v[236:239], v[216:219], v[26:29]
	v_mfma_f32_16x16x32_bf16 v[30:33], v[240:243], v[216:219], v[30:33]
	v_mfma_f32_16x16x32_bf16 v[34:37], v[228:231], v[220:223], v[34:37]
	v_mfma_f32_16x16x32_bf16 v[38:41], v[232:235], v[220:223], v[38:41]
	v_mfma_f32_16x16x32_bf16 v[42:45], v[236:239], v[220:223], v[42:45]
	v_mfma_f32_16x16x32_bf16 v[46:49], v[240:243], v[220:223], v[46:49]
	v_mfma_f32_16x16x32_bf16 v[50:53], v[228:231], v[224:227], v[50:53]
	v_mfma_f32_16x16x32_bf16 v[54:57], v[232:235], v[224:227], v[54:57]
	v_mfma_f32_16x16x32_bf16 v[58:61], v[236:239], v[224:227], v[58:61]
	v_mfma_f32_16x16x32_bf16 v[62:65], v[240:243], v[224:227], v[62:65]
	s_setprio 0
	s_nop 7
	v_lshlrev_b32_e32 v212, 16, v174
	v_and_b32_e32 v213, 0xffff0000, v174
	v_lshlrev_b32_e32 v214, 16, v175
	v_and_b32_e32 v215, 0xffff0000, v175
	v_pk_fma_f32 v[66:67], v[2:3], v[212:213], v[66:67]
	v_pk_fma_f32 v[68:69], v[4:5], v[214:215], v[68:69]
	v_lshlrev_b32_e32 v216, 16, v176
	v_and_b32_e32 v217, 0xffff0000, v176
	v_lshlrev_b32_e32 v218, 16, v177
	v_and_b32_e32 v219, 0xffff0000, v177
	v_pk_fma_f32 v[70:71], v[6:7], v[216:217], v[70:71]
	v_pk_fma_f32 v[72:73], v[8:9], v[218:219], v[72:73]
	v_lshlrev_b32_e32 v220, 16, v178
	v_and_b32_e32 v221, 0xffff0000, v178
	v_lshlrev_b32_e32 v222, 16, v179
	v_and_b32_e32 v223, 0xffff0000, v179
	v_pk_fma_f32 v[74:75], v[10:11], v[220:221], v[74:75]
	v_pk_fma_f32 v[76:77], v[12:13], v[222:223], v[76:77]
	v_lshlrev_b32_e32 v224, 16, v180
	v_and_b32_e32 v225, 0xffff0000, v180
	v_lshlrev_b32_e32 v226, 16, v181
	v_and_b32_e32 v227, 0xffff0000, v181
	v_pk_fma_f32 v[78:79], v[14:15], v[224:225], v[78:79]
	v_pk_fma_f32 v[80:81], v[16:17], v[226:227], v[80:81]
	v_lshlrev_b32_e32 v228, 16, v182
	v_and_b32_e32 v229, 0xffff0000, v182
	v_lshlrev_b32_e32 v230, 16, v183
	v_and_b32_e32 v231, 0xffff0000, v183
	v_pk_fma_f32 v[82:83], v[18:19], v[228:229], v[82:83]
	v_pk_fma_f32 v[84:85], v[20:21], v[230:231], v[84:85]
	v_lshlrev_b32_e32 v232, 16, v184
	v_and_b32_e32 v233, 0xffff0000, v184
	v_lshlrev_b32_e32 v234, 16, v185
	v_and_b32_e32 v235, 0xffff0000, v185
	v_pk_fma_f32 v[86:87], v[22:23], v[232:233], v[86:87]
	v_pk_fma_f32 v[88:89], v[24:25], v[234:235], v[88:89]
	v_lshlrev_b32_e32 v236, 16, v186
	v_and_b32_e32 v237, 0xffff0000, v186
	v_lshlrev_b32_e32 v238, 16, v187
	v_and_b32_e32 v239, 0xffff0000, v187
	v_pk_fma_f32 v[90:91], v[26:27], v[236:237], v[90:91]
	v_pk_fma_f32 v[92:93], v[28:29], v[238:239], v[92:93]
	v_lshlrev_b32_e32 v240, 16, v188
	v_and_b32_e32 v241, 0xffff0000, v188
	v_lshlrev_b32_e32 v242, 16, v189
	v_and_b32_e32 v243, 0xffff0000, v189
	v_pk_fma_f32 v[94:95], v[30:31], v[240:241], v[94:95]
	v_pk_fma_f32 v[96:97], v[32:33], v[242:243], v[96:97]
	v_lshlrev_b32_e32 v212, 16, v190
	v_and_b32_e32 v213, 0xffff0000, v190
	v_lshlrev_b32_e32 v214, 16, v191
	v_and_b32_e32 v215, 0xffff0000, v191
	v_pk_fma_f32 v[98:99], v[34:35], v[212:213], v[98:99]
	v_pk_fma_f32 v[100:101], v[36:37], v[214:215], v[100:101]
	v_lshlrev_b32_e32 v216, 16, v192
	v_and_b32_e32 v217, 0xffff0000, v192
	v_lshlrev_b32_e32 v218, 16, v193
	v_and_b32_e32 v219, 0xffff0000, v193
	v_pk_fma_f32 v[102:103], v[38:39], v[216:217], v[102:103]
	v_pk_fma_f32 v[104:105], v[40:41], v[218:219], v[104:105]
	v_lshlrev_b32_e32 v220, 16, v244
	v_and_b32_e32 v221, 0xffff0000, v244
	v_lshlrev_b32_e32 v222, 16, v245
	v_and_b32_e32 v223, 0xffff0000, v245
	v_pk_fma_f32 v[106:107], v[42:43], v[220:221], v[106:107]
	v_pk_fma_f32 v[108:109], v[44:45], v[222:223], v[108:109]
	v_lshlrev_b32_e32 v224, 16, v246
	v_and_b32_e32 v225, 0xffff0000, v246
	v_lshlrev_b32_e32 v226, 16, v247
	v_and_b32_e32 v227, 0xffff0000, v247
	v_pk_fma_f32 v[110:111], v[46:47], v[224:225], v[110:111]
	v_pk_fma_f32 v[112:113], v[48:49], v[226:227], v[112:113]
	v_lshlrev_b32_e32 v228, 16, v248
	v_and_b32_e32 v229, 0xffff0000, v248
	v_lshlrev_b32_e32 v230, 16, v249
	v_and_b32_e32 v231, 0xffff0000, v249
	v_pk_fma_f32 v[114:115], v[50:51], v[228:229], v[114:115]
	v_pk_fma_f32 v[116:117], v[52:53], v[230:231], v[116:117]
	v_lshlrev_b32_e32 v232, 16, v250
	v_and_b32_e32 v233, 0xffff0000, v250
	v_lshlrev_b32_e32 v234, 16, v251
	v_and_b32_e32 v235, 0xffff0000, v251
	v_pk_fma_f32 v[118:119], v[54:55], v[232:233], v[118:119]
	v_pk_fma_f32 v[120:121], v[56:57], v[234:235], v[120:121]
	v_lshlrev_b32_e32 v236, 16, v166
	v_and_b32_e32 v237, 0xffff0000, v166
	v_lshlrev_b32_e32 v238, 16, v167
	v_and_b32_e32 v239, 0xffff0000, v167
	v_pk_fma_f32 v[122:123], v[58:59], v[236:237], v[122:123]
	v_pk_fma_f32 v[124:125], v[60:61], v[238:239], v[124:125]
	v_lshlrev_b32_e32 v240, 16, v194
	v_and_b32_e32 v241, 0xffff0000, v194
	v_lshlrev_b32_e32 v242, 16, v195
	v_and_b32_e32 v243, 0xffff0000, v195
	v_pk_fma_f32 v[126:127], v[62:63], v[240:241], v[126:127]
	v_pk_fma_f32 v[128:129], v[64:65], v[242:243], v[128:129]
	s_waitcnt vmcnt(6)
	s_barrier
	v_add_u32_e32 v204, 0xc000, v200
	v_add_u32_e32 v205, 0xc000, v202
	ds_read_b128 v[130:133], v204 offset:0
	ds_read_b128 v[134:137], v204 offset:2048
	ds_read_b128 v[138:141], v204 offset:4096
	ds_read_b128 v[142:145], v204 offset:6144
	ds_read_b128 v[146:149], v205 offset:0
	ds_read_b128 v[150:153], v205 offset:2048
	ds_read_b128 v[154:157], v205 offset:4096
	ds_read_b128 v[158:161], v205 offset:6144
	v_add_u32_e32 v204, 0xc000, v201
	v_add_u32_e32 v205, 0xc000, v203
	ds_read_b128 v[212:215], v204 offset:0
	ds_read_b128 v[216:219], v204 offset:2048
	ds_read_b128 v[220:223], v204 offset:4096
	ds_read_b128 v[224:227], v204 offset:6144
	ds_read_b128 v[228:231], v205 offset:0
	ds_read_b128 v[232:235], v205 offset:2048
	ds_read_b128 v[236:239], v205 offset:4096
	ds_read_b128 v[240:243], v205 offset:6144
	s_add_u32 m0, s76, 0x0
	s_nop 0
	global_load_lds_dwordx4 v196, s[68:69]
	s_add_u32 m0, s76, 0x2000
	s_nop 0
	global_load_lds_dwordx4 v197, s[68:69]
	s_add_u32 m0, s76, 0x4000
	s_nop 0
	global_load_lds_dwordx4 v198, s[68:69]
	s_add_u32 m0, s76, 0x6000
	s_nop 0
	global_load_lds_dwordx4 v199, s[68:69]
	s_add_u32 m0, s76, 0x8000
	s_nop 0
	global_load_lds_dwordx4 v196, s[70:71]
	s_add_u32 m0, s76, 0xa000
	s_nop 0
	global_load_lds_dwordx4 v197, s[70:71]
	s_add_u32 s68, s68, 0x80
	s_addc_u32 s69, s69, 0
	s_add_u32 s70, s70, 0x80
	s_addc_u32 s71, s71, 0
	global_load_dwordx2 v[174:175], v206, s[72:73] offset:0
	global_load_dwordx2 v[176:177], v206, s[72:73] offset:32
	global_load_dwordx2 v[178:179], v206, s[72:73] offset:64
	global_load_dwordx2 v[180:181], v206, s[72:73] offset:96
	global_load_dwordx2 v[182:183], v207, s[72:73] offset:0
	global_load_dwordx2 v[184:185], v207, s[72:73] offset:32
	s_waitcnt lgkmcnt(0)
	s_barrier
	s_setprio 1
	v_mfma_f32_16x16x32_bf16 v[2:5], v[146:149], v[130:133], 0
	v_mfma_f32_16x16x32_bf16 v[6:9], v[150:153], v[130:133], 0
	v_mfma_f32_16x16x32_bf16 v[10:13], v[154:157], v[130:133], 0
	v_mfma_f32_16x16x32_bf16 v[14:17], v[158:161], v[130:133], 0
	v_mfma_f32_16x16x32_bf16 v[18:21], v[146:149], v[134:137], 0
	v_mfma_f32_16x16x32_bf16 v[22:25], v[150:153], v[134:137], 0
	v_mfma_f32_16x16x32_bf16 v[26:29], v[154:157], v[134:137], 0
	v_mfma_f32_16x16x32_bf16 v[30:33], v[158:161], v[134:137], 0
	v_mfma_f32_16x16x32_bf16 v[34:37], v[146:149], v[138:141], 0
	v_mfma_f32_16x16x32_bf16 v[38:41], v[150:153], v[138:141], 0
	v_mfma_f32_16x16x32_bf16 v[42:45], v[154:157], v[138:141], 0
	v_mfma_f32_16x16x32_bf16 v[46:49], v[158:161], v[138:141], 0
	v_mfma_f32_16x16x32_bf16 v[50:53], v[146:149], v[142:145], 0
	v_mfma_f32_16x16x32_bf16 v[54:57], v[150:153], v[142:145], 0
	v_mfma_f32_16x16x32_bf16 v[58:61], v[154:157], v[142:145], 0
	v_mfma_f32_16x16x32_bf16 v[62:65], v[158:161], v[142:145], 0
	v_mfma_f32_16x16x32_bf16 v[2:5], v[228:231], v[212:215], v[2:5]
	v_mfma_f32_16x16x32_bf16 v[6:9], v[232:235], v[212:215], v[6:9]
	v_mfma_f32_16x16x32_bf16 v[10:13], v[236:239], v[212:215], v[10:13]
	v_mfma_f32_16x16x32_bf16 v[14:17], v[240:243], v[212:215], v[14:17]
	v_mfma_f32_16x16x32_bf16 v[18:21], v[228:231], v[216:219], v[18:21]
	v_mfma_f32_16x16x32_bf16 v[22:25], v[232:235], v[216:219], v[22:25]
	v_mfma_f32_16x16x32_bf16 v[26:29], v[236:239], v[216:219], v[26:29]
	v_mfma_f32_16x16x32_bf16 v[30:33], v[240:243], v[216:219], v[30:33]
	v_mfma_f32_16x16x32_bf16 v[34:37], v[228:231], v[220:223], v[34:37]
	v_mfma_f32_16x16x32_bf16 v[38:41], v[232:235], v[220:223], v[38:41]
	v_mfma_f32_16x16x32_bf16 v[42:45], v[236:239], v[220:223], v[42:45]
	v_mfma_f32_16x16x32_bf16 v[46:49], v[240:243], v[220:223], v[46:49]
	v_mfma_f32_16x16x32_bf16 v[50:53], v[228:231], v[224:227], v[50:53]
	v_mfma_f32_16x16x32_bf16 v[54:57], v[232:235], v[224:227], v[54:57]
	v_mfma_f32_16x16x32_bf16 v[58:61], v[236:239], v[224:227], v[58:61]
	v_mfma_f32_16x16x32_bf16 v[62:65], v[240:243], v[224:227], v[62:65]
	s_setprio 0
	s_waitcnt vmcnt(12)
	s_barrier
	v_add_u32_e32 v204, 0x18000, v200
	v_add_u32_e32 v205, 0x18000, v202
	ds_read_b128 v[130:133], v204 offset:0
	ds_read_b128 v[134:137], v204 offset:2048
	ds_read_b128 v[138:141], v204 offset:4096
	ds_read_b128 v[142:145], v204 offset:6144
	ds_read_b128 v[146:149], v205 offset:0
	ds_read_b128 v[150:153], v205 offset:2048
	ds_read_b128 v[154:157], v205 offset:4096
	ds_read_b128 v[158:161], v205 offset:6144
	v_add_u32_e32 v204, 0x18000, v201
	v_add_u32_e32 v205, 0x18000, v203
	ds_read_b128 v[212:215], v204 offset:0
	ds_read_b128 v[216:219], v204 offset:2048
	ds_read_b128 v[220:223], v204 offset:4096
	ds_read_b128 v[224:227], v204 offset:6144
	ds_read_b128 v[228:231], v205 offset:0
	ds_read_b128 v[232:235], v205 offset:2048
	ds_read_b128 v[236:239], v205 offset:4096
	ds_read_b128 v[240:243], v205 offset:6144
	s_add_u32 m0, s76, 0xc000
	s_nop 0
	global_load_lds_dwordx4 v196, s[68:69]
	s_add_u32 m0, s76, 0xe000
	s_nop 0
	global_load_lds_dwordx4 v197, s[68:69]
	s_add_u32 m0, s76, 0x10000
	s_nop 0
	global_load_lds_dwordx4 v198, s[68:69]
	s_add_u32 m0, s76, 0x12000
	s_nop 0
	global_load_lds_dwordx4 v199, s[68:69]
	s_add_u32 m0, s76, 0x14000
	s_nop 0
	global_load_lds_dwordx4 v196, s[70:71]
	s_add_u32 m0, s76, 0x16000
	s_nop 0
	global_load_lds_dwordx4 v197, s[70:71]
	s_add_u32 s68, s68, 0x80
	s_addc_u32 s69, s69, 0
	s_add_u32 s70, s70, 0x80
	s_addc_u32 s71, s71, 0
	global_load_dwordx2 v[186:187], v207, s[72:73] offset:64
	global_load_dwordx2 v[188:189], v207, s[72:73] offset:96
	global_load_dwordx2 v[190:191], v208, s[72:73] offset:0
	global_load_dwordx2 v[192:193], v208, s[72:73] offset:32
	global_load_dwordx2 v[244:245], v208, s[72:73] offset:64
	global_load_dwordx2 v[246:247], v208, s[72:73] offset:96
	s_waitcnt lgkmcnt(0)
	s_barrier
	s_setprio 1
	v_mfma_f32_16x16x32_bf16 v[2:5], v[146:149], v[130:133], v[2:5]
	v_mfma_f32_16x16x32_bf16 v[6:9], v[150:153], v[130:133], v[6:9]
	v_mfma_f32_16x16x32_bf16 v[10:13], v[154:157], v[130:133], v[10:13]
	v_mfma_f32_16x16x32_bf16 v[14:17], v[158:161], v[130:133], v[14:17]
	v_mfma_f32_16x16x32_bf16 v[18:21], v[146:149], v[134:137], v[18:21]
	v_mfma_f32_16x16x32_bf16 v[22:25], v[150:153], v[134:137], v[22:25]
	v_mfma_f32_16x16x32_bf16 v[26:29], v[154:157], v[134:137], v[26:29]
	v_mfma_f32_16x16x32_bf16 v[30:33], v[158:161], v[134:137], v[30:33]
	v_mfma_f32_16x16x32_bf16 v[34:37], v[146:149], v[138:141], v[34:37]
	v_mfma_f32_16x16x32_bf16 v[38:41], v[150:153], v[138:141], v[38:41]
	v_mfma_f32_16x16x32_bf16 v[42:45], v[154:157], v[138:141], v[42:45]
	v_mfma_f32_16x16x32_bf16 v[46:49], v[158:161], v[138:141], v[46:49]
	v_mfma_f32_16x16x32_bf16 v[50:53], v[146:149], v[142:145], v[50:53]
	v_mfma_f32_16x16x32_bf16 v[54:57], v[150:153], v[142:145], v[54:57]
	v_mfma_f32_16x16x32_bf16 v[58:61], v[154:157], v[142:145], v[58:61]
	v_mfma_f32_16x16x32_bf16 v[62:65], v[158:161], v[142:145], v[62:65]
	v_mfma_f32_16x16x32_bf16 v[2:5], v[228:231], v[212:215], v[2:5]
	v_mfma_f32_16x16x32_bf16 v[6:9], v[232:235], v[212:215], v[6:9]
	v_mfma_f32_16x16x32_bf16 v[10:13], v[236:239], v[212:215], v[10:13]
	v_mfma_f32_16x16x32_bf16 v[14:17], v[240:243], v[212:215], v[14:17]
	v_mfma_f32_16x16x32_bf16 v[18:21], v[228:231], v[216:219], v[18:21]
	v_mfma_f32_16x16x32_bf16 v[22:25], v[232:235], v[216:219], v[22:25]
	v_mfma_f32_16x16x32_bf16 v[26:29], v[236:239], v[216:219], v[26:29]
	v_mfma_f32_16x16x32_bf16 v[30:33], v[240:243], v[216:219], v[30:33]
	v_mfma_f32_16x16x32_bf16 v[34:37], v[228:231], v[220:223], v[34:37]
	v_mfma_f32_16x16x32_bf16 v[38:41], v[232:235], v[220:223], v[38:41]
	v_mfma_f32_16x16x32_bf16 v[42:45], v[236:239], v[220:223], v[42:45]
	v_mfma_f32_16x16x32_bf16 v[46:49], v[240:243], v[220:223], v[46:49]
	v_mfma_f32_16x16x32_bf16 v[50:53], v[228:231], v[224:227], v[50:53]
	v_mfma_f32_16x16x32_bf16 v[54:57], v[232:235], v[224:227], v[54:57]
	v_mfma_f32_16x16x32_bf16 v[58:61], v[236:239], v[224:227], v[58:61]
	v_mfma_f32_16x16x32_bf16 v[62:65], v[240:243], v[224:227], v[62:65]
	s_setprio 0
	s_waitcnt vmcnt(18)
	s_barrier
	v_add_u32_e32 v204, 0x0, v200
	v_add_u32_e32 v205, 0x0, v202
	ds_read_b128 v[130:133], v204 offset:0
	ds_read_b128 v[134:137], v204 offset:2048
	ds_read_b128 v[138:141], v204 offset:4096
	ds_read_b128 v[142:145], v204 offset:6144
	ds_read_b128 v[146:149], v205 offset:0
	ds_read_b128 v[150:153], v205 offset:2048
	ds_read_b128 v[154:157], v205 offset:4096
	ds_read_b128 v[158:161], v205 offset:6144
	v_add_u32_e32 v204, 0x0, v201
	v_add_u32_e32 v205, 0x0, v203
	ds_read_b128 v[212:215], v204 offset:0
	ds_read_b128 v[216:219], v204 offset:2048
	ds_read_b128 v[220:223], v204 offset:4096
	ds_read_b128 v[224:227], v204 offset:6144
	ds_read_b128 v[228:231], v205 offset:0
	ds_read_b128 v[232:235], v205 offset:2048
	ds_read_b128 v[236:239], v205 offset:4096
	ds_read_b128 v[240:243], v205 offset:6144
	s_add_u32 m0, s76, 0x18000
	s_nop 0
	global_load_lds_dwordx4 v196, s[68:69]
	s_add_u32 m0, s76, 0x1a000
	s_nop 0
	global_load_lds_dwordx4 v197, s[68:69]
	s_add_u32 m0, s76, 0x1c000
	s_nop 0
	global_load_lds_dwordx4 v198, s[68:69]
	s_add_u32 m0, s76, 0x1e000
	s_nop 0
	global_load_lds_dwordx4 v199, s[68:69]
	s_add_u32 m0, s76, 0x20000
	s_nop 0
	global_load_lds_dwordx4 v196, s[70:71]
	s_add_u32 m0, s76, 0x22000
	s_nop 0
	global_load_lds_dwordx4 v197, s[70:71]
	s_add_u32 s68, s68, 0x80
	s_addc_u32 s69, s69, 0
	s_add_u32 s70, s70, 0x80
	s_addc_u32 s71, s71, 0
	global_load_dwordx2 v[248:249], v209, s[72:73] offset:0
	global_load_dwordx2 v[250:251], v209, s[72:73] offset:32
	global_load_dwordx2 v[166:167], v209, s[72:73] offset:64
	global_load_dwordx2 v[194:195], v209, s[72:73] offset:96
	s_add_u32 s72, s72, 0x800
	s_addc_u32 s73, s73, 0
	s_waitcnt lgkmcnt(0)
	s_barrier
	s_setprio 1
	v_mfma_f32_16x16x32_bf16 v[2:5], v[146:149], v[130:133], v[2:5]
	v_mfma_f32_16x16x32_bf16 v[6:9], v[150:153], v[130:133], v[6:9]
	v_mfma_f32_16x16x32_bf16 v[10:13], v[154:157], v[130:133], v[10:13]
	v_mfma_f32_16x16x32_bf16 v[14:17], v[158:161], v[130:133], v[14:17]
	v_mfma_f32_16x16x32_bf16 v[18:21], v[146:149], v[134:137], v[18:21]
	v_mfma_f32_16x16x32_bf16 v[22:25], v[150:153], v[134:137], v[22:25]
	v_mfma_f32_16x16x32_bf16 v[26:29], v[154:157], v[134:137], v[26:29]
	v_mfma_f32_16x16x32_bf16 v[30:33], v[158:161], v[134:137], v[30:33]
	v_mfma_f32_16x16x32_bf16 v[34:37], v[146:149], v[138:141], v[34:37]
	v_mfma_f32_16x16x32_bf16 v[38:41], v[150:153], v[138:141], v[38:41]
	v_mfma_f32_16x16x32_bf16 v[42:45], v[154:157], v[138:141], v[42:45]
	v_mfma_f32_16x16x32_bf16 v[46:49], v[158:161], v[138:141], v[46:49]
	v_mfma_f32_16x16x32_bf16 v[50:53], v[146:149], v[142:145], v[50:53]
	v_mfma_f32_16x16x32_bf16 v[54:57], v[150:153], v[142:145], v[54:57]
	v_mfma_f32_16x16x32_bf16 v[58:61], v[154:157], v[142:145], v[58:61]
	v_mfma_f32_16x16x32_bf16 v[62:65], v[158:161], v[142:145], v[62:65]
	v_mfma_f32_16x16x32_bf16 v[2:5], v[228:231], v[212:215], v[2:5]
	v_mfma_f32_16x16x32_bf16 v[6:9], v[232:235], v[212:215], v[6:9]
	v_mfma_f32_16x16x32_bf16 v[10:13], v[236:239], v[212:215], v[10:13]
	v_mfma_f32_16x16x32_bf16 v[14:17], v[240:243], v[212:215], v[14:17]
	v_mfma_f32_16x16x32_bf16 v[18:21], v[228:231], v[216:219], v[18:21]
	v_mfma_f32_16x16x32_bf16 v[22:25], v[232:235], v[216:219], v[22:25]
	v_mfma_f32_16x16x32_bf16 v[26:29], v[236:239], v[216:219], v[26:29]
	v_mfma_f32_16x16x32_bf16 v[30:33], v[240:243], v[216:219], v[30:33]
	v_mfma_f32_16x16x32_bf16 v[34:37], v[228:231], v[220:223], v[34:37]
	v_mfma_f32_16x16x32_bf16 v[38:41], v[232:235], v[220:223], v[38:41]
	v_mfma_f32_16x16x32_bf16 v[42:45], v[236:239], v[220:223], v[42:45]
	v_mfma_f32_16x16x32_bf16 v[46:49], v[240:243], v[220:223], v[46:49]
	v_mfma_f32_16x16x32_bf16 v[50:53], v[228:231], v[224:227], v[50:53]
	v_mfma_f32_16x16x32_bf16 v[54:57], v[232:235], v[224:227], v[54:57]
	v_mfma_f32_16x16x32_bf16 v[58:61], v[236:239], v[224:227], v[58:61]
	v_mfma_f32_16x16x32_bf16 v[62:65], v[240:243], v[224:227], v[62:65]
	s_setprio 0
	s_waitcnt vmcnt(16)
	s_barrier
	v_add_u32_e32 v204, 0xc000, v200
	v_add_u32_e32 v205, 0xc000, v202
	ds_read_b128 v[130:133], v204 offset:0
	ds_read_b128 v[134:137], v204 offset:2048
	ds_read_b128 v[138:141], v204 offset:4096
	ds_read_b128 v[142:145], v204 offset:6144
	ds_read_b128 v[146:149], v205 offset:0
	ds_read_b128 v[150:153], v205 offset:2048
	ds_read_b128 v[154:157], v205 offset:4096
	ds_read_b128 v[158:161], v205 offset:6144
	v_add_u32_e32 v204, 0xc000, v201
	v_add_u32_e32 v205, 0xc000, v203
	ds_read_b128 v[212:215], v204 offset:0
	ds_read_b128 v[216:219], v204 offset:2048
	ds_read_b128 v[220:223], v204 offset:4096
	ds_read_b128 v[224:227], v204 offset:6144
	ds_read_b128 v[228:231], v205 offset:0
	ds_read_b128 v[232:235], v205 offset:2048
	ds_read_b128 v[236:239], v205 offset:4096
	ds_read_b128 v[240:243], v205 offset:6144
	s_add_u32 m0, s76, 0x0
	s_nop 0
	global_load_lds_dwordx4 v196, s[68:69]
	s_add_u32 m0, s76, 0x2000
	s_nop 0
	global_load_lds_dwordx4 v197, s[68:69]
	s_add_u32 m0, s76, 0x4000
	s_nop 0
	global_load_lds_dwordx4 v198, s[68:69]
	s_add_u32 m0, s76, 0x6000
	s_nop 0
	global_load_lds_dwordx4 v199, s[68:69]
	s_add_u32 m0, s76, 0x8000
	s_nop 0
	global_load_lds_dwordx4 v196, s[70:71]
	s_add_u32 m0, s76, 0xa000
	s_nop 0
	global_load_lds_dwordx4 v197, s[70:71]
	s_add_u32 s68, s68, 0x80
	s_addc_u32 s69, s69, 0
	s_add_u32 s70, s70, 0x80
	s_addc_u32 s71, s71, 0
	s_waitcnt lgkmcnt(0)
	s_barrier
	s_setprio 1
	v_mfma_f32_16x16x32_bf16 v[2:5], v[146:149], v[130:133], v[2:5]
	v_mfma_f32_16x16x32_bf16 v[6:9], v[150:153], v[130:133], v[6:9]
	v_mfma_f32_16x16x32_bf16 v[10:13], v[154:157], v[130:133], v[10:13]
	v_mfma_f32_16x16x32_bf16 v[14:17], v[158:161], v[130:133], v[14:17]
	v_mfma_f32_16x16x32_bf16 v[18:21], v[146:149], v[134:137], v[18:21]
	v_mfma_f32_16x16x32_bf16 v[22:25], v[150:153], v[134:137], v[22:25]
	v_mfma_f32_16x16x32_bf16 v[26:29], v[154:157], v[134:137], v[26:29]
	v_mfma_f32_16x16x32_bf16 v[30:33], v[158:161], v[134:137], v[30:33]
	v_mfma_f32_16x16x32_bf16 v[34:37], v[146:149], v[138:141], v[34:37]
	v_mfma_f32_16x16x32_bf16 v[38:41], v[150:153], v[138:141], v[38:41]
	v_mfma_f32_16x16x32_bf16 v[42:45], v[154:157], v[138:141], v[42:45]
	v_mfma_f32_16x16x32_bf16 v[46:49], v[158:161], v[138:141], v[46:49]
	v_mfma_f32_16x16x32_bf16 v[50:53], v[146:149], v[142:145], v[50:53]
	v_mfma_f32_16x16x32_bf16 v[54:57], v[150:153], v[142:145], v[54:57]
	v_mfma_f32_16x16x32_bf16 v[58:61], v[154:157], v[142:145], v[58:61]
	v_mfma_f32_16x16x32_bf16 v[62:65], v[158:161], v[142:145], v[62:65]
	v_mfma_f32_16x16x32_bf16 v[2:5], v[228:231], v[212:215], v[2:5]
	v_mfma_f32_16x16x32_bf16 v[6:9], v[232:235], v[212:215], v[6:9]
	v_mfma_f32_16x16x32_bf16 v[10:13], v[236:239], v[212:215], v[10:13]
	v_mfma_f32_16x16x32_bf16 v[14:17], v[240:243], v[212:215], v[14:17]
	v_mfma_f32_16x16x32_bf16 v[18:21], v[228:231], v[216:219], v[18:21]
	v_mfma_f32_16x16x32_bf16 v[22:25], v[232:235], v[216:219], v[22:25]
	v_mfma_f32_16x16x32_bf16 v[26:29], v[236:239], v[216:219], v[26:29]
	v_mfma_f32_16x16x32_bf16 v[30:33], v[240:243], v[216:219], v[30:33]
	v_mfma_f32_16x16x32_bf16 v[34:37], v[228:231], v[220:223], v[34:37]
	v_mfma_f32_16x16x32_bf16 v[38:41], v[232:235], v[220:223], v[38:41]
	v_mfma_f32_16x16x32_bf16 v[42:45], v[236:239], v[220:223], v[42:45]
	v_mfma_f32_16x16x32_bf16 v[46:49], v[240:243], v[220:223], v[46:49]
	v_mfma_f32_16x16x32_bf16 v[50:53], v[228:231], v[224:227], v[50:53]
	v_mfma_f32_16x16x32_bf16 v[54:57], v[232:235], v[224:227], v[54:57]
	v_mfma_f32_16x16x32_bf16 v[58:61], v[236:239], v[224:227], v[58:61]
	v_mfma_f32_16x16x32_bf16 v[62:65], v[240:243], v[224:227], v[62:65]
	s_setprio 0
	s_waitcnt vmcnt(10)
	s_barrier
	v_add_u32_e32 v204, 0x18000, v200
	v_add_u32_e32 v205, 0x18000, v202
	ds_read_b128 v[130:133], v204 offset:0
	ds_read_b128 v[134:137], v204 offset:2048
	ds_read_b128 v[138:141], v204 offset:4096
	ds_read_b128 v[142:145], v204 offset:6144
	ds_read_b128 v[146:149], v205 offset:0
	ds_read_b128 v[150:153], v205 offset:2048
	ds_read_b128 v[154:157], v205 offset:4096
	ds_read_b128 v[158:161], v205 offset:6144
	v_add_u32_e32 v204, 0x18000, v201
	v_add_u32_e32 v205, 0x18000, v203
	ds_read_b128 v[212:215], v204 offset:0
	ds_read_b128 v[216:219], v204 offset:2048
	ds_read_b128 v[220:223], v204 offset:4096
	ds_read_b128 v[224:227], v204 offset:6144
	ds_read_b128 v[228:231], v205 offset:0
	ds_read_b128 v[232:235], v205 offset:2048
	ds_read_b128 v[236:239], v205 offset:4096
	ds_read_b128 v[240:243], v205 offset:6144
	s_add_u32 m0, s76, 0xc000
	s_nop 0
	global_load_lds_dwordx4 v196, s[68:69]
	s_add_u32 m0, s76, 0xe000
	s_nop 0
	global_load_lds_dwordx4 v197, s[68:69]
	s_add_u32 m0, s76, 0x10000
	s_nop 0
	global_load_lds_dwordx4 v198, s[68:69]
	s_add_u32 m0, s76, 0x12000
	s_nop 0
	global_load_lds_dwordx4 v199, s[68:69]
	s_add_u32 m0, s76, 0x14000
	s_nop 0
	global_load_lds_dwordx4 v196, s[70:71]
	s_add_u32 m0, s76, 0x16000
	s_nop 0
	global_load_lds_dwordx4 v197, s[70:71]
	s_add_u32 s68, s68, 0x80
	s_addc_u32 s69, s69, 0
	s_add_u32 s70, s70, 0x80
	s_addc_u32 s71, s71, 0
	s_waitcnt lgkmcnt(0)
	s_barrier
	s_setprio 1
	v_mfma_f32_16x16x32_bf16 v[2:5], v[146:149], v[130:133], v[2:5]
	v_mfma_f32_16x16x32_bf16 v[6:9], v[150:153], v[130:133], v[6:9]
	v_mfma_f32_16x16x32_bf16 v[10:13], v[154:157], v[130:133], v[10:13]
	v_mfma_f32_16x16x32_bf16 v[14:17], v[158:161], v[130:133], v[14:17]
	v_mfma_f32_16x16x32_bf16 v[18:21], v[146:149], v[134:137], v[18:21]
	v_mfma_f32_16x16x32_bf16 v[22:25], v[150:153], v[134:137], v[22:25]
	v_mfma_f32_16x16x32_bf16 v[26:29], v[154:157], v[134:137], v[26:29]
	v_mfma_f32_16x16x32_bf16 v[30:33], v[158:161], v[134:137], v[30:33]
	v_mfma_f32_16x16x32_bf16 v[34:37], v[146:149], v[138:141], v[34:37]
	v_mfma_f32_16x16x32_bf16 v[38:41], v[150:153], v[138:141], v[38:41]
	v_mfma_f32_16x16x32_bf16 v[42:45], v[154:157], v[138:141], v[42:45]
	v_mfma_f32_16x16x32_bf16 v[46:49], v[158:161], v[138:141], v[46:49]
	v_mfma_f32_16x16x32_bf16 v[50:53], v[146:149], v[142:145], v[50:53]
	v_mfma_f32_16x16x32_bf16 v[54:57], v[150:153], v[142:145], v[54:57]
	v_mfma_f32_16x16x32_bf16 v[58:61], v[154:157], v[142:145], v[58:61]
	v_mfma_f32_16x16x32_bf16 v[62:65], v[158:161], v[142:145], v[62:65]
	v_mfma_f32_16x16x32_bf16 v[2:5], v[228:231], v[212:215], v[2:5]
	v_mfma_f32_16x16x32_bf16 v[6:9], v[232:235], v[212:215], v[6:9]
	v_mfma_f32_16x16x32_bf16 v[10:13], v[236:239], v[212:215], v[10:13]
	v_mfma_f32_16x16x32_bf16 v[14:17], v[240:243], v[212:215], v[14:17]
	v_mfma_f32_16x16x32_bf16 v[18:21], v[228:231], v[216:219], v[18:21]
	v_mfma_f32_16x16x32_bf16 v[22:25], v[232:235], v[216:219], v[22:25]
	v_mfma_f32_16x16x32_bf16 v[26:29], v[236:239], v[216:219], v[26:29]
	v_mfma_f32_16x16x32_bf16 v[30:33], v[240:243], v[216:219], v[30:33]
	v_mfma_f32_16x16x32_bf16 v[34:37], v[228:231], v[220:223], v[34:37]
	v_mfma_f32_16x16x32_bf16 v[38:41], v[232:235], v[220:223], v[38:41]
	v_mfma_f32_16x16x32_bf16 v[42:45], v[236:239], v[220:223], v[42:45]
	v_mfma_f32_16x16x32_bf16 v[46:49], v[240:243], v[220:223], v[46:49]
	v_mfma_f32_16x16x32_bf16 v[50:53], v[228:231], v[224:227], v[50:53]
	v_mfma_f32_16x16x32_bf16 v[54:57], v[232:235], v[224:227], v[54:57]
	v_mfma_f32_16x16x32_bf16 v[58:61], v[236:239], v[224:227], v[58:61]
	v_mfma_f32_16x16x32_bf16 v[62:65], v[240:243], v[224:227], v[62:65]
	s_setprio 0
	s_waitcnt vmcnt(6)
	s_barrier
	v_add_u32_e32 v204, 0x0, v200
	v_add_u32_e32 v205, 0x0, v202
	ds_read_b128 v[130:133], v204 offset:0
	ds_read_b128 v[134:137], v204 offset:2048
	ds_read_b128 v[138:141], v204 offset:4096
	ds_read_b128 v[142:145], v204 offset:6144
	ds_read_b128 v[146:149], v205 offset:0
	ds_read_b128 v[150:153], v205 offset:2048
	ds_read_b128 v[154:157], v205 offset:4096
	ds_read_b128 v[158:161], v205 offset:6144
	v_add_u32_e32 v204, 0x0, v201
	v_add_u32_e32 v205, 0x0, v203
	ds_read_b128 v[212:215], v204 offset:0
	ds_read_b128 v[216:219], v204 offset:2048
	ds_read_b128 v[220:223], v204 offset:4096
	ds_read_b128 v[224:227], v204 offset:6144
	ds_read_b128 v[228:231], v205 offset:0
	ds_read_b128 v[232:235], v205 offset:2048
	ds_read_b128 v[236:239], v205 offset:4096
	ds_read_b128 v[240:243], v205 offset:6144
	s_add_u32 m0, s76, 0x18000
	s_nop 0
	global_load_lds_dwordx4 v196, s[68:69]
	s_add_u32 m0, s76, 0x1a000
	s_nop 0
	global_load_lds_dwordx4 v197, s[68:69]
	s_add_u32 m0, s76, 0x1c000
	s_nop 0
	global_load_lds_dwordx4 v198, s[68:69]
	s_add_u32 m0, s76, 0x1e000
	s_nop 0
	global_load_lds_dwordx4 v199, s[68:69]
	s_add_u32 m0, s76, 0x20000
	s_nop 0
	global_load_lds_dwordx4 v196, s[70:71]
	s_add_u32 m0, s76, 0x22000
	s_nop 0
	global_load_lds_dwordx4 v197, s[70:71]
	s_add_u32 s68, s68, 0x80
	s_addc_u32 s69, s69, 0
	s_add_u32 s70, s70, 0x80
	s_addc_u32 s71, s71, 0
	s_waitcnt lgkmcnt(0)
	s_barrier
	s_setprio 1
	v_mfma_f32_16x16x32_bf16 v[2:5], v[146:149], v[130:133], v[2:5]
	v_mfma_f32_16x16x32_bf16 v[6:9], v[150:153], v[130:133], v[6:9]
	v_mfma_f32_16x16x32_bf16 v[10:13], v[154:157], v[130:133], v[10:13]
	v_mfma_f32_16x16x32_bf16 v[14:17], v[158:161], v[130:133], v[14:17]
	v_mfma_f32_16x16x32_bf16 v[18:21], v[146:149], v[134:137], v[18:21]
	v_mfma_f32_16x16x32_bf16 v[22:25], v[150:153], v[134:137], v[22:25]
	v_mfma_f32_16x16x32_bf16 v[26:29], v[154:157], v[134:137], v[26:29]
	v_mfma_f32_16x16x32_bf16 v[30:33], v[158:161], v[134:137], v[30:33]
	v_mfma_f32_16x16x32_bf16 v[34:37], v[146:149], v[138:141], v[34:37]
	v_mfma_f32_16x16x32_bf16 v[38:41], v[150:153], v[138:141], v[38:41]
	v_mfma_f32_16x16x32_bf16 v[42:45], v[154:157], v[138:141], v[42:45]
	v_mfma_f32_16x16x32_bf16 v[46:49], v[158:161], v[138:141], v[46:49]
	v_mfma_f32_16x16x32_bf16 v[50:53], v[146:149], v[142:145], v[50:53]
	v_mfma_f32_16x16x32_bf16 v[54:57], v[150:153], v[142:145], v[54:57]
	v_mfma_f32_16x16x32_bf16 v[58:61], v[154:157], v[142:145], v[58:61]
	v_mfma_f32_16x16x32_bf16 v[62:65], v[158:161], v[142:145], v[62:65]
	v_mfma_f32_16x16x32_bf16 v[2:5], v[228:231], v[212:215], v[2:5]
	v_mfma_f32_16x16x32_bf16 v[6:9], v[232:235], v[212:215], v[6:9]
	v_mfma_f32_16x16x32_bf16 v[10:13], v[236:239], v[212:215], v[10:13]
	v_mfma_f32_16x16x32_bf16 v[14:17], v[240:243], v[212:215], v[14:17]
	v_mfma_f32_16x16x32_bf16 v[18:21], v[228:231], v[216:219], v[18:21]
	v_mfma_f32_16x16x32_bf16 v[22:25], v[232:235], v[216:219], v[22:25]
	v_mfma_f32_16x16x32_bf16 v[26:29], v[236:239], v[216:219], v[26:29]
	v_mfma_f32_16x16x32_bf16 v[30:33], v[240:243], v[216:219], v[30:33]
	v_mfma_f32_16x16x32_bf16 v[34:37], v[228:231], v[220:223], v[34:37]
	v_mfma_f32_16x16x32_bf16 v[38:41], v[232:235], v[220:223], v[38:41]
	v_mfma_f32_16x16x32_bf16 v[42:45], v[236:239], v[220:223], v[42:45]
	v_mfma_f32_16x16x32_bf16 v[46:49], v[240:243], v[220:223], v[46:49]
	v_mfma_f32_16x16x32_bf16 v[50:53], v[228:231], v[224:227], v[50:53]
	v_mfma_f32_16x16x32_bf16 v[54:57], v[232:235], v[224:227], v[54:57]
	v_mfma_f32_16x16x32_bf16 v[58:61], v[236:239], v[224:227], v[58:61]
	v_mfma_f32_16x16x32_bf16 v[62:65], v[240:243], v[224:227], v[62:65]
	s_setprio 0
	s_waitcnt vmcnt(6)
	s_barrier
	v_add_u32_e32 v204, 0xc000, v200
	v_add_u32_e32 v205, 0xc000, v202
	ds_read_b128 v[130:133], v204 offset:0
	ds_read_b128 v[134:137], v204 offset:2048
	ds_read_b128 v[138:141], v204 offset:4096
	ds_read_b128 v[142:145], v204 offset:6144
	ds_read_b128 v[146:149], v205 offset:0
	ds_read_b128 v[150:153], v205 offset:2048
	ds_read_b128 v[154:157], v205 offset:4096
	ds_read_b128 v[158:161], v205 offset:6144
	v_add_u32_e32 v204, 0xc000, v201
	v_add_u32_e32 v205, 0xc000, v203
	ds_read_b128 v[212:215], v204 offset:0
	ds_read_b128 v[216:219], v204 offset:2048
	ds_read_b128 v[220:223], v204 offset:4096
	ds_read_b128 v[224:227], v204 offset:6144
	ds_read_b128 v[228:231], v205 offset:0
	ds_read_b128 v[232:235], v205 offset:2048
	ds_read_b128 v[236:239], v205 offset:4096
	ds_read_b128 v[240:243], v205 offset:6144
	s_waitcnt lgkmcnt(0)
	s_barrier
	s_setprio 1
	v_mfma_f32_16x16x32_bf16 v[2:5], v[146:149], v[130:133], v[2:5]
	v_mfma_f32_16x16x32_bf16 v[6:9], v[150:153], v[130:133], v[6:9]
	v_mfma_f32_16x16x32_bf16 v[10:13], v[154:157], v[130:133], v[10:13]
	v_mfma_f32_16x16x32_bf16 v[14:17], v[158:161], v[130:133], v[14:17]
	v_mfma_f32_16x16x32_bf16 v[18:21], v[146:149], v[134:137], v[18:21]
	v_mfma_f32_16x16x32_bf16 v[22:25], v[150:153], v[134:137], v[22:25]
	v_mfma_f32_16x16x32_bf16 v[26:29], v[154:157], v[134:137], v[26:29]
	v_mfma_f32_16x16x32_bf16 v[30:33], v[158:161], v[134:137], v[30:33]
	v_mfma_f32_16x16x32_bf16 v[34:37], v[146:149], v[138:141], v[34:37]
	v_mfma_f32_16x16x32_bf16 v[38:41], v[150:153], v[138:141], v[38:41]
	v_mfma_f32_16x16x32_bf16 v[42:45], v[154:157], v[138:141], v[42:45]
	v_mfma_f32_16x16x32_bf16 v[46:49], v[158:161], v[138:141], v[46:49]
	v_mfma_f32_16x16x32_bf16 v[50:53], v[146:149], v[142:145], v[50:53]
	v_mfma_f32_16x16x32_bf16 v[54:57], v[150:153], v[142:145], v[54:57]
	v_mfma_f32_16x16x32_bf16 v[58:61], v[154:157], v[142:145], v[58:61]
	v_mfma_f32_16x16x32_bf16 v[62:65], v[158:161], v[142:145], v[62:65]
	v_mfma_f32_16x16x32_bf16 v[2:5], v[228:231], v[212:215], v[2:5]
	v_mfma_f32_16x16x32_bf16 v[6:9], v[232:235], v[212:215], v[6:9]
	v_mfma_f32_16x16x32_bf16 v[10:13], v[236:239], v[212:215], v[10:13]
	v_mfma_f32_16x16x32_bf16 v[14:17], v[240:243], v[212:215], v[14:17]
	v_mfma_f32_16x16x32_bf16 v[18:21], v[228:231], v[216:219], v[18:21]
	v_mfma_f32_16x16x32_bf16 v[22:25], v[232:235], v[216:219], v[22:25]
	v_mfma_f32_16x16x32_bf16 v[26:29], v[236:239], v[216:219], v[26:29]
	v_mfma_f32_16x16x32_bf16 v[30:33], v[240:243], v[216:219], v[30:33]
	v_mfma_f32_16x16x32_bf16 v[34:37], v[228:231], v[220:223], v[34:37]
	v_mfma_f32_16x16x32_bf16 v[38:41], v[232:235], v[220:223], v[38:41]
	v_mfma_f32_16x16x32_bf16 v[42:45], v[236:239], v[220:223], v[42:45]
	v_mfma_f32_16x16x32_bf16 v[46:49], v[240:243], v[220:223], v[46:49]
	v_mfma_f32_16x16x32_bf16 v[50:53], v[228:231], v[224:227], v[50:53]
	v_mfma_f32_16x16x32_bf16 v[54:57], v[232:235], v[224:227], v[54:57]
	v_mfma_f32_16x16x32_bf16 v[58:61], v[236:239], v[224:227], v[58:61]
	v_mfma_f32_16x16x32_bf16 v[62:65], v[240:243], v[224:227], v[62:65]
	s_setprio 0
	s_waitcnt vmcnt(0)
	s_barrier
	v_add_u32_e32 v204, 0x18000, v200
	v_add_u32_e32 v205, 0x18000, v202
	ds_read_b128 v[130:133], v204 offset:0
	ds_read_b128 v[134:137], v204 offset:2048
	ds_read_b128 v[138:141], v204 offset:4096
	ds_read_b128 v[142:145], v204 offset:6144
	ds_read_b128 v[146:149], v205 offset:0
	ds_read_b128 v[150:153], v205 offset:2048
	ds_read_b128 v[154:157], v205 offset:4096
	ds_read_b128 v[158:161], v205 offset:6144
	v_add_u32_e32 v204, 0x18000, v201
	v_add_u32_e32 v205, 0x18000, v203
	ds_read_b128 v[212:215], v204 offset:0
	ds_read_b128 v[216:219], v204 offset:2048
	ds_read_b128 v[220:223], v204 offset:4096
	ds_read_b128 v[224:227], v204 offset:6144
	ds_read_b128 v[228:231], v205 offset:0
	ds_read_b128 v[232:235], v205 offset:2048
	ds_read_b128 v[236:239], v205 offset:4096
	ds_read_b128 v[240:243], v205 offset:6144
	s_waitcnt lgkmcnt(0)
	s_barrier
	s_setprio 1
	v_mfma_f32_16x16x32_bf16 v[2:5], v[146:149], v[130:133], v[2:5]
	v_mfma_f32_16x16x32_bf16 v[6:9], v[150:153], v[130:133], v[6:9]
	v_mfma_f32_16x16x32_bf16 v[10:13], v[154:157], v[130:133], v[10:13]
	v_mfma_f32_16x16x32_bf16 v[14:17], v[158:161], v[130:133], v[14:17]
	v_mfma_f32_16x16x32_bf16 v[18:21], v[146:149], v[134:137], v[18:21]
	v_mfma_f32_16x16x32_bf16 v[22:25], v[150:153], v[134:137], v[22:25]
	v_mfma_f32_16x16x32_bf16 v[26:29], v[154:157], v[134:137], v[26:29]
	v_mfma_f32_16x16x32_bf16 v[30:33], v[158:161], v[134:137], v[30:33]
	v_mfma_f32_16x16x32_bf16 v[34:37], v[146:149], v[138:141], v[34:37]
	v_mfma_f32_16x16x32_bf16 v[38:41], v[150:153], v[138:141], v[38:41]
	v_mfma_f32_16x16x32_bf16 v[42:45], v[154:157], v[138:141], v[42:45]
	v_mfma_f32_16x16x32_bf16 v[46:49], v[158:161], v[138:141], v[46:49]
	v_mfma_f32_16x16x32_bf16 v[50:53], v[146:149], v[142:145], v[50:53]
	v_mfma_f32_16x16x32_bf16 v[54:57], v[150:153], v[142:145], v[54:57]
	v_mfma_f32_16x16x32_bf16 v[58:61], v[154:157], v[142:145], v[58:61]
	v_mfma_f32_16x16x32_bf16 v[62:65], v[158:161], v[142:145], v[62:65]
	v_mfma_f32_16x16x32_bf16 v[2:5], v[228:231], v[212:215], v[2:5]
	v_mfma_f32_16x16x32_bf16 v[6:9], v[232:235], v[212:215], v[6:9]
	v_mfma_f32_16x16x32_bf16 v[10:13], v[236:239], v[212:215], v[10:13]
	v_mfma_f32_16x16x32_bf16 v[14:17], v[240:243], v[212:215], v[14:17]
	v_mfma_f32_16x16x32_bf16 v[18:21], v[228:231], v[216:219], v[18:21]
	v_mfma_f32_16x16x32_bf16 v[22:25], v[232:235], v[216:219], v[22:25]
	v_mfma_f32_16x16x32_bf16 v[26:29], v[236:239], v[216:219], v[26:29]
	v_mfma_f32_16x16x32_bf16 v[30:33], v[240:243], v[216:219], v[30:33]
	v_mfma_f32_16x16x32_bf16 v[34:37], v[228:231], v[220:223], v[34:37]
	v_mfma_f32_16x16x32_bf16 v[38:41], v[232:235], v[220:223], v[38:41]
	v_mfma_f32_16x16x32_bf16 v[42:45], v[236:239], v[220:223], v[42:45]
	v_mfma_f32_16x16x32_bf16 v[46:49], v[240:243], v[220:223], v[46:49]
	v_mfma_f32_16x16x32_bf16 v[50:53], v[228:231], v[224:227], v[50:53]
	v_mfma_f32_16x16x32_bf16 v[54:57], v[232:235], v[224:227], v[54:57]
	v_mfma_f32_16x16x32_bf16 v[58:61], v[236:239], v[224:227], v[58:61]
	v_mfma_f32_16x16x32_bf16 v[62:65], v[240:243], v[224:227], v[62:65]
	s_setprio 0
	s_nop 7
	v_lshlrev_b32_e32 v212, 16, v174
	v_and_b32_e32 v213, 0xffff0000, v174
	v_lshlrev_b32_e32 v214, 16, v175
	v_and_b32_e32 v215, 0xffff0000, v175
	v_pk_fma_f32 v[66:67], v[2:3], v[212:213], v[66:67]
	v_pk_fma_f32 v[68:69], v[4:5], v[214:215], v[68:69]
	s_nop 0
	v_cvt_pk_bf16_f32 v66, v66, v67
	v_cvt_pk_bf16_f32 v67, v68, v69
	global_store_dwordx2 v210, v[66:67], s[74:75] offset:0
	v_lshlrev_b32_e32 v216, 16, v176
	v_and_b32_e32 v217, 0xffff0000, v176
	v_lshlrev_b32_e32 v218, 16, v177
	v_and_b32_e32 v219, 0xffff0000, v177
	v_pk_fma_f32 v[70:71], v[6:7], v[216:217], v[70:71]
	v_pk_fma_f32 v[72:73], v[8:9], v[218:219], v[72:73]
	s_nop 0
	v_cvt_pk_bf16_f32 v70, v70, v71
	v_cvt_pk_bf16_f32 v71, v72, v73
	global_store_dwordx2 v210, v[70:71], s[74:75] offset:32
	v_lshlrev_b32_e32 v220, 16, v178
	v_and_b32_e32 v221, 0xffff0000, v178
	v_lshlrev_b32_e32 v222, 16, v179
	v_and_b32_e32 v223, 0xffff0000, v179
	v_pk_fma_f32 v[74:75], v[10:11], v[220:221], v[74:75]
	v_pk_fma_f32 v[76:77], v[12:13], v[222:223], v[76:77]
	s_nop 0
	v_cvt_pk_bf16_f32 v74, v74, v75
	v_cvt_pk_bf16_f32 v75, v76, v77
	global_store_dwordx2 v210, v[74:75], s[74:75] offset:64
	v_lshlrev_b32_e32 v224, 16, v180
	v_and_b32_e32 v225, 0xffff0000, v180
	v_lshlrev_b32_e32 v226, 16, v181
	v_and_b32_e32 v227, 0xffff0000, v181
	v_pk_fma_f32 v[78:79], v[14:15], v[224:225], v[78:79]
	v_pk_fma_f32 v[80:81], v[16:17], v[226:227], v[80:81]
	s_nop 0
	v_cvt_pk_bf16_f32 v78, v78, v79
	v_cvt_pk_bf16_f32 v79, v80, v81
	global_store_dwordx2 v210, v[78:79], s[74:75] offset:96
	v_lshlrev_b32_e32 v228, 16, v182
	v_and_b32_e32 v229, 0xffff0000, v182
	v_lshlrev_b32_e32 v230, 16, v183
	v_and_b32_e32 v231, 0xffff0000, v183
	v_pk_fma_f32 v[82:83], v[18:19], v[228:229], v[82:83]
	v_pk_fma_f32 v[84:85], v[20:21], v[230:231], v[84:85]
	s_nop 0
	v_cvt_pk_bf16_f32 v82, v82, v83
	v_cvt_pk_bf16_f32 v83, v84, v85
	global_store_dwordx2 v211, v[82:83], s[74:75] offset:0
	v_lshlrev_b32_e32 v232, 16, v184
	v_and_b32_e32 v233, 0xffff0000, v184
	v_lshlrev_b32_e32 v234, 16, v185
	v_and_b32_e32 v235, 0xffff0000, v185
	v_pk_fma_f32 v[86:87], v[22:23], v[232:233], v[86:87]
	v_pk_fma_f32 v[88:89], v[24:25], v[234:235], v[88:89]
	s_nop 0
	v_cvt_pk_bf16_f32 v86, v86, v87
	v_cvt_pk_bf16_f32 v87, v88, v89
	global_store_dwordx2 v211, v[86:87], s[74:75] offset:32
	v_lshlrev_b32_e32 v236, 16, v186
	v_and_b32_e32 v237, 0xffff0000, v186
	v_lshlrev_b32_e32 v238, 16, v187
	v_and_b32_e32 v239, 0xffff0000, v187
	v_pk_fma_f32 v[90:91], v[26:27], v[236:237], v[90:91]
	v_pk_fma_f32 v[92:93], v[28:29], v[238:239], v[92:93]
	s_nop 0
	v_cvt_pk_bf16_f32 v90, v90, v91
	v_cvt_pk_bf16_f32 v91, v92, v93
	global_store_dwordx2 v211, v[90:91], s[74:75] offset:64
	v_lshlrev_b32_e32 v240, 16, v188
	v_and_b32_e32 v241, 0xffff0000, v188
	v_lshlrev_b32_e32 v242, 16, v189
	v_and_b32_e32 v243, 0xffff0000, v189
	v_pk_fma_f32 v[94:95], v[30:31], v[240:241], v[94:95]
	v_pk_fma_f32 v[96:97], v[32:33], v[242:243], v[96:97]
	s_nop 0
	v_cvt_pk_bf16_f32 v94, v94, v95
	v_cvt_pk_bf16_f32 v95, v96, v97
	global_store_dwordx2 v211, v[94:95], s[74:75] offset:96
	v_lshlrev_b32_e32 v212, 16, v190
	v_and_b32_e32 v213, 0xffff0000, v190
	v_lshlrev_b32_e32 v214, 16, v191
	v_and_b32_e32 v215, 0xffff0000, v191
	v_pk_fma_f32 v[98:99], v[34:35], v[212:213], v[98:99]
	v_pk_fma_f32 v[100:101], v[36:37], v[214:215], v[100:101]
	s_nop 0
	v_cvt_pk_bf16_f32 v98, v98, v99
	v_cvt_pk_bf16_f32 v99, v100, v101
	global_store_dwordx2 v168, v[98:99], s[74:75] offset:0
	v_lshlrev_b32_e32 v216, 16, v192
	v_and_b32_e32 v217, 0xffff0000, v192
	v_lshlrev_b32_e32 v218, 16, v193
	v_and_b32_e32 v219, 0xffff0000, v193
	v_pk_fma_f32 v[102:103], v[38:39], v[216:217], v[102:103]
	v_pk_fma_f32 v[104:105], v[40:41], v[218:219], v[104:105]
	s_nop 0
	v_cvt_pk_bf16_f32 v102, v102, v103
	v_cvt_pk_bf16_f32 v103, v104, v105
	global_store_dwordx2 v168, v[102:103], s[74:75] offset:32
	v_lshlrev_b32_e32 v220, 16, v244
	v_and_b32_e32 v221, 0xffff0000, v244
	v_lshlrev_b32_e32 v222, 16, v245
	v_and_b32_e32 v223, 0xffff0000, v245
	v_pk_fma_f32 v[106:107], v[42:43], v[220:221], v[106:107]
	v_pk_fma_f32 v[108:109], v[44:45], v[222:223], v[108:109]
	s_nop 0
	v_cvt_pk_bf16_f32 v106, v106, v107
	v_cvt_pk_bf16_f32 v107, v108, v109
	global_store_dwordx2 v168, v[106:107], s[74:75] offset:64
	v_lshlrev_b32_e32 v224, 16, v246
	v_and_b32_e32 v225, 0xffff0000, v246
	v_lshlrev_b32_e32 v226, 16, v247
	v_and_b32_e32 v227, 0xffff0000, v247
	v_pk_fma_f32 v[110:111], v[46:47], v[224:225], v[110:111]
	v_pk_fma_f32 v[112:113], v[48:49], v[226:227], v[112:113]
	s_nop 0
	v_cvt_pk_bf16_f32 v110, v110, v111
	v_cvt_pk_bf16_f32 v111, v112, v113
	global_store_dwordx2 v168, v[110:111], s[74:75] offset:96
	v_lshlrev_b32_e32 v228, 16, v248
	v_and_b32_e32 v229, 0xffff0000, v248
	v_lshlrev_b32_e32 v230, 16, v249
	v_and_b32_e32 v231, 0xffff0000, v249
	v_pk_fma_f32 v[114:115], v[50:51], v[228:229], v[114:115]
	v_pk_fma_f32 v[116:117], v[52:53], v[230:231], v[116:117]
	s_nop 0
	v_cvt_pk_bf16_f32 v114, v114, v115
	v_cvt_pk_bf16_f32 v115, v116, v117
	global_store_dwordx2 v169, v[114:115], s[74:75] offset:0
	v_lshlrev_b32_e32 v232, 16, v250
	v_and_b32_e32 v233, 0xffff0000, v250
	v_lshlrev_b32_e32 v234, 16, v251
	v_and_b32_e32 v235, 0xffff0000, v251
	v_pk_fma_f32 v[118:119], v[54:55], v[232:233], v[118:119]
	v_pk_fma_f32 v[120:121], v[56:57], v[234:235], v[120:121]
	s_nop 0
	v_cvt_pk_bf16_f32 v118, v118, v119
	v_cvt_pk_bf16_f32 v119, v120, v121
	global_store_dwordx2 v169, v[118:119], s[74:75] offset:32
	v_lshlrev_b32_e32 v236, 16, v166
	v_and_b32_e32 v237, 0xffff0000, v166
	v_lshlrev_b32_e32 v238, 16, v167
	v_and_b32_e32 v239, 0xffff0000, v167
	v_pk_fma_f32 v[122:123], v[58:59], v[236:237], v[122:123]
	v_pk_fma_f32 v[124:125], v[60:61], v[238:239], v[124:125]
	s_nop 0
	v_cvt_pk_bf16_f32 v122, v122, v123
	v_cvt_pk_bf16_f32 v123, v124, v125
	global_store_dwordx2 v169, v[122:123], s[74:75] offset:64
	v_lshlrev_b32_e32 v240, 16, v194
	v_and_b32_e32 v241, 0xffff0000, v194
	v_lshlrev_b32_e32 v242, 16, v195
	v_and_b32_e32 v243, 0xffff0000, v195
	v_pk_fma_f32 v[126:127], v[62:63], v[240:241], v[126:127]
	v_pk_fma_f32 v[128:129], v[64:65], v[242:243], v[128:129]
	s_nop 0
	v_cvt_pk_bf16_f32 v126, v126, v127
	v_cvt_pk_bf16_f32 v127, v128, v129
	global_store_dwordx2 v169, v[126:127], s[74:75] offset:96
	s_barrier
	s_branch .Lbr_join
.Lbr_streamB:
	s_barrier
	v_add_u32_e32 v204, 0x0, v200
	v_add_u32_e32 v205, 0x0, v202
	ds_read_b128 v[130:133], v204 offset:0
	ds_read_b128 v[134:137], v204 offset:2048
	ds_read_b128 v[138:141], v204 offset:4096
	ds_read_b128 v[142:145], v204 offset:6144
	ds_read_b128 v[146:149], v205 offset:0
	ds_read_b128 v[150:153], v205 offset:2048
	ds_read_b128 v[154:157], v205 offset:4096
	ds_read_b128 v[158:161], v205 offset:6144
	v_add_u32_e32 v204, 0x0, v201
	v_add_u32_e32 v205, 0x0, v203
	ds_read_b128 v[212:215], v204 offset:0
	ds_read_b128 v[216:219], v204 offset:2048
	ds_read_b128 v[220:223], v204 offset:4096
	ds_read_b128 v[224:227], v204 offset:6144
	ds_read_b128 v[228:231], v205 offset:0
	ds_read_b128 v[232:235], v205 offset:2048
	ds_read_b128 v[236:239], v205 offset:4096
	ds_read_b128 v[240:243], v205 offset:6144
	s_add_u32 m0, s76, 0x18000
	s_nop 0
	global_load_lds_dwordx4 v196, s[68:69]
	s_add_u32 m0, s76, 0x1a000
	s_nop 0
	global_load_lds_dwordx4 v197, s[68:69]
	s_add_u32 m0, s76, 0x1c000
	s_nop 0
	global_load_lds_dwordx4 v198, s[68:69]
	s_add_u32 m0, s76, 0x1e000
	s_nop 0
	global_load_lds_dwordx4 v199, s[68:69]
	s_add_u32 m0, s76, 0x20000
	s_nop 0
	global_load_lds_dwordx4 v196, s[70:71]
	s_add_u32 m0, s76, 0x22000
	s_nop 0
	global_load_lds_dwordx4 v197, s[70:71]
	s_add_u32 s68, s68, 0x80
	s_addc_u32 s69, s69, 0
	s_add_u32 s70, s70, 0x80
	s_addc_u32 s71, s71, 0
	global_load_dwordx2 v[174:175], v206, s[72:73] offset:0
	global_load_dwordx2 v[176:177], v206, s[72:73] offset:32
	global_load_dwordx2 v[178:179], v206, s[72:73] offset:64
	global_load_dwordx2 v[180:181], v206, s[72:73] offset:96
	global_load_dwordx2 v[182:183], v207, s[72:73] offset:0
	global_load_dwordx2 v[184:185], v207, s[72:73] offset:32
	s_waitcnt vmcnt(12)
	s_waitcnt lgkmcnt(0)
	s_barrier
	s_setprio 1
	v_mfma_f32_16x16x32_bf16 v[2:5], v[146:149], v[130:133], 0
	v_mfma_f32_16x16x32_bf16 v[6:9], v[150:153], v[130:133], 0
	v_mfma_f32_16x16x32_bf16 v[10:13], v[154:157], v[130:133], 0
	v_mfma_f32_16x16x32_bf16 v[14:17], v[158:161], v[130:133], 0
	v_mfma_f32_16x16x32_bf16 v[18:21], v[146:149], v[134:137], 0
	v_mfma_f32_16x16x32_bf16 v[22:25], v[150:153], v[134:137], 0
	v_mfma_f32_16x16x32_bf16 v[26:29], v[154:157], v[134:137], 0
	v_mfma_f32_16x16x32_bf16 v[30:33], v[158:161], v[134:137], 0
	v_mfma_f32_16x16x32_bf16 v[34:37], v[146:149], v[138:141], 0
	v_mfma_f32_16x16x32_bf16 v[38:41], v[150:153], v[138:141], 0
	v_mfma_f32_16x16x32_bf16 v[42:45], v[154:157], v[138:141], 0
	v_mfma_f32_16x16x32_bf16 v[46:49], v[158:161], v[138:141], 0
	v_mfma_f32_16x16x32_bf16 v[50:53], v[146:149], v[142:145], 0
	v_mfma_f32_16x16x32_bf16 v[54:57], v[150:153], v[142:145], 0
	v_mfma_f32_16x16x32_bf16 v[58:61], v[154:157], v[142:145], 0
	v_mfma_f32_16x16x32_bf16 v[62:65], v[158:161], v[142:145], 0
	v_mfma_f32_16x16x32_bf16 v[2:5], v[228:231], v[212:215], v[2:5]
	v_mfma_f32_16x16x32_bf16 v[6:9], v[232:235], v[212:215], v[6:9]
	v_mfma_f32_16x16x32_bf16 v[10:13], v[236:239], v[212:215], v[10:13]
	v_mfma_f32_16x16x32_bf16 v[14:17], v[240:243], v[212:215], v[14:17]
	v_mfma_f32_16x16x32_bf16 v[18:21], v[228:231], v[216:219], v[18:21]
	v_mfma_f32_16x16x32_bf16 v[22:25], v[232:235], v[216:219], v[22:25]
	v_mfma_f32_16x16x32_bf16 v[26:29], v[236:239], v[216:219], v[26:29]
	v_mfma_f32_16x16x32_bf16 v[30:33], v[240:243], v[216:219], v[30:33]
	v_mfma_f32_16x16x32_bf16 v[34:37], v[228:231], v[220:223], v[34:37]
	v_mfma_f32_16x16x32_bf16 v[38:41], v[232:235], v[220:223], v[38:41]
	v_mfma_f32_16x16x32_bf16 v[42:45], v[236:239], v[220:223], v[42:45]
	v_mfma_f32_16x16x32_bf16 v[46:49], v[240:243], v[220:223], v[46:49]
	v_mfma_f32_16x16x32_bf16 v[50:53], v[228:231], v[224:227], v[50:53]
	v_mfma_f32_16x16x32_bf16 v[54:57], v[232:235], v[224:227], v[54:57]
	v_mfma_f32_16x16x32_bf16 v[58:61], v[236:239], v[224:227], v[58:61]
	v_mfma_f32_16x16x32_bf16 v[62:65], v[240:243], v[224:227], v[62:65]
	s_setprio 0
	s_barrier
	v_add_u32_e32 v204, 0xc000, v200
	v_add_u32_e32 v205, 0xc000, v202
	ds_read_b128 v[130:133], v204 offset:0
	ds_read_b128 v[134:137], v204 offset:2048
	ds_read_b128 v[138:141], v204 offset:4096
	ds_read_b128 v[142:145], v204 offset:6144
	ds_read_b128 v[146:149], v205 offset:0
	ds_read_b128 v[150:153], v205 offset:2048
	ds_read_b128 v[154:157], v205 offset:4096
	ds_read_b128 v[158:161], v205 offset:6144
	v_add_u32_e32 v204, 0xc000, v201
	v_add_u32_e32 v205, 0xc000, v203
	ds_read_b128 v[212:215], v204 offset:0
	ds_read_b128 v[216:219], v204 offset:2048
	ds_read_b128 v[220:223], v204 offset:4096
	ds_read_b128 v[224:227], v204 offset:6144
	ds_read_b128 v[228:231], v205 offset:0
	ds_read_b128 v[232:235], v205 offset:2048
	ds_read_b128 v[236:239], v205 offset:4096
	ds_read_b128 v[240:243], v205 offset:6144
	s_add_u32 m0, s76, 0x0
	s_nop 0
	global_load_lds_dwordx4 v196, s[68:69]
	s_add_u32 m0, s76, 0x2000
	s_nop 0
	global_load_lds_dwordx4 v197, s[68:69]
	s_add_u32 m0, s76, 0x4000
	s_nop 0
	global_load_lds_dwordx4 v198, s[68:69]
	s_add_u32 m0, s76, 0x6000
	s_nop 0
	global_load_lds_dwordx4 v199, s[68:69]
	s_add_u32 m0, s76, 0x8000
	s_nop 0
	global_load_lds_dwordx4 v196, s[70:71]
	s_add_u32 m0, s76, 0xa000
	s_nop 0
	global_load_lds_dwordx4 v197, s[70:71]
	s_add_u32 s68, s68, 0x80
	s_addc_u32 s69, s69, 0
	s_add_u32 s70, s70, 0x80
	s_addc_u32 s71, s71, 0
	global_load_dwordx2 v[186:187], v207, s[72:73] offset:64
	global_load_dwordx2 v[188:189], v207, s[72:73] offset:96
	global_load_dwordx2 v[190:191], v208, s[72:73] offset:0
	global_load_dwordx2 v[192:193], v208, s[72:73] offset:32
	global_load_dwordx2 v[244:245], v208, s[72:73] offset:64
	global_load_dwordx2 v[246:247], v208, s[72:73] offset:96
	s_waitcnt vmcnt(18)
	s_waitcnt lgkmcnt(0)
	s_barrier
	s_setprio 1
	v_mfma_f32_16x16x32_bf16 v[2:5], v[146:149], v[130:133], v[2:5]
	v_mfma_f32_16x16x32_bf16 v[6:9], v[150:153], v[130:133], v[6:9]
	v_mfma_f32_16x16x32_bf16 v[10:13], v[154:157], v[130:133], v[10:13]
	v_mfma_f32_16x16x32_bf16 v[14:17], v[158:161], v[130:133], v[14:17]
	v_mfma_f32_16x16x32_bf16 v[18:21], v[146:149], v[134:137], v[18:21]
	v_mfma_f32_16x16x32_bf16 v[22:25], v[150:153], v[134:137], v[22:25]
	v_mfma_f32_16x16x32_bf16 v[26:29], v[154:157], v[134:137], v[26:29]
	v_mfma_f32_16x16x32_bf16 v[30:33], v[158:161], v[134:137], v[30:33]
	v_mfma_f32_16x16x32_bf16 v[34:37], v[146:149], v[138:141], v[34:37]
	v_mfma_f32_16x16x32_bf16 v[38:41], v[150:153], v[138:141], v[38:41]
	v_mfma_f32_16x16x32_bf16 v[42:45], v[154:157], v[138:141], v[42:45]
	v_mfma_f32_16x16x32_bf16 v[46:49], v[158:161], v[138:141], v[46:49]
	v_mfma_f32_16x16x32_bf16 v[50:53], v[146:149], v[142:145], v[50:53]
	v_mfma_f32_16x16x32_bf16 v[54:57], v[150:153], v[142:145], v[54:57]
	v_mfma_f32_16x16x32_bf16 v[58:61], v[154:157], v[142:145], v[58:61]
	v_mfma_f32_16x16x32_bf16 v[62:65], v[158:161], v[142:145], v[62:65]
	v_mfma_f32_16x16x32_bf16 v[2:5], v[228:231], v[212:215], v[2:5]
	v_mfma_f32_16x16x32_bf16 v[6:9], v[232:235], v[212:215], v[6:9]
	v_mfma_f32_16x16x32_bf16 v[10:13], v[236:239], v[212:215], v[10:13]
	v_mfma_f32_16x16x32_bf16 v[14:17], v[240:243], v[212:215], v[14:17]
	v_mfma_f32_16x16x32_bf16 v[18:21], v[228:231], v[216:219], v[18:21]
	v_mfma_f32_16x16x32_bf16 v[22:25], v[232:235], v[216:219], v[22:25]
	v_mfma_f32_16x16x32_bf16 v[26:29], v[236:239], v[216:219], v[26:29]
	v_mfma_f32_16x16x32_bf16 v[30:33], v[240:243], v[216:219], v[30:33]
	v_mfma_f32_16x16x32_bf16 v[34:37], v[228:231], v[220:223], v[34:37]
	v_mfma_f32_16x16x32_bf16 v[38:41], v[232:235], v[220:223], v[38:41]
	v_mfma_f32_16x16x32_bf16 v[42:45], v[236:239], v[220:223], v[42:45]
	v_mfma_f32_16x16x32_bf16 v[46:49], v[240:243], v[220:223], v[46:49]
	v_mfma_f32_16x16x32_bf16 v[50:53], v[228:231], v[224:227], v[50:53]
	v_mfma_f32_16x16x32_bf16 v[54:57], v[232:235], v[224:227], v[54:57]
	v_mfma_f32_16x16x32_bf16 v[58:61], v[236:239], v[224:227], v[58:61]
	v_mfma_f32_16x16x32_bf16 v[62:65], v[240:243], v[224:227], v[62:65]
	s_setprio 0
	s_barrier
	v_add_u32_e32 v204, 0x18000, v200
	v_add_u32_e32 v205, 0x18000, v202
	ds_read_b128 v[130:133], v204 offset:0
	ds_read_b128 v[134:137], v204 offset:2048
	ds_read_b128 v[138:141], v204 offset:4096
	ds_read_b128 v[142:145], v204 offset:6144
	ds_read_b128 v[146:149], v205 offset:0
	ds_read_b128 v[150:153], v205 offset:2048
	ds_read_b128 v[154:157], v205 offset:4096
	ds_read_b128 v[158:161], v205 offset:6144
	v_add_u32_e32 v204, 0x18000, v201
	v_add_u32_e32 v205, 0x18000, v203
	ds_read_b128 v[212:215], v204 offset:0
	ds_read_b128 v[216:219], v204 offset:2048
	ds_read_b128 v[220:223], v204 offset:4096
	ds_read_b128 v[224:227], v204 offset:6144
	ds_read_b128 v[228:231], v205 offset:0
	ds_read_b128 v[232:235], v205 offset:2048
	ds_read_b128 v[236:239], v205 offset:4096
	ds_read_b128 v[240:243], v205 offset:6144
	s_add_u32 m0, s76, 0xc000
	s_nop 0
	global_load_lds_dwordx4 v196, s[68:69]
	s_add_u32 m0, s76, 0xe000
	s_nop 0
	global_load_lds_dwordx4 v197, s[68:69]
	s_add_u32 m0, s76, 0x10000
	s_nop 0
	global_load_lds_dwordx4 v198, s[68:69]
	s_add_u32 m0, s76, 0x12000
	s_nop 0
	global_load_lds_dwordx4 v199, s[68:69]
	s_add_u32 m0, s76, 0x14000
	s_nop 0
	global_load_lds_dwordx4 v196, s[70:71]
	s_add_u32 m0, s76, 0x16000
	s_nop 0
	global_load_lds_dwordx4 v197, s[70:71]
	s_add_u32 s68, s68, 0x80
	s_addc_u32 s69, s69, 0
	s_add_u32 s70, s70, 0x80
	s_addc_u32 s71, s71, 0
	global_load_dwordx2 v[248:249], v209, s[72:73] offset:0
	global_load_dwordx2 v[250:251], v209, s[72:73] offset:32
	global_load_dwordx2 v[166:167], v209, s[72:73] offset:64
	global_load_dwordx2 v[194:195], v209, s[72:73] offset:96
	s_add_u32 s72, s72, 0x800
	s_addc_u32 s73, s73, 0
	s_waitcnt vmcnt(16)
	s_waitcnt lgkmcnt(0)
	s_barrier
	s_setprio 1
	v_mfma_f32_16x16x32_bf16 v[2:5], v[146:149], v[130:133], v[2:5]
	v_mfma_f32_16x16x32_bf16 v[6:9], v[150:153], v[130:133], v[6:9]
	v_mfma_f32_16x16x32_bf16 v[10:13], v[154:157], v[130:133], v[10:13]
	v_mfma_f32_16x16x32_bf16 v[14:17], v[158:161], v[130:133], v[14:17]
	v_mfma_f32_16x16x32_bf16 v[18:21], v[146:149], v[134:137], v[18:21]
	v_mfma_f32_16x16x32_bf16 v[22:25], v[150:153], v[134:137], v[22:25]
	v_mfma_f32_16x16x32_bf16 v[26:29], v[154:157], v[134:137], v[26:29]
	v_mfma_f32_16x16x32_bf16 v[30:33], v[158:161], v[134:137], v[30:33]
	v_mfma_f32_16x16x32_bf16 v[34:37], v[146:149], v[138:141], v[34:37]
	v_mfma_f32_16x16x32_bf16 v[38:41], v[150:153], v[138:141], v[38:41]
	v_mfma_f32_16x16x32_bf16 v[42:45], v[154:157], v[138:141], v[42:45]
	v_mfma_f32_16x16x32_bf16 v[46:49], v[158:161], v[138:141], v[46:49]
	v_mfma_f32_16x16x32_bf16 v[50:53], v[146:149], v[142:145], v[50:53]
	v_mfma_f32_16x16x32_bf16 v[54:57], v[150:153], v[142:145], v[54:57]
	v_mfma_f32_16x16x32_bf16 v[58:61], v[154:157], v[142:145], v[58:61]
	v_mfma_f32_16x16x32_bf16 v[62:65], v[158:161], v[142:145], v[62:65]
	v_mfma_f32_16x16x32_bf16 v[2:5], v[228:231], v[212:215], v[2:5]
	v_mfma_f32_16x16x32_bf16 v[6:9], v[232:235], v[212:215], v[6:9]
	v_mfma_f32_16x16x32_bf16 v[10:13], v[236:239], v[212:215], v[10:13]
	v_mfma_f32_16x16x32_bf16 v[14:17], v[240:243], v[212:215], v[14:17]
	v_mfma_f32_16x16x32_bf16 v[18:21], v[228:231], v[216:219], v[18:21]
	v_mfma_f32_16x16x32_bf16 v[22:25], v[232:235], v[216:219], v[22:25]
	v_mfma_f32_16x16x32_bf16 v[26:29], v[236:239], v[216:219], v[26:29]
	v_mfma_f32_16x16x32_bf16 v[30:33], v[240:243], v[216:219], v[30:33]
	v_mfma_f32_16x16x32_bf16 v[34:37], v[228:231], v[220:223], v[34:37]
	v_mfma_f32_16x16x32_bf16 v[38:41], v[232:235], v[220:223], v[38:41]
	v_mfma_f32_16x16x32_bf16 v[42:45], v[236:239], v[220:223], v[42:45]
	v_mfma_f32_16x16x32_bf16 v[46:49], v[240:243], v[220:223], v[46:49]
	v_mfma_f32_16x16x32_bf16 v[50:53], v[228:231], v[224:227], v[50:53]
	v_mfma_f32_16x16x32_bf16 v[54:57], v[232:235], v[224:227], v[54:57]
	v_mfma_f32_16x16x32_bf16 v[58:61], v[236:239], v[224:227], v[58:61]
	v_mfma_f32_16x16x32_bf16 v[62:65], v[240:243], v[224:227], v[62:65]
	s_setprio 0
	s_barrier
	v_add_u32_e32 v204, 0x0, v200
	v_add_u32_e32 v205, 0x0, v202
	ds_read_b128 v[130:133], v204 offset:0
	ds_read_b128 v[134:137], v204 offset:2048
	ds_read_b128 v[138:141], v204 offset:4096
	ds_read_b128 v[142:145], v204 offset:6144
	ds_read_b128 v[146:149], v205 offset:0
	ds_read_b128 v[150:153], v205 offset:2048
	ds_read_b128 v[154:157], v205 offset:4096
	ds_read_b128 v[158:161], v205 offset:6144
	v_add_u32_e32 v204, 0x0, v201
	v_add_u32_e32 v205, 0x0, v203
	ds_read_b128 v[212:215], v204 offset:0
	ds_read_b128 v[216:219], v204 offset:2048
	ds_read_b128 v[220:223], v204 offset:4096
	ds_read_b128 v[224:227], v204 offset:6144
	ds_read_b128 v[228:231], v205 offset:0
	ds_read_b128 v[232:235], v205 offset:2048
	ds_read_b128 v[236:239], v205 offset:4096
	ds_read_b128 v[240:243], v205 offset:6144
	s_add_u32 m0, s76, 0x18000
	s_nop 0
	global_load_lds_dwordx4 v196, s[68:69]
	s_add_u32 m0, s76, 0x1a000
	s_nop 0
	global_load_lds_dwordx4 v197, s[68:69]
	s_add_u32 m0, s76, 0x1c000
	s_nop 0
	global_load_lds_dwordx4 v198, s[68:69]
	s_add_u32 m0, s76, 0x1e000
	s_nop 0
	global_load_lds_dwordx4 v199, s[68:69]
	s_add_u32 m0, s76, 0x20000
	s_nop 0
	global_load_lds_dwordx4 v196, s[70:71]
	s_add_u32 m0, s76, 0x22000
	s_nop 0
	global_load_lds_dwordx4 v197, s[70:71]
	s_add_u32 s68, s68, 0x80
	s_addc_u32 s69, s69, 0
	s_add_u32 s70, s70, 0x80
	s_addc_u32 s71, s71, 0
	s_waitcnt vmcnt(10)
	s_waitcnt lgkmcnt(0)
	s_barrier
	s_setprio 1
	v_mfma_f32_16x16x32_bf16 v[2:5], v[146:149], v[130:133], v[2:5]
	v_mfma_f32_16x16x32_bf16 v[6:9], v[150:153], v[130:133], v[6:9]
	v_mfma_f32_16x16x32_bf16 v[10:13], v[154:157], v[130:133], v[10:13]
	v_mfma_f32_16x16x32_bf16 v[14:17], v[158:161], v[130:133], v[14:17]
	v_mfma_f32_16x16x32_bf16 v[18:21], v[146:149], v[134:137], v[18:21]
	v_mfma_f32_16x16x32_bf16 v[22:25], v[150:153], v[134:137], v[22:25]
	v_mfma_f32_16x16x32_bf16 v[26:29], v[154:157], v[134:137], v[26:29]
	v_mfma_f32_16x16x32_bf16 v[30:33], v[158:161], v[134:137], v[30:33]
	v_mfma_f32_16x16x32_bf16 v[34:37], v[146:149], v[138:141], v[34:37]
	v_mfma_f32_16x16x32_bf16 v[38:41], v[150:153], v[138:141], v[38:41]
	v_mfma_f32_16x16x32_bf16 v[42:45], v[154:157], v[138:141], v[42:45]
	v_mfma_f32_16x16x32_bf16 v[46:49], v[158:161], v[138:141], v[46:49]
	v_mfma_f32_16x16x32_bf16 v[50:53], v[146:149], v[142:145], v[50:53]
	v_mfma_f32_16x16x32_bf16 v[54:57], v[150:153], v[142:145], v[54:57]
	v_mfma_f32_16x16x32_bf16 v[58:61], v[154:157], v[142:145], v[58:61]
	v_mfma_f32_16x16x32_bf16 v[62:65], v[158:161], v[142:145], v[62:65]
	v_mfma_f32_16x16x32_bf16 v[2:5], v[228:231], v[212:215], v[2:5]
	v_mfma_f32_16x16x32_bf16 v[6:9], v[232:235], v[212:215], v[6:9]
	v_mfma_f32_16x16x32_bf16 v[10:13], v[236:239], v[212:215], v[10:13]
	v_mfma_f32_16x16x32_bf16 v[14:17], v[240:243], v[212:215], v[14:17]
	v_mfma_f32_16x16x32_bf16 v[18:21], v[228:231], v[216:219], v[18:21]
	v_mfma_f32_16x16x32_bf16 v[22:25], v[232:235], v[216:219], v[22:25]
	v_mfma_f32_16x16x32_bf16 v[26:29], v[236:239], v[216:219], v[26:29]
	v_mfma_f32_16x16x32_bf16 v[30:33], v[240:243], v[216:219], v[30:33]
	v_mfma_f32_16x16x32_bf16 v[34:37], v[228:231], v[220:223], v[34:37]
	v_mfma_f32_16x16x32_bf16 v[38:41], v[232:235], v[220:223], v[38:41]
	v_mfma_f32_16x16x32_bf16 v[42:45], v[236:239], v[220:223], v[42:45]
	v_mfma_f32_16x16x32_bf16 v[46:49], v[240:243], v[220:223], v[46:49]
	v_mfma_f32_16x16x32_bf16 v[50:53], v[228:231], v[224:227], v[50:53]
	v_mfma_f32_16x16x32_bf16 v[54:57], v[232:235], v[224:227], v[54:57]
	v_mfma_f32_16x16x32_bf16 v[58:61], v[236:239], v[224:227], v[58:61]
	v_mfma_f32_16x16x32_bf16 v[62:65], v[240:243], v[224:227], v[62:65]
	s_setprio 0
	s_barrier
	v_add_u32_e32 v204, 0xc000, v200
	v_add_u32_e32 v205, 0xc000, v202
	ds_read_b128 v[130:133], v204 offset:0
	ds_read_b128 v[134:137], v204 offset:2048
	ds_read_b128 v[138:141], v204 offset:4096
	ds_read_b128 v[142:145], v204 offset:6144
	ds_read_b128 v[146:149], v205 offset:0
	ds_read_b128 v[150:153], v205 offset:2048
	ds_read_b128 v[154:157], v205 offset:4096
	ds_read_b128 v[158:161], v205 offset:6144
	v_add_u32_e32 v204, 0xc000, v201
	v_add_u32_e32 v205, 0xc000, v203
	ds_read_b128 v[212:215], v204 offset:0
	ds_read_b128 v[216:219], v204 offset:2048
	ds_read_b128 v[220:223], v204 offset:4096
	ds_read_b128 v[224:227], v204 offset:6144
	ds_read_b128 v[228:231], v205 offset:0
	ds_read_b128 v[232:235], v205 offset:2048
	ds_read_b128 v[236:239], v205 offset:4096
	ds_read_b128 v[240:243], v205 offset:6144
	s_add_u32 m0, s76, 0x0
	s_nop 0
	global_load_lds_dwordx4 v196, s[68:69]
	s_add_u32 m0, s76, 0x2000
	s_nop 0
	global_load_lds_dwordx4 v197, s[68:69]
	s_add_u32 m0, s76, 0x4000
	s_nop 0
	global_load_lds_dwordx4 v198, s[68:69]
	s_add_u32 m0, s76, 0x6000
	s_nop 0
	global_load_lds_dwordx4 v199, s[68:69]
	s_add_u32 m0, s76, 0x8000
	s_nop 0
	global_load_lds_dwordx4 v196, s[70:71]
	s_add_u32 m0, s76, 0xa000
	s_nop 0
	global_load_lds_dwordx4 v197, s[70:71]
	s_add_u32 s68, s68, 0x80
	s_addc_u32 s69, s69, 0
	s_add_u32 s70, s70, 0x80
	s_addc_u32 s71, s71, 0
	s_waitcnt vmcnt(6)
	s_waitcnt lgkmcnt(0)
	s_barrier
	s_setprio 1
	v_mfma_f32_16x16x32_bf16 v[2:5], v[146:149], v[130:133], v[2:5]
	v_mfma_f32_16x16x32_bf16 v[6:9], v[150:153], v[130:133], v[6:9]
	v_mfma_f32_16x16x32_bf16 v[10:13], v[154:157], v[130:133], v[10:13]
	v_mfma_f32_16x16x32_bf16 v[14:17], v[158:161], v[130:133], v[14:17]
	v_mfma_f32_16x16x32_bf16 v[18:21], v[146:149], v[134:137], v[18:21]
	v_mfma_f32_16x16x32_bf16 v[22:25], v[150:153], v[134:137], v[22:25]
	v_mfma_f32_16x16x32_bf16 v[26:29], v[154:157], v[134:137], v[26:29]
	v_mfma_f32_16x16x32_bf16 v[30:33], v[158:161], v[134:137], v[30:33]
	v_mfma_f32_16x16x32_bf16 v[34:37], v[146:149], v[138:141], v[34:37]
	v_mfma_f32_16x16x32_bf16 v[38:41], v[150:153], v[138:141], v[38:41]
	v_mfma_f32_16x16x32_bf16 v[42:45], v[154:157], v[138:141], v[42:45]
	v_mfma_f32_16x16x32_bf16 v[46:49], v[158:161], v[138:141], v[46:49]
	v_mfma_f32_16x16x32_bf16 v[50:53], v[146:149], v[142:145], v[50:53]
	v_mfma_f32_16x16x32_bf16 v[54:57], v[150:153], v[142:145], v[54:57]
	v_mfma_f32_16x16x32_bf16 v[58:61], v[154:157], v[142:145], v[58:61]
	v_mfma_f32_16x16x32_bf16 v[62:65], v[158:161], v[142:145], v[62:65]
	v_mfma_f32_16x16x32_bf16 v[2:5], v[228:231], v[212:215], v[2:5]
	v_mfma_f32_16x16x32_bf16 v[6:9], v[232:235], v[212:215], v[6:9]
	v_mfma_f32_16x16x32_bf16 v[10:13], v[236:239], v[212:215], v[10:13]
	v_mfma_f32_16x16x32_bf16 v[14:17], v[240:243], v[212:215], v[14:17]
	v_mfma_f32_16x16x32_bf16 v[18:21], v[228:231], v[216:219], v[18:21]
	v_mfma_f32_16x16x32_bf16 v[22:25], v[232:235], v[216:219], v[22:25]
	v_mfma_f32_16x16x32_bf16 v[26:29], v[236:239], v[216:219], v[26:29]
	v_mfma_f32_16x16x32_bf16 v[30:33], v[240:243], v[216:219], v[30:33]
	v_mfma_f32_16x16x32_bf16 v[34:37], v[228:231], v[220:223], v[34:37]
	v_mfma_f32_16x16x32_bf16 v[38:41], v[232:235], v[220:223], v[38:41]
	v_mfma_f32_16x16x32_bf16 v[42:45], v[236:239], v[220:223], v[42:45]
	v_mfma_f32_16x16x32_bf16 v[46:49], v[240:243], v[220:223], v[46:49]
	v_mfma_f32_16x16x32_bf16 v[50:53], v[228:231], v[224:227], v[50:53]
	v_mfma_f32_16x16x32_bf16 v[54:57], v[232:235], v[224:227], v[54:57]
	v_mfma_f32_16x16x32_bf16 v[58:61], v[236:239], v[224:227], v[58:61]
	v_mfma_f32_16x16x32_bf16 v[62:65], v[240:243], v[224:227], v[62:65]
	s_setprio 0
	s_barrier
	v_add_u32_e32 v204, 0x18000, v200
	v_add_u32_e32 v205, 0x18000, v202
	ds_read_b128 v[130:133], v204 offset:0
	ds_read_b128 v[134:137], v204 offset:2048
	ds_read_b128 v[138:141], v204 offset:4096
	ds_read_b128 v[142:145], v204 offset:6144
	ds_read_b128 v[146:149], v205 offset:0
	ds_read_b128 v[150:153], v205 offset:2048
	ds_read_b128 v[154:157], v205 offset:4096
	ds_read_b128 v[158:161], v205 offset:6144
	v_add_u32_e32 v204, 0x18000, v201
	v_add_u32_e32 v205, 0x18000, v203
	ds_read_b128 v[212:215], v204 offset:0
	ds_read_b128 v[216:219], v204 offset:2048
	ds_read_b128 v[220:223], v204 offset:4096
	ds_read_b128 v[224:227], v204 offset:6144
	ds_read_b128 v[228:231], v205 offset:0
	ds_read_b128 v[232:235], v205 offset:2048
	ds_read_b128 v[236:239], v205 offset:4096
	ds_read_b128 v[240:243], v205 offset:6144
	s_add_u32 m0, s76, 0xc000
	s_nop 0
	global_load_lds_dwordx4 v196, s[68:69]
	s_add_u32 m0, s76, 0xe000
	s_nop 0
	global_load_lds_dwordx4 v197, s[68:69]
	s_add_u32 m0, s76, 0x10000
	s_nop 0
	global_load_lds_dwordx4 v198, s[68:69]
	s_add_u32 m0, s76, 0x12000
	s_nop 0
	global_load_lds_dwordx4 v199, s[68:69]
	s_add_u32 m0, s76, 0x14000
	s_nop 0
	global_load_lds_dwordx4 v196, s[70:71]
	s_add_u32 m0, s76, 0x16000
	s_nop 0
	global_load_lds_dwordx4 v197, s[70:71]
	s_add_u32 s68, s68, 0x80
	s_addc_u32 s69, s69, 0
	s_add_u32 s70, s70, 0x80
	s_addc_u32 s71, s71, 0
	s_waitcnt vmcnt(6)
	s_waitcnt lgkmcnt(0)
	s_barrier
	s_setprio 1
	v_mfma_f32_16x16x32_bf16 v[2:5], v[146:149], v[130:133], v[2:5]
	v_mfma_f32_16x16x32_bf16 v[6:9], v[150:153], v[130:133], v[6:9]
	v_mfma_f32_16x16x32_bf16 v[10:13], v[154:157], v[130:133], v[10:13]
	v_mfma_f32_16x16x32_bf16 v[14:17], v[158:161], v[130:133], v[14:17]
	v_mfma_f32_16x16x32_bf16 v[18:21], v[146:149], v[134:137], v[18:21]
	v_mfma_f32_16x16x32_bf16 v[22:25], v[150:153], v[134:137], v[22:25]
	v_mfma_f32_16x16x32_bf16 v[26:29], v[154:157], v[134:137], v[26:29]
	v_mfma_f32_16x16x32_bf16 v[30:33], v[158:161], v[134:137], v[30:33]
	v_mfma_f32_16x16x32_bf16 v[34:37], v[146:149], v[138:141], v[34:37]
	v_mfma_f32_16x16x32_bf16 v[38:41], v[150:153], v[138:141], v[38:41]
	v_mfma_f32_16x16x32_bf16 v[42:45], v[154:157], v[138:141], v[42:45]
	v_mfma_f32_16x16x32_bf16 v[46:49], v[158:161], v[138:141], v[46:49]
	v_mfma_f32_16x16x32_bf16 v[50:53], v[146:149], v[142:145], v[50:53]
	v_mfma_f32_16x16x32_bf16 v[54:57], v[150:153], v[142:145], v[54:57]
	v_mfma_f32_16x16x32_bf16 v[58:61], v[154:157], v[142:145], v[58:61]
	v_mfma_f32_16x16x32_bf16 v[62:65], v[158:161], v[142:145], v[62:65]
	v_mfma_f32_16x16x32_bf16 v[2:5], v[228:231], v[212:215], v[2:5]
	v_mfma_f32_16x16x32_bf16 v[6:9], v[232:235], v[212:215], v[6:9]
	v_mfma_f32_16x16x32_bf16 v[10:13], v[236:239], v[212:215], v[10:13]
	v_mfma_f32_16x16x32_bf16 v[14:17], v[240:243], v[212:215], v[14:17]
	v_mfma_f32_16x16x32_bf16 v[18:21], v[228:231], v[216:219], v[18:21]
	v_mfma_f32_16x16x32_bf16 v[22:25], v[232:235], v[216:219], v[22:25]
	v_mfma_f32_16x16x32_bf16 v[26:29], v[236:239], v[216:219], v[26:29]
	v_mfma_f32_16x16x32_bf16 v[30:33], v[240:243], v[216:219], v[30:33]
	v_mfma_f32_16x16x32_bf16 v[34:37], v[228:231], v[220:223], v[34:37]
	v_mfma_f32_16x16x32_bf16 v[38:41], v[232:235], v[220:223], v[38:41]
	v_mfma_f32_16x16x32_bf16 v[42:45], v[236:239], v[220:223], v[42:45]
	v_mfma_f32_16x16x32_bf16 v[46:49], v[240:243], v[220:223], v[46:49]
	v_mfma_f32_16x16x32_bf16 v[50:53], v[228:231], v[224:227], v[50:53]
	v_mfma_f32_16x16x32_bf16 v[54:57], v[232:235], v[224:227], v[54:57]
	v_mfma_f32_16x16x32_bf16 v[58:61], v[236:239], v[224:227], v[58:61]
	v_mfma_f32_16x16x32_bf16 v[62:65], v[240:243], v[224:227], v[62:65]
	s_setprio 0
	s_barrier
	v_add_u32_e32 v204, 0x0, v200
	v_add_u32_e32 v205, 0x0, v202
	ds_read_b128 v[130:133], v204 offset:0
	ds_read_b128 v[134:137], v204 offset:2048
	ds_read_b128 v[138:141], v204 offset:4096
	ds_read_b128 v[142:145], v204 offset:6144
	ds_read_b128 v[146:149], v205 offset:0
	ds_read_b128 v[150:153], v205 offset:2048
	ds_read_b128 v[154:157], v205 offset:4096
	ds_read_b128 v[158:161], v205 offset:6144
	v_add_u32_e32 v204, 0x0, v201
	v_add_u32_e32 v205, 0x0, v203
	ds_read_b128 v[212:215], v204 offset:0
	ds_read_b128 v[216:219], v204 offset:2048
	ds_read_b128 v[220:223], v204 offset:4096
	ds_read_b128 v[224:227], v204 offset:6144
	ds_read_b128 v[228:231], v205 offset:0
	ds_read_b128 v[232:235], v205 offset:2048
	ds_read_b128 v[236:239], v205 offset:4096
	ds_read_b128 v[240:243], v205 offset:6144
	s_add_u32 m0, s76, 0x18000
	s_nop 0
	global_load_lds_dwordx4 v196, s[68:69]
	s_add_u32 m0, s76, 0x1a000
	s_nop 0
	global_load_lds_dwordx4 v197, s[68:69]
	s_add_u32 m0, s76, 0x1c000
	s_nop 0
	global_load_lds_dwordx4 v198, s[68:69]
	s_add_u32 m0, s76, 0x1e000
	s_nop 0
	global_load_lds_dwordx4 v199, s[68:69]
	s_add_u32 m0, s76, 0x20000
	s_nop 0
	global_load_lds_dwordx4 v196, s[70:71]
	s_add_u32 m0, s76, 0x22000
	s_nop 0
	global_load_lds_dwordx4 v197, s[70:71]
	s_add_u32 s68, s68, 0x80
	s_addc_u32 s69, s69, 0
	s_add_u32 s70, s70, 0x80
	s_addc_u32 s71, s71, 0
	s_waitcnt vmcnt(6)
	s_waitcnt lgkmcnt(0)
	s_barrier
	s_setprio 1
	v_mfma_f32_16x16x32_bf16 v[2:5], v[146:149], v[130:133], v[2:5]
	v_mfma_f32_16x16x32_bf16 v[6:9], v[150:153], v[130:133], v[6:9]
	v_mfma_f32_16x16x32_bf16 v[10:13], v[154:157], v[130:133], v[10:13]
	v_mfma_f32_16x16x32_bf16 v[14:17], v[158:161], v[130:133], v[14:17]
	v_mfma_f32_16x16x32_bf16 v[18:21], v[146:149], v[134:137], v[18:21]
	v_mfma_f32_16x16x32_bf16 v[22:25], v[150:153], v[134:137], v[22:25]
	v_mfma_f32_16x16x32_bf16 v[26:29], v[154:157], v[134:137], v[26:29]
	v_mfma_f32_16x16x32_bf16 v[30:33], v[158:161], v[134:137], v[30:33]
	v_mfma_f32_16x16x32_bf16 v[34:37], v[146:149], v[138:141], v[34:37]
	v_mfma_f32_16x16x32_bf16 v[38:41], v[150:153], v[138:141], v[38:41]
	v_mfma_f32_16x16x32_bf16 v[42:45], v[154:157], v[138:141], v[42:45]
	v_mfma_f32_16x16x32_bf16 v[46:49], v[158:161], v[138:141], v[46:49]
	v_mfma_f32_16x16x32_bf16 v[50:53], v[146:149], v[142:145], v[50:53]
	v_mfma_f32_16x16x32_bf16 v[54:57], v[150:153], v[142:145], v[54:57]
	v_mfma_f32_16x16x32_bf16 v[58:61], v[154:157], v[142:145], v[58:61]
	v_mfma_f32_16x16x32_bf16 v[62:65], v[158:161], v[142:145], v[62:65]
	v_mfma_f32_16x16x32_bf16 v[2:5], v[228:231], v[212:215], v[2:5]
	v_mfma_f32_16x16x32_bf16 v[6:9], v[232:235], v[212:215], v[6:9]
	v_mfma_f32_16x16x32_bf16 v[10:13], v[236:239], v[212:215], v[10:13]
	v_mfma_f32_16x16x32_bf16 v[14:17], v[240:243], v[212:215], v[14:17]
	v_mfma_f32_16x16x32_bf16 v[18:21], v[228:231], v[216:219], v[18:21]
	v_mfma_f32_16x16x32_bf16 v[22:25], v[232:235], v[216:219], v[22:25]
	v_mfma_f32_16x16x32_bf16 v[26:29], v[236:239], v[216:219], v[26:29]
	v_mfma_f32_16x16x32_bf16 v[30:33], v[240:243], v[216:219], v[30:33]
	v_mfma_f32_16x16x32_bf16 v[34:37], v[228:231], v[220:223], v[34:37]
	v_mfma_f32_16x16x32_bf16 v[38:41], v[232:235], v[220:223], v[38:41]
	v_mfma_f32_16x16x32_bf16 v[42:45], v[236:239], v[220:223], v[42:45]
	v_mfma_f32_16x16x32_bf16 v[46:49], v[240:243], v[220:223], v[46:49]
	v_mfma_f32_16x16x32_bf16 v[50:53], v[228:231], v[224:227], v[50:53]
	v_mfma_f32_16x16x32_bf16 v[54:57], v[232:235], v[224:227], v[54:57]
	v_mfma_f32_16x16x32_bf16 v[58:61], v[236:239], v[224:227], v[58:61]
	v_mfma_f32_16x16x32_bf16 v[62:65], v[240:243], v[224:227], v[62:65]
	s_setprio 0
	s_barrier
	v_add_u32_e32 v204, 0xc000, v200
	v_add_u32_e32 v205, 0xc000, v202
	ds_read_b128 v[130:133], v204 offset:0
	ds_read_b128 v[134:137], v204 offset:2048
	ds_read_b128 v[138:141], v204 offset:4096
	ds_read_b128 v[142:145], v204 offset:6144
	ds_read_b128 v[146:149], v205 offset:0
	ds_read_b128 v[150:153], v205 offset:2048
	ds_read_b128 v[154:157], v205 offset:4096
	ds_read_b128 v[158:161], v205 offset:6144
	v_add_u32_e32 v204, 0xc000, v201
	v_add_u32_e32 v205, 0xc000, v203
	ds_read_b128 v[212:215], v204 offset:0
	ds_read_b128 v[216:219], v204 offset:2048
	ds_read_b128 v[220:223], v204 offset:4096
	ds_read_b128 v[224:227], v204 offset:6144
	ds_read_b128 v[228:231], v205 offset:0
	ds_read_b128 v[232:235], v205 offset:2048
	ds_read_b128 v[236:239], v205 offset:4096
	ds_read_b128 v[240:243], v205 offset:6144
	s_add_u32 m0, s76, 0x0
	s_nop 0
	global_load_lds_dwordx4 v196, s[68:69]
	s_add_u32 m0, s76, 0x2000
	s_nop 0
	global_load_lds_dwordx4 v197, s[68:69]
	s_add_u32 m0, s76, 0x4000
	s_nop 0
	global_load_lds_dwordx4 v198, s[68:69]
	s_add_u32 m0, s76, 0x6000
	s_nop 0
	global_load_lds_dwordx4 v199, s[68:69]
	s_add_u32 m0, s76, 0x8000
	s_nop 0
	global_load_lds_dwordx4 v196, s[70:71]
	s_add_u32 m0, s76, 0xa000
	s_nop 0
	global_load_lds_dwordx4 v197, s[70:71]
	s_add_u32 s68, s68, 0x80
	s_addc_u32 s69, s69, 0
	s_add_u32 s70, s70, 0x80
	s_addc_u32 s71, s71, 0
	s_waitcnt vmcnt(6)
	s_waitcnt lgkmcnt(0)
	s_barrier
	s_setprio 1
	v_mfma_f32_16x16x32_bf16 v[2:5], v[146:149], v[130:133], v[2:5]
	v_mfma_f32_16x16x32_bf16 v[6:9], v[150:153], v[130:133], v[6:9]
	v_mfma_f32_16x16x32_bf16 v[10:13], v[154:157], v[130:133], v[10:13]
	v_mfma_f32_16x16x32_bf16 v[14:17], v[158:161], v[130:133], v[14:17]
	v_mfma_f32_16x16x32_bf16 v[18:21], v[146:149], v[134:137], v[18:21]
	v_mfma_f32_16x16x32_bf16 v[22:25], v[150:153], v[134:137], v[22:25]
	v_mfma_f32_16x16x32_bf16 v[26:29], v[154:157], v[134:137], v[26:29]
	v_mfma_f32_16x16x32_bf16 v[30:33], v[158:161], v[134:137], v[30:33]
	v_mfma_f32_16x16x32_bf16 v[34:37], v[146:149], v[138:141], v[34:37]
	v_mfma_f32_16x16x32_bf16 v[38:41], v[150:153], v[138:141], v[38:41]
	v_mfma_f32_16x16x32_bf16 v[42:45], v[154:157], v[138:141], v[42:45]
	v_mfma_f32_16x16x32_bf16 v[46:49], v[158:161], v[138:141], v[46:49]
	v_mfma_f32_16x16x32_bf16 v[50:53], v[146:149], v[142:145], v[50:53]
	v_mfma_f32_16x16x32_bf16 v[54:57], v[150:153], v[142:145], v[54:57]
	v_mfma_f32_16x16x32_bf16 v[58:61], v[154:157], v[142:145], v[58:61]
	v_mfma_f32_16x16x32_bf16 v[62:65], v[158:161], v[142:145], v[62:65]
	v_mfma_f32_16x16x32_bf16 v[2:5], v[228:231], v[212:215], v[2:5]
	v_mfma_f32_16x16x32_bf16 v[6:9], v[232:235], v[212:215], v[6:9]
	v_mfma_f32_16x16x32_bf16 v[10:13], v[236:239], v[212:215], v[10:13]
	v_mfma_f32_16x16x32_bf16 v[14:17], v[240:243], v[212:215], v[14:17]
	v_mfma_f32_16x16x32_bf16 v[18:21], v[228:231], v[216:219], v[18:21]
	v_mfma_f32_16x16x32_bf16 v[22:25], v[232:235], v[216:219], v[22:25]
	v_mfma_f32_16x16x32_bf16 v[26:29], v[236:239], v[216:219], v[26:29]
	v_mfma_f32_16x16x32_bf16 v[30:33], v[240:243], v[216:219], v[30:33]
	v_mfma_f32_16x16x32_bf16 v[34:37], v[228:231], v[220:223], v[34:37]
	v_mfma_f32_16x16x32_bf16 v[38:41], v[232:235], v[220:223], v[38:41]
	v_mfma_f32_16x16x32_bf16 v[42:45], v[236:239], v[220:223], v[42:45]
	v_mfma_f32_16x16x32_bf16 v[46:49], v[240:243], v[220:223], v[46:49]
	v_mfma_f32_16x16x32_bf16 v[50:53], v[228:231], v[224:227], v[50:53]
	v_mfma_f32_16x16x32_bf16 v[54:57], v[232:235], v[224:227], v[54:57]
	v_mfma_f32_16x16x32_bf16 v[58:61], v[236:239], v[224:227], v[58:61]
	v_mfma_f32_16x16x32_bf16 v[62:65], v[240:243], v[224:227], v[62:65]
	s_setprio 0
	s_nop 7
	v_lshlrev_b32_e32 v212, 16, v174
	v_and_b32_e32 v213, 0xffff0000, v174
	v_lshlrev_b32_e32 v214, 16, v175
	v_and_b32_e32 v215, 0xffff0000, v175
	v_pk_fma_f32 v[66:67], v[2:3], v[212:213], v[66:67]
	v_pk_fma_f32 v[68:69], v[4:5], v[214:215], v[68:69]
	v_lshlrev_b32_e32 v216, 16, v176
	v_and_b32_e32 v217, 0xffff0000, v176
	v_lshlrev_b32_e32 v218, 16, v177
	v_and_b32_e32 v219, 0xffff0000, v177
	v_pk_fma_f32 v[70:71], v[6:7], v[216:217], v[70:71]
	v_pk_fma_f32 v[72:73], v[8:9], v[218:219], v[72:73]
	v_lshlrev_b32_e32 v220, 16, v178
	v_and_b32_e32 v221, 0xffff0000, v178
	v_lshlrev_b32_e32 v222, 16, v179
	v_and_b32_e32 v223, 0xffff0000, v179
	v_pk_fma_f32 v[74:75], v[10:11], v[220:221], v[74:75]
	v_pk_fma_f32 v[76:77], v[12:13], v[222:223], v[76:77]
	v_lshlrev_b32_e32 v224, 16, v180
	v_and_b32_e32 v225, 0xffff0000, v180
	v_lshlrev_b32_e32 v226, 16, v181
	v_and_b32_e32 v227, 0xffff0000, v181
	v_pk_fma_f32 v[78:79], v[14:15], v[224:225], v[78:79]
	v_pk_fma_f32 v[80:81], v[16:17], v[226:227], v[80:81]
	v_lshlrev_b32_e32 v228, 16, v182
	v_and_b32_e32 v229, 0xffff0000, v182
	v_lshlrev_b32_e32 v230, 16, v183
	v_and_b32_e32 v231, 0xffff0000, v183
	v_pk_fma_f32 v[82:83], v[18:19], v[228:229], v[82:83]
	v_pk_fma_f32 v[84:85], v[20:21], v[230:231], v[84:85]
	v_lshlrev_b32_e32 v232, 16, v184
	v_and_b32_e32 v233, 0xffff0000, v184
	v_lshlrev_b32_e32 v234, 16, v185
	v_and_b32_e32 v235, 0xffff0000, v185
	v_pk_fma_f32 v[86:87], v[22:23], v[232:233], v[86:87]
	v_pk_fma_f32 v[88:89], v[24:25], v[234:235], v[88:89]
	v_lshlrev_b32_e32 v236, 16, v186
	v_and_b32_e32 v237, 0xffff0000, v186
	v_lshlrev_b32_e32 v238, 16, v187
	v_and_b32_e32 v239, 0xffff0000, v187
	v_pk_fma_f32 v[90:91], v[26:27], v[236:237], v[90:91]
	v_pk_fma_f32 v[92:93], v[28:29], v[238:239], v[92:93]
	v_lshlrev_b32_e32 v240, 16, v188
	v_and_b32_e32 v241, 0xffff0000, v188
	v_lshlrev_b32_e32 v242, 16, v189
	v_and_b32_e32 v243, 0xffff0000, v189
	v_pk_fma_f32 v[94:95], v[30:31], v[240:241], v[94:95]
	v_pk_fma_f32 v[96:97], v[32:33], v[242:243], v[96:97]
	v_lshlrev_b32_e32 v212, 16, v190
	v_and_b32_e32 v213, 0xffff0000, v190
	v_lshlrev_b32_e32 v214, 16, v191
	v_and_b32_e32 v215, 0xffff0000, v191
	v_pk_fma_f32 v[98:99], v[34:35], v[212:213], v[98:99]
	v_pk_fma_f32 v[100:101], v[36:37], v[214:215], v[100:101]
	v_lshlrev_b32_e32 v216, 16, v192
	v_and_b32_e32 v217, 0xffff0000, v192
	v_lshlrev_b32_e32 v218, 16, v193
	v_and_b32_e32 v219, 0xffff0000, v193
	v_pk_fma_f32 v[102:103], v[38:39], v[216:217], v[102:103]
	v_pk_fma_f32 v[104:105], v[40:41], v[218:219], v[104:105]
	v_lshlrev_b32_e32 v220, 16, v244
	v_and_b32_e32 v221, 0xffff0000, v244
	v_lshlrev_b32_e32 v222, 16, v245
	v_and_b32_e32 v223, 0xffff0000, v245
	v_pk_fma_f32 v[106:107], v[42:43], v[220:221], v[106:107]
	v_pk_fma_f32 v[108:109], v[44:45], v[222:223], v[108:109]
	v_lshlrev_b32_e32 v224, 16, v246
	v_and_b32_e32 v225, 0xffff0000, v246
	v_lshlrev_b32_e32 v226, 16, v247
	v_and_b32_e32 v227, 0xffff0000, v247
	v_pk_fma_f32 v[110:111], v[46:47], v[224:225], v[110:111]
	v_pk_fma_f32 v[112:113], v[48:49], v[226:227], v[112:113]
	v_lshlrev_b32_e32 v228, 16, v248
	v_and_b32_e32 v229, 0xffff0000, v248
	v_lshlrev_b32_e32 v230, 16, v249
	v_and_b32_e32 v231, 0xffff0000, v249
	v_pk_fma_f32 v[114:115], v[50:51], v[228:229], v[114:115]
	v_pk_fma_f32 v[116:117], v[52:53], v[230:231], v[116:117]
	v_lshlrev_b32_e32 v232, 16, v250
	v_and_b32_e32 v233, 0xffff0000, v250
	v_lshlrev_b32_e32 v234, 16, v251
	v_and_b32_e32 v235, 0xffff0000, v251
	v_pk_fma_f32 v[118:119], v[54:55], v[232:233], v[118:119]
	v_pk_fma_f32 v[120:121], v[56:57], v[234:235], v[120:121]
	v_lshlrev_b32_e32 v236, 16, v166
	v_and_b32_e32 v237, 0xffff0000, v166
	v_lshlrev_b32_e32 v238, 16, v167
	v_and_b32_e32 v239, 0xffff0000, v167
	v_pk_fma_f32 v[122:123], v[58:59], v[236:237], v[122:123]
	v_pk_fma_f32 v[124:125], v[60:61], v[238:239], v[124:125]
	v_lshlrev_b32_e32 v240, 16, v194
	v_and_b32_e32 v241, 0xffff0000, v194
	v_lshlrev_b32_e32 v242, 16, v195
	v_and_b32_e32 v243, 0xffff0000, v195
	v_pk_fma_f32 v[126:127], v[62:63], v[240:241], v[126:127]
	v_pk_fma_f32 v[128:129], v[64:65], v[242:243], v[128:129]
	s_barrier
	v_add_u32_e32 v204, 0x18000, v200
	v_add_u32_e32 v205, 0x18000, v202
	ds_read_b128 v[130:133], v204 offset:0
	ds_read_b128 v[134:137], v204 offset:2048
	ds_read_b128 v[138:141], v204 offset:4096
	ds_read_b128 v[142:145], v204 offset:6144
	ds_read_b128 v[146:149], v205 offset:0
	ds_read_b128 v[150:153], v205 offset:2048
	ds_read_b128 v[154:157], v205 offset:4096
	ds_read_b128 v[158:161], v205 offset:6144
	v_add_u32_e32 v204, 0x18000, v201
	v_add_u32_e32 v205, 0x18000, v203
	ds_read_b128 v[212:215], v204 offset:0
	ds_read_b128 v[216:219], v204 offset:2048
	ds_read_b128 v[220:223], v204 offset:4096
	ds_read_b128 v[224:227], v204 offset:6144
	ds_read_b128 v[228:231], v205 offset:0
	ds_read_b128 v[232:235], v205 offset:2048
	ds_read_b128 v[236:239], v205 offset:4096
	ds_read_b128 v[240:243], v205 offset:6144
	s_add_u32 m0, s76, 0xc000
	s_nop 0
	global_load_lds_dwordx4 v196, s[68:69]
	s_add_u32 m0, s76, 0xe000
	s_nop 0
	global_load_lds_dwordx4 v197, s[68:69]
	s_add_u32 m0, s76, 0x10000
	s_nop 0
	global_load_lds_dwordx4 v198, s[68:69]
	s_add_u32 m0, s76, 0x12000
	s_nop 0
	global_load_lds_dwordx4 v199, s[68:69]
	s_add_u32 m0, s76, 0x14000
	s_nop 0
	global_load_lds_dwordx4 v196, s[70:71]
	s_add_u32 m0, s76, 0x16000
	s_nop 0
	global_load_lds_dwordx4 v197, s[70:71]
	s_add_u32 s68, s68, 0x80
	s_addc_u32 s69, s69, 0
	s_add_u32 s70, s70, 0x80
	s_addc_u32 s71, s71, 0
	global_load_dwordx2 v[174:175], v206, s[72:73] offset:0
	global_load_dwordx2 v[176:177], v206, s[72:73] offset:32
	global_load_dwordx2 v[178:179], v206, s[72:73] offset:64
	global_load_dwordx2 v[180:181], v206, s[72:73] offset:96
	global_load_dwordx2 v[182:183], v207, s[72:73] offset:0
	global_load_dwordx2 v[184:185], v207, s[72:73] offset:32
	s_waitcnt vmcnt(12)
	s_waitcnt lgkmcnt(0)
	s_barrier
	s_setprio 1
	v_mfma_f32_16x16x32_bf16 v[2:5], v[146:149], v[130:133], 0
	v_mfma_f32_16x16x32_bf16 v[6:9], v[150:153], v[130:133], 0
	v_mfma_f32_16x16x32_bf16 v[10:13], v[154:157], v[130:133], 0
	v_mfma_f32_16x16x32_bf16 v[14:17], v[158:161], v[130:133], 0
	v_mfma_f32_16x16x32_bf16 v[18:21], v[146:149], v[134:137], 0
	v_mfma_f32_16x16x32_bf16 v[22:25], v[150:153], v[134:137], 0
	v_mfma_f32_16x16x32_bf16 v[26:29], v[154:157], v[134:137], 0
	v_mfma_f32_16x16x32_bf16 v[30:33], v[158:161], v[134:137], 0
	v_mfma_f32_16x16x32_bf16 v[34:37], v[146:149], v[138:141], 0
	v_mfma_f32_16x16x32_bf16 v[38:41], v[150:153], v[138:141], 0
	v_mfma_f32_16x16x32_bf16 v[42:45], v[154:157], v[138:141], 0
	v_mfma_f32_16x16x32_bf16 v[46:49], v[158:161], v[138:141], 0
	v_mfma_f32_16x16x32_bf16 v[50:53], v[146:149], v[142:145], 0
	v_mfma_f32_16x16x32_bf16 v[54:57], v[150:153], v[142:145], 0
	v_mfma_f32_16x16x32_bf16 v[58:61], v[154:157], v[142:145], 0
	v_mfma_f32_16x16x32_bf16 v[62:65], v[158:161], v[142:145], 0
	v_mfma_f32_16x16x32_bf16 v[2:5], v[228:231], v[212:215], v[2:5]
	v_mfma_f32_16x16x32_bf16 v[6:9], v[232:235], v[212:215], v[6:9]
	v_mfma_f32_16x16x32_bf16 v[10:13], v[236:239], v[212:215], v[10:13]
	v_mfma_f32_16x16x32_bf16 v[14:17], v[240:243], v[212:215], v[14:17]
	v_mfma_f32_16x16x32_bf16 v[18:21], v[228:231], v[216:219], v[18:21]
	v_mfma_f32_16x16x32_bf16 v[22:25], v[232:235], v[216:219], v[22:25]
	v_mfma_f32_16x16x32_bf16 v[26:29], v[236:239], v[216:219], v[26:29]
	v_mfma_f32_16x16x32_bf16 v[30:33], v[240:243], v[216:219], v[30:33]
	v_mfma_f32_16x16x32_bf16 v[34:37], v[228:231], v[220:223], v[34:37]
	v_mfma_f32_16x16x32_bf16 v[38:41], v[232:235], v[220:223], v[38:41]
	v_mfma_f32_16x16x32_bf16 v[42:45], v[236:239], v[220:223], v[42:45]
	v_mfma_f32_16x16x32_bf16 v[46:49], v[240:243], v[220:223], v[46:49]
	v_mfma_f32_16x16x32_bf16 v[50:53], v[228:231], v[224:227], v[50:53]
	v_mfma_f32_16x16x32_bf16 v[54:57], v[232:235], v[224:227], v[54:57]
	v_mfma_f32_16x16x32_bf16 v[58:61], v[236:239], v[224:227], v[58:61]
	v_mfma_f32_16x16x32_bf16 v[62:65], v[240:243], v[224:227], v[62:65]
	s_setprio 0
	s_barrier
	v_add_u32_e32 v204, 0x0, v200
	v_add_u32_e32 v205, 0x0, v202
	ds_read_b128 v[130:133], v204 offset:0
	ds_read_b128 v[134:137], v204 offset:2048
	ds_read_b128 v[138:141], v204 offset:4096
	ds_read_b128 v[142:145], v204 offset:6144
	ds_read_b128 v[146:149], v205 offset:0
	ds_read_b128 v[150:153], v205 offset:2048
	ds_read_b128 v[154:157], v205 offset:4096
	ds_read_b128 v[158:161], v205 offset:6144
	v_add_u32_e32 v204, 0x0, v201
	v_add_u32_e32 v205, 0x0, v203
	ds_read_b128 v[212:215], v204 offset:0
	ds_read_b128 v[216:219], v204 offset:2048
	ds_read_b128 v[220:223], v204 offset:4096
	ds_read_b128 v[224:227], v204 offset:6144
	ds_read_b128 v[228:231], v205 offset:0
	ds_read_b128 v[232:235], v205 offset:2048
	ds_read_b128 v[236:239], v205 offset:4096
	ds_read_b128 v[240:243], v205 offset:6144
	s_add_u32 m0, s76, 0x18000
	s_nop 0
	global_load_lds_dwordx4 v196, s[68:69]
	s_add_u32 m0, s76, 0x1a000
	s_nop 0
	global_load_lds_dwordx4 v197, s[68:69]
	s_add_u32 m0, s76, 0x1c000
	s_nop 0
	global_load_lds_dwordx4 v198, s[68:69]
	s_add_u32 m0, s76, 0x1e000
	s_nop 0
	global_load_lds_dwordx4 v199, s[68:69]
	s_add_u32 m0, s76, 0x20000
	s_nop 0
	global_load_lds_dwordx4 v196, s[70:71]
	s_add_u32 m0, s76, 0x22000
	s_nop 0
	global_load_lds_dwordx4 v197, s[70:71]
	s_add_u32 s68, s68, 0x80
	s_addc_u32 s69, s69, 0
	s_add_u32 s70, s70, 0x80
	s_addc_u32 s71, s71, 0
	global_load_dwordx2 v[186:187], v207, s[72:73] offset:64
	global_load_dwordx2 v[188:189], v207, s[72:73] offset:96
	global_load_dwordx2 v[190:191], v208, s[72:73] offset:0
	global_load_dwordx2 v[192:193], v208, s[72:73] offset:32
	global_load_dwordx2 v[244:245], v208, s[72:73] offset:64
	global_load_dwordx2 v[246:247], v208, s[72:73] offset:96
	s_waitcnt vmcnt(18)
	s_waitcnt lgkmcnt(0)
	s_barrier
	s_setprio 1
	v_mfma_f32_16x16x32_bf16 v[2:5], v[146:149], v[130:133], v[2:5]
	v_mfma_f32_16x16x32_bf16 v[6:9], v[150:153], v[130:133], v[6:9]
	v_mfma_f32_16x16x32_bf16 v[10:13], v[154:157], v[130:133], v[10:13]
	v_mfma_f32_16x16x32_bf16 v[14:17], v[158:161], v[130:133], v[14:17]
	v_mfma_f32_16x16x32_bf16 v[18:21], v[146:149], v[134:137], v[18:21]
	v_mfma_f32_16x16x32_bf16 v[22:25], v[150:153], v[134:137], v[22:25]
	v_mfma_f32_16x16x32_bf16 v[26:29], v[154:157], v[134:137], v[26:29]
	v_mfma_f32_16x16x32_bf16 v[30:33], v[158:161], v[134:137], v[30:33]
	v_mfma_f32_16x16x32_bf16 v[34:37], v[146:149], v[138:141], v[34:37]
	v_mfma_f32_16x16x32_bf16 v[38:41], v[150:153], v[138:141], v[38:41]
	v_mfma_f32_16x16x32_bf16 v[42:45], v[154:157], v[138:141], v[42:45]
	v_mfma_f32_16x16x32_bf16 v[46:49], v[158:161], v[138:141], v[46:49]
	v_mfma_f32_16x16x32_bf16 v[50:53], v[146:149], v[142:145], v[50:53]
	v_mfma_f32_16x16x32_bf16 v[54:57], v[150:153], v[142:145], v[54:57]
	v_mfma_f32_16x16x32_bf16 v[58:61], v[154:157], v[142:145], v[58:61]
	v_mfma_f32_16x16x32_bf16 v[62:65], v[158:161], v[142:145], v[62:65]
	v_mfma_f32_16x16x32_bf16 v[2:5], v[228:231], v[212:215], v[2:5]
	v_mfma_f32_16x16x32_bf16 v[6:9], v[232:235], v[212:215], v[6:9]
	v_mfma_f32_16x16x32_bf16 v[10:13], v[236:239], v[212:215], v[10:13]
	v_mfma_f32_16x16x32_bf16 v[14:17], v[240:243], v[212:215], v[14:17]
	v_mfma_f32_16x16x32_bf16 v[18:21], v[228:231], v[216:219], v[18:21]
	v_mfma_f32_16x16x32_bf16 v[22:25], v[232:235], v[216:219], v[22:25]
	v_mfma_f32_16x16x32_bf16 v[26:29], v[236:239], v[216:219], v[26:29]
	v_mfma_f32_16x16x32_bf16 v[30:33], v[240:243], v[216:219], v[30:33]
	v_mfma_f32_16x16x32_bf16 v[34:37], v[228:231], v[220:223], v[34:37]
	v_mfma_f32_16x16x32_bf16 v[38:41], v[232:235], v[220:223], v[38:41]
	v_mfma_f32_16x16x32_bf16 v[42:45], v[236:239], v[220:223], v[42:45]
	v_mfma_f32_16x16x32_bf16 v[46:49], v[240:243], v[220:223], v[46:49]
	v_mfma_f32_16x16x32_bf16 v[50:53], v[228:231], v[224:227], v[50:53]
	v_mfma_f32_16x16x32_bf16 v[54:57], v[232:235], v[224:227], v[54:57]
	v_mfma_f32_16x16x32_bf16 v[58:61], v[236:239], v[224:227], v[58:61]
	v_mfma_f32_16x16x32_bf16 v[62:65], v[240:243], v[224:227], v[62:65]
	s_setprio 0
	s_barrier
	v_add_u32_e32 v204, 0xc000, v200
	v_add_u32_e32 v205, 0xc000, v202
	ds_read_b128 v[130:133], v204 offset:0
	ds_read_b128 v[134:137], v204 offset:2048
	ds_read_b128 v[138:141], v204 offset:4096
	ds_read_b128 v[142:145], v204 offset:6144
	ds_read_b128 v[146:149], v205 offset:0
	ds_read_b128 v[150:153], v205 offset:2048
	ds_read_b128 v[154:157], v205 offset:4096
	ds_read_b128 v[158:161], v205 offset:6144
	v_add_u32_e32 v204, 0xc000, v201
	v_add_u32_e32 v205, 0xc000, v203
	ds_read_b128 v[212:215], v204 offset:0
	ds_read_b128 v[216:219], v204 offset:2048
	ds_read_b128 v[220:223], v204 offset:4096
	ds_read_b128 v[224:227], v204 offset:6144
	ds_read_b128 v[228:231], v205 offset:0
	ds_read_b128 v[232:235], v205 offset:2048
	ds_read_b128 v[236:239], v205 offset:4096
	ds_read_b128 v[240:243], v205 offset:6144
	s_add_u32 m0, s76, 0x0
	s_nop 0
	global_load_lds_dwordx4 v196, s[68:69]
	s_add_u32 m0, s76, 0x2000
	s_nop 0
	global_load_lds_dwordx4 v197, s[68:69]
	s_add_u32 m0, s76, 0x4000
	s_nop 0
	global_load_lds_dwordx4 v198, s[68:69]
	s_add_u32 m0, s76, 0x6000
	s_nop 0
	global_load_lds_dwordx4 v199, s[68:69]
	s_add_u32 m0, s76, 0x8000
	s_nop 0
	global_load_lds_dwordx4 v196, s[70:71]
	s_add_u32 m0, s76, 0xa000
	s_nop 0
	global_load_lds_dwordx4 v197, s[70:71]
	s_add_u32 s68, s68, 0x80
	s_addc_u32 s69, s69, 0
	s_add_u32 s70, s70, 0x80
	s_addc_u32 s71, s71, 0
	global_load_dwordx2 v[248:249], v209, s[72:73] offset:0
	global_load_dwordx2 v[250:251], v209, s[72:73] offset:32
	global_load_dwordx2 v[166:167], v209, s[72:73] offset:64
	global_load_dwordx2 v[194:195], v209, s[72:73] offset:96
	s_add_u32 s72, s72, 0x800
	s_addc_u32 s73, s73, 0
	s_waitcnt vmcnt(16)
	s_waitcnt lgkmcnt(0)
	s_barrier
	s_setprio 1
	v_mfma_f32_16x16x32_bf16 v[2:5], v[146:149], v[130:133], v[2:5]
	v_mfma_f32_16x16x32_bf16 v[6:9], v[150:153], v[130:133], v[6:9]
	v_mfma_f32_16x16x32_bf16 v[10:13], v[154:157], v[130:133], v[10:13]
	v_mfma_f32_16x16x32_bf16 v[14:17], v[158:161], v[130:133], v[14:17]
	v_mfma_f32_16x16x32_bf16 v[18:21], v[146:149], v[134:137], v[18:21]
	v_mfma_f32_16x16x32_bf16 v[22:25], v[150:153], v[134:137], v[22:25]
	v_mfma_f32_16x16x32_bf16 v[26:29], v[154:157], v[134:137], v[26:29]
	v_mfma_f32_16x16x32_bf16 v[30:33], v[158:161], v[134:137], v[30:33]
	v_mfma_f32_16x16x32_bf16 v[34:37], v[146:149], v[138:141], v[34:37]
	v_mfma_f32_16x16x32_bf16 v[38:41], v[150:153], v[138:141], v[38:41]
	v_mfma_f32_16x16x32_bf16 v[42:45], v[154:157], v[138:141], v[42:45]
	v_mfma_f32_16x16x32_bf16 v[46:49], v[158:161], v[138:141], v[46:49]
	v_mfma_f32_16x16x32_bf16 v[50:53], v[146:149], v[142:145], v[50:53]
	v_mfma_f32_16x16x32_bf16 v[54:57], v[150:153], v[142:145], v[54:57]
	v_mfma_f32_16x16x32_bf16 v[58:61], v[154:157], v[142:145], v[58:61]
	v_mfma_f32_16x16x32_bf16 v[62:65], v[158:161], v[142:145], v[62:65]
	v_mfma_f32_16x16x32_bf16 v[2:5], v[228:231], v[212:215], v[2:5]
	v_mfma_f32_16x16x32_bf16 v[6:9], v[232:235], v[212:215], v[6:9]
	v_mfma_f32_16x16x32_bf16 v[10:13], v[236:239], v[212:215], v[10:13]
	v_mfma_f32_16x16x32_bf16 v[14:17], v[240:243], v[212:215], v[14:17]
	v_mfma_f32_16x16x32_bf16 v[18:21], v[228:231], v[216:219], v[18:21]
	v_mfma_f32_16x16x32_bf16 v[22:25], v[232:235], v[216:219], v[22:25]
	v_mfma_f32_16x16x32_bf16 v[26:29], v[236:239], v[216:219], v[26:29]
	v_mfma_f32_16x16x32_bf16 v[30:33], v[240:243], v[216:219], v[30:33]
	v_mfma_f32_16x16x32_bf16 v[34:37], v[228:231], v[220:223], v[34:37]
	v_mfma_f32_16x16x32_bf16 v[38:41], v[232:235], v[220:223], v[38:41]
	v_mfma_f32_16x16x32_bf16 v[42:45], v[236:239], v[220:223], v[42:45]
	v_mfma_f32_16x16x32_bf16 v[46:49], v[240:243], v[220:223], v[46:49]
	v_mfma_f32_16x16x32_bf16 v[50:53], v[228:231], v[224:227], v[50:53]
	v_mfma_f32_16x16x32_bf16 v[54:57], v[232:235], v[224:227], v[54:57]
	v_mfma_f32_16x16x32_bf16 v[58:61], v[236:239], v[224:227], v[58:61]
	v_mfma_f32_16x16x32_bf16 v[62:65], v[240:243], v[224:227], v[62:65]
	s_setprio 0
	s_barrier
	v_add_u32_e32 v204, 0x18000, v200
	v_add_u32_e32 v205, 0x18000, v202
	ds_read_b128 v[130:133], v204 offset:0
	ds_read_b128 v[134:137], v204 offset:2048
	ds_read_b128 v[138:141], v204 offset:4096
	ds_read_b128 v[142:145], v204 offset:6144
	ds_read_b128 v[146:149], v205 offset:0
	ds_read_b128 v[150:153], v205 offset:2048
	ds_read_b128 v[154:157], v205 offset:4096
	ds_read_b128 v[158:161], v205 offset:6144
	v_add_u32_e32 v204, 0x18000, v201
	v_add_u32_e32 v205, 0x18000, v203
	ds_read_b128 v[212:215], v204 offset:0
	ds_read_b128 v[216:219], v204 offset:2048
	ds_read_b128 v[220:223], v204 offset:4096
	ds_read_b128 v[224:227], v204 offset:6144
	ds_read_b128 v[228:231], v205 offset:0
	ds_read_b128 v[232:235], v205 offset:2048
	ds_read_b128 v[236:239], v205 offset:4096
	ds_read_b128 v[240:243], v205 offset:6144
	s_add_u32 m0, s76, 0xc000
	s_nop 0
	global_load_lds_dwordx4 v196, s[68:69]
	s_add_u32 m0, s76, 0xe000
	s_nop 0
	global_load_lds_dwordx4 v197, s[68:69]
	s_add_u32 m0, s76, 0x10000
	s_nop 0
	global_load_lds_dwordx4 v198, s[68:69]
	s_add_u32 m0, s76, 0x12000
	s_nop 0
	global_load_lds_dwordx4 v199, s[68:69]
	s_add_u32 m0, s76, 0x14000
	s_nop 0
	global_load_lds_dwordx4 v196, s[70:71]
	s_add_u32 m0, s76, 0x16000
	s_nop 0
	global_load_lds_dwordx4 v197, s[70:71]
	s_add_u32 s68, s68, 0x80
	s_addc_u32 s69, s69, 0
	s_add_u32 s70, s70, 0x80
	s_addc_u32 s71, s71, 0
	s_waitcnt vmcnt(10)
	s_waitcnt lgkmcnt(0)
	s_barrier
	s_setprio 1
	v_mfma_f32_16x16x32_bf16 v[2:5], v[146:149], v[130:133], v[2:5]
	v_mfma_f32_16x16x32_bf16 v[6:9], v[150:153], v[130:133], v[6:9]
	v_mfma_f32_16x16x32_bf16 v[10:13], v[154:157], v[130:133], v[10:13]
	v_mfma_f32_16x16x32_bf16 v[14:17], v[158:161], v[130:133], v[14:17]
	v_mfma_f32_16x16x32_bf16 v[18:21], v[146:149], v[134:137], v[18:21]
	v_mfma_f32_16x16x32_bf16 v[22:25], v[150:153], v[134:137], v[22:25]
	v_mfma_f32_16x16x32_bf16 v[26:29], v[154:157], v[134:137], v[26:29]
	v_mfma_f32_16x16x32_bf16 v[30:33], v[158:161], v[134:137], v[30:33]
	v_mfma_f32_16x16x32_bf16 v[34:37], v[146:149], v[138:141], v[34:37]
	v_mfma_f32_16x16x32_bf16 v[38:41], v[150:153], v[138:141], v[38:41]
	v_mfma_f32_16x16x32_bf16 v[42:45], v[154:157], v[138:141], v[42:45]
	v_mfma_f32_16x16x32_bf16 v[46:49], v[158:161], v[138:141], v[46:49]
	v_mfma_f32_16x16x32_bf16 v[50:53], v[146:149], v[142:145], v[50:53]
	v_mfma_f32_16x16x32_bf16 v[54:57], v[150:153], v[142:145], v[54:57]
	v_mfma_f32_16x16x32_bf16 v[58:61], v[154:157], v[142:145], v[58:61]
	v_mfma_f32_16x16x32_bf16 v[62:65], v[158:161], v[142:145], v[62:65]
	v_mfma_f32_16x16x32_bf16 v[2:5], v[228:231], v[212:215], v[2:5]
	v_mfma_f32_16x16x32_bf16 v[6:9], v[232:235], v[212:215], v[6:9]
	v_mfma_f32_16x16x32_bf16 v[10:13], v[236:239], v[212:215], v[10:13]
	v_mfma_f32_16x16x32_bf16 v[14:17], v[240:243], v[212:215], v[14:17]
	v_mfma_f32_16x16x32_bf16 v[18:21], v[228:231], v[216:219], v[18:21]
	v_mfma_f32_16x16x32_bf16 v[22:25], v[232:235], v[216:219], v[22:25]
	v_mfma_f32_16x16x32_bf16 v[26:29], v[236:239], v[216:219], v[26:29]
	v_mfma_f32_16x16x32_bf16 v[30:33], v[240:243], v[216:219], v[30:33]
	v_mfma_f32_16x16x32_bf16 v[34:37], v[228:231], v[220:223], v[34:37]
	v_mfma_f32_16x16x32_bf16 v[38:41], v[232:235], v[220:223], v[38:41]
	v_mfma_f32_16x16x32_bf16 v[42:45], v[236:239], v[220:223], v[42:45]
	v_mfma_f32_16x16x32_bf16 v[46:49], v[240:243], v[220:223], v[46:49]
	v_mfma_f32_16x16x32_bf16 v[50:53], v[228:231], v[224:227], v[50:53]
	v_mfma_f32_16x16x32_bf16 v[54:57], v[232:235], v[224:227], v[54:57]
	v_mfma_f32_16x16x32_bf16 v[58:61], v[236:239], v[224:227], v[58:61]
	v_mfma_f32_16x16x32_bf16 v[62:65], v[240:243], v[224:227], v[62:65]
	s_setprio 0
	s_barrier
	v_add_u32_e32 v204, 0x0, v200
	v_add_u32_e32 v205, 0x0, v202
	ds_read_b128 v[130:133], v204 offset:0
	ds_read_b128 v[134:137], v204 offset:2048
	ds_read_b128 v[138:141], v204 offset:4096
	ds_read_b128 v[142:145], v204 offset:6144
	ds_read_b128 v[146:149], v205 offset:0
	ds_read_b128 v[150:153], v205 offset:2048
	ds_read_b128 v[154:157], v205 offset:4096
	ds_read_b128 v[158:161], v205 offset:6144
	v_add_u32_e32 v204, 0x0, v201
	v_add_u32_e32 v205, 0x0, v203
	ds_read_b128 v[212:215], v204 offset:0
	ds_read_b128 v[216:219], v204 offset:2048
	ds_read_b128 v[220:223], v204 offset:4096
	ds_read_b128 v[224:227], v204 offset:6144
	ds_read_b128 v[228:231], v205 offset:0
	ds_read_b128 v[232:235], v205 offset:2048
	ds_read_b128 v[236:239], v205 offset:4096
	ds_read_b128 v[240:243], v205 offset:6144
	s_add_u32 m0, s76, 0x18000
	s_nop 0
	global_load_lds_dwordx4 v196, s[68:69]
	s_add_u32 m0, s76, 0x1a000
	s_nop 0
	global_load_lds_dwordx4 v197, s[68:69]
	s_add_u32 m0, s76, 0x1c000
	s_nop 0
	global_load_lds_dwordx4 v198, s[68:69]
	s_add_u32 m0, s76, 0x1e000
	s_nop 0
	global_load_lds_dwordx4 v199, s[68:69]
	s_add_u32 m0, s76, 0x20000
	s_nop 0
	global_load_lds_dwordx4 v196, s[70:71]
	s_add_u32 m0, s76, 0x22000
	s_nop 0
	global_load_lds_dwordx4 v197, s[70:71]
	s_add_u32 s68, s68, 0x80
	s_addc_u32 s69, s69, 0
	s_add_u32 s70, s70, 0x80
	s_addc_u32 s71, s71, 0
	s_waitcnt vmcnt(6)
	s_waitcnt lgkmcnt(0)
	s_barrier
	s_setprio 1
	v_mfma_f32_16x16x32_bf16 v[2:5], v[146:149], v[130:133], v[2:5]
	v_mfma_f32_16x16x32_bf16 v[6:9], v[150:153], v[130:133], v[6:9]
	v_mfma_f32_16x16x32_bf16 v[10:13], v[154:157], v[130:133], v[10:13]
	v_mfma_f32_16x16x32_bf16 v[14:17], v[158:161], v[130:133], v[14:17]
	v_mfma_f32_16x16x32_bf16 v[18:21], v[146:149], v[134:137], v[18:21]
	v_mfma_f32_16x16x32_bf16 v[22:25], v[150:153], v[134:137], v[22:25]
	v_mfma_f32_16x16x32_bf16 v[26:29], v[154:157], v[134:137], v[26:29]
	v_mfma_f32_16x16x32_bf16 v[30:33], v[158:161], v[134:137], v[30:33]
	v_mfma_f32_16x16x32_bf16 v[34:37], v[146:149], v[138:141], v[34:37]
	v_mfma_f32_16x16x32_bf16 v[38:41], v[150:153], v[138:141], v[38:41]
	v_mfma_f32_16x16x32_bf16 v[42:45], v[154:157], v[138:141], v[42:45]
	v_mfma_f32_16x16x32_bf16 v[46:49], v[158:161], v[138:141], v[46:49]
	v_mfma_f32_16x16x32_bf16 v[50:53], v[146:149], v[142:145], v[50:53]
	v_mfma_f32_16x16x32_bf16 v[54:57], v[150:153], v[142:145], v[54:57]
	v_mfma_f32_16x16x32_bf16 v[58:61], v[154:157], v[142:145], v[58:61]
	v_mfma_f32_16x16x32_bf16 v[62:65], v[158:161], v[142:145], v[62:65]
	v_mfma_f32_16x16x32_bf16 v[2:5], v[228:231], v[212:215], v[2:5]
	v_mfma_f32_16x16x32_bf16 v[6:9], v[232:235], v[212:215], v[6:9]
	v_mfma_f32_16x16x32_bf16 v[10:13], v[236:239], v[212:215], v[10:13]
	v_mfma_f32_16x16x32_bf16 v[14:17], v[240:243], v[212:215], v[14:17]
	v_mfma_f32_16x16x32_bf16 v[18:21], v[228:231], v[216:219], v[18:21]
	v_mfma_f32_16x16x32_bf16 v[22:25], v[232:235], v[216:219], v[22:25]
	v_mfma_f32_16x16x32_bf16 v[26:29], v[236:239], v[216:219], v[26:29]
	v_mfma_f32_16x16x32_bf16 v[30:33], v[240:243], v[216:219], v[30:33]
	v_mfma_f32_16x16x32_bf16 v[34:37], v[228:231], v[220:223], v[34:37]
	v_mfma_f32_16x16x32_bf16 v[38:41], v[232:235], v[220:223], v[38:41]
	v_mfma_f32_16x16x32_bf16 v[42:45], v[236:239], v[220:223], v[42:45]
	v_mfma_f32_16x16x32_bf16 v[46:49], v[240:243], v[220:223], v[46:49]
	v_mfma_f32_16x16x32_bf16 v[50:53], v[228:231], v[224:227], v[50:53]
	v_mfma_f32_16x16x32_bf16 v[54:57], v[232:235], v[224:227], v[54:57]
	v_mfma_f32_16x16x32_bf16 v[58:61], v[236:239], v[224:227], v[58:61]
	v_mfma_f32_16x16x32_bf16 v[62:65], v[240:243], v[224:227], v[62:65]
	s_setprio 0
	s_barrier
	v_add_u32_e32 v204, 0xc000, v200
	v_add_u32_e32 v205, 0xc000, v202
	ds_read_b128 v[130:133], v204 offset:0
	ds_read_b128 v[134:137], v204 offset:2048
	ds_read_b128 v[138:141], v204 offset:4096
	ds_read_b128 v[142:145], v204 offset:6144
	ds_read_b128 v[146:149], v205 offset:0
	ds_read_b128 v[150:153], v205 offset:2048
	ds_read_b128 v[154:157], v205 offset:4096
	ds_read_b128 v[158:161], v205 offset:6144
	v_add_u32_e32 v204, 0xc000, v201
	v_add_u32_e32 v205, 0xc000, v203
	ds_read_b128 v[212:215], v204 offset:0
	ds_read_b128 v[216:219], v204 offset:2048
	ds_read_b128 v[220:223], v204 offset:4096
	ds_read_b128 v[224:227], v204 offset:6144
	ds_read_b128 v[228:231], v205 offset:0
	ds_read_b128 v[232:235], v205 offset:2048
	ds_read_b128 v[236:239], v205 offset:4096
	ds_read_b128 v[240:243], v205 offset:6144
	s_add_u32 m0, s76, 0x0
	s_nop 0
	global_load_lds_dwordx4 v196, s[68:69]
	s_add_u32 m0, s76, 0x2000
	s_nop 0
	global_load_lds_dwordx4 v197, s[68:69]
	s_add_u32 m0, s76, 0x4000
	s_nop 0
	global_load_lds_dwordx4 v198, s[68:69]
	s_add_u32 m0, s76, 0x6000
	s_nop 0
	global_load_lds_dwordx4 v199, s[68:69]
	s_add_u32 m0, s76, 0x8000
	s_nop 0
	global_load_lds_dwordx4 v196, s[70:71]
	s_add_u32 m0, s76, 0xa000
	s_nop 0
	global_load_lds_dwordx4 v197, s[70:71]
	s_add_u32 s68, s68, 0x80
	s_addc_u32 s69, s69, 0
	s_add_u32 s70, s70, 0x80
	s_addc_u32 s71, s71, 0
	s_waitcnt vmcnt(6)
	s_waitcnt lgkmcnt(0)
	s_barrier
	s_setprio 1
	v_mfma_f32_16x16x32_bf16 v[2:5], v[146:149], v[130:133], v[2:5]
	v_mfma_f32_16x16x32_bf16 v[6:9], v[150:153], v[130:133], v[6:9]
	v_mfma_f32_16x16x32_bf16 v[10:13], v[154:157], v[130:133], v[10:13]
	v_mfma_f32_16x16x32_bf16 v[14:17], v[158:161], v[130:133], v[14:17]
	v_mfma_f32_16x16x32_bf16 v[18:21], v[146:149], v[134:137], v[18:21]
	v_mfma_f32_16x16x32_bf16 v[22:25], v[150:153], v[134:137], v[22:25]
	v_mfma_f32_16x16x32_bf16 v[26:29], v[154:157], v[134:137], v[26:29]
	v_mfma_f32_16x16x32_bf16 v[30:33], v[158:161], v[134:137], v[30:33]
	v_mfma_f32_16x16x32_bf16 v[34:37], v[146:149], v[138:141], v[34:37]
	v_mfma_f32_16x16x32_bf16 v[38:41], v[150:153], v[138:141], v[38:41]
	v_mfma_f32_16x16x32_bf16 v[42:45], v[154:157], v[138:141], v[42:45]
	v_mfma_f32_16x16x32_bf16 v[46:49], v[158:161], v[138:141], v[46:49]
	v_mfma_f32_16x16x32_bf16 v[50:53], v[146:149], v[142:145], v[50:53]
	v_mfma_f32_16x16x32_bf16 v[54:57], v[150:153], v[142:145], v[54:57]
	v_mfma_f32_16x16x32_bf16 v[58:61], v[154:157], v[142:145], v[58:61]
	v_mfma_f32_16x16x32_bf16 v[62:65], v[158:161], v[142:145], v[62:65]
	v_mfma_f32_16x16x32_bf16 v[2:5], v[228:231], v[212:215], v[2:5]
	v_mfma_f32_16x16x32_bf16 v[6:9], v[232:235], v[212:215], v[6:9]
	v_mfma_f32_16x16x32_bf16 v[10:13], v[236:239], v[212:215], v[10:13]
	v_mfma_f32_16x16x32_bf16 v[14:17], v[240:243], v[212:215], v[14:17]
	v_mfma_f32_16x16x32_bf16 v[18:21], v[228:231], v[216:219], v[18:21]
	v_mfma_f32_16x16x32_bf16 v[22:25], v[232:235], v[216:219], v[22:25]
	v_mfma_f32_16x16x32_bf16 v[26:29], v[236:239], v[216:219], v[26:29]
	v_mfma_f32_16x16x32_bf16 v[30:33], v[240:243], v[216:219], v[30:33]
	v_mfma_f32_16x16x32_bf16 v[34:37], v[228:231], v[220:223], v[34:37]
	v_mfma_f32_16x16x32_bf16 v[38:41], v[232:235], v[220:223], v[38:41]
	v_mfma_f32_16x16x32_bf16 v[42:45], v[236:239], v[220:223], v[42:45]
	v_mfma_f32_16x16x32_bf16 v[46:49], v[240:243], v[220:223], v[46:49]
	v_mfma_f32_16x16x32_bf16 v[50:53], v[228:231], v[224:227], v[50:53]
	v_mfma_f32_16x16x32_bf16 v[54:57], v[232:235], v[224:227], v[54:57]
	v_mfma_f32_16x16x32_bf16 v[58:61], v[236:239], v[224:227], v[58:61]
	v_mfma_f32_16x16x32_bf16 v[62:65], v[240:243], v[224:227], v[62:65]
	s_setprio 0
	s_barrier
	v_add_u32_e32 v204, 0x18000, v200
	v_add_u32_e32 v205, 0x18000, v202
	ds_read_b128 v[130:133], v204 offset:0
	ds_read_b128 v[134:137], v204 offset:2048
	ds_read_b128 v[138:141], v204 offset:4096
	ds_read_b128 v[142:145], v204 offset:6144
	ds_read_b128 v[146:149], v205 offset:0
	ds_read_b128 v[150:153], v205 offset:2048
	ds_read_b128 v[154:157], v205 offset:4096
	ds_read_b128 v[158:161], v205 offset:6144
	v_add_u32_e32 v204, 0x18000, v201
	v_add_u32_e32 v205, 0x18000, v203
	ds_read_b128 v[212:215], v204 offset:0
	ds_read_b128 v[216:219], v204 offset:2048
	ds_read_b128 v[220:223], v204 offset:4096
	ds_read_b128 v[224:227], v204 offset:6144
	ds_read_b128 v[228:231], v205 offset:0
	ds_read_b128 v[232:235], v205 offset:2048
	ds_read_b128 v[236:239], v205 offset:4096
	ds_read_b128 v[240:243], v205 offset:6144
	s_add_u32 m0, s76, 0xc000
	s_nop 0
	global_load_lds_dwordx4 v196, s[68:69]
	s_add_u32 m0, s76, 0xe000
	s_nop 0
	global_load_lds_dwordx4 v197, s[68:69]
	s_add_u32 m0, s76, 0x10000
	s_nop 0
	global_load_lds_dwordx4 v198, s[68:69]
	s_add_u32 m0, s76, 0x12000
	s_nop 0
	global_load_lds_dwordx4 v199, s[68:69]
	s_add_u32 m0, s76, 0x14000
	s_nop 0
	global_load_lds_dwordx4 v196, s[70:71]
	s_add_u32 m0, s76, 0x16000
	s_nop 0
	global_load_lds_dwordx4 v197, s[70:71]
	s_add_u32 s68, s68, 0x80
	s_addc_u32 s69, s69, 0
	s_add_u32 s70, s70, 0x80
	s_addc_u32 s71, s71, 0
	s_waitcnt vmcnt(6)
	s_waitcnt lgkmcnt(0)
	s_barrier
	s_setprio 1
	v_mfma_f32_16x16x32_bf16 v[2:5], v[146:149], v[130:133], v[2:5]
	v_mfma_f32_16x16x32_bf16 v[6:9], v[150:153], v[130:133], v[6:9]
	v_mfma_f32_16x16x32_bf16 v[10:13], v[154:157], v[130:133], v[10:13]
	v_mfma_f32_16x16x32_bf16 v[14:17], v[158:161], v[130:133], v[14:17]
	v_mfma_f32_16x16x32_bf16 v[18:21], v[146:149], v[134:137], v[18:21]
	v_mfma_f32_16x16x32_bf16 v[22:25], v[150:153], v[134:137], v[22:25]
	v_mfma_f32_16x16x32_bf16 v[26:29], v[154:157], v[134:137], v[26:29]
	v_mfma_f32_16x16x32_bf16 v[30:33], v[158:161], v[134:137], v[30:33]
	v_mfma_f32_16x16x32_bf16 v[34:37], v[146:149], v[138:141], v[34:37]
	v_mfma_f32_16x16x32_bf16 v[38:41], v[150:153], v[138:141], v[38:41]
	v_mfma_f32_16x16x32_bf16 v[42:45], v[154:157], v[138:141], v[42:45]
	v_mfma_f32_16x16x32_bf16 v[46:49], v[158:161], v[138:141], v[46:49]
	v_mfma_f32_16x16x32_bf16 v[50:53], v[146:149], v[142:145], v[50:53]
	v_mfma_f32_16x16x32_bf16 v[54:57], v[150:153], v[142:145], v[54:57]
	v_mfma_f32_16x16x32_bf16 v[58:61], v[154:157], v[142:145], v[58:61]
	v_mfma_f32_16x16x32_bf16 v[62:65], v[158:161], v[142:145], v[62:65]
	v_mfma_f32_16x16x32_bf16 v[2:5], v[228:231], v[212:215], v[2:5]
	v_mfma_f32_16x16x32_bf16 v[6:9], v[232:235], v[212:215], v[6:9]
	v_mfma_f32_16x16x32_bf16 v[10:13], v[236:239], v[212:215], v[10:13]
	v_mfma_f32_16x16x32_bf16 v[14:17], v[240:243], v[212:215], v[14:17]
	v_mfma_f32_16x16x32_bf16 v[18:21], v[228:231], v[216:219], v[18:21]
	v_mfma_f32_16x16x32_bf16 v[22:25], v[232:235], v[216:219], v[22:25]
	v_mfma_f32_16x16x32_bf16 v[26:29], v[236:239], v[216:219], v[26:29]
	v_mfma_f32_16x16x32_bf16 v[30:33], v[240:243], v[216:219], v[30:33]
	v_mfma_f32_16x16x32_bf16 v[34:37], v[228:231], v[220:223], v[34:37]
	v_mfma_f32_16x16x32_bf16 v[38:41], v[232:235], v[220:223], v[38:41]
	v_mfma_f32_16x16x32_bf16 v[42:45], v[236:239], v[220:223], v[42:45]
	v_mfma_f32_16x16x32_bf16 v[46:49], v[240:243], v[220:223], v[46:49]
	v_mfma_f32_16x16x32_bf16 v[50:53], v[228:231], v[224:227], v[50:53]
	v_mfma_f32_16x16x32_bf16 v[54:57], v[232:235], v[224:227], v[54:57]
	v_mfma_f32_16x16x32_bf16 v[58:61], v[236:239], v[224:227], v[58:61]
	v_mfma_f32_16x16x32_bf16 v[62:65], v[240:243], v[224:227], v[62:65]
	s_setprio 0
	s_barrier
	v_add_u32_e32 v204, 0x0, v200
	v_add_u32_e32 v205, 0x0, v202
	ds_read_b128 v[130:133], v204 offset:0
	ds_read_b128 v[134:137], v204 offset:2048
	ds_read_b128 v[138:141], v204 offset:4096
	ds_read_b128 v[142:145], v204 offset:6144
	ds_read_b128 v[146:149], v205 offset:0
	ds_read_b128 v[150:153], v205 offset:2048
	ds_read_b128 v[154:157], v205 offset:4096
	ds_read_b128 v[158:161], v205 offset:6144
	v_add_u32_e32 v204, 0x0, v201
	v_add_u32_e32 v205, 0x0, v203
	ds_read_b128 v[212:215], v204 offset:0
	ds_read_b128 v[216:219], v204 offset:2048
	ds_read_b128 v[220:223], v204 offset:4096
	ds_read_b128 v[224:227], v204 offset:6144
	ds_read_b128 v[228:231], v205 offset:0
	ds_read_b128 v[232:235], v205 offset:2048
	ds_read_b128 v[236:239], v205 offset:4096
	ds_read_b128 v[240:243], v205 offset:6144
	s_add_u32 m0, s76, 0x18000
	s_nop 0
	global_load_lds_dwordx4 v196, s[68:69]
	s_add_u32 m0, s76, 0x1a000
	s_nop 0
	global_load_lds_dwordx4 v197, s[68:69]
	s_add_u32 m0, s76, 0x1c000
	s_nop 0
	global_load_lds_dwordx4 v198, s[68:69]
	s_add_u32 m0, s76, 0x1e000
	s_nop 0
	global_load_lds_dwordx4 v199, s[68:69]
	s_add_u32 m0, s76, 0x20000
	s_nop 0
	global_load_lds_dwordx4 v196, s[70:71]
	s_add_u32 m0, s76, 0x22000
	s_nop 0
	global_load_lds_dwordx4 v197, s[70:71]
	s_add_u32 s68, s68, 0x80
	s_addc_u32 s69, s69, 0
	s_add_u32 s70, s70, 0x80
	s_addc_u32 s71, s71, 0
	s_waitcnt vmcnt(6)
	s_waitcnt lgkmcnt(0)
	s_barrier
	s_setprio 1
	v_mfma_f32_16x16x32_bf16 v[2:5], v[146:149], v[130:133], v[2:5]
	v_mfma_f32_16x16x32_bf16 v[6:9], v[150:153], v[130:133], v[6:9]
	v_mfma_f32_16x16x32_bf16 v[10:13], v[154:157], v[130:133], v[10:13]
	v_mfma_f32_16x16x32_bf16 v[14:17], v[158:161], v[130:133], v[14:17]
	v_mfma_f32_16x16x32_bf16 v[18:21], v[146:149], v[134:137], v[18:21]
	v_mfma_f32_16x16x32_bf16 v[22:25], v[150:153], v[134:137], v[22:25]
	v_mfma_f32_16x16x32_bf16 v[26:29], v[154:157], v[134:137], v[26:29]
	v_mfma_f32_16x16x32_bf16 v[30:33], v[158:161], v[134:137], v[30:33]
	v_mfma_f32_16x16x32_bf16 v[34:37], v[146:149], v[138:141], v[34:37]
	v_mfma_f32_16x16x32_bf16 v[38:41], v[150:153], v[138:141], v[38:41]
	v_mfma_f32_16x16x32_bf16 v[42:45], v[154:157], v[138:141], v[42:45]
	v_mfma_f32_16x16x32_bf16 v[46:49], v[158:161], v[138:141], v[46:49]
	v_mfma_f32_16x16x32_bf16 v[50:53], v[146:149], v[142:145], v[50:53]
	v_mfma_f32_16x16x32_bf16 v[54:57], v[150:153], v[142:145], v[54:57]
	v_mfma_f32_16x16x32_bf16 v[58:61], v[154:157], v[142:145], v[58:61]
	v_mfma_f32_16x16x32_bf16 v[62:65], v[158:161], v[142:145], v[62:65]
	v_mfma_f32_16x16x32_bf16 v[2:5], v[228:231], v[212:215], v[2:5]
	v_mfma_f32_16x16x32_bf16 v[6:9], v[232:235], v[212:215], v[6:9]
	v_mfma_f32_16x16x32_bf16 v[10:13], v[236:239], v[212:215], v[10:13]
	v_mfma_f32_16x16x32_bf16 v[14:17], v[240:243], v[212:215], v[14:17]
	v_mfma_f32_16x16x32_bf16 v[18:21], v[228:231], v[216:219], v[18:21]
	v_mfma_f32_16x16x32_bf16 v[22:25], v[232:235], v[216:219], v[22:25]
	v_mfma_f32_16x16x32_bf16 v[26:29], v[236:239], v[216:219], v[26:29]
	v_mfma_f32_16x16x32_bf16 v[30:33], v[240:243], v[216:219], v[30:33]
	v_mfma_f32_16x16x32_bf16 v[34:37], v[228:231], v[220:223], v[34:37]
	v_mfma_f32_16x16x32_bf16 v[38:41], v[232:235], v[220:223], v[38:41]
	v_mfma_f32_16x16x32_bf16 v[42:45], v[236:239], v[220:223], v[42:45]
	v_mfma_f32_16x16x32_bf16 v[46:49], v[240:243], v[220:223], v[46:49]
	v_mfma_f32_16x16x32_bf16 v[50:53], v[228:231], v[224:227], v[50:53]
	v_mfma_f32_16x16x32_bf16 v[54:57], v[232:235], v[224:227], v[54:57]
	v_mfma_f32_16x16x32_bf16 v[58:61], v[236:239], v[224:227], v[58:61]
	v_mfma_f32_16x16x32_bf16 v[62:65], v[240:243], v[224:227], v[62:65]
	s_setprio 0
	s_nop 7
	v_lshlrev_b32_e32 v212, 16, v174
	v_and_b32_e32 v213, 0xffff0000, v174
	v_lshlrev_b32_e32 v214, 16, v175
	v_and_b32_e32 v215, 0xffff0000, v175
	v_pk_fma_f32 v[66:67], v[2:3], v[212:213], v[66:67]
	v_pk_fma_f32 v[68:69], v[4:5], v[214:215], v[68:69]
	v_lshlrev_b32_e32 v216, 16, v176
	v_and_b32_e32 v217, 0xffff0000, v176
	v_lshlrev_b32_e32 v218, 16, v177
	v_and_b32_e32 v219, 0xffff0000, v177
	v_pk_fma_f32 v[70:71], v[6:7], v[216:217], v[70:71]
	v_pk_fma_f32 v[72:73], v[8:9], v[218:219], v[72:73]
	v_lshlrev_b32_e32 v220, 16, v178
	v_and_b32_e32 v221, 0xffff0000, v178
	v_lshlrev_b32_e32 v222, 16, v179
	v_and_b32_e32 v223, 0xffff0000, v179
	v_pk_fma_f32 v[74:75], v[10:11], v[220:221], v[74:75]
	v_pk_fma_f32 v[76:77], v[12:13], v[222:223], v[76:77]
	v_lshlrev_b32_e32 v224, 16, v180
	v_and_b32_e32 v225, 0xffff0000, v180
	v_lshlrev_b32_e32 v226, 16, v181
	v_and_b32_e32 v227, 0xffff0000, v181
	v_pk_fma_f32 v[78:79], v[14:15], v[224:225], v[78:79]
	v_pk_fma_f32 v[80:81], v[16:17], v[226:227], v[80:81]
	v_lshlrev_b32_e32 v228, 16, v182
	v_and_b32_e32 v229, 0xffff0000, v182
	v_lshlrev_b32_e32 v230, 16, v183
	v_and_b32_e32 v231, 0xffff0000, v183
	v_pk_fma_f32 v[82:83], v[18:19], v[228:229], v[82:83]
	v_pk_fma_f32 v[84:85], v[20:21], v[230:231], v[84:85]
	v_lshlrev_b32_e32 v232, 16, v184
	v_and_b32_e32 v233, 0xffff0000, v184
	v_lshlrev_b32_e32 v234, 16, v185
	v_and_b32_e32 v235, 0xffff0000, v185
	v_pk_fma_f32 v[86:87], v[22:23], v[232:233], v[86:87]
	v_pk_fma_f32 v[88:89], v[24:25], v[234:235], v[88:89]
	v_lshlrev_b32_e32 v236, 16, v186
	v_and_b32_e32 v237, 0xffff0000, v186
	v_lshlrev_b32_e32 v238, 16, v187
	v_and_b32_e32 v239, 0xffff0000, v187
	v_pk_fma_f32 v[90:91], v[26:27], v[236:237], v[90:91]
	v_pk_fma_f32 v[92:93], v[28:29], v[238:239], v[92:93]
	v_lshlrev_b32_e32 v240, 16, v188
	v_and_b32_e32 v241, 0xffff0000, v188
	v_lshlrev_b32_e32 v242, 16, v189
	v_and_b32_e32 v243, 0xffff0000, v189
	v_pk_fma_f32 v[94:95], v[30:31], v[240:241], v[94:95]
	v_pk_fma_f32 v[96:97], v[32:33], v[242:243], v[96:97]
	v_lshlrev_b32_e32 v212, 16, v190
	v_and_b32_e32 v213, 0xffff0000, v190
	v_lshlrev_b32_e32 v214, 16, v191
	v_and_b32_e32 v215, 0xffff0000, v191
	v_pk_fma_f32 v[98:99], v[34:35], v[212:213], v[98:99]
	v_pk_fma_f32 v[100:101], v[36:37], v[214:215], v[100:101]
	v_lshlrev_b32_e32 v216, 16, v192
	v_and_b32_e32 v217, 0xffff0000, v192
	v_lshlrev_b32_e32 v218, 16, v193
	v_and_b32_e32 v219, 0xffff0000, v193
	v_pk_fma_f32 v[102:103], v[38:39], v[216:217], v[102:103]
	v_pk_fma_f32 v[104:105], v[40:41], v[218:219], v[104:105]
	v_lshlrev_b32_e32 v220, 16, v244
	v_and_b32_e32 v221, 0xffff0000, v244
	v_lshlrev_b32_e32 v222, 16, v245
	v_and_b32_e32 v223, 0xffff0000, v245
	v_pk_fma_f32 v[106:107], v[42:43], v[220:221], v[106:107]
	v_pk_fma_f32 v[108:109], v[44:45], v[222:223], v[108:109]
	v_lshlrev_b32_e32 v224, 16, v246
	v_and_b32_e32 v225, 0xffff0000, v246
	v_lshlrev_b32_e32 v226, 16, v247
	v_and_b32_e32 v227, 0xffff0000, v247
	v_pk_fma_f32 v[110:111], v[46:47], v[224:225], v[110:111]
	v_pk_fma_f32 v[112:113], v[48:49], v[226:227], v[112:113]
	v_lshlrev_b32_e32 v228, 16, v248
	v_and_b32_e32 v229, 0xffff0000, v248
	v_lshlrev_b32_e32 v230, 16, v249
	v_and_b32_e32 v231, 0xffff0000, v249
	v_pk_fma_f32 v[114:115], v[50:51], v[228:229], v[114:115]
	v_pk_fma_f32 v[116:117], v[52:53], v[230:231], v[116:117]
	v_lshlrev_b32_e32 v232, 16, v250
	v_and_b32_e32 v233, 0xffff0000, v250
	v_lshlrev_b32_e32 v234, 16, v251
	v_and_b32_e32 v235, 0xffff0000, v251
	v_pk_fma_f32 v[118:119], v[54:55], v[232:233], v[118:119]
	v_pk_fma_f32 v[120:121], v[56:57], v[234:235], v[120:121]
	v_lshlrev_b32_e32 v236, 16, v166
	v_and_b32_e32 v237, 0xffff0000, v166
	v_lshlrev_b32_e32 v238, 16, v167
	v_and_b32_e32 v239, 0xffff0000, v167
	v_pk_fma_f32 v[122:123], v[58:59], v[236:237], v[122:123]
	v_pk_fma_f32 v[124:125], v[60:61], v[238:239], v[124:125]
	v_lshlrev_b32_e32 v240, 16, v194
	v_and_b32_e32 v241, 0xffff0000, v194
	v_lshlrev_b32_e32 v242, 16, v195
	v_and_b32_e32 v243, 0xffff0000, v195
	v_pk_fma_f32 v[126:127], v[62:63], v[240:241], v[126:127]
	v_pk_fma_f32 v[128:129], v[64:65], v[242:243], v[128:129]
	s_barrier
	v_add_u32_e32 v204, 0xc000, v200
	v_add_u32_e32 v205, 0xc000, v202
	ds_read_b128 v[130:133], v204 offset:0
	ds_read_b128 v[134:137], v204 offset:2048
	ds_read_b128 v[138:141], v204 offset:4096
	ds_read_b128 v[142:145], v204 offset:6144
	ds_read_b128 v[146:149], v205 offset:0
	ds_read_b128 v[150:153], v205 offset:2048
	ds_read_b128 v[154:157], v205 offset:4096
	ds_read_b128 v[158:161], v205 offset:6144
	v_add_u32_e32 v204, 0xc000, v201
	v_add_u32_e32 v205, 0xc000, v203
	ds_read_b128 v[212:215], v204 offset:0
	ds_read_b128 v[216:219], v204 offset:2048
	ds_read_b128 v[220:223], v204 offset:4096
	ds_read_b128 v[224:227], v204 offset:6144
	ds_read_b128 v[228:231], v205 offset:0
	ds_read_b128 v[232:235], v205 offset:2048
	ds_read_b128 v[236:239], v205 offset:4096
	ds_read_b128 v[240:243], v205 offset:6144
	s_add_u32 m0, s76, 0x0
	s_nop 0
	global_load_lds_dwordx4 v196, s[68:69]
	s_add_u32 m0, s76, 0x2000
	s_nop 0
	global_load_lds_dwordx4 v197, s[68:69]
	s_add_u32 m0, s76, 0x4000
	s_nop 0
	global_load_lds_dwordx4 v198, s[68:69]
	s_add_u32 m0, s76, 0x6000
	s_nop 0
	global_load_lds_dwordx4 v199, s[68:69]
	s_add_u32 m0, s76, 0x8000
	s_nop 0
	global_load_lds_dwordx4 v196, s[70:71]
	s_add_u32 m0, s76, 0xa000
	s_nop 0
	global_load_lds_dwordx4 v197, s[70:71]
	s_add_u32 s68, s68, 0x80
	s_addc_u32 s69, s69, 0
	s_add_u32 s70, s70, 0x80
	s_addc_u32 s71, s71, 0
	global_load_dwordx2 v[174:175], v206, s[72:73] offset:0
	global_load_dwordx2 v[176:177], v206, s[72:73] offset:32
	global_load_dwordx2 v[178:179], v206, s[72:73] offset:64
	global_load_dwordx2 v[180:181], v206, s[72:73] offset:96
	global_load_dwordx2 v[182:183], v207, s[72:73] offset:0
	global_load_dwordx2 v[184:185], v207, s[72:73] offset:32
	s_waitcnt vmcnt(12)
	s_waitcnt lgkmcnt(0)
	s_barrier
	s_setprio 1
	v_mfma_f32_16x16x32_bf16 v[2:5], v[146:149], v[130:133], 0
	v_mfma_f32_16x16x32_bf16 v[6:9], v[150:153], v[130:133], 0
	v_mfma_f32_16x16x32_bf16 v[10:13], v[154:157], v[130:133], 0
	v_mfma_f32_16x16x32_bf16 v[14:17], v[158:161], v[130:133], 0
	v_mfma_f32_16x16x32_bf16 v[18:21], v[146:149], v[134:137], 0
	v_mfma_f32_16x16x32_bf16 v[22:25], v[150:153], v[134:137], 0
	v_mfma_f32_16x16x32_bf16 v[26:29], v[154:157], v[134:137], 0
	v_mfma_f32_16x16x32_bf16 v[30:33], v[158:161], v[134:137], 0
	v_mfma_f32_16x16x32_bf16 v[34:37], v[146:149], v[138:141], 0
	v_mfma_f32_16x16x32_bf16 v[38:41], v[150:153], v[138:141], 0
	v_mfma_f32_16x16x32_bf16 v[42:45], v[154:157], v[138:141], 0
	v_mfma_f32_16x16x32_bf16 v[46:49], v[158:161], v[138:141], 0
	v_mfma_f32_16x16x32_bf16 v[50:53], v[146:149], v[142:145], 0
	v_mfma_f32_16x16x32_bf16 v[54:57], v[150:153], v[142:145], 0
	v_mfma_f32_16x16x32_bf16 v[58:61], v[154:157], v[142:145], 0
	v_mfma_f32_16x16x32_bf16 v[62:65], v[158:161], v[142:145], 0
	v_mfma_f32_16x16x32_bf16 v[2:5], v[228:231], v[212:215], v[2:5]
	v_mfma_f32_16x16x32_bf16 v[6:9], v[232:235], v[212:215], v[6:9]
	v_mfma_f32_16x16x32_bf16 v[10:13], v[236:239], v[212:215], v[10:13]
	v_mfma_f32_16x16x32_bf16 v[14:17], v[240:243], v[212:215], v[14:17]
	v_mfma_f32_16x16x32_bf16 v[18:21], v[228:231], v[216:219], v[18:21]
	v_mfma_f32_16x16x32_bf16 v[22:25], v[232:235], v[216:219], v[22:25]
	v_mfma_f32_16x16x32_bf16 v[26:29], v[236:239], v[216:219], v[26:29]
	v_mfma_f32_16x16x32_bf16 v[30:33], v[240:243], v[216:219], v[30:33]
	v_mfma_f32_16x16x32_bf16 v[34:37], v[228:231], v[220:223], v[34:37]
	v_mfma_f32_16x16x32_bf16 v[38:41], v[232:235], v[220:223], v[38:41]
	v_mfma_f32_16x16x32_bf16 v[42:45], v[236:239], v[220:223], v[42:45]
	v_mfma_f32_16x16x32_bf16 v[46:49], v[240:243], v[220:223], v[46:49]
	v_mfma_f32_16x16x32_bf16 v[50:53], v[228:231], v[224:227], v[50:53]
	v_mfma_f32_16x16x32_bf16 v[54:57], v[232:235], v[224:227], v[54:57]
	v_mfma_f32_16x16x32_bf16 v[58:61], v[236:239], v[224:227], v[58:61]
	v_mfma_f32_16x16x32_bf16 v[62:65], v[240:243], v[224:227], v[62:65]
	s_setprio 0
	s_barrier
	v_add_u32_e32 v204, 0x18000, v200
	v_add_u32_e32 v205, 0x18000, v202
	ds_read_b128 v[130:133], v204 offset:0
	ds_read_b128 v[134:137], v204 offset:2048
	ds_read_b128 v[138:141], v204 offset:4096
	ds_read_b128 v[142:145], v204 offset:6144
	ds_read_b128 v[146:149], v205 offset:0
	ds_read_b128 v[150:153], v205 offset:2048
	ds_read_b128 v[154:157], v205 offset:4096
	ds_read_b128 v[158:161], v205 offset:6144
	v_add_u32_e32 v204, 0x18000, v201
	v_add_u32_e32 v205, 0x18000, v203
	ds_read_b128 v[212:215], v204 offset:0
	ds_read_b128 v[216:219], v204 offset:2048
	ds_read_b128 v[220:223], v204 offset:4096
	ds_read_b128 v[224:227], v204 offset:6144
	ds_read_b128 v[228:231], v205 offset:0
	ds_read_b128 v[232:235], v205 offset:2048
	ds_read_b128 v[236:239], v205 offset:4096
	ds_read_b128 v[240:243], v205 offset:6144
	s_add_u32 m0, s76, 0xc000
	s_nop 0
	global_load_lds_dwordx4 v196, s[68:69]
	s_add_u32 m0, s76, 0xe000
	s_nop 0
	global_load_lds_dwordx4 v197, s[68:69]
	s_add_u32 m0, s76, 0x10000
	s_nop 0
	global_load_lds_dwordx4 v198, s[68:69]
	s_add_u32 m0, s76, 0x12000
	s_nop 0
	global_load_lds_dwordx4 v199, s[68:69]
	s_add_u32 m0, s76, 0x14000
	s_nop 0
	global_load_lds_dwordx4 v196, s[70:71]
	s_add_u32 m0, s76, 0x16000
	s_nop 0
	global_load_lds_dwordx4 v197, s[70:71]
	s_add_u32 s68, s68, 0x80
	s_addc_u32 s69, s69, 0
	s_add_u32 s70, s70, 0x80
	s_addc_u32 s71, s71, 0
	global_load_dwordx2 v[186:187], v207, s[72:73] offset:64
	global_load_dwordx2 v[188:189], v207, s[72:73] offset:96
	global_load_dwordx2 v[190:191], v208, s[72:73] offset:0
	global_load_dwordx2 v[192:193], v208, s[72:73] offset:32
	global_load_dwordx2 v[244:245], v208, s[72:73] offset:64
	global_load_dwordx2 v[246:247], v208, s[72:73] offset:96
	s_waitcnt vmcnt(18)
	s_waitcnt lgkmcnt(0)
	s_barrier
	s_setprio 1
	v_mfma_f32_16x16x32_bf16 v[2:5], v[146:149], v[130:133], v[2:5]
	v_mfma_f32_16x16x32_bf16 v[6:9], v[150:153], v[130:133], v[6:9]
	v_mfma_f32_16x16x32_bf16 v[10:13], v[154:157], v[130:133], v[10:13]
	v_mfma_f32_16x16x32_bf16 v[14:17], v[158:161], v[130:133], v[14:17]
	v_mfma_f32_16x16x32_bf16 v[18:21], v[146:149], v[134:137], v[18:21]
	v_mfma_f32_16x16x32_bf16 v[22:25], v[150:153], v[134:137], v[22:25]
	v_mfma_f32_16x16x32_bf16 v[26:29], v[154:157], v[134:137], v[26:29]
	v_mfma_f32_16x16x32_bf16 v[30:33], v[158:161], v[134:137], v[30:33]
	v_mfma_f32_16x16x32_bf16 v[34:37], v[146:149], v[138:141], v[34:37]
	v_mfma_f32_16x16x32_bf16 v[38:41], v[150:153], v[138:141], v[38:41]
	v_mfma_f32_16x16x32_bf16 v[42:45], v[154:157], v[138:141], v[42:45]
	v_mfma_f32_16x16x32_bf16 v[46:49], v[158:161], v[138:141], v[46:49]
	v_mfma_f32_16x16x32_bf16 v[50:53], v[146:149], v[142:145], v[50:53]
	v_mfma_f32_16x16x32_bf16 v[54:57], v[150:153], v[142:145], v[54:57]
	v_mfma_f32_16x16x32_bf16 v[58:61], v[154:157], v[142:145], v[58:61]
	v_mfma_f32_16x16x32_bf16 v[62:65], v[158:161], v[142:145], v[62:65]
	v_mfma_f32_16x16x32_bf16 v[2:5], v[228:231], v[212:215], v[2:5]
	v_mfma_f32_16x16x32_bf16 v[6:9], v[232:235], v[212:215], v[6:9]
	v_mfma_f32_16x16x32_bf16 v[10:13], v[236:239], v[212:215], v[10:13]
	v_mfma_f32_16x16x32_bf16 v[14:17], v[240:243], v[212:215], v[14:17]
	v_mfma_f32_16x16x32_bf16 v[18:21], v[228:231], v[216:219], v[18:21]
	v_mfma_f32_16x16x32_bf16 v[22:25], v[232:235], v[216:219], v[22:25]
	v_mfma_f32_16x16x32_bf16 v[26:29], v[236:239], v[216:219], v[26:29]
	v_mfma_f32_16x16x32_bf16 v[30:33], v[240:243], v[216:219], v[30:33]
	v_mfma_f32_16x16x32_bf16 v[34:37], v[228:231], v[220:223], v[34:37]
	v_mfma_f32_16x16x32_bf16 v[38:41], v[232:235], v[220:223], v[38:41]
	v_mfma_f32_16x16x32_bf16 v[42:45], v[236:239], v[220:223], v[42:45]
	v_mfma_f32_16x16x32_bf16 v[46:49], v[240:243], v[220:223], v[46:49]
	v_mfma_f32_16x16x32_bf16 v[50:53], v[228:231], v[224:227], v[50:53]
	v_mfma_f32_16x16x32_bf16 v[54:57], v[232:235], v[224:227], v[54:57]
	v_mfma_f32_16x16x32_bf16 v[58:61], v[236:239], v[224:227], v[58:61]
	v_mfma_f32_16x16x32_bf16 v[62:65], v[240:243], v[224:227], v[62:65]
	s_setprio 0
	s_barrier
	v_add_u32_e32 v204, 0x0, v200
	v_add_u32_e32 v205, 0x0, v202
	ds_read_b128 v[130:133], v204 offset:0
	ds_read_b128 v[134:137], v204 offset:2048
	ds_read_b128 v[138:141], v204 offset:4096
	ds_read_b128 v[142:145], v204 offset:6144
	ds_read_b128 v[146:149], v205 offset:0
	ds_read_b128 v[150:153], v205 offset:2048
	ds_read_b128 v[154:157], v205 offset:4096
	ds_read_b128 v[158:161], v205 offset:6144
	v_add_u32_e32 v204, 0x0, v201
	v_add_u32_e32 v205, 0x0, v203
	ds_read_b128 v[212:215], v204 offset:0
	ds_read_b128 v[216:219], v204 offset:2048
	ds_read_b128 v[220:223], v204 offset:4096
	ds_read_b128 v[224:227], v204 offset:6144
	ds_read_b128 v[228:231], v205 offset:0
	ds_read_b128 v[232:235], v205 offset:2048
	ds_read_b128 v[236:239], v205 offset:4096
	ds_read_b128 v[240:243], v205 offset:6144
	s_add_u32 m0, s76, 0x18000
	s_nop 0
	global_load_lds_dwordx4 v196, s[68:69]
	s_add_u32 m0, s76, 0x1a000
	s_nop 0
	global_load_lds_dwordx4 v197, s[68:69]
	s_add_u32 m0, s76, 0x1c000
	s_nop 0
	global_load_lds_dwordx4 v198, s[68:69]
	s_add_u32 m0, s76, 0x1e000
	s_nop 0
	global_load_lds_dwordx4 v199, s[68:69]
	s_add_u32 m0, s76, 0x20000
	s_nop 0
	global_load_lds_dwordx4 v196, s[70:71]
	s_add_u32 m0, s76, 0x22000
	s_nop 0
	global_load_lds_dwordx4 v197, s[70:71]
	s_add_u32 s68, s68, 0x80
	s_addc_u32 s69, s69, 0
	s_add_u32 s70, s70, 0x80
	s_addc_u32 s71, s71, 0
	global_load_dwordx2 v[248:249], v209, s[72:73] offset:0
	global_load_dwordx2 v[250:251], v209, s[72:73] offset:32
	global_load_dwordx2 v[166:167], v209, s[72:73] offset:64
	global_load_dwordx2 v[194:195], v209, s[72:73] offset:96
	s_add_u32 s72, s72, 0x800
	s_addc_u32 s73, s73, 0
	s_waitcnt vmcnt(16)
	s_waitcnt lgkmcnt(0)
	s_barrier
	s_setprio 1
	v_mfma_f32_16x16x32_bf16 v[2:5], v[146:149], v[130:133], v[2:5]
	v_mfma_f32_16x16x32_bf16 v[6:9], v[150:153], v[130:133], v[6:9]
	v_mfma_f32_16x16x32_bf16 v[10:13], v[154:157], v[130:133], v[10:13]
	v_mfma_f32_16x16x32_bf16 v[14:17], v[158:161], v[130:133], v[14:17]
	v_mfma_f32_16x16x32_bf16 v[18:21], v[146:149], v[134:137], v[18:21]
	v_mfma_f32_16x16x32_bf16 v[22:25], v[150:153], v[134:137], v[22:25]
	v_mfma_f32_16x16x32_bf16 v[26:29], v[154:157], v[134:137], v[26:29]
	v_mfma_f32_16x16x32_bf16 v[30:33], v[158:161], v[134:137], v[30:33]
	v_mfma_f32_16x16x32_bf16 v[34:37], v[146:149], v[138:141], v[34:37]
	v_mfma_f32_16x16x32_bf16 v[38:41], v[150:153], v[138:141], v[38:41]
	v_mfma_f32_16x16x32_bf16 v[42:45], v[154:157], v[138:141], v[42:45]
	v_mfma_f32_16x16x32_bf16 v[46:49], v[158:161], v[138:141], v[46:49]
	v_mfma_f32_16x16x32_bf16 v[50:53], v[146:149], v[142:145], v[50:53]
	v_mfma_f32_16x16x32_bf16 v[54:57], v[150:153], v[142:145], v[54:57]
	v_mfma_f32_16x16x32_bf16 v[58:61], v[154:157], v[142:145], v[58:61]
	v_mfma_f32_16x16x32_bf16 v[62:65], v[158:161], v[142:145], v[62:65]
	v_mfma_f32_16x16x32_bf16 v[2:5], v[228:231], v[212:215], v[2:5]
	v_mfma_f32_16x16x32_bf16 v[6:9], v[232:235], v[212:215], v[6:9]
	v_mfma_f32_16x16x32_bf16 v[10:13], v[236:239], v[212:215], v[10:13]
	v_mfma_f32_16x16x32_bf16 v[14:17], v[240:243], v[212:215], v[14:17]
	v_mfma_f32_16x16x32_bf16 v[18:21], v[228:231], v[216:219], v[18:21]
	v_mfma_f32_16x16x32_bf16 v[22:25], v[232:235], v[216:219], v[22:25]
	v_mfma_f32_16x16x32_bf16 v[26:29], v[236:239], v[216:219], v[26:29]
	v_mfma_f32_16x16x32_bf16 v[30:33], v[240:243], v[216:219], v[30:33]
	v_mfma_f32_16x16x32_bf16 v[34:37], v[228:231], v[220:223], v[34:37]
	v_mfma_f32_16x16x32_bf16 v[38:41], v[232:235], v[220:223], v[38:41]
	v_mfma_f32_16x16x32_bf16 v[42:45], v[236:239], v[220:223], v[42:45]
	v_mfma_f32_16x16x32_bf16 v[46:49], v[240:243], v[220:223], v[46:49]
	v_mfma_f32_16x16x32_bf16 v[50:53], v[228:231], v[224:227], v[50:53]
	v_mfma_f32_16x16x32_bf16 v[54:57], v[232:235], v[224:227], v[54:57]
	v_mfma_f32_16x16x32_bf16 v[58:61], v[236:239], v[224:227], v[58:61]
	v_mfma_f32_16x16x32_bf16 v[62:65], v[240:243], v[224:227], v[62:65]
	s_setprio 0
	s_barrier
	v_add_u32_e32 v204, 0xc000, v200
	v_add_u32_e32 v205, 0xc000, v202
	ds_read_b128 v[130:133], v204 offset:0
	ds_read_b128 v[134:137], v204 offset:2048
	ds_read_b128 v[138:141], v204 offset:4096
	ds_read_b128 v[142:145], v204 offset:6144
	ds_read_b128 v[146:149], v205 offset:0
	ds_read_b128 v[150:153], v205 offset:2048
	ds_read_b128 v[154:157], v205 offset:4096
	ds_read_b128 v[158:161], v205 offset:6144
	v_add_u32_e32 v204, 0xc000, v201
	v_add_u32_e32 v205, 0xc000, v203
	ds_read_b128 v[212:215], v204 offset:0
	ds_read_b128 v[216:219], v204 offset:2048
	ds_read_b128 v[220:223], v204 offset:4096
	ds_read_b128 v[224:227], v204 offset:6144
	ds_read_b128 v[228:231], v205 offset:0
	ds_read_b128 v[232:235], v205 offset:2048
	ds_read_b128 v[236:239], v205 offset:4096
	ds_read_b128 v[240:243], v205 offset:6144
	s_add_u32 m0, s76, 0x0
	s_nop 0
	global_load_lds_dwordx4 v196, s[68:69]
	s_add_u32 m0, s76, 0x2000
	s_nop 0
	global_load_lds_dwordx4 v197, s[68:69]
	s_add_u32 m0, s76, 0x4000
	s_nop 0
	global_load_lds_dwordx4 v198, s[68:69]
	s_add_u32 m0, s76, 0x6000
	s_nop 0
	global_load_lds_dwordx4 v199, s[68:69]
	s_add_u32 m0, s76, 0x8000
	s_nop 0
	global_load_lds_dwordx4 v196, s[70:71]
	s_add_u32 m0, s76, 0xa000
	s_nop 0
	global_load_lds_dwordx4 v197, s[70:71]
	s_add_u32 s68, s68, 0x80
	s_addc_u32 s69, s69, 0
	s_add_u32 s70, s70, 0x80
	s_addc_u32 s71, s71, 0
	s_waitcnt vmcnt(10)
	s_waitcnt lgkmcnt(0)
	s_barrier
	s_setprio 1
	v_mfma_f32_16x16x32_bf16 v[2:5], v[146:149], v[130:133], v[2:5]
	v_mfma_f32_16x16x32_bf16 v[6:9], v[150:153], v[130:133], v[6:9]
	v_mfma_f32_16x16x32_bf16 v[10:13], v[154:157], v[130:133], v[10:13]
	v_mfma_f32_16x16x32_bf16 v[14:17], v[158:161], v[130:133], v[14:17]
	v_mfma_f32_16x16x32_bf16 v[18:21], v[146:149], v[134:137], v[18:21]
	v_mfma_f32_16x16x32_bf16 v[22:25], v[150:153], v[134:137], v[22:25]
	v_mfma_f32_16x16x32_bf16 v[26:29], v[154:157], v[134:137], v[26:29]
	v_mfma_f32_16x16x32_bf16 v[30:33], v[158:161], v[134:137], v[30:33]
	v_mfma_f32_16x16x32_bf16 v[34:37], v[146:149], v[138:141], v[34:37]
	v_mfma_f32_16x16x32_bf16 v[38:41], v[150:153], v[138:141], v[38:41]
	v_mfma_f32_16x16x32_bf16 v[42:45], v[154:157], v[138:141], v[42:45]
	v_mfma_f32_16x16x32_bf16 v[46:49], v[158:161], v[138:141], v[46:49]
	v_mfma_f32_16x16x32_bf16 v[50:53], v[146:149], v[142:145], v[50:53]
	v_mfma_f32_16x16x32_bf16 v[54:57], v[150:153], v[142:145], v[54:57]
	v_mfma_f32_16x16x32_bf16 v[58:61], v[154:157], v[142:145], v[58:61]
	v_mfma_f32_16x16x32_bf16 v[62:65], v[158:161], v[142:145], v[62:65]
	v_mfma_f32_16x16x32_bf16 v[2:5], v[228:231], v[212:215], v[2:5]
	v_mfma_f32_16x16x32_bf16 v[6:9], v[232:235], v[212:215], v[6:9]
	v_mfma_f32_16x16x32_bf16 v[10:13], v[236:239], v[212:215], v[10:13]
	v_mfma_f32_16x16x32_bf16 v[14:17], v[240:243], v[212:215], v[14:17]
	v_mfma_f32_16x16x32_bf16 v[18:21], v[228:231], v[216:219], v[18:21]
	v_mfma_f32_16x16x32_bf16 v[22:25], v[232:235], v[216:219], v[22:25]
	v_mfma_f32_16x16x32_bf16 v[26:29], v[236:239], v[216:219], v[26:29]
	v_mfma_f32_16x16x32_bf16 v[30:33], v[240:243], v[216:219], v[30:33]
	v_mfma_f32_16x16x32_bf16 v[34:37], v[228:231], v[220:223], v[34:37]
	v_mfma_f32_16x16x32_bf16 v[38:41], v[232:235], v[220:223], v[38:41]
	v_mfma_f32_16x16x32_bf16 v[42:45], v[236:239], v[220:223], v[42:45]
	v_mfma_f32_16x16x32_bf16 v[46:49], v[240:243], v[220:223], v[46:49]
	v_mfma_f32_16x16x32_bf16 v[50:53], v[228:231], v[224:227], v[50:53]
	v_mfma_f32_16x16x32_bf16 v[54:57], v[232:235], v[224:227], v[54:57]
	v_mfma_f32_16x16x32_bf16 v[58:61], v[236:239], v[224:227], v[58:61]
	v_mfma_f32_16x16x32_bf16 v[62:65], v[240:243], v[224:227], v[62:65]
	s_setprio 0
	s_barrier
	v_add_u32_e32 v204, 0x18000, v200
	v_add_u32_e32 v205, 0x18000, v202
	ds_read_b128 v[130:133], v204 offset:0
	ds_read_b128 v[134:137], v204 offset:2048
	ds_read_b128 v[138:141], v204 offset:4096
	ds_read_b128 v[142:145], v204 offset:6144
	ds_read_b128 v[146:149], v205 offset:0
	ds_read_b128 v[150:153], v205 offset:2048
	ds_read_b128 v[154:157], v205 offset:4096
	ds_read_b128 v[158:161], v205 offset:6144
	v_add_u32_e32 v204, 0x18000, v201
	v_add_u32_e32 v205, 0x18000, v203
	ds_read_b128 v[212:215], v204 offset:0
	ds_read_b128 v[216:219], v204 offset:2048
	ds_read_b128 v[220:223], v204 offset:4096
	ds_read_b128 v[224:227], v204 offset:6144
	ds_read_b128 v[228:231], v205 offset:0
	ds_read_b128 v[232:235], v205 offset:2048
	ds_read_b128 v[236:239], v205 offset:4096
	ds_read_b128 v[240:243], v205 offset:6144
	s_add_u32 m0, s76, 0xc000
	s_nop 0
	global_load_lds_dwordx4 v196, s[68:69]
	s_add_u32 m0, s76, 0xe000
	s_nop 0
	global_load_lds_dwordx4 v197, s[68:69]
	s_add_u32 m0, s76, 0x10000
	s_nop 0
	global_load_lds_dwordx4 v198, s[68:69]
	s_add_u32 m0, s76, 0x12000
	s_nop 0
	global_load_lds_dwordx4 v199, s[68:69]
	s_add_u32 m0, s76, 0x14000
	s_nop 0
	global_load_lds_dwordx4 v196, s[70:71]
	s_add_u32 m0, s76, 0x16000
	s_nop 0
	global_load_lds_dwordx4 v197, s[70:71]
	s_add_u32 s68, s68, 0x80
	s_addc_u32 s69, s69, 0
	s_add_u32 s70, s70, 0x80
	s_addc_u32 s71, s71, 0
	s_waitcnt vmcnt(6)
	s_waitcnt lgkmcnt(0)
	s_barrier
	s_setprio 1
	v_mfma_f32_16x16x32_bf16 v[2:5], v[146:149], v[130:133], v[2:5]
	v_mfma_f32_16x16x32_bf16 v[6:9], v[150:153], v[130:133], v[6:9]
	v_mfma_f32_16x16x32_bf16 v[10:13], v[154:157], v[130:133], v[10:13]
	v_mfma_f32_16x16x32_bf16 v[14:17], v[158:161], v[130:133], v[14:17]
	v_mfma_f32_16x16x32_bf16 v[18:21], v[146:149], v[134:137], v[18:21]
	v_mfma_f32_16x16x32_bf16 v[22:25], v[150:153], v[134:137], v[22:25]
	v_mfma_f32_16x16x32_bf16 v[26:29], v[154:157], v[134:137], v[26:29]
	v_mfma_f32_16x16x32_bf16 v[30:33], v[158:161], v[134:137], v[30:33]
	v_mfma_f32_16x16x32_bf16 v[34:37], v[146:149], v[138:141], v[34:37]
	v_mfma_f32_16x16x32_bf16 v[38:41], v[150:153], v[138:141], v[38:41]
	v_mfma_f32_16x16x32_bf16 v[42:45], v[154:157], v[138:141], v[42:45]
	v_mfma_f32_16x16x32_bf16 v[46:49], v[158:161], v[138:141], v[46:49]
	v_mfma_f32_16x16x32_bf16 v[50:53], v[146:149], v[142:145], v[50:53]
	v_mfma_f32_16x16x32_bf16 v[54:57], v[150:153], v[142:145], v[54:57]
	v_mfma_f32_16x16x32_bf16 v[58:61], v[154:157], v[142:145], v[58:61]
	v_mfma_f32_16x16x32_bf16 v[62:65], v[158:161], v[142:145], v[62:65]
	v_mfma_f32_16x16x32_bf16 v[2:5], v[228:231], v[212:215], v[2:5]
	v_mfma_f32_16x16x32_bf16 v[6:9], v[232:235], v[212:215], v[6:9]
	v_mfma_f32_16x16x32_bf16 v[10:13], v[236:239], v[212:215], v[10:13]
	v_mfma_f32_16x16x32_bf16 v[14:17], v[240:243], v[212:215], v[14:17]
	v_mfma_f32_16x16x32_bf16 v[18:21], v[228:231], v[216:219], v[18:21]
	v_mfma_f32_16x16x32_bf16 v[22:25], v[232:235], v[216:219], v[22:25]
	v_mfma_f32_16x16x32_bf16 v[26:29], v[236:239], v[216:219], v[26:29]
	v_mfma_f32_16x16x32_bf16 v[30:33], v[240:243], v[216:219], v[30:33]
	v_mfma_f32_16x16x32_bf16 v[34:37], v[228:231], v[220:223], v[34:37]
	v_mfma_f32_16x16x32_bf16 v[38:41], v[232:235], v[220:223], v[38:41]
	v_mfma_f32_16x16x32_bf16 v[42:45], v[236:239], v[220:223], v[42:45]
	v_mfma_f32_16x16x32_bf16 v[46:49], v[240:243], v[220:223], v[46:49]
	v_mfma_f32_16x16x32_bf16 v[50:53], v[228:231], v[224:227], v[50:53]
	v_mfma_f32_16x16x32_bf16 v[54:57], v[232:235], v[224:227], v[54:57]
	v_mfma_f32_16x16x32_bf16 v[58:61], v[236:239], v[224:227], v[58:61]
	v_mfma_f32_16x16x32_bf16 v[62:65], v[240:243], v[224:227], v[62:65]
	s_setprio 0
	s_barrier
	v_add_u32_e32 v204, 0x0, v200
	v_add_u32_e32 v205, 0x0, v202
	ds_read_b128 v[130:133], v204 offset:0
	ds_read_b128 v[134:137], v204 offset:2048
	ds_read_b128 v[138:141], v204 offset:4096
	ds_read_b128 v[142:145], v204 offset:6144
	ds_read_b128 v[146:149], v205 offset:0
	ds_read_b128 v[150:153], v205 offset:2048
	ds_read_b128 v[154:157], v205 offset:4096
	ds_read_b128 v[158:161], v205 offset:6144
	v_add_u32_e32 v204, 0x0, v201
	v_add_u32_e32 v205, 0x0, v203
	ds_read_b128 v[212:215], v204 offset:0
	ds_read_b128 v[216:219], v204 offset:2048
	ds_read_b128 v[220:223], v204 offset:4096
	ds_read_b128 v[224:227], v204 offset:6144
	ds_read_b128 v[228:231], v205 offset:0
	ds_read_b128 v[232:235], v205 offset:2048
	ds_read_b128 v[236:239], v205 offset:4096
	ds_read_b128 v[240:243], v205 offset:6144
	s_add_u32 m0, s76, 0x18000
	s_nop 0
	global_load_lds_dwordx4 v196, s[68:69]
	s_add_u32 m0, s76, 0x1a000
	s_nop 0
	global_load_lds_dwordx4 v197, s[68:69]
	s_add_u32 m0, s76, 0x1c000
	s_nop 0
	global_load_lds_dwordx4 v198, s[68:69]
	s_add_u32 m0, s76, 0x1e000
	s_nop 0
	global_load_lds_dwordx4 v199, s[68:69]
	s_add_u32 m0, s76, 0x20000
	s_nop 0
	global_load_lds_dwordx4 v196, s[70:71]
	s_add_u32 m0, s76, 0x22000
	s_nop 0
	global_load_lds_dwordx4 v197, s[70:71]
	s_add_u32 s68, s68, 0x80
	s_addc_u32 s69, s69, 0
	s_add_u32 s70, s70, 0x80
	s_addc_u32 s71, s71, 0
	s_waitcnt vmcnt(6)
	s_waitcnt lgkmcnt(0)
	s_barrier
	s_setprio 1
	v_mfma_f32_16x16x32_bf16 v[2:5], v[146:149], v[130:133], v[2:5]
	v_mfma_f32_16x16x32_bf16 v[6:9], v[150:153], v[130:133], v[6:9]
	v_mfma_f32_16x16x32_bf16 v[10:13], v[154:157], v[130:133], v[10:13]
	v_mfma_f32_16x16x32_bf16 v[14:17], v[158:161], v[130:133], v[14:17]
	v_mfma_f32_16x16x32_bf16 v[18:21], v[146:149], v[134:137], v[18:21]
	v_mfma_f32_16x16x32_bf16 v[22:25], v[150:153], v[134:137], v[22:25]
	v_mfma_f32_16x16x32_bf16 v[26:29], v[154:157], v[134:137], v[26:29]
	v_mfma_f32_16x16x32_bf16 v[30:33], v[158:161], v[134:137], v[30:33]
	v_mfma_f32_16x16x32_bf16 v[34:37], v[146:149], v[138:141], v[34:37]
	v_mfma_f32_16x16x32_bf16 v[38:41], v[150:153], v[138:141], v[38:41]
	v_mfma_f32_16x16x32_bf16 v[42:45], v[154:157], v[138:141], v[42:45]
	v_mfma_f32_16x16x32_bf16 v[46:49], v[158:161], v[138:141], v[46:49]
	v_mfma_f32_16x16x32_bf16 v[50:53], v[146:149], v[142:145], v[50:53]
	v_mfma_f32_16x16x32_bf16 v[54:57], v[150:153], v[142:145], v[54:57]
	v_mfma_f32_16x16x32_bf16 v[58:61], v[154:157], v[142:145], v[58:61]
	v_mfma_f32_16x16x32_bf16 v[62:65], v[158:161], v[142:145], v[62:65]
	v_mfma_f32_16x16x32_bf16 v[2:5], v[228:231], v[212:215], v[2:5]
	v_mfma_f32_16x16x32_bf16 v[6:9], v[232:235], v[212:215], v[6:9]
	v_mfma_f32_16x16x32_bf16 v[10:13], v[236:239], v[212:215], v[10:13]
	v_mfma_f32_16x16x32_bf16 v[14:17], v[240:243], v[212:215], v[14:17]
	v_mfma_f32_16x16x32_bf16 v[18:21], v[228:231], v[216:219], v[18:21]
	v_mfma_f32_16x16x32_bf16 v[22:25], v[232:235], v[216:219], v[22:25]
	v_mfma_f32_16x16x32_bf16 v[26:29], v[236:239], v[216:219], v[26:29]
	v_mfma_f32_16x16x32_bf16 v[30:33], v[240:243], v[216:219], v[30:33]
	v_mfma_f32_16x16x32_bf16 v[34:37], v[228:231], v[220:223], v[34:37]
	v_mfma_f32_16x16x32_bf16 v[38:41], v[232:235], v[220:223], v[38:41]
	v_mfma_f32_16x16x32_bf16 v[42:45], v[236:239], v[220:223], v[42:45]
	v_mfma_f32_16x16x32_bf16 v[46:49], v[240:243], v[220:223], v[46:49]
	v_mfma_f32_16x16x32_bf16 v[50:53], v[228:231], v[224:227], v[50:53]
	v_mfma_f32_16x16x32_bf16 v[54:57], v[232:235], v[224:227], v[54:57]
	v_mfma_f32_16x16x32_bf16 v[58:61], v[236:239], v[224:227], v[58:61]
	v_mfma_f32_16x16x32_bf16 v[62:65], v[240:243], v[224:227], v[62:65]
	s_setprio 0
	s_barrier
	v_add_u32_e32 v204, 0xc000, v200
	v_add_u32_e32 v205, 0xc000, v202
	ds_read_b128 v[130:133], v204 offset:0
	ds_read_b128 v[134:137], v204 offset:2048
	ds_read_b128 v[138:141], v204 offset:4096
	ds_read_b128 v[142:145], v204 offset:6144
	ds_read_b128 v[146:149], v205 offset:0
	ds_read_b128 v[150:153], v205 offset:2048
	ds_read_b128 v[154:157], v205 offset:4096
	ds_read_b128 v[158:161], v205 offset:6144
	v_add_u32_e32 v204, 0xc000, v201
	v_add_u32_e32 v205, 0xc000, v203
	ds_read_b128 v[212:215], v204 offset:0
	ds_read_b128 v[216:219], v204 offset:2048
	ds_read_b128 v[220:223], v204 offset:4096
	ds_read_b128 v[224:227], v204 offset:6144
	ds_read_b128 v[228:231], v205 offset:0
	ds_read_b128 v[232:235], v205 offset:2048
	ds_read_b128 v[236:239], v205 offset:4096
	ds_read_b128 v[240:243], v205 offset:6144
	s_waitcnt vmcnt(0)
	s_waitcnt lgkmcnt(0)
	s_barrier
	s_setprio 1
	v_mfma_f32_16x16x32_bf16 v[2:5], v[146:149], v[130:133], v[2:5]
	v_mfma_f32_16x16x32_bf16 v[6:9], v[150:153], v[130:133], v[6:9]
	v_mfma_f32_16x16x32_bf16 v[10:13], v[154:157], v[130:133], v[10:13]
	v_mfma_f32_16x16x32_bf16 v[14:17], v[158:161], v[130:133], v[14:17]
	v_mfma_f32_16x16x32_bf16 v[18:21], v[146:149], v[134:137], v[18:21]
	v_mfma_f32_16x16x32_bf16 v[22:25], v[150:153], v[134:137], v[22:25]
	v_mfma_f32_16x16x32_bf16 v[26:29], v[154:157], v[134:137], v[26:29]
	v_mfma_f32_16x16x32_bf16 v[30:33], v[158:161], v[134:137], v[30:33]
	v_mfma_f32_16x16x32_bf16 v[34:37], v[146:149], v[138:141], v[34:37]
	v_mfma_f32_16x16x32_bf16 v[38:41], v[150:153], v[138:141], v[38:41]
	v_mfma_f32_16x16x32_bf16 v[42:45], v[154:157], v[138:141], v[42:45]
	v_mfma_f32_16x16x32_bf16 v[46:49], v[158:161], v[138:141], v[46:49]
	v_mfma_f32_16x16x32_bf16 v[50:53], v[146:149], v[142:145], v[50:53]
	v_mfma_f32_16x16x32_bf16 v[54:57], v[150:153], v[142:145], v[54:57]
	v_mfma_f32_16x16x32_bf16 v[58:61], v[154:157], v[142:145], v[58:61]
	v_mfma_f32_16x16x32_bf16 v[62:65], v[158:161], v[142:145], v[62:65]
	v_mfma_f32_16x16x32_bf16 v[2:5], v[228:231], v[212:215], v[2:5]
	v_mfma_f32_16x16x32_bf16 v[6:9], v[232:235], v[212:215], v[6:9]
	v_mfma_f32_16x16x32_bf16 v[10:13], v[236:239], v[212:215], v[10:13]
	v_mfma_f32_16x16x32_bf16 v[14:17], v[240:243], v[212:215], v[14:17]
	v_mfma_f32_16x16x32_bf16 v[18:21], v[228:231], v[216:219], v[18:21]
	v_mfma_f32_16x16x32_bf16 v[22:25], v[232:235], v[216:219], v[22:25]
	v_mfma_f32_16x16x32_bf16 v[26:29], v[236:239], v[216:219], v[26:29]
	v_mfma_f32_16x16x32_bf16 v[30:33], v[240:243], v[216:219], v[30:33]
	v_mfma_f32_16x16x32_bf16 v[34:37], v[228:231], v[220:223], v[34:37]
	v_mfma_f32_16x16x32_bf16 v[38:41], v[232:235], v[220:223], v[38:41]
	v_mfma_f32_16x16x32_bf16 v[42:45], v[236:239], v[220:223], v[42:45]
	v_mfma_f32_16x16x32_bf16 v[46:49], v[240:243], v[220:223], v[46:49]
	v_mfma_f32_16x16x32_bf16 v[50:53], v[228:231], v[224:227], v[50:53]
	v_mfma_f32_16x16x32_bf16 v[54:57], v[232:235], v[224:227], v[54:57]
	v_mfma_f32_16x16x32_bf16 v[58:61], v[236:239], v[224:227], v[58:61]
	v_mfma_f32_16x16x32_bf16 v[62:65], v[240:243], v[224:227], v[62:65]
	s_setprio 0
	s_barrier
	v_add_u32_e32 v204, 0x18000, v200
	v_add_u32_e32 v205, 0x18000, v202
	ds_read_b128 v[130:133], v204 offset:0
	ds_read_b128 v[134:137], v204 offset:2048
	ds_read_b128 v[138:141], v204 offset:4096
	ds_read_b128 v[142:145], v204 offset:6144
	ds_read_b128 v[146:149], v205 offset:0
	ds_read_b128 v[150:153], v205 offset:2048
	ds_read_b128 v[154:157], v205 offset:4096
	ds_read_b128 v[158:161], v205 offset:6144
	v_add_u32_e32 v204, 0x18000, v201
	v_add_u32_e32 v205, 0x18000, v203
	ds_read_b128 v[212:215], v204 offset:0
	ds_read_b128 v[216:219], v204 offset:2048
	ds_read_b128 v[220:223], v204 offset:4096
	ds_read_b128 v[224:227], v204 offset:6144
	ds_read_b128 v[228:231], v205 offset:0
	ds_read_b128 v[232:235], v205 offset:2048
	ds_read_b128 v[236:239], v205 offset:4096
	ds_read_b128 v[240:243], v205 offset:6144
	s_waitcnt lgkmcnt(0)
	s_barrier
	s_setprio 1
	v_mfma_f32_16x16x32_bf16 v[2:5], v[146:149], v[130:133], v[2:5]
	v_mfma_f32_16x16x32_bf16 v[6:9], v[150:153], v[130:133], v[6:9]
	v_mfma_f32_16x16x32_bf16 v[10:13], v[154:157], v[130:133], v[10:13]
	v_mfma_f32_16x16x32_bf16 v[14:17], v[158:161], v[130:133], v[14:17]
	v_mfma_f32_16x16x32_bf16 v[18:21], v[146:149], v[134:137], v[18:21]
	v_mfma_f32_16x16x32_bf16 v[22:25], v[150:153], v[134:137], v[22:25]
	v_mfma_f32_16x16x32_bf16 v[26:29], v[154:157], v[134:137], v[26:29]
	v_mfma_f32_16x16x32_bf16 v[30:33], v[158:161], v[134:137], v[30:33]
	v_mfma_f32_16x16x32_bf16 v[34:37], v[146:149], v[138:141], v[34:37]
	v_mfma_f32_16x16x32_bf16 v[38:41], v[150:153], v[138:141], v[38:41]
	v_mfma_f32_16x16x32_bf16 v[42:45], v[154:157], v[138:141], v[42:45]
	v_mfma_f32_16x16x32_bf16 v[46:49], v[158:161], v[138:141], v[46:49]
	v_mfma_f32_16x16x32_bf16 v[50:53], v[146:149], v[142:145], v[50:53]
	v_mfma_f32_16x16x32_bf16 v[54:57], v[150:153], v[142:145], v[54:57]
	v_mfma_f32_16x16x32_bf16 v[58:61], v[154:157], v[142:145], v[58:61]
	v_mfma_f32_16x16x32_bf16 v[62:65], v[158:161], v[142:145], v[62:65]
	v_mfma_f32_16x16x32_bf16 v[2:5], v[228:231], v[212:215], v[2:5]
	v_mfma_f32_16x16x32_bf16 v[6:9], v[232:235], v[212:215], v[6:9]
	v_mfma_f32_16x16x32_bf16 v[10:13], v[236:239], v[212:215], v[10:13]
	v_mfma_f32_16x16x32_bf16 v[14:17], v[240:243], v[212:215], v[14:17]
	v_mfma_f32_16x16x32_bf16 v[18:21], v[228:231], v[216:219], v[18:21]
	v_mfma_f32_16x16x32_bf16 v[22:25], v[232:235], v[216:219], v[22:25]
	v_mfma_f32_16x16x32_bf16 v[26:29], v[236:239], v[216:219], v[26:29]
	v_mfma_f32_16x16x32_bf16 v[30:33], v[240:243], v[216:219], v[30:33]
	v_mfma_f32_16x16x32_bf16 v[34:37], v[228:231], v[220:223], v[34:37]
	v_mfma_f32_16x16x32_bf16 v[38:41], v[232:235], v[220:223], v[38:41]
	v_mfma_f32_16x16x32_bf16 v[42:45], v[236:239], v[220:223], v[42:45]
	v_mfma_f32_16x16x32_bf16 v[46:49], v[240:243], v[220:223], v[46:49]
	v_mfma_f32_16x16x32_bf16 v[50:53], v[228:231], v[224:227], v[50:53]
	v_mfma_f32_16x16x32_bf16 v[54:57], v[232:235], v[224:227], v[54:57]
	v_mfma_f32_16x16x32_bf16 v[58:61], v[236:239], v[224:227], v[58:61]
	v_mfma_f32_16x16x32_bf16 v[62:65], v[240:243], v[224:227], v[62:65]
	s_setprio 0
	s_nop 7
	v_lshlrev_b32_e32 v212, 16, v174
	v_and_b32_e32 v213, 0xffff0000, v174
	v_lshlrev_b32_e32 v214, 16, v175
	v_and_b32_e32 v215, 0xffff0000, v175
	v_pk_fma_f32 v[66:67], v[2:3], v[212:213], v[66:67]
	v_pk_fma_f32 v[68:69], v[4:5], v[214:215], v[68:69]
	s_nop 0
	v_cvt_pk_bf16_f32 v66, v66, v67
	v_cvt_pk_bf16_f32 v67, v68, v69
	global_store_dwordx2 v210, v[66:67], s[74:75] offset:0
	v_lshlrev_b32_e32 v216, 16, v176
	v_and_b32_e32 v217, 0xffff0000, v176
	v_lshlrev_b32_e32 v218, 16, v177
	v_and_b32_e32 v219, 0xffff0000, v177
	v_pk_fma_f32 v[70:71], v[6:7], v[216:217], v[70:71]
	v_pk_fma_f32 v[72:73], v[8:9], v[218:219], v[72:73]
	s_nop 0
	v_cvt_pk_bf16_f32 v70, v70, v71
	v_cvt_pk_bf16_f32 v71, v72, v73
	global_store_dwordx2 v210, v[70:71], s[74:75] offset:32
	v_lshlrev_b32_e32 v220, 16, v178
	v_and_b32_e32 v221, 0xffff0000, v178
	v_lshlrev_b32_e32 v222, 16, v179
	v_and_b32_e32 v223, 0xffff0000, v179
	v_pk_fma_f32 v[74:75], v[10:11], v[220:221], v[74:75]
	v_pk_fma_f32 v[76:77], v[12:13], v[222:223], v[76:77]
	s_nop 0
	v_cvt_pk_bf16_f32 v74, v74, v75
	v_cvt_pk_bf16_f32 v75, v76, v77
	global_store_dwordx2 v210, v[74:75], s[74:75] offset:64
	v_lshlrev_b32_e32 v224, 16, v180
	v_and_b32_e32 v225, 0xffff0000, v180
	v_lshlrev_b32_e32 v226, 16, v181
	v_and_b32_e32 v227, 0xffff0000, v181
	v_pk_fma_f32 v[78:79], v[14:15], v[224:225], v[78:79]
	v_pk_fma_f32 v[80:81], v[16:17], v[226:227], v[80:81]
	s_nop 0
	v_cvt_pk_bf16_f32 v78, v78, v79
	v_cvt_pk_bf16_f32 v79, v80, v81
	global_store_dwordx2 v210, v[78:79], s[74:75] offset:96
	v_lshlrev_b32_e32 v228, 16, v182
	v_and_b32_e32 v229, 0xffff0000, v182
	v_lshlrev_b32_e32 v230, 16, v183
	v_and_b32_e32 v231, 0xffff0000, v183
	v_pk_fma_f32 v[82:83], v[18:19], v[228:229], v[82:83]
	v_pk_fma_f32 v[84:85], v[20:21], v[230:231], v[84:85]
	s_nop 0
	v_cvt_pk_bf16_f32 v82, v82, v83
	v_cvt_pk_bf16_f32 v83, v84, v85
	global_store_dwordx2 v211, v[82:83], s[74:75] offset:0
	v_lshlrev_b32_e32 v232, 16, v184
	v_and_b32_e32 v233, 0xffff0000, v184
	v_lshlrev_b32_e32 v234, 16, v185
	v_and_b32_e32 v235, 0xffff0000, v185
	v_pk_fma_f32 v[86:87], v[22:23], v[232:233], v[86:87]
	v_pk_fma_f32 v[88:89], v[24:25], v[234:235], v[88:89]
	s_nop 0
	v_cvt_pk_bf16_f32 v86, v86, v87
	v_cvt_pk_bf16_f32 v87, v88, v89
	global_store_dwordx2 v211, v[86:87], s[74:75] offset:32
	v_lshlrev_b32_e32 v236, 16, v186
	v_and_b32_e32 v237, 0xffff0000, v186
	v_lshlrev_b32_e32 v238, 16, v187
	v_and_b32_e32 v239, 0xffff0000, v187
	v_pk_fma_f32 v[90:91], v[26:27], v[236:237], v[90:91]
	v_pk_fma_f32 v[92:93], v[28:29], v[238:239], v[92:93]
	s_nop 0
	v_cvt_pk_bf16_f32 v90, v90, v91
	v_cvt_pk_bf16_f32 v91, v92, v93
	global_store_dwordx2 v211, v[90:91], s[74:75] offset:64
	v_lshlrev_b32_e32 v240, 16, v188
	v_and_b32_e32 v241, 0xffff0000, v188
	v_lshlrev_b32_e32 v242, 16, v189
	v_and_b32_e32 v243, 0xffff0000, v189
	v_pk_fma_f32 v[94:95], v[30:31], v[240:241], v[94:95]
	v_pk_fma_f32 v[96:97], v[32:33], v[242:243], v[96:97]
	s_nop 0
	v_cvt_pk_bf16_f32 v94, v94, v95
	v_cvt_pk_bf16_f32 v95, v96, v97
	global_store_dwordx2 v211, v[94:95], s[74:75] offset:96
	v_lshlrev_b32_e32 v212, 16, v190
	v_and_b32_e32 v213, 0xffff0000, v190
	v_lshlrev_b32_e32 v214, 16, v191
	v_and_b32_e32 v215, 0xffff0000, v191
	v_pk_fma_f32 v[98:99], v[34:35], v[212:213], v[98:99]
	v_pk_fma_f32 v[100:101], v[36:37], v[214:215], v[100:101]
	s_nop 0
	v_cvt_pk_bf16_f32 v98, v98, v99
	v_cvt_pk_bf16_f32 v99, v100, v101
	global_store_dwordx2 v168, v[98:99], s[74:75] offset:0
	v_lshlrev_b32_e32 v216, 16, v192
	v_and_b32_e32 v217, 0xffff0000, v192
	v_lshlrev_b32_e32 v218, 16, v193
	v_and_b32_e32 v219, 0xffff0000, v193
	v_pk_fma_f32 v[102:103], v[38:39], v[216:217], v[102:103]
	v_pk_fma_f32 v[104:105], v[40:41], v[218:219], v[104:105]
	s_nop 0
	v_cvt_pk_bf16_f32 v102, v102, v103
	v_cvt_pk_bf16_f32 v103, v104, v105
	global_store_dwordx2 v168, v[102:103], s[74:75] offset:32
	v_lshlrev_b32_e32 v220, 16, v244
	v_and_b32_e32 v221, 0xffff0000, v244
	v_lshlrev_b32_e32 v222, 16, v245
	v_and_b32_e32 v223, 0xffff0000, v245
	v_pk_fma_f32 v[106:107], v[42:43], v[220:221], v[106:107]
	v_pk_fma_f32 v[108:109], v[44:45], v[222:223], v[108:109]
	s_nop 0
	v_cvt_pk_bf16_f32 v106, v106, v107
	v_cvt_pk_bf16_f32 v107, v108, v109
	global_store_dwordx2 v168, v[106:107], s[74:75] offset:64
	v_lshlrev_b32_e32 v224, 16, v246
	v_and_b32_e32 v225, 0xffff0000, v246
	v_lshlrev_b32_e32 v226, 16, v247
	v_and_b32_e32 v227, 0xffff0000, v247
	v_pk_fma_f32 v[110:111], v[46:47], v[224:225], v[110:111]
	v_pk_fma_f32 v[112:113], v[48:49], v[226:227], v[112:113]
	s_nop 0
	v_cvt_pk_bf16_f32 v110, v110, v111
	v_cvt_pk_bf16_f32 v111, v112, v113
	global_store_dwordx2 v168, v[110:111], s[74:75] offset:96
	v_lshlrev_b32_e32 v228, 16, v248
	v_and_b32_e32 v229, 0xffff0000, v248
	v_lshlrev_b32_e32 v230, 16, v249
	v_and_b32_e32 v231, 0xffff0000, v249
	v_pk_fma_f32 v[114:115], v[50:51], v[228:229], v[114:115]
	v_pk_fma_f32 v[116:117], v[52:53], v[230:231], v[116:117]
	s_nop 0
	v_cvt_pk_bf16_f32 v114, v114, v115
	v_cvt_pk_bf16_f32 v115, v116, v117
	global_store_dwordx2 v169, v[114:115], s[74:75] offset:0
	v_lshlrev_b32_e32 v232, 16, v250
	v_and_b32_e32 v233, 0xffff0000, v250
	v_lshlrev_b32_e32 v234, 16, v251
	v_and_b32_e32 v235, 0xffff0000, v251
	v_pk_fma_f32 v[118:119], v[54:55], v[232:233], v[118:119]
	v_pk_fma_f32 v[120:121], v[56:57], v[234:235], v[120:121]
	s_nop 0
	v_cvt_pk_bf16_f32 v118, v118, v119
	v_cvt_pk_bf16_f32 v119, v120, v121
	global_store_dwordx2 v169, v[118:119], s[74:75] offset:32
	v_lshlrev_b32_e32 v236, 16, v166
	v_and_b32_e32 v237, 0xffff0000, v166
	v_lshlrev_b32_e32 v238, 16, v167
	v_and_b32_e32 v239, 0xffff0000, v167
	v_pk_fma_f32 v[122:123], v[58:59], v[236:237], v[122:123]
	v_pk_fma_f32 v[124:125], v[60:61], v[238:239], v[124:125]
	s_nop 0
	v_cvt_pk_bf16_f32 v122, v122, v123
	v_cvt_pk_bf16_f32 v123, v124, v125
	global_store_dwordx2 v169, v[122:123], s[74:75] offset:64
	v_lshlrev_b32_e32 v240, 16, v194
	v_and_b32_e32 v241, 0xffff0000, v194
	v_lshlrev_b32_e32 v242, 16, v195
	v_and_b32_e32 v243, 0xffff0000, v195
	v_pk_fma_f32 v[126:127], v[62:63], v[240:241], v[126:127]
	v_pk_fma_f32 v[128:129], v[64:65], v[242:243], v[128:129]
	s_nop 0
	v_cvt_pk_bf16_f32 v126, v126, v127
	v_cvt_pk_bf16_f32 v127, v128, v129
	global_store_dwordx2 v169, v[126:127], s[74:75] offset:96
